# v27 with the priority lowered after MFMA 20 instead of 23
# baseline (speedup 1.0000x reference)
;     ...
;   __syncthreads();
;   G2_STAGE(0); G2_STAGE(1);
;   const int fsw = (0x78 >> (((r16 >> 2) & 3) * 2)) & 3;
;   const int aoff = (wm * 128 + r16) * 64 + ((quad ^ fsw) << 4);
;   const int boff = 16384 + (wn * 64 + r16) * 64 + ((quad ^ fsw) << 4);
;   for (int kt = 0; kt < nk; kt++) {
;     if (kt + 1 < nk) asm volatile("s_waitcnt vmcnt(6)" ::: "memory");
;     else asm volatile("s_waitcnt vmcnt(0)" ::: "memory");
;     __builtin_amdgcn_s_barrier();
;     asm volatile("" ::: "memory");
;     if (kt + 2 < nk) G2_STAGE(kt + 2);
;     const char* cS = smem + (kt % 3) * 24576;
;     bf16x8 xa[8], wb[4];
; #pragma unroll
;     for (int f = 0; f < 8; f++) xa[f] = *(const bf16x8*)(cS + aoff + f * 1024);
; #pragma unroll
;     for (int f = 0; f < 4; f++) wb[f] = *(const bf16x8*)(cS + boff + f * 1024);
; #pragma unroll
;     for (int nf = 0; nf < 4; nf++)
; #pragma unroll
;       for (int mf = 0; mf < 8; mf++)
;         acc[nf][mf] = __builtin_amdgcn_mfma_f32_16x16x32_bf16(wb[nf], xa[mf], acc[nf][mf], 0, 0, 0);
.Lta11_loop:
	.p2align 3
	s_waitcnt vmcnt(6) lgkmcnt(0)
	s_barrier
	s_setprio 1
	v_add_u32_e32 v144, s40, v136
	v_mfma_f32_16x16x32_bf16 v[126:129], v[184:187], v[146:149], v[126:129]
	ds_read_b128 v[200:203], v144 offset:0
	v_mfma_f32_16x16x32_bf16 v[122:125], v[184:187], v[152:155], v[122:125]
	ds_read_b128 v[204:207], v144 offset:1024
	v_mfma_f32_16x16x32_bf16 v[118:121], v[184:187], v[156:159], v[118:121]
	ds_read_b128 v[208:211], v144 offset:2048
	v_mfma_f32_16x16x32_bf16 v[114:117], v[184:187], v[162:165], v[114:117]
	ds_read_b128 v[212:215], v144 offset:3072
	v_mfma_f32_16x16x32_bf16 v[110:113], v[184:187], v[166:169], v[110:113]
	ds_read_b128 v[216:219], v144 offset:4096
	v_mfma_f32_16x16x32_bf16 v[106:109], v[184:187], v[170:173], v[106:109]
	ds_read_b128 v[220:223], v144 offset:5120
	v_mfma_f32_16x16x32_bf16 v[102:105], v[184:187], v[176:179], v[102:105]
	ds_read_b128 v[224:227], v144 offset:6144
	v_mfma_f32_16x16x32_bf16 v[98:101], v[184:187], v[180:183], v[98:101]
	ds_read_b128 v[228:231], v144 offset:7168
	v_mfma_f32_16x16x32_bf16 v[94:97], v[188:191], v[146:149], v[94:97]
	v_add_u32_e64 v144, s40, v137
	v_mfma_f32_16x16x32_bf16 v[90:93], v[188:191], v[152:155], v[90:93]
	v_mfma_f32_16x16x32_bf16 v[86:89], v[188:191], v[156:159], v[86:89]
	ds_read_b128 v[232:235], v144 offset:16384
	v_mfma_f32_16x16x32_bf16 v[82:85], v[188:191], v[162:165], v[82:85]
	ds_read_b128 v[236:239], v144 offset:17408
	v_mfma_f32_16x16x32_bf16 v[78:81], v[188:191], v[166:169], v[78:81]
	ds_read_b128 v[240:243], v144 offset:18432
	v_mfma_f32_16x16x32_bf16 v[74:77], v[188:191], v[170:173], v[74:77]
	ds_read_b128 v[244:247], v144 offset:19456
	v_mfma_f32_16x16x32_bf16 v[70:73], v[188:191], v[176:179], v[70:73]
	s_add_i32 s42, s46, s41
	s_mov_b32 m0, s42
	v_lshl_add_u64 v[142:143], v[132:133], 0, s[2:3]
	v_mfma_f32_16x16x32_bf16 v[66:69], v[188:191], v[180:183], v[66:69]
	global_load_lds_dwordx4 v[132:133], off
	s_add_i32 m0, m0, 0x1000
	v_mfma_f32_16x16x32_bf16 v[62:65], v[192:195], v[146:149], v[62:65]
	v_mfma_f32_16x16x32_bf16 v[58:61], v[192:195], v[152:155], v[58:61]
	v_mfma_f32_16x16x32_bf16 v[54:57], v[192:195], v[156:159], v[54:57]
	global_load_lds_dwordx4 v[142:143], off
	v_lshl_add_u64 v[142:143], v[142:143], 0, s[2:3]
	s_add_i32 m0, m0, 0x1000
	v_mfma_f32_16x16x32_bf16 v[50:53], v[192:195], v[162:165], v[50:53]
	v_mfma_f32_16x16x32_bf16 v[46:49], v[192:195], v[166:169], v[46:49]
	s_setprio 0
	s_nop 0
	v_mfma_f32_16x16x32_bf16 v[42:45], v[192:195], v[170:173], v[42:45]
	global_load_lds_dwordx4 v[142:143], off
	v_lshl_add_u64 v[142:143], v[142:143], 0, s[2:3]
	s_add_i32 m0, m0, 0x1000
	v_mfma_f32_16x16x32_bf16 v[38:41], v[192:195], v[176:179], v[38:41]
	v_mfma_f32_16x16x32_bf16 v[34:37], v[192:195], v[180:183], v[34:37]
	v_mfma_f32_16x16x32_bf16 v[30:33], v[196:199], v[146:149], v[30:33]
	global_load_lds_dwordx4 v[142:143], off
	s_add_i32 m0, m0, 0x1000
	v_lshl_add_u64 v[142:143], v[134:135], 0, s[2:3]
	v_mfma_f32_16x16x32_bf16 v[26:29], v[196:199], v[152:155], v[26:29]
	v_mfma_f32_16x16x32_bf16 v[22:25], v[196:199], v[156:159], v[22:25]
	v_mfma_f32_16x16x32_bf16 v[18:21], v[196:199], v[162:165], v[18:21]
	global_load_lds_dwordx4 v[134:135], off
	s_add_i32 m0, m0, 0x1000
	v_lshl_add_u64 v[132:133], v[132:133], 0, s[12:13]
	v_mfma_f32_16x16x32_bf16 v[14:17], v[196:199], v[166:169], v[14:17]
	v_mfma_f32_16x16x32_bf16 v[10:13], v[196:199], v[170:173], v[10:13]
	v_mfma_f32_16x16x32_bf16 v[6:9], v[196:199], v[176:179], v[6:9]
	global_load_lds_dwordx4 v[142:143], off
	v_lshl_add_u64 v[134:135], v[134:135], 0, s[4:5]
	v_mfma_f32_16x16x32_bf16 v[2:5], v[196:199], v[180:183], v[2:5]
	s_mov_b32 s41, s40
	s_nop 0
	s_add_i32 s40, s40, 0x6000
	s_cmp_eq_u32 s40, 0x12000
	s_cselect_b32 s40, 0, s40
	s_nop 0
	.p2align 3
	s_waitcnt vmcnt(6) lgkmcnt(0)
	s_barrier
	s_setprio 1
	v_add_u32_e32 v144, s40, v136
	v_mfma_f32_16x16x32_bf16 v[126:129], v[232:235], v[200:203], v[126:129]
	ds_read_b128 v[146:149], v144 offset:0
	v_mfma_f32_16x16x32_bf16 v[122:125], v[232:235], v[204:207], v[122:125]
	ds_read_b128 v[152:155], v144 offset:1024
	v_mfma_f32_16x16x32_bf16 v[118:121], v[232:235], v[208:211], v[118:121]
	ds_read_b128 v[156:159], v144 offset:2048
	v_mfma_f32_16x16x32_bf16 v[114:117], v[232:235], v[212:215], v[114:117]
	ds_read_b128 v[162:165], v144 offset:3072
	v_mfma_f32_16x16x32_bf16 v[110:113], v[232:235], v[216:219], v[110:113]
	ds_read_b128 v[166:169], v144 offset:4096
	v_mfma_f32_16x16x32_bf16 v[106:109], v[232:235], v[220:223], v[106:109]
	ds_read_b128 v[170:173], v144 offset:5120
	v_mfma_f32_16x16x32_bf16 v[102:105], v[232:235], v[224:227], v[102:105]
	ds_read_b128 v[176:179], v144 offset:6144
	v_mfma_f32_16x16x32_bf16 v[98:101], v[232:235], v[228:231], v[98:101]
	ds_read_b128 v[180:183], v144 offset:7168
	v_mfma_f32_16x16x32_bf16 v[94:97], v[236:239], v[200:203], v[94:97]
	v_add_u32_e64 v144, s40, v137
	v_mfma_f32_16x16x32_bf16 v[90:93], v[236:239], v[204:207], v[90:93]
	v_mfma_f32_16x16x32_bf16 v[86:89], v[236:239], v[208:211], v[86:89]
	ds_read_b128 v[184:187], v144 offset:16384
	v_mfma_f32_16x16x32_bf16 v[82:85], v[236:239], v[212:215], v[82:85]
	ds_read_b128 v[188:191], v144 offset:17408
	v_mfma_f32_16x16x32_bf16 v[78:81], v[236:239], v[216:219], v[78:81]
	ds_read_b128 v[192:195], v144 offset:18432
	v_mfma_f32_16x16x32_bf16 v[74:77], v[236:239], v[220:223], v[74:77]
	ds_read_b128 v[196:199], v144 offset:19456
	v_mfma_f32_16x16x32_bf16 v[70:73], v[236:239], v[224:227], v[70:73]
	s_add_i32 s42, s46, s41
	s_mov_b32 m0, s42
	v_lshl_add_u64 v[142:143], v[132:133], 0, s[2:3]
	v_mfma_f32_16x16x32_bf16 v[66:69], v[236:239], v[228:231], v[66:69]
;     ...
;   __syncthreads();
;   G2_STAGE(0); G2_STAGE(1);
;   const int fsw = (0x78 >> (((r16 >> 2) & 3) * 2)) & 3;
;   const int aoff = (wm * 128 + r16) * 64 + ((quad ^ fsw) << 4);
;   const int boff = 16384 + (wn * 64 + r16) * 64 + ((quad ^ fsw) << 4);
;   for (int kt = 0; kt < nk; kt++) {
;     if (kt + 1 < nk) asm volatile("s_waitcnt vmcnt(6)" ::: "memory");
;     else asm volatile("s_waitcnt vmcnt(0)" ::: "memory");
;     __builtin_amdgcn_s_barrier();
;     asm volatile("" ::: "memory");
;     if (kt + 2 < nk) G2_STAGE(kt + 2);
;     const char* cS = smem + (kt % 3) * 24576;
;     bf16x8 xa[8], wb[4];
; #pragma unroll
;     for (int f = 0; f < 8; f++) xa[f] = *(const bf16x8*)(cS + aoff + f * 1024);
; #pragma unroll
;     for (int f = 0; f < 4; f++) wb[f] = *(const bf16x8*)(cS + boff + f * 1024);
; #pragma unroll
;     for (int nf = 0; nf < 4; nf++)
; #pragma unroll
;       for (int mf = 0; mf < 8; mf++)
;         acc[nf][mf] = __builtin_amdgcn_mfma_f32_16x16x32_bf16(wb[nf], xa[mf], acc[nf][mf], 0, 0, 0);
;   }
	global_load_lds_dwordx4 v[132:133], off
	s_add_i32 m0, m0, 0x1000
	v_mfma_f32_16x16x32_bf16 v[62:65], v[240:243], v[200:203], v[62:65]
	v_mfma_f32_16x16x32_bf16 v[58:61], v[240:243], v[204:207], v[58:61]
	v_mfma_f32_16x16x32_bf16 v[54:57], v[240:243], v[208:211], v[54:57]
	global_load_lds_dwordx4 v[142:143], off
	v_lshl_add_u64 v[142:143], v[142:143], 0, s[2:3]
	s_add_i32 m0, m0, 0x1000
	v_mfma_f32_16x16x32_bf16 v[50:53], v[240:243], v[212:215], v[50:53]
	v_mfma_f32_16x16x32_bf16 v[46:49], v[240:243], v[216:219], v[46:49]
	s_setprio 0
	s_nop 0
	v_mfma_f32_16x16x32_bf16 v[42:45], v[240:243], v[220:223], v[42:45]
	global_load_lds_dwordx4 v[142:143], off
	v_lshl_add_u64 v[142:143], v[142:143], 0, s[2:3]
	s_add_i32 m0, m0, 0x1000
	v_mfma_f32_16x16x32_bf16 v[38:41], v[240:243], v[224:227], v[38:41]
	v_mfma_f32_16x16x32_bf16 v[34:37], v[240:243], v[228:231], v[34:37]
	v_mfma_f32_16x16x32_bf16 v[30:33], v[244:247], v[200:203], v[30:33]
	global_load_lds_dwordx4 v[142:143], off
	s_add_i32 m0, m0, 0x1000
	v_lshl_add_u64 v[142:143], v[134:135], 0, s[2:3]
	v_mfma_f32_16x16x32_bf16 v[26:29], v[244:247], v[204:207], v[26:29]
	v_mfma_f32_16x16x32_bf16 v[22:25], v[244:247], v[208:211], v[22:25]
	v_mfma_f32_16x16x32_bf16 v[18:21], v[244:247], v[212:215], v[18:21]
	global_load_lds_dwordx4 v[134:135], off
	s_add_i32 m0, m0, 0x1000
	v_lshl_add_u64 v[132:133], v[132:133], 0, s[12:13]
	v_mfma_f32_16x16x32_bf16 v[14:17], v[244:247], v[216:219], v[14:17]
	v_mfma_f32_16x16x32_bf16 v[10:13], v[244:247], v[220:223], v[10:13]
	v_mfma_f32_16x16x32_bf16 v[6:9], v[244:247], v[224:227], v[6:9]
	global_load_lds_dwordx4 v[142:143], off
	v_lshl_add_u64 v[134:135], v[134:135], 0, s[4:5]
	v_mfma_f32_16x16x32_bf16 v[2:5], v[244:247], v[228:231], v[2:5]
	s_mov_b32 s41, s40
	s_nop 0
	s_add_i32 s40, s40, 0x6000
	s_cmp_eq_u32 s40, 0x12000
	s_cselect_b32 s40, 0, s40
	s_nop 0
	s_sub_i32 s39, s39, 1
	s_cmp_lg_u32 s39, 0
	s_cbranch_scc1 .Lta11_loop
	.p2align 3
	s_waitcnt vmcnt(6) lgkmcnt(0)
	s_barrier
	s_setprio 1
	v_add_u32_e32 v144, s40, v136
	v_mfma_f32_16x16x32_bf16 v[126:129], v[184:187], v[146:149], v[126:129]
	ds_read_b128 v[200:203], v144 offset:0
	v_mfma_f32_16x16x32_bf16 v[122:125], v[184:187], v[152:155], v[122:125]
	ds_read_b128 v[204:207], v144 offset:1024
	v_mfma_f32_16x16x32_bf16 v[118:121], v[184:187], v[156:159], v[118:121]
	ds_read_b128 v[208:211], v144 offset:2048
	v_mfma_f32_16x16x32_bf16 v[114:117], v[184:187], v[162:165], v[114:117]
	ds_read_b128 v[212:215], v144 offset:3072
	v_mfma_f32_16x16x32_bf16 v[110:113], v[184:187], v[166:169], v[110:113]
	ds_read_b128 v[216:219], v144 offset:4096
	v_mfma_f32_16x16x32_bf16 v[106:109], v[184:187], v[170:173], v[106:109]
	ds_read_b128 v[220:223], v144 offset:5120
	v_mfma_f32_16x16x32_bf16 v[102:105], v[184:187], v[176:179], v[102:105]
	ds_read_b128 v[224:227], v144 offset:6144
	v_mfma_f32_16x16x32_bf16 v[98:101], v[184:187], v[180:183], v[98:101]
	ds_read_b128 v[228:231], v144 offset:7168
	v_mfma_f32_16x16x32_bf16 v[94:97], v[188:191], v[146:149], v[94:97]
	v_add_u32_e64 v144, s40, v137
	v_mfma_f32_16x16x32_bf16 v[90:93], v[188:191], v[152:155], v[90:93]
	v_mfma_f32_16x16x32_bf16 v[86:89], v[188:191], v[156:159], v[86:89]
	ds_read_b128 v[232:235], v144 offset:16384
	v_mfma_f32_16x16x32_bf16 v[82:85], v[188:191], v[162:165], v[82:85]
	ds_read_b128 v[236:239], v144 offset:17408
	v_mfma_f32_16x16x32_bf16 v[78:81], v[188:191], v[166:169], v[78:81]
	ds_read_b128 v[240:243], v144 offset:18432
	v_mfma_f32_16x16x32_bf16 v[74:77], v[188:191], v[170:173], v[74:77]
	ds_read_b128 v[244:247], v144 offset:19456
	v_mfma_f32_16x16x32_bf16 v[70:73], v[188:191], v[176:179], v[70:73]
	s_add_i32 s42, s46, s41
	s_mov_b32 m0, s42
	v_lshl_add_u64 v[142:143], v[132:133], 0, s[2:3]
	v_mfma_f32_16x16x32_bf16 v[66:69], v[188:191], v[180:183], v[66:69]
	global_load_lds_dwordx4 v[132:133], off
	s_add_i32 m0, m0, 0x1000
	v_mfma_f32_16x16x32_bf16 v[62:65], v[192:195], v[146:149], v[62:65]
	v_mfma_f32_16x16x32_bf16 v[58:61], v[192:195], v[152:155], v[58:61]
	v_mfma_f32_16x16x32_bf16 v[54:57], v[192:195], v[156:159], v[54:57]
	global_load_lds_dwordx4 v[142:143], off
	v_lshl_add_u64 v[142:143], v[142:143], 0, s[2:3]
	s_add_i32 m0, m0, 0x1000
	v_mfma_f32_16x16x32_bf16 v[50:53], v[192:195], v[162:165], v[50:53]
	v_mfma_f32_16x16x32_bf16 v[46:49], v[192:195], v[166:169], v[46:49]
	s_setprio 0
	s_nop 0
	v_mfma_f32_16x16x32_bf16 v[42:45], v[192:195], v[170:173], v[42:45]
	global_load_lds_dwordx4 v[142:143], off
	v_lshl_add_u64 v[142:143], v[142:143], 0, s[2:3]
	s_add_i32 m0, m0, 0x1000
	v_mfma_f32_16x16x32_bf16 v[38:41], v[192:195], v[176:179], v[38:41]
	v_mfma_f32_16x16x32_bf16 v[34:37], v[192:195], v[180:183], v[34:37]
	v_mfma_f32_16x16x32_bf16 v[30:33], v[196:199], v[146:149], v[30:33]
	global_load_lds_dwordx4 v[142:143], off
	s_add_i32 m0, m0, 0x1000
	v_lshl_add_u64 v[142:143], v[134:135], 0, s[2:3]
	v_mfma_f32_16x16x32_bf16 v[26:29], v[196:199], v[152:155], v[26:29]
	v_mfma_f32_16x16x32_bf16 v[22:25], v[196:199], v[156:159], v[22:25]
	v_mfma_f32_16x16x32_bf16 v[18:21], v[196:199], v[162:165], v[18:21]
	global_load_lds_dwordx4 v[134:135], off
	s_add_i32 m0, m0, 0x1000
	v_lshl_add_u64 v[132:133], v[132:133], 0, s[12:13]
	v_mfma_f32_16x16x32_bf16 v[14:17], v[196:199], v[166:169], v[14:17]
	v_mfma_f32_16x16x32_bf16 v[10:13], v[196:199], v[170:173], v[10:13]
	v_mfma_f32_16x16x32_bf16 v[6:9], v[196:199], v[176:179], v[6:9]
	global_load_lds_dwordx4 v[142:143], off
	v_lshl_add_u64 v[134:135], v[134:135], 0, s[4:5]
	v_mfma_f32_16x16x32_bf16 v[2:5], v[196:199], v[180:183], v[2:5]
	s_mov_b32 s41, s40
	s_nop 0
	s_add_i32 s40, s40, 0x6000
	s_cmp_eq_u32 s40, 0x12000
	s_cselect_b32 s40, 0, s40
	s_nop 0
	.p2align 3
	s_waitcnt vmcnt(6) lgkmcnt(0)
	s_barrier
;     ...
;   for (int kt = 0; kt < nk; kt++) {
;     if (kt + 1 < nk) asm volatile("s_waitcnt vmcnt(6)" ::: "memory");
;     else asm volatile("s_waitcnt vmcnt(0)" ::: "memory");
;     __builtin_amdgcn_s_barrier();
;     asm volatile("" ::: "memory");
;     if (kt + 2 < nk) G2_STAGE(kt + 2);
;     const char* cS = smem + (kt % 3) * 24576;
;     bf16x8 xa[8], wb[4];
; #pragma unroll
;     for (int f = 0; f < 8; f++) xa[f] = *(const bf16x8*)(cS + aoff + f * 1024);
; #pragma unroll
;     for (int f = 0; f < 4; f++) wb[f] = *(const bf16x8*)(cS + boff + f * 1024);
; #pragma unroll
;     for (int nf = 0; nf < 4; nf++)
; #pragma unroll
;       for (int mf = 0; mf < 8; mf++)
;         acc[nf][mf] = __builtin_amdgcn_mfma_f32_16x16x32_bf16(wb[nf], xa[mf], acc[nf][mf], 0, 0, 0);
;   }
	s_setprio 1
	v_add_u32_e32 v144, s40, v136
	v_mfma_f32_16x16x32_bf16 v[126:129], v[232:235], v[200:203], v[126:129]
	ds_read_b128 v[146:149], v144 offset:0
	v_mfma_f32_16x16x32_bf16 v[122:125], v[232:235], v[204:207], v[122:125]
	ds_read_b128 v[152:155], v144 offset:1024
	v_mfma_f32_16x16x32_bf16 v[118:121], v[232:235], v[208:211], v[118:121]
	ds_read_b128 v[156:159], v144 offset:2048
	v_mfma_f32_16x16x32_bf16 v[114:117], v[232:235], v[212:215], v[114:117]
	ds_read_b128 v[162:165], v144 offset:3072
	v_mfma_f32_16x16x32_bf16 v[110:113], v[232:235], v[216:219], v[110:113]
	ds_read_b128 v[166:169], v144 offset:4096
	v_mfma_f32_16x16x32_bf16 v[106:109], v[232:235], v[220:223], v[106:109]
	ds_read_b128 v[170:173], v144 offset:5120
	v_mfma_f32_16x16x32_bf16 v[102:105], v[232:235], v[224:227], v[102:105]
	ds_read_b128 v[176:179], v144 offset:6144
	v_mfma_f32_16x16x32_bf16 v[98:101], v[232:235], v[228:231], v[98:101]
	ds_read_b128 v[180:183], v144 offset:7168
	v_mfma_f32_16x16x32_bf16 v[94:97], v[236:239], v[200:203], v[94:97]
	v_add_u32_e64 v144, s40, v137
	v_mfma_f32_16x16x32_bf16 v[90:93], v[236:239], v[204:207], v[90:93]
	v_mfma_f32_16x16x32_bf16 v[86:89], v[236:239], v[208:211], v[86:89]
	ds_read_b128 v[184:187], v144 offset:16384
	v_mfma_f32_16x16x32_bf16 v[82:85], v[236:239], v[212:215], v[82:85]
	ds_read_b128 v[188:191], v144 offset:17408
	v_mfma_f32_16x16x32_bf16 v[78:81], v[236:239], v[216:219], v[78:81]
	ds_read_b128 v[192:195], v144 offset:18432
	v_mfma_f32_16x16x32_bf16 v[74:77], v[236:239], v[220:223], v[74:77]
	ds_read_b128 v[196:199], v144 offset:19456
	v_mfma_f32_16x16x32_bf16 v[70:73], v[236:239], v[224:227], v[70:73]
	v_mfma_f32_16x16x32_bf16 v[66:69], v[236:239], v[228:231], v[66:69]
	v_mfma_f32_16x16x32_bf16 v[62:65], v[240:243], v[200:203], v[62:65]
	v_mfma_f32_16x16x32_bf16 v[58:61], v[240:243], v[204:207], v[58:61]
	v_mfma_f32_16x16x32_bf16 v[54:57], v[240:243], v[208:211], v[54:57]
	v_mfma_f32_16x16x32_bf16 v[50:53], v[240:243], v[212:215], v[50:53]
	v_mfma_f32_16x16x32_bf16 v[46:49], v[240:243], v[216:219], v[46:49]
	s_setprio 0
	s_nop 0
	v_mfma_f32_16x16x32_bf16 v[42:45], v[240:243], v[220:223], v[42:45]
	v_mfma_f32_16x16x32_bf16 v[38:41], v[240:243], v[224:227], v[38:41]
	v_mfma_f32_16x16x32_bf16 v[34:37], v[240:243], v[228:231], v[34:37]
	v_mfma_f32_16x16x32_bf16 v[30:33], v[244:247], v[200:203], v[30:33]
	v_mfma_f32_16x16x32_bf16 v[26:29], v[244:247], v[204:207], v[26:29]
	v_mfma_f32_16x16x32_bf16 v[22:25], v[244:247], v[208:211], v[22:25]
	v_mfma_f32_16x16x32_bf16 v[18:21], v[244:247], v[212:215], v[18:21]
	v_mfma_f32_16x16x32_bf16 v[14:17], v[244:247], v[216:219], v[14:17]
	v_mfma_f32_16x16x32_bf16 v[10:13], v[244:247], v[220:223], v[10:13]
	v_mfma_f32_16x16x32_bf16 v[6:9], v[244:247], v[224:227], v[6:9]
	v_mfma_f32_16x16x32_bf16 v[2:5], v[244:247], v[228:231], v[2:5]
	s_mov_b32 s41, s40
	s_nop 0
	s_add_i32 s40, s40, 0x6000
	s_cmp_eq_u32 s40, 0x12000
	s_cselect_b32 s40, 0, s40
	s_nop 0
	.p2align 3
	s_waitcnt vmcnt(0) lgkmcnt(0)
	s_barrier
	s_setprio 1
	v_add_u32_e32 v144, s40, v136
	v_mfma_f32_16x16x32_bf16 v[126:129], v[184:187], v[146:149], v[126:129]
	ds_read_b128 v[200:203], v144 offset:0
	v_mfma_f32_16x16x32_bf16 v[122:125], v[184:187], v[152:155], v[122:125]
	ds_read_b128 v[204:207], v144 offset:1024
	v_mfma_f32_16x16x32_bf16 v[118:121], v[184:187], v[156:159], v[118:121]
	ds_read_b128 v[208:211], v144 offset:2048
	v_mfma_f32_16x16x32_bf16 v[114:117], v[184:187], v[162:165], v[114:117]
	ds_read_b128 v[212:215], v144 offset:3072
	v_mfma_f32_16x16x32_bf16 v[110:113], v[184:187], v[166:169], v[110:113]
	ds_read_b128 v[216:219], v144 offset:4096
	v_mfma_f32_16x16x32_bf16 v[106:109], v[184:187], v[170:173], v[106:109]
	ds_read_b128 v[220:223], v144 offset:5120
	v_mfma_f32_16x16x32_bf16 v[102:105], v[184:187], v[176:179], v[102:105]
	ds_read_b128 v[224:227], v144 offset:6144
	v_mfma_f32_16x16x32_bf16 v[98:101], v[184:187], v[180:183], v[98:101]
	ds_read_b128 v[228:231], v144 offset:7168
	v_mfma_f32_16x16x32_bf16 v[94:97], v[188:191], v[146:149], v[94:97]
	v_add_u32_e64 v144, s40, v137
	v_mfma_f32_16x16x32_bf16 v[90:93], v[188:191], v[152:155], v[90:93]
	v_mfma_f32_16x16x32_bf16 v[86:89], v[188:191], v[156:159], v[86:89]
	ds_read_b128 v[232:235], v144 offset:16384
	v_mfma_f32_16x16x32_bf16 v[82:85], v[188:191], v[162:165], v[82:85]
	ds_read_b128 v[236:239], v144 offset:17408
	v_mfma_f32_16x16x32_bf16 v[78:81], v[188:191], v[166:169], v[78:81]
	ds_read_b128 v[240:243], v144 offset:18432
	v_mfma_f32_16x16x32_bf16 v[74:77], v[188:191], v[170:173], v[74:77]
	ds_read_b128 v[244:247], v144 offset:19456
	v_mfma_f32_16x16x32_bf16 v[70:73], v[188:191], v[176:179], v[70:73]
	v_mfma_f32_16x16x32_bf16 v[66:69], v[188:191], v[180:183], v[66:69]
	v_mfma_f32_16x16x32_bf16 v[62:65], v[192:195], v[146:149], v[62:65]
	v_mfma_f32_16x16x32_bf16 v[58:61], v[192:195], v[152:155], v[58:61]
	v_mfma_f32_16x16x32_bf16 v[54:57], v[192:195], v[156:159], v[54:57]
	v_mfma_f32_16x16x32_bf16 v[50:53], v[192:195], v[162:165], v[50:53]
	v_mfma_f32_16x16x32_bf16 v[46:49], v[192:195], v[166:169], v[46:49]
	s_setprio 0
	s_nop 0
	v_mfma_f32_16x16x32_bf16 v[42:45], v[192:195], v[170:173], v[42:45]
	v_mfma_f32_16x16x32_bf16 v[38:41], v[192:195], v[176:179], v[38:41]
	v_mfma_f32_16x16x32_bf16 v[34:37], v[192:195], v[180:183], v[34:37]
	v_mfma_f32_16x16x32_bf16 v[30:33], v[196:199], v[146:149], v[30:33]
	v_mfma_f32_16x16x32_bf16 v[26:29], v[196:199], v[152:155], v[26:29]
	v_mfma_f32_16x16x32_bf16 v[22:25], v[196:199], v[156:159], v[22:25]
	v_mfma_f32_16x16x32_bf16 v[18:21], v[196:199], v[162:165], v[18:21]
	v_mfma_f32_16x16x32_bf16 v[14:17], v[196:199], v[166:169], v[14:17]
	v_mfma_f32_16x16x32_bf16 v[10:13], v[196:199], v[170:173], v[10:13]
	v_mfma_f32_16x16x32_bf16 v[6:9], v[196:199], v[176:179], v[6:9]
	v_mfma_f32_16x16x32_bf16 v[2:5], v[196:199], v[180:183], v[2:5]
	s_mov_b32 s41, s40
	s_nop 0
	s_add_i32 s40, s40, 0x6000
	s_cmp_eq_u32 s40, 0x12000
	s_cselect_b32 s40, 0, s40
	s_nop 0
	s_mov_b32 s4, 0x8000
	s_mov_b32 s5, 0
	s_mov_b32 s10, 0x10000
	s_mov_b32 s11, 0
	s_mov_b32 s44, 0x3fd744fd
	.p2align 3
	s_waitcnt lgkmcnt(0)
; DEVI unsigned pack2(float a, float b) { return __builtin_bit_cast(unsigned, __builtin_convertvector((f32x2_t){a, b}, bf16x2_t)); }
; DEVI float blo(unsigned u) { return __uint_as_float(u << 16); }
; DEVI float bhi(unsigned u) { return __uint_as_float(u & 0xffff0000u); }
;     ...
;     for (int nf = 0; nf < 4; nf++)
; #pragma unroll
;       for (int mf = 0; mf < 8; mf++)
;         acc[nf][mf] = __builtin_amdgcn_mfma_f32_16x16x32_bf16(wb[nf], xa[mf], acc[nf][mf], 0, 0, 0);
;   }
;     ...
; #pragma unroll
;   for (int mf = 0; mf < 8; mf++) {
;     const int row = m0 + wm * 128 + mf * 16 + r16;
;     if (EPI == EPI_SWIGLU) {
; #pragma unroll
;       for (int nf = 0; nf < 2; nf++) {
;         const int hcol = (n0 >> 1) + wn * 32 + nf * 16 + quad * 4;
;         f32x4 g = acc[nf][mf], u = acc[nf + 2][mf];
;         u32x2 pk;
;         pk[0] = pack2(siluf_(g[0]) * u[0], siluf_(g[1]) * u[1]);
;         pk[1] = pack2(siluf_(g[2]) * u[2], siluf_(g[3]) * u[3]);
;         *(u32x2*)(outb + (size_t)row * DFF + hcol) = pk;
;       }
;     } else {
; #pragma unroll
;       for (int nf = 0; nf < 4; nf++) {
;         const int col = n0 + wn * 64 + nf * 16 + quad * 4;
;         f32x4 a = acc[nf][mf];
;         if (EPI == EPI_RESID || EPI == EPI_RESID_ATOMIC) {
;           f32x4 x = a;
;           if (EPI == EPI_RESID || kpart == 0) {
;             const u32x2 xr = *(const u32x2*)((const u16*)(p.ws + WS_XB) + (size_t)row * 1024 + col);
;             x[0] += ALPHA * blo(xr[0]); x[1] += ALPHA * bhi(xr[0]); x[2] += ALPHA * blo(xr[1]); x[3] += ALPHA * bhi(xr[1]);
;           }
;           if (EPI == EPI_RESID) *(f32x4*)((float*)(p.ws + WS_XF) + (size_t)row * 1024 + col) = x;
;           else *(f32x4*)((float*)(p.ws + WS_SLAB) + ((size_t)kpart * 512 + (row - T_P)) * 1024 + col) = x;
; DEVI void run_phase(const Params& p, int ph, char* smem) {
;     ...
;       for (int t = xcd_first_tile(); t < 512 + 16 * 11; t += xcd_tile_step()) {
;         if (t < 512) {
;           int mt_, nt_; tile_coords(t, 64, 8, mt_, nt_);
;           gemm_tile256<EPI_RESID>(p, hb, DFF, Bt, DFF, mt_ * 256, nt_ * 128, nullptr, 0, smem);
;         } else {
;           const int u_ = t - 512, tl_ = u_ / 11, q_ = u_ - tl_ * 11;
;           gemm_tile256<EPI_RESID_ATOMIC>(p, hb, DFF, Bt, DFF, (64 + (tl_ & 1)) * 256, (tl_ >> 1) * 128, nullptr, 0, smem, q_ * 256, 8, q_);
;         }
	s_nop 0
	v_mfma_f32_16x16x32_bf16 v[126:129], v[232:235], v[200:203], v[126:129]
	v_mfma_f32_16x16x32_bf16 v[122:125], v[232:235], v[204:207], v[122:125]
	v_mfma_f32_16x16x32_bf16 v[118:121], v[232:235], v[208:211], v[118:121]
	v_mfma_f32_16x16x32_bf16 v[114:117], v[232:235], v[212:215], v[114:117]
	v_mfma_f32_16x16x32_bf16 v[110:113], v[232:235], v[216:219], v[110:113]
	v_mfma_f32_16x16x32_bf16 v[106:109], v[232:235], v[220:223], v[106:109]
	v_mfma_f32_16x16x32_bf16 v[102:105], v[232:235], v[224:227], v[102:105]
	v_mfma_f32_16x16x32_bf16 v[98:101], v[232:235], v[228:231], v[98:101]
	v_mfma_f32_16x16x32_bf16 v[94:97], v[236:239], v[200:203], v[94:97]
	v_mfma_f32_16x16x32_bf16 v[90:93], v[236:239], v[204:207], v[90:93]
	v_mfma_f32_16x16x32_bf16 v[86:89], v[236:239], v[208:211], v[86:89]
	v_mfma_f32_16x16x32_bf16 v[82:85], v[236:239], v[212:215], v[82:85]
	v_mfma_f32_16x16x32_bf16 v[78:81], v[236:239], v[216:219], v[78:81]
	v_mfma_f32_16x16x32_bf16 v[74:77], v[236:239], v[220:223], v[74:77]
	v_mfma_f32_16x16x32_bf16 v[70:73], v[236:239], v[224:227], v[70:73]
	v_mfma_f32_16x16x32_bf16 v[66:69], v[236:239], v[228:231], v[66:69]
	v_mfma_f32_16x16x32_bf16 v[62:65], v[240:243], v[200:203], v[62:65]
	v_mfma_f32_16x16x32_bf16 v[58:61], v[240:243], v[204:207], v[58:61]
	v_mfma_f32_16x16x32_bf16 v[54:57], v[240:243], v[208:211], v[54:57]
	v_mfma_f32_16x16x32_bf16 v[50:53], v[240:243], v[212:215], v[50:53]
	v_mfma_f32_16x16x32_bf16 v[46:49], v[240:243], v[216:219], v[46:49]
	v_mfma_f32_16x16x32_bf16 v[42:45], v[240:243], v[220:223], v[42:45]
	v_mfma_f32_16x16x32_bf16 v[38:41], v[240:243], v[224:227], v[38:41]
	v_mfma_f32_16x16x32_bf16 v[34:37], v[240:243], v[228:231], v[34:37]
	v_mfma_f32_16x16x32_bf16 v[30:33], v[244:247], v[200:203], v[30:33]
	v_mfma_f32_16x16x32_bf16 v[26:29], v[244:247], v[204:207], v[26:29]
	v_mfma_f32_16x16x32_bf16 v[22:25], v[244:247], v[208:211], v[22:25]
	v_mfma_f32_16x16x32_bf16 v[18:21], v[244:247], v[212:215], v[18:21]
	v_mfma_f32_16x16x32_bf16 v[14:17], v[244:247], v[216:219], v[14:17]
	v_mfma_f32_16x16x32_bf16 v[10:13], v[244:247], v[220:223], v[10:13]
	v_mfma_f32_16x16x32_bf16 v[6:9], v[244:247], v[224:227], v[6:9]
	v_mfma_f32_16x16x32_bf16 v[2:5], v[244:247], v[228:231], v[2:5]
	s_mov_b32 m0, s43
	s_cmp_eq_u32 s47, 0
	s_cbranch_scc1 .Lta11_first
	s_nop 7
	global_store_dwordx4 v[140:141], v[126:129], off offset:0
	global_store_dwordx4 v[140:141], v[94:97], off offset:64
	global_store_dwordx4 v[140:141], v[62:65], off offset:128
	global_store_dwordx4 v[140:141], v[30:33], off offset:192
	v_lshl_add_u64 v[140:141], v[140:141], 0, s[10:11]
	global_store_dwordx4 v[140:141], v[122:125], off offset:0
	global_store_dwordx4 v[140:141], v[90:93], off offset:64
	global_store_dwordx4 v[140:141], v[58:61], off offset:128
	global_store_dwordx4 v[140:141], v[26:29], off offset:192
	v_lshl_add_u64 v[140:141], v[140:141], 0, s[10:11]
	global_store_dwordx4 v[140:141], v[118:121], off offset:0
	global_store_dwordx4 v[140:141], v[86:89], off offset:64
	global_store_dwordx4 v[140:141], v[54:57], off offset:128
	global_store_dwordx4 v[140:141], v[22:25], off offset:192
	v_lshl_add_u64 v[140:141], v[140:141], 0, s[10:11]
	global_store_dwordx4 v[140:141], v[114:117], off offset:0
	global_store_dwordx4 v[140:141], v[82:85], off offset:64
	global_store_dwordx4 v[140:141], v[50:53], off offset:128
	global_store_dwordx4 v[140:141], v[18:21], off offset:192
	v_lshl_add_u64 v[140:141], v[140:141], 0, s[10:11]
	global_store_dwordx4 v[140:141], v[110:113], off offset:0
	global_store_dwordx4 v[140:141], v[78:81], off offset:64
	global_store_dwordx4 v[140:141], v[46:49], off offset:128
	global_store_dwordx4 v[140:141], v[14:17], off offset:192
	v_lshl_add_u64 v[140:141], v[140:141], 0, s[10:11]
	global_store_dwordx4 v[140:141], v[106:109], off offset:0
	global_store_dwordx4 v[140:141], v[74:77], off offset:64
	global_store_dwordx4 v[140:141], v[42:45], off offset:128
	global_store_dwordx4 v[140:141], v[10:13], off offset:192
	v_lshl_add_u64 v[140:141], v[140:141], 0, s[10:11]
	global_store_dwordx4 v[140:141], v[102:105], off offset:0
	global_store_dwordx4 v[140:141], v[70:73], off offset:64
	global_store_dwordx4 v[140:141], v[38:41], off offset:128
	global_store_dwordx4 v[140:141], v[6:9], off offset:192
	v_lshl_add_u64 v[140:141], v[140:141], 0, s[10:11]
	global_store_dwordx4 v[140:141], v[98:101], off offset:0
	global_store_dwordx4 v[140:141], v[66:69], off offset:64
	global_store_dwordx4 v[140:141], v[34:37], off offset:128
	global_store_dwordx4 v[140:141], v[2:5], off offset:192
	v_readlane_b32 s39, v250, 7
	s_cmpk_lg_u32 s39, 0x200
	s_cbranch_scc1 .Lta11_ar1
	s_mov_b32 s39, 1
	v_writelane_b32 v255, s39, 41
	v_readlane_b32 s40, v250, 0
	s_lshr_b32 s41, s40, 3
	s_and_b32 s40, s40, 7
	s_lshl_b32 s40, s40, 6
	s_add_i32 s40, s40, s41
	s_sub_i32 s38, s40, 0x200

;     ...
;   __syncthreads();
;   G2_STAGE(0); G2_STAGE(1);
;   const int fsw = (0x78 >> (((r16 >> 2) & 3) * 2)) & 3;
;   const int aoff = (wm * 128 + r16) * 64 + ((quad ^ fsw) << 4);
;   const int boff = 16384 + (wn * 64 + r16) * 64 + ((quad ^ fsw) << 4);
;   for (int kt = 0; kt < nk; kt++) {
;     if (kt + 1 < nk) asm volatile("s_waitcnt vmcnt(6)" ::: "memory");
;     else asm volatile("s_waitcnt vmcnt(0)" ::: "memory");
;     __builtin_amdgcn_s_barrier();
;     asm volatile("" ::: "memory");
;     if (kt + 2 < nk) G2_STAGE(kt + 2);
;     const char* cS = smem + (kt % 3) * 24576;
;     bf16x8 xa[8], wb[4];
; #pragma unroll
;     for (int f = 0; f < 8; f++) xa[f] = *(const bf16x8*)(cS + aoff + f * 1024);
; #pragma unroll
;     for (int f = 0; f < 4; f++) wb[f] = *(const bf16x8*)(cS + boff + f * 1024);
; #pragma unroll
;     for (int nf = 0; nf < 4; nf++)
; #pragma unroll
;       for (int mf = 0; mf < 8; mf++)
;         acc[nf][mf] = __builtin_amdgcn_mfma_f32_16x16x32_bf16(wb[nf], xa[mf], acc[nf][mf], 0, 0, 0);
;   }
.Lt11_loop:
	.p2align 3
	s_waitcnt vmcnt(6) lgkmcnt(0)
	s_barrier
	s_setprio 1
	v_add_u32_e32 v144, s40, v136
	v_mfma_f32_16x16x32_bf16 v[126:129], v[184:187], v[146:149], v[126:129]
	ds_read_b128 v[200:203], v144 offset:0
	v_mfma_f32_16x16x32_bf16 v[122:125], v[184:187], v[152:155], v[122:125]
	ds_read_b128 v[204:207], v144 offset:1024
	v_mfma_f32_16x16x32_bf16 v[118:121], v[184:187], v[156:159], v[118:121]
	ds_read_b128 v[208:211], v144 offset:2048
	v_mfma_f32_16x16x32_bf16 v[114:117], v[184:187], v[162:165], v[114:117]
	ds_read_b128 v[212:215], v144 offset:3072
	v_mfma_f32_16x16x32_bf16 v[110:113], v[184:187], v[166:169], v[110:113]
	ds_read_b128 v[216:219], v144 offset:4096
	v_mfma_f32_16x16x32_bf16 v[106:109], v[184:187], v[170:173], v[106:109]
	ds_read_b128 v[220:223], v144 offset:5120
	v_mfma_f32_16x16x32_bf16 v[102:105], v[184:187], v[176:179], v[102:105]
	ds_read_b128 v[224:227], v144 offset:6144
	v_mfma_f32_16x16x32_bf16 v[98:101], v[184:187], v[180:183], v[98:101]
	ds_read_b128 v[228:231], v144 offset:7168
	v_mfma_f32_16x16x32_bf16 v[94:97], v[188:191], v[146:149], v[94:97]
	v_add_u32_e64 v144, s40, v137
	v_mfma_f32_16x16x32_bf16 v[90:93], v[188:191], v[152:155], v[90:93]
	v_mfma_f32_16x16x32_bf16 v[86:89], v[188:191], v[156:159], v[86:89]
	ds_read_b128 v[232:235], v144 offset:16384
	v_mfma_f32_16x16x32_bf16 v[82:85], v[188:191], v[162:165], v[82:85]
	ds_read_b128 v[236:239], v144 offset:17408
	v_mfma_f32_16x16x32_bf16 v[78:81], v[188:191], v[166:169], v[78:81]
	ds_read_b128 v[240:243], v144 offset:18432
	v_mfma_f32_16x16x32_bf16 v[74:77], v[188:191], v[170:173], v[74:77]
	ds_read_b128 v[244:247], v144 offset:19456
	v_mfma_f32_16x16x32_bf16 v[70:73], v[188:191], v[176:179], v[70:73]
	s_add_i32 s42, s46, s41
	s_mov_b32 m0, s42
	v_lshl_add_u64 v[142:143], v[132:133], 0, s[2:3]
	v_mfma_f32_16x16x32_bf16 v[66:69], v[188:191], v[180:183], v[66:69]
	global_load_lds_dwordx4 v[132:133], off
	s_add_i32 m0, m0, 0x1000
	v_mfma_f32_16x16x32_bf16 v[62:65], v[192:195], v[146:149], v[62:65]
	v_mfma_f32_16x16x32_bf16 v[58:61], v[192:195], v[152:155], v[58:61]
	v_mfma_f32_16x16x32_bf16 v[54:57], v[192:195], v[156:159], v[54:57]
	global_load_lds_dwordx4 v[142:143], off
	v_lshl_add_u64 v[142:143], v[142:143], 0, s[2:3]
	s_add_i32 m0, m0, 0x1000
	v_mfma_f32_16x16x32_bf16 v[50:53], v[192:195], v[162:165], v[50:53]
	v_mfma_f32_16x16x32_bf16 v[46:49], v[192:195], v[166:169], v[46:49]
	s_setprio 0
	s_nop 0
	v_mfma_f32_16x16x32_bf16 v[42:45], v[192:195], v[170:173], v[42:45]
	global_load_lds_dwordx4 v[142:143], off
	v_lshl_add_u64 v[142:143], v[142:143], 0, s[2:3]
	s_add_i32 m0, m0, 0x1000
	v_mfma_f32_16x16x32_bf16 v[38:41], v[192:195], v[176:179], v[38:41]
	v_mfma_f32_16x16x32_bf16 v[34:37], v[192:195], v[180:183], v[34:37]
	v_mfma_f32_16x16x32_bf16 v[30:33], v[196:199], v[146:149], v[30:33]
	global_load_lds_dwordx4 v[142:143], off
	s_add_i32 m0, m0, 0x1000
	v_lshl_add_u64 v[142:143], v[134:135], 0, s[2:3]
	v_mfma_f32_16x16x32_bf16 v[26:29], v[196:199], v[152:155], v[26:29]
	v_mfma_f32_16x16x32_bf16 v[22:25], v[196:199], v[156:159], v[22:25]
	v_mfma_f32_16x16x32_bf16 v[18:21], v[196:199], v[162:165], v[18:21]
	global_load_lds_dwordx4 v[134:135], off
	s_add_i32 m0, m0, 0x1000
	v_lshl_add_u64 v[132:133], v[132:133], 0, s[12:13]
	v_mfma_f32_16x16x32_bf16 v[14:17], v[196:199], v[166:169], v[14:17]
	v_mfma_f32_16x16x32_bf16 v[10:13], v[196:199], v[170:173], v[10:13]
	v_mfma_f32_16x16x32_bf16 v[6:9], v[196:199], v[176:179], v[6:9]
	global_load_lds_dwordx4 v[142:143], off
	v_lshl_add_u64 v[134:135], v[134:135], 0, s[4:5]
	v_mfma_f32_16x16x32_bf16 v[2:5], v[196:199], v[180:183], v[2:5]
	s_mov_b32 s41, s40
	s_nop 0
	s_add_i32 s40, s40, 0x6000
	s_cmp_eq_u32 s40, 0x12000
	s_cselect_b32 s40, 0, s40
	s_nop 0
	.p2align 3
	s_waitcnt vmcnt(6) lgkmcnt(0)
	s_barrier
	s_setprio 1
	v_add_u32_e32 v144, s40, v136
	v_mfma_f32_16x16x32_bf16 v[126:129], v[232:235], v[200:203], v[126:129]
	ds_read_b128 v[146:149], v144 offset:0
	v_mfma_f32_16x16x32_bf16 v[122:125], v[232:235], v[204:207], v[122:125]
	ds_read_b128 v[152:155], v144 offset:1024
	v_mfma_f32_16x16x32_bf16 v[118:121], v[232:235], v[208:211], v[118:121]
	ds_read_b128 v[156:159], v144 offset:2048
	v_mfma_f32_16x16x32_bf16 v[114:117], v[232:235], v[212:215], v[114:117]
	ds_read_b128 v[162:165], v144 offset:3072
	v_mfma_f32_16x16x32_bf16 v[110:113], v[232:235], v[216:219], v[110:113]
	ds_read_b128 v[166:169], v144 offset:4096
	v_mfma_f32_16x16x32_bf16 v[106:109], v[232:235], v[220:223], v[106:109]
	ds_read_b128 v[170:173], v144 offset:5120
	v_mfma_f32_16x16x32_bf16 v[102:105], v[232:235], v[224:227], v[102:105]
	ds_read_b128 v[176:179], v144 offset:6144
	v_mfma_f32_16x16x32_bf16 v[98:101], v[232:235], v[228:231], v[98:101]
	ds_read_b128 v[180:183], v144 offset:7168
	v_mfma_f32_16x16x32_bf16 v[94:97], v[236:239], v[200:203], v[94:97]
	v_add_u32_e64 v144, s40, v137
	v_mfma_f32_16x16x32_bf16 v[90:93], v[236:239], v[204:207], v[90:93]
	v_mfma_f32_16x16x32_bf16 v[86:89], v[236:239], v[208:211], v[86:89]
	ds_read_b128 v[184:187], v144 offset:16384
	v_mfma_f32_16x16x32_bf16 v[82:85], v[236:239], v[212:215], v[82:85]
	ds_read_b128 v[188:191], v144 offset:17408
	v_mfma_f32_16x16x32_bf16 v[78:81], v[236:239], v[216:219], v[78:81]
	ds_read_b128 v[192:195], v144 offset:18432
	v_mfma_f32_16x16x32_bf16 v[74:77], v[236:239], v[220:223], v[74:77]
	ds_read_b128 v[196:199], v144 offset:19456
	v_mfma_f32_16x16x32_bf16 v[70:73], v[236:239], v[224:227], v[70:73]
	s_add_i32 s42, s46, s41
	s_mov_b32 m0, s42
	v_lshl_add_u64 v[142:143], v[132:133], 0, s[2:3]
	v_mfma_f32_16x16x32_bf16 v[66:69], v[236:239], v[228:231], v[66:69]
;     ...
;   __syncthreads();
;   G2_STAGE(0); G2_STAGE(1);
;   const int fsw = (0x78 >> (((r16 >> 2) & 3) * 2)) & 3;
;   const int aoff = (wm * 128 + r16) * 64 + ((quad ^ fsw) << 4);
;   const int boff = 16384 + (wn * 64 + r16) * 64 + ((quad ^ fsw) << 4);
;   for (int kt = 0; kt < nk; kt++) {
;     if (kt + 1 < nk) asm volatile("s_waitcnt vmcnt(6)" ::: "memory");
;     else asm volatile("s_waitcnt vmcnt(0)" ::: "memory");
;     __builtin_amdgcn_s_barrier();
;     asm volatile("" ::: "memory");
;     if (kt + 2 < nk) G2_STAGE(kt + 2);
;     const char* cS = smem + (kt % 3) * 24576;
;     bf16x8 xa[8], wb[4];
; #pragma unroll
;     for (int f = 0; f < 8; f++) xa[f] = *(const bf16x8*)(cS + aoff + f * 1024);
; #pragma unroll
;     for (int f = 0; f < 4; f++) wb[f] = *(const bf16x8*)(cS + boff + f * 1024);
; #pragma unroll
;     for (int nf = 0; nf < 4; nf++)
; #pragma unroll
;       for (int mf = 0; mf < 8; mf++)
;         acc[nf][mf] = __builtin_amdgcn_mfma_f32_16x16x32_bf16(wb[nf], xa[mf], acc[nf][mf], 0, 0, 0);
;   }
	global_load_lds_dwordx4 v[132:133], off
	s_add_i32 m0, m0, 0x1000
	v_mfma_f32_16x16x32_bf16 v[62:65], v[240:243], v[200:203], v[62:65]
	v_mfma_f32_16x16x32_bf16 v[58:61], v[240:243], v[204:207], v[58:61]
	v_mfma_f32_16x16x32_bf16 v[54:57], v[240:243], v[208:211], v[54:57]
	global_load_lds_dwordx4 v[142:143], off
	v_lshl_add_u64 v[142:143], v[142:143], 0, s[2:3]
	s_add_i32 m0, m0, 0x1000
	v_mfma_f32_16x16x32_bf16 v[50:53], v[240:243], v[212:215], v[50:53]
	v_mfma_f32_16x16x32_bf16 v[46:49], v[240:243], v[216:219], v[46:49]
	s_setprio 0
	s_nop 0
	v_mfma_f32_16x16x32_bf16 v[42:45], v[240:243], v[220:223], v[42:45]
	global_load_lds_dwordx4 v[142:143], off
	v_lshl_add_u64 v[142:143], v[142:143], 0, s[2:3]
	s_add_i32 m0, m0, 0x1000
	v_mfma_f32_16x16x32_bf16 v[38:41], v[240:243], v[224:227], v[38:41]
	v_mfma_f32_16x16x32_bf16 v[34:37], v[240:243], v[228:231], v[34:37]
	v_mfma_f32_16x16x32_bf16 v[30:33], v[244:247], v[200:203], v[30:33]
	global_load_lds_dwordx4 v[142:143], off
	s_add_i32 m0, m0, 0x1000
	v_lshl_add_u64 v[142:143], v[134:135], 0, s[2:3]
	v_mfma_f32_16x16x32_bf16 v[26:29], v[244:247], v[204:207], v[26:29]
	v_mfma_f32_16x16x32_bf16 v[22:25], v[244:247], v[208:211], v[22:25]
	v_mfma_f32_16x16x32_bf16 v[18:21], v[244:247], v[212:215], v[18:21]
	global_load_lds_dwordx4 v[134:135], off
	s_add_i32 m0, m0, 0x1000
	v_lshl_add_u64 v[132:133], v[132:133], 0, s[12:13]
	v_mfma_f32_16x16x32_bf16 v[14:17], v[244:247], v[216:219], v[14:17]
	v_mfma_f32_16x16x32_bf16 v[10:13], v[244:247], v[220:223], v[10:13]
	v_mfma_f32_16x16x32_bf16 v[6:9], v[244:247], v[224:227], v[6:9]
	global_load_lds_dwordx4 v[142:143], off
	v_lshl_add_u64 v[134:135], v[134:135], 0, s[4:5]
	v_mfma_f32_16x16x32_bf16 v[2:5], v[244:247], v[228:231], v[2:5]
	s_mov_b32 s41, s40
	s_nop 0
	s_add_i32 s40, s40, 0x6000
	s_cmp_eq_u32 s40, 0x12000
	s_cselect_b32 s40, 0, s40
	s_nop 0
	s_sub_i32 s39, s39, 1
	s_cmp_lg_u32 s39, 0
	s_cbranch_scc1 .Lt11_loop
	.p2align 3
	s_waitcnt vmcnt(6) lgkmcnt(0)
	s_barrier
	s_setprio 1
	v_add_u32_e32 v144, s40, v136
	v_mfma_f32_16x16x32_bf16 v[126:129], v[184:187], v[146:149], v[126:129]
	ds_read_b128 v[200:203], v144 offset:0
	v_mfma_f32_16x16x32_bf16 v[122:125], v[184:187], v[152:155], v[122:125]
	ds_read_b128 v[204:207], v144 offset:1024
	v_mfma_f32_16x16x32_bf16 v[118:121], v[184:187], v[156:159], v[118:121]
	ds_read_b128 v[208:211], v144 offset:2048
	v_mfma_f32_16x16x32_bf16 v[114:117], v[184:187], v[162:165], v[114:117]
	ds_read_b128 v[212:215], v144 offset:3072
	v_mfma_f32_16x16x32_bf16 v[110:113], v[184:187], v[166:169], v[110:113]
	ds_read_b128 v[216:219], v144 offset:4096
	v_mfma_f32_16x16x32_bf16 v[106:109], v[184:187], v[170:173], v[106:109]
	ds_read_b128 v[220:223], v144 offset:5120
	v_mfma_f32_16x16x32_bf16 v[102:105], v[184:187], v[176:179], v[102:105]
	ds_read_b128 v[224:227], v144 offset:6144
	v_mfma_f32_16x16x32_bf16 v[98:101], v[184:187], v[180:183], v[98:101]
	ds_read_b128 v[228:231], v144 offset:7168
	v_mfma_f32_16x16x32_bf16 v[94:97], v[188:191], v[146:149], v[94:97]
	v_add_u32_e64 v144, s40, v137
	v_mfma_f32_16x16x32_bf16 v[90:93], v[188:191], v[152:155], v[90:93]
	v_mfma_f32_16x16x32_bf16 v[86:89], v[188:191], v[156:159], v[86:89]
	ds_read_b128 v[232:235], v144 offset:16384
	v_mfma_f32_16x16x32_bf16 v[82:85], v[188:191], v[162:165], v[82:85]
	ds_read_b128 v[236:239], v144 offset:17408
	v_mfma_f32_16x16x32_bf16 v[78:81], v[188:191], v[166:169], v[78:81]
	ds_read_b128 v[240:243], v144 offset:18432
	v_mfma_f32_16x16x32_bf16 v[74:77], v[188:191], v[170:173], v[74:77]
	ds_read_b128 v[244:247], v144 offset:19456
	v_mfma_f32_16x16x32_bf16 v[70:73], v[188:191], v[176:179], v[70:73]
	s_add_i32 s42, s46, s41
	s_mov_b32 m0, s42
	v_lshl_add_u64 v[142:143], v[132:133], 0, s[2:3]
	v_mfma_f32_16x16x32_bf16 v[66:69], v[188:191], v[180:183], v[66:69]
	global_load_lds_dwordx4 v[132:133], off
	s_add_i32 m0, m0, 0x1000
	v_mfma_f32_16x16x32_bf16 v[62:65], v[192:195], v[146:149], v[62:65]
	v_mfma_f32_16x16x32_bf16 v[58:61], v[192:195], v[152:155], v[58:61]
	v_mfma_f32_16x16x32_bf16 v[54:57], v[192:195], v[156:159], v[54:57]
	global_load_lds_dwordx4 v[142:143], off
	v_lshl_add_u64 v[142:143], v[142:143], 0, s[2:3]
	s_add_i32 m0, m0, 0x1000
	v_mfma_f32_16x16x32_bf16 v[50:53], v[192:195], v[162:165], v[50:53]
	v_mfma_f32_16x16x32_bf16 v[46:49], v[192:195], v[166:169], v[46:49]
	s_setprio 0
	s_nop 0
	v_mfma_f32_16x16x32_bf16 v[42:45], v[192:195], v[170:173], v[42:45]
	global_load_lds_dwordx4 v[142:143], off
	v_lshl_add_u64 v[142:143], v[142:143], 0, s[2:3]
	s_add_i32 m0, m0, 0x1000
	v_mfma_f32_16x16x32_bf16 v[38:41], v[192:195], v[176:179], v[38:41]
	v_mfma_f32_16x16x32_bf16 v[34:37], v[192:195], v[180:183], v[34:37]
	v_mfma_f32_16x16x32_bf16 v[30:33], v[196:199], v[146:149], v[30:33]
	global_load_lds_dwordx4 v[142:143], off
	s_add_i32 m0, m0, 0x1000
	v_lshl_add_u64 v[142:143], v[134:135], 0, s[2:3]
	v_mfma_f32_16x16x32_bf16 v[26:29], v[196:199], v[152:155], v[26:29]
	v_mfma_f32_16x16x32_bf16 v[22:25], v[196:199], v[156:159], v[22:25]
	v_mfma_f32_16x16x32_bf16 v[18:21], v[196:199], v[162:165], v[18:21]
	global_load_lds_dwordx4 v[134:135], off
	s_add_i32 m0, m0, 0x1000
	v_lshl_add_u64 v[132:133], v[132:133], 0, s[12:13]
	v_mfma_f32_16x16x32_bf16 v[14:17], v[196:199], v[166:169], v[14:17]
	v_mfma_f32_16x16x32_bf16 v[10:13], v[196:199], v[170:173], v[10:13]
	v_mfma_f32_16x16x32_bf16 v[6:9], v[196:199], v[176:179], v[6:9]
	global_load_lds_dwordx4 v[142:143], off
	v_lshl_add_u64 v[134:135], v[134:135], 0, s[4:5]
	v_mfma_f32_16x16x32_bf16 v[2:5], v[196:199], v[180:183], v[2:5]
	s_mov_b32 s41, s40
	s_nop 0
	s_add_i32 s40, s40, 0x6000
	s_cmp_eq_u32 s40, 0x12000
	s_cselect_b32 s40, 0, s40
	s_nop 0
	.p2align 3
	s_waitcnt vmcnt(6) lgkmcnt(0)
	s_barrier
;     ...
;   for (int kt = 0; kt < nk; kt++) {
;     if (kt + 1 < nk) asm volatile("s_waitcnt vmcnt(6)" ::: "memory");
;     else asm volatile("s_waitcnt vmcnt(0)" ::: "memory");
;     __builtin_amdgcn_s_barrier();
;     asm volatile("" ::: "memory");
;     if (kt + 2 < nk) G2_STAGE(kt + 2);
;     const char* cS = smem + (kt % 3) * 24576;
;     bf16x8 xa[8], wb[4];
; #pragma unroll
;     for (int f = 0; f < 8; f++) xa[f] = *(const bf16x8*)(cS + aoff + f * 1024);
; #pragma unroll
;     for (int f = 0; f < 4; f++) wb[f] = *(const bf16x8*)(cS + boff + f * 1024);
; #pragma unroll
;     for (int nf = 0; nf < 4; nf++)
; #pragma unroll
;       for (int mf = 0; mf < 8; mf++)
;         acc[nf][mf] = __builtin_amdgcn_mfma_f32_16x16x32_bf16(wb[nf], xa[mf], acc[nf][mf], 0, 0, 0);
;   }
	s_setprio 1
	v_add_u32_e32 v144, s40, v136
	v_mfma_f32_16x16x32_bf16 v[126:129], v[232:235], v[200:203], v[126:129]
	ds_read_b128 v[146:149], v144 offset:0
	v_mfma_f32_16x16x32_bf16 v[122:125], v[232:235], v[204:207], v[122:125]
	ds_read_b128 v[152:155], v144 offset:1024
	v_mfma_f32_16x16x32_bf16 v[118:121], v[232:235], v[208:211], v[118:121]
	ds_read_b128 v[156:159], v144 offset:2048
	v_mfma_f32_16x16x32_bf16 v[114:117], v[232:235], v[212:215], v[114:117]
	ds_read_b128 v[162:165], v144 offset:3072
	v_mfma_f32_16x16x32_bf16 v[110:113], v[232:235], v[216:219], v[110:113]
	ds_read_b128 v[166:169], v144 offset:4096
	v_mfma_f32_16x16x32_bf16 v[106:109], v[232:235], v[220:223], v[106:109]
	ds_read_b128 v[170:173], v144 offset:5120
	v_mfma_f32_16x16x32_bf16 v[102:105], v[232:235], v[224:227], v[102:105]
	ds_read_b128 v[176:179], v144 offset:6144
	v_mfma_f32_16x16x32_bf16 v[98:101], v[232:235], v[228:231], v[98:101]
	ds_read_b128 v[180:183], v144 offset:7168
	v_mfma_f32_16x16x32_bf16 v[94:97], v[236:239], v[200:203], v[94:97]
	v_add_u32_e64 v144, s40, v137
	v_mfma_f32_16x16x32_bf16 v[90:93], v[236:239], v[204:207], v[90:93]
	v_mfma_f32_16x16x32_bf16 v[86:89], v[236:239], v[208:211], v[86:89]
	ds_read_b128 v[184:187], v144 offset:16384
	v_mfma_f32_16x16x32_bf16 v[82:85], v[236:239], v[212:215], v[82:85]
	ds_read_b128 v[188:191], v144 offset:17408
	v_mfma_f32_16x16x32_bf16 v[78:81], v[236:239], v[216:219], v[78:81]
	ds_read_b128 v[192:195], v144 offset:18432
	v_mfma_f32_16x16x32_bf16 v[74:77], v[236:239], v[220:223], v[74:77]
	ds_read_b128 v[196:199], v144 offset:19456
	v_mfma_f32_16x16x32_bf16 v[70:73], v[236:239], v[224:227], v[70:73]
	v_mfma_f32_16x16x32_bf16 v[66:69], v[236:239], v[228:231], v[66:69]
	v_mfma_f32_16x16x32_bf16 v[62:65], v[240:243], v[200:203], v[62:65]
	v_mfma_f32_16x16x32_bf16 v[58:61], v[240:243], v[204:207], v[58:61]
	v_mfma_f32_16x16x32_bf16 v[54:57], v[240:243], v[208:211], v[54:57]
	v_mfma_f32_16x16x32_bf16 v[50:53], v[240:243], v[212:215], v[50:53]
	v_mfma_f32_16x16x32_bf16 v[46:49], v[240:243], v[216:219], v[46:49]
	s_setprio 0
	s_nop 0
	v_mfma_f32_16x16x32_bf16 v[42:45], v[240:243], v[220:223], v[42:45]
	v_mfma_f32_16x16x32_bf16 v[38:41], v[240:243], v[224:227], v[38:41]
	v_mfma_f32_16x16x32_bf16 v[34:37], v[240:243], v[228:231], v[34:37]
	v_mfma_f32_16x16x32_bf16 v[30:33], v[244:247], v[200:203], v[30:33]
	v_mfma_f32_16x16x32_bf16 v[26:29], v[244:247], v[204:207], v[26:29]
	v_mfma_f32_16x16x32_bf16 v[22:25], v[244:247], v[208:211], v[22:25]
	v_mfma_f32_16x16x32_bf16 v[18:21], v[244:247], v[212:215], v[18:21]
	v_mfma_f32_16x16x32_bf16 v[14:17], v[244:247], v[216:219], v[14:17]
	v_mfma_f32_16x16x32_bf16 v[10:13], v[244:247], v[220:223], v[10:13]
	v_mfma_f32_16x16x32_bf16 v[6:9], v[244:247], v[224:227], v[6:9]
	v_mfma_f32_16x16x32_bf16 v[2:5], v[244:247], v[228:231], v[2:5]
	s_mov_b32 s41, s40
	s_nop 0
	s_add_i32 s40, s40, 0x6000
	s_cmp_eq_u32 s40, 0x12000
	s_cselect_b32 s40, 0, s40
	s_nop 0
	.p2align 3
	s_waitcnt vmcnt(0) lgkmcnt(0)
	s_barrier
	s_setprio 1
	v_add_u32_e32 v144, s40, v136
	v_mfma_f32_16x16x32_bf16 v[126:129], v[184:187], v[146:149], v[126:129]
	ds_read_b128 v[200:203], v144 offset:0
	v_mfma_f32_16x16x32_bf16 v[122:125], v[184:187], v[152:155], v[122:125]
	ds_read_b128 v[204:207], v144 offset:1024
	v_mfma_f32_16x16x32_bf16 v[118:121], v[184:187], v[156:159], v[118:121]
	ds_read_b128 v[208:211], v144 offset:2048
	v_mfma_f32_16x16x32_bf16 v[114:117], v[184:187], v[162:165], v[114:117]
	ds_read_b128 v[212:215], v144 offset:3072
	v_mfma_f32_16x16x32_bf16 v[110:113], v[184:187], v[166:169], v[110:113]
	ds_read_b128 v[216:219], v144 offset:4096
	v_mfma_f32_16x16x32_bf16 v[106:109], v[184:187], v[170:173], v[106:109]
	ds_read_b128 v[220:223], v144 offset:5120
	v_mfma_f32_16x16x32_bf16 v[102:105], v[184:187], v[176:179], v[102:105]
	ds_read_b128 v[224:227], v144 offset:6144
	v_mfma_f32_16x16x32_bf16 v[98:101], v[184:187], v[180:183], v[98:101]
	ds_read_b128 v[228:231], v144 offset:7168
	v_mfma_f32_16x16x32_bf16 v[94:97], v[188:191], v[146:149], v[94:97]
	v_add_u32_e64 v144, s40, v137
	v_mfma_f32_16x16x32_bf16 v[90:93], v[188:191], v[152:155], v[90:93]
	v_mfma_f32_16x16x32_bf16 v[86:89], v[188:191], v[156:159], v[86:89]
	ds_read_b128 v[232:235], v144 offset:16384
	v_mfma_f32_16x16x32_bf16 v[82:85], v[188:191], v[162:165], v[82:85]
	ds_read_b128 v[236:239], v144 offset:17408
	v_mfma_f32_16x16x32_bf16 v[78:81], v[188:191], v[166:169], v[78:81]
	ds_read_b128 v[240:243], v144 offset:18432
	v_mfma_f32_16x16x32_bf16 v[74:77], v[188:191], v[170:173], v[74:77]
	ds_read_b128 v[244:247], v144 offset:19456
	v_mfma_f32_16x16x32_bf16 v[70:73], v[188:191], v[176:179], v[70:73]
	v_mfma_f32_16x16x32_bf16 v[66:69], v[188:191], v[180:183], v[66:69]
	v_mfma_f32_16x16x32_bf16 v[62:65], v[192:195], v[146:149], v[62:65]
	v_mfma_f32_16x16x32_bf16 v[58:61], v[192:195], v[152:155], v[58:61]
	v_mfma_f32_16x16x32_bf16 v[54:57], v[192:195], v[156:159], v[54:57]
	v_mfma_f32_16x16x32_bf16 v[50:53], v[192:195], v[162:165], v[50:53]
	v_mfma_f32_16x16x32_bf16 v[46:49], v[192:195], v[166:169], v[46:49]
	s_setprio 0
	s_nop 0
	v_mfma_f32_16x16x32_bf16 v[42:45], v[192:195], v[170:173], v[42:45]
	v_mfma_f32_16x16x32_bf16 v[38:41], v[192:195], v[176:179], v[38:41]
	v_mfma_f32_16x16x32_bf16 v[34:37], v[192:195], v[180:183], v[34:37]
	v_mfma_f32_16x16x32_bf16 v[30:33], v[196:199], v[146:149], v[30:33]
	v_mfma_f32_16x16x32_bf16 v[26:29], v[196:199], v[152:155], v[26:29]
	v_mfma_f32_16x16x32_bf16 v[22:25], v[196:199], v[156:159], v[22:25]
	v_mfma_f32_16x16x32_bf16 v[18:21], v[196:199], v[162:165], v[18:21]
	v_mfma_f32_16x16x32_bf16 v[14:17], v[196:199], v[166:169], v[14:17]
	v_mfma_f32_16x16x32_bf16 v[10:13], v[196:199], v[170:173], v[10:13]
	v_mfma_f32_16x16x32_bf16 v[6:9], v[196:199], v[176:179], v[6:9]
	v_mfma_f32_16x16x32_bf16 v[2:5], v[196:199], v[180:183], v[2:5]
	s_mov_b32 s41, s40
	s_nop 0
	s_add_i32 s40, s40, 0x6000
	s_cmp_eq_u32 s40, 0x12000
	s_cselect_b32 s40, 0, s40
	s_nop 0
	s_mov_b32 s4, 0x8000
	s_mov_b32 s5, 0
	s_mov_b32 s10, 0x10000
	s_mov_b32 s11, 0
	s_mov_b32 s44, 0x3fd744fd
	.p2align 3
	s_waitcnt lgkmcnt(0)
; DEVI unsigned pack2(float a, float b) { return __builtin_bit_cast(unsigned, __builtin_convertvector((f32x2_t){a, b}, bf16x2_t)); }
; DEVI float blo(unsigned u) { return __uint_as_float(u << 16); }
; DEVI float bhi(unsigned u) { return __uint_as_float(u & 0xffff0000u); }
; DEVI float siluf_(float x) { return x * __builtin_amdgcn_rcpf(1.f + __expf(-x)); }
;     ...
;     for (int nf = 0; nf < 4; nf++)
; #pragma unroll
;       for (int mf = 0; mf < 8; mf++)
;         acc[nf][mf] = __builtin_amdgcn_mfma_f32_16x16x32_bf16(wb[nf], xa[mf], acc[nf][mf], 0, 0, 0);
;   }
;     ...
; #pragma unroll
;   for (int mf = 0; mf < 8; mf++) {
;     const int row = m0 + wm * 128 + mf * 16 + r16;
;     if (EPI == EPI_SWIGLU) {
; #pragma unroll
;       for (int nf = 0; nf < 2; nf++) {
;         const int hcol = (n0 >> 1) + wn * 32 + nf * 16 + quad * 4;
;         f32x4 g = acc[nf][mf], u = acc[nf + 2][mf];
;         u32x2 pk;
;         pk[0] = pack2(siluf_(g[0]) * u[0], siluf_(g[1]) * u[1]);
;         pk[1] = pack2(siluf_(g[2]) * u[2], siluf_(g[3]) * u[3]);
;         *(u32x2*)(outb + (size_t)row * DFF + hcol) = pk;
;       }
;     } else {
; #pragma unroll
;       for (int nf = 0; nf < 4; nf++) {
;         const int col = n0 + wn * 64 + nf * 16 + quad * 4;
;         f32x4 a = acc[nf][mf];
;         if (EPI == EPI_RESID || EPI == EPI_RESID_ATOMIC) {
;           f32x4 x = a;
;           if (EPI == EPI_RESID || kpart == 0) {
;             const u32x2 xr = *(const u32x2*)((const u16*)(p.ws + WS_XB) + (size_t)row * 1024 + col);
;             x[0] += ALPHA * blo(xr[0]); x[1] += ALPHA * bhi(xr[0]); x[2] += ALPHA * blo(xr[1]); x[3] += ALPHA * bhi(xr[1]);
;           }
;           if (EPI == EPI_RESID) *(f32x4*)((float*)(p.ws + WS_XF) + (size_t)row * 1024 + col) = x;
;           else *(f32x4*)((float*)(p.ws + WS_SLAB) + ((size_t)kpart * 512 + (row - T_P)) * 1024 + col) = x;
	s_nop 0
	v_mfma_f32_16x16x32_bf16 v[126:129], v[232:235], v[200:203], v[126:129]
	v_mfma_f32_16x16x32_bf16 v[122:125], v[232:235], v[204:207], v[122:125]
	v_mfma_f32_16x16x32_bf16 v[118:121], v[232:235], v[208:211], v[118:121]
	v_mfma_f32_16x16x32_bf16 v[114:117], v[232:235], v[212:215], v[114:117]
	v_mfma_f32_16x16x32_bf16 v[110:113], v[232:235], v[216:219], v[110:113]
	global_load_dwordx4 v[146:149], v[138:139], off offset:0
	v_mfma_f32_16x16x32_bf16 v[106:109], v[232:235], v[220:223], v[106:109]
	v_mfma_f32_16x16x32_bf16 v[102:105], v[232:235], v[224:227], v[102:105]
	global_load_dwordx4 v[152:155], v[138:139], off offset:128
	v_mfma_f32_16x16x32_bf16 v[98:101], v[232:235], v[228:231], v[98:101]
	v_lshl_add_u64 v[138:139], v[138:139], 0, s[4:5]
	v_mfma_f32_16x16x32_bf16 v[94:97], v[236:239], v[200:203], v[94:97]
	global_load_dwordx4 v[156:159], v[138:139], off offset:0
	v_mfma_f32_16x16x32_bf16 v[90:93], v[236:239], v[204:207], v[90:93]
	v_mfma_f32_16x16x32_bf16 v[86:89], v[236:239], v[208:211], v[86:89]
	global_load_dwordx4 v[162:165], v[138:139], off offset:128
	v_mfma_f32_16x16x32_bf16 v[82:85], v[236:239], v[212:215], v[82:85]
	v_lshl_add_u64 v[138:139], v[138:139], 0, s[4:5]
	v_mfma_f32_16x16x32_bf16 v[78:81], v[236:239], v[216:219], v[78:81]
	global_load_dwordx4 v[166:169], v[138:139], off offset:0
	v_mfma_f32_16x16x32_bf16 v[74:77], v[236:239], v[220:223], v[74:77]
	v_mfma_f32_16x16x32_bf16 v[70:73], v[236:239], v[224:227], v[70:73]
	global_load_dwordx4 v[170:173], v[138:139], off offset:128
	v_mfma_f32_16x16x32_bf16 v[66:69], v[236:239], v[228:231], v[66:69]
	v_lshl_add_u64 v[138:139], v[138:139], 0, s[4:5]
	v_mfma_f32_16x16x32_bf16 v[62:65], v[240:243], v[200:203], v[62:65]
	global_load_dwordx4 v[176:179], v[138:139], off offset:0
	v_mfma_f32_16x16x32_bf16 v[58:61], v[240:243], v[204:207], v[58:61]
	v_mfma_f32_16x16x32_bf16 v[54:57], v[240:243], v[208:211], v[54:57]
	global_load_dwordx4 v[180:183], v[138:139], off offset:128
	v_mfma_f32_16x16x32_bf16 v[50:53], v[240:243], v[212:215], v[50:53]
	v_lshl_add_u64 v[138:139], v[138:139], 0, s[4:5]
	v_mfma_f32_16x16x32_bf16 v[46:49], v[240:243], v[216:219], v[46:49]
	global_load_dwordx4 v[184:187], v[138:139], off offset:0
	v_mfma_f32_16x16x32_bf16 v[42:45], v[240:243], v[220:223], v[42:45]
	v_mfma_f32_16x16x32_bf16 v[38:41], v[240:243], v[224:227], v[38:41]
	global_load_dwordx4 v[188:191], v[138:139], off offset:128
	v_mfma_f32_16x16x32_bf16 v[34:37], v[240:243], v[228:231], v[34:37]
	v_lshl_add_u64 v[138:139], v[138:139], 0, s[4:5]
	v_mfma_f32_16x16x32_bf16 v[30:33], v[244:247], v[200:203], v[30:33]
	global_load_dwordx4 v[192:195], v[138:139], off offset:0
	v_mfma_f32_16x16x32_bf16 v[26:29], v[244:247], v[204:207], v[26:29]
	v_mfma_f32_16x16x32_bf16 v[22:25], v[244:247], v[208:211], v[22:25]
	global_load_dwordx4 v[196:199], v[138:139], off offset:128
	v_mfma_f32_16x16x32_bf16 v[18:21], v[244:247], v[212:215], v[18:21]
	v_lshl_add_u64 v[138:139], v[138:139], 0, s[4:5]
	v_mfma_f32_16x16x32_bf16 v[14:17], v[244:247], v[216:219], v[14:17]
	v_mfma_f32_16x16x32_bf16 v[10:13], v[244:247], v[220:223], v[10:13]
	v_mfma_f32_16x16x32_bf16 v[6:9], v[244:247], v[224:227], v[6:9]
	v_mfma_f32_16x16x32_bf16 v[2:5], v[244:247], v[228:231], v[2:5]
	s_mov_b32 m0, s43
	global_load_dwordx4 v[200:203], v[138:139], off offset:0
	global_load_dwordx4 v[204:207], v[138:139], off offset:128
	v_lshl_add_u64 v[138:139], v[138:139], 0, s[4:5]
	global_load_dwordx4 v[208:211], v[138:139], off offset:0
	global_load_dwordx4 v[212:215], v[138:139], off offset:128
	v_lshl_add_u64 v[138:139], v[138:139], 0, s[4:5]
	s_nop 7
	v_and_b32_e32 v228, 1, v145
	v_cmp_ne_u32_e32 vcc, 0, v228
	v_mov_b32_e32 v229, 0xfffff040
	v_cndmask_b32_e32 v230, 0, v229, vcc
	v_ashrrev_i32_e32 v231, 31, v230
	v_lshl_add_u64 v[140:141], v[140:141], 0, v[230:231]
	v_add_co_u32_e32 v142, vcc, 0x1000, v140
	s_nop 0
	v_addc_co_u32_e32 v143, vcc, 0, v141, vcc
	v_cmp_ne_u32_e32 vcc, 0, v228
	s_waitcnt vmcnt(15)
	v_permlane16_swap_b32_e32 v146, v148
	v_permlane16_swap_b32_e32 v147, v149
	v_lshlrev_b32_e32 v216, 16, v146
	v_and_b32_e32 v146, 0xffff0000, v146
	v_lshlrev_b32_e32 v217, 16, v147
	v_and_b32_e32 v147, 0xffff0000, v147
	v_fmac_f32_e32 v126, s44, v216
	v_fmac_f32_e32 v127, s44, v146
	v_fmac_f32_e32 v128, s44, v217
	v_fmac_f32_e32 v129, s44, v147
	v_lshlrev_b32_e32 v216, 16, v148
	v_and_b32_e32 v148, 0xffff0000, v148
	v_lshlrev_b32_e32 v217, 16, v149
	v_and_b32_e32 v149, 0xffff0000, v149
	v_fmac_f32_e32 v94, s44, v216
	v_fmac_f32_e32 v95, s44, v148
	v_fmac_f32_e32 v96, s44, v217
	v_fmac_f32_e32 v97, s44, v149
	v_mov_b32_dpp v220, v94 quad_perm:[1,0,3,2] row_mask:0xf bank_mask:0xf
	v_mov_b32_dpp v221, v95 quad_perm:[1,0,3,2] row_mask:0xf bank_mask:0xf
	v_mov_b32_dpp v222, v96 quad_perm:[1,0,3,2] row_mask:0xf bank_mask:0xf
	v_mov_b32_dpp v223, v97 quad_perm:[1,0,3,2] row_mask:0xf bank_mask:0xf
	v_mov_b32_dpp v224, v126 quad_perm:[1,0,3,2] row_mask:0xf bank_mask:0xf
	v_mov_b32_dpp v225, v127 quad_perm:[1,0,3,2] row_mask:0xf bank_mask:0xf
	v_mov_b32_dpp v226, v128 quad_perm:[1,0,3,2] row_mask:0xf bank_mask:0xf
	v_mov_b32_dpp v227, v129 quad_perm:[1,0,3,2] row_mask:0xf bank_mask:0xf
	v_cndmask_b32_e32 v94, v224, v94, vcc
	v_cndmask_b32_e32 v95, v225, v95, vcc
	v_cndmask_b32_e32 v96, v226, v96, vcc
	v_cndmask_b32_e32 v97, v227, v97, vcc
	v_cndmask_b32_e32 v126, v126, v220, vcc
	v_cndmask_b32_e32 v127, v127, v221, vcc
	v_cndmask_b32_e32 v128, v128, v222, vcc
	v_cndmask_b32_e32 v129, v129, v223, vcc
	global_store_dwordx4 v[140:141], v[126:129], off
	global_store_dwordx4 v[142:143], v[94:97], off
	s_waitcnt vmcnt(16)
; DEVI float blo(unsigned u) { return __uint_as_float(u << 16); }
; DEVI float bhi(unsigned u) { return __uint_as_float(u & 0xffff0000u); }
;     ...
;       for (int nf = 0; nf < 4; nf++) {
;         const int col = n0 + wn * 64 + nf * 16 + quad * 4;
;         f32x4 a = acc[nf][mf];
;         if (EPI == EPI_RESID || EPI == EPI_RESID_ATOMIC) {
;           f32x4 x = a;
;           if (EPI == EPI_RESID || kpart == 0) {
;             const u32x2 xr = *(const u32x2*)((const u16*)(p.ws + WS_XB) + (size_t)row * 1024 + col);
;             x[0] += ALPHA * blo(xr[0]); x[1] += ALPHA * bhi(xr[0]); x[2] += ALPHA * blo(xr[1]); x[3] += ALPHA * bhi(xr[1]);
;           }
;           if (EPI == EPI_RESID) *(f32x4*)((float*)(p.ws + WS_XF) + (size_t)row * 1024 + col) = x;
;           else *(f32x4*)((float*)(p.ws + WS_SLAB) + ((size_t)kpart * 512 + (row - T_P)) * 1024 + col) = x;
	v_permlane16_swap_b32_e32 v152, v154
	v_permlane16_swap_b32_e32 v153, v155
	v_lshlrev_b32_e32 v216, 16, v152
	v_and_b32_e32 v152, 0xffff0000, v152
	v_lshlrev_b32_e32 v217, 16, v153
	v_and_b32_e32 v153, 0xffff0000, v153
	v_fmac_f32_e32 v62, s44, v216
	v_fmac_f32_e32 v63, s44, v152
	v_fmac_f32_e32 v64, s44, v217
	v_fmac_f32_e32 v65, s44, v153
	v_lshlrev_b32_e32 v216, 16, v154
	v_and_b32_e32 v154, 0xffff0000, v154
	v_lshlrev_b32_e32 v217, 16, v155
	v_and_b32_e32 v155, 0xffff0000, v155
	v_fmac_f32_e32 v30, s44, v216
	v_fmac_f32_e32 v31, s44, v154
	v_fmac_f32_e32 v32, s44, v217
	v_fmac_f32_e32 v33, s44, v155
	v_mov_b32_dpp v220, v30 quad_perm:[1,0,3,2] row_mask:0xf bank_mask:0xf
	v_mov_b32_dpp v221, v31 quad_perm:[1,0,3,2] row_mask:0xf bank_mask:0xf
	v_mov_b32_dpp v222, v32 quad_perm:[1,0,3,2] row_mask:0xf bank_mask:0xf
	v_mov_b32_dpp v223, v33 quad_perm:[1,0,3,2] row_mask:0xf bank_mask:0xf
	v_mov_b32_dpp v224, v62 quad_perm:[1,0,3,2] row_mask:0xf bank_mask:0xf
	v_mov_b32_dpp v225, v63 quad_perm:[1,0,3,2] row_mask:0xf bank_mask:0xf
	v_mov_b32_dpp v226, v64 quad_perm:[1,0,3,2] row_mask:0xf bank_mask:0xf
	v_mov_b32_dpp v227, v65 quad_perm:[1,0,3,2] row_mask:0xf bank_mask:0xf
	v_cndmask_b32_e32 v30, v224, v30, vcc
	v_cndmask_b32_e32 v31, v225, v31, vcc
	v_cndmask_b32_e32 v32, v226, v32, vcc
	v_cndmask_b32_e32 v33, v227, v33, vcc
	v_cndmask_b32_e32 v62, v62, v220, vcc
	v_cndmask_b32_e32 v63, v63, v221, vcc
	v_cndmask_b32_e32 v64, v64, v222, vcc
	v_cndmask_b32_e32 v65, v65, v223, vcc
	global_store_dwordx4 v[140:141], v[62:65], off offset:128
	global_store_dwordx4 v[142:143], v[30:33], off offset:128
	v_lshl_add_u64 v[140:141], v[140:141], 0, s[10:11]
	v_lshl_add_u64 v[142:143], v[142:143], 0, s[10:11]
	s_waitcnt vmcnt(17)
	v_permlane16_swap_b32_e32 v156, v158
	v_permlane16_swap_b32_e32 v157, v159
	v_lshlrev_b32_e32 v216, 16, v156
	v_and_b32_e32 v156, 0xffff0000, v156
	v_lshlrev_b32_e32 v217, 16, v157
	v_and_b32_e32 v157, 0xffff0000, v157
	v_fmac_f32_e32 v122, s44, v216
	v_fmac_f32_e32 v123, s44, v156
	v_fmac_f32_e32 v124, s44, v217
	v_fmac_f32_e32 v125, s44, v157
	v_lshlrev_b32_e32 v216, 16, v158
	v_and_b32_e32 v158, 0xffff0000, v158
	v_lshlrev_b32_e32 v217, 16, v159
	v_and_b32_e32 v159, 0xffff0000, v159
	v_fmac_f32_e32 v90, s44, v216
	v_fmac_f32_e32 v91, s44, v158
	v_fmac_f32_e32 v92, s44, v217
	v_fmac_f32_e32 v93, s44, v159
	v_mov_b32_dpp v220, v90 quad_perm:[1,0,3,2] row_mask:0xf bank_mask:0xf
	v_mov_b32_dpp v221, v91 quad_perm:[1,0,3,2] row_mask:0xf bank_mask:0xf
	v_mov_b32_dpp v222, v92 quad_perm:[1,0,3,2] row_mask:0xf bank_mask:0xf
	v_mov_b32_dpp v223, v93 quad_perm:[1,0,3,2] row_mask:0xf bank_mask:0xf
	v_mov_b32_dpp v224, v122 quad_perm:[1,0,3,2] row_mask:0xf bank_mask:0xf
	v_mov_b32_dpp v225, v123 quad_perm:[1,0,3,2] row_mask:0xf bank_mask:0xf
	v_mov_b32_dpp v226, v124 quad_perm:[1,0,3,2] row_mask:0xf bank_mask:0xf
	v_mov_b32_dpp v227, v125 quad_perm:[1,0,3,2] row_mask:0xf bank_mask:0xf
	v_cndmask_b32_e32 v90, v224, v90, vcc
	v_cndmask_b32_e32 v91, v225, v91, vcc
	v_cndmask_b32_e32 v92, v226, v92, vcc
	v_cndmask_b32_e32 v93, v227, v93, vcc
	v_cndmask_b32_e32 v122, v122, v220, vcc
	v_cndmask_b32_e32 v123, v123, v221, vcc
	v_cndmask_b32_e32 v124, v124, v222, vcc
	v_cndmask_b32_e32 v125, v125, v223, vcc
	global_store_dwordx4 v[140:141], v[122:125], off
	global_store_dwordx4 v[142:143], v[90:93], off
	s_waitcnt vmcnt(18)
	v_permlane16_swap_b32_e32 v162, v164
	v_permlane16_swap_b32_e32 v163, v165
	v_lshlrev_b32_e32 v216, 16, v162
	v_and_b32_e32 v162, 0xffff0000, v162
	v_lshlrev_b32_e32 v217, 16, v163
	v_and_b32_e32 v163, 0xffff0000, v163
	v_fmac_f32_e32 v58, s44, v216
	v_fmac_f32_e32 v59, s44, v162
	v_fmac_f32_e32 v60, s44, v217
	v_fmac_f32_e32 v61, s44, v163
	v_lshlrev_b32_e32 v216, 16, v164
	v_and_b32_e32 v164, 0xffff0000, v164
	v_lshlrev_b32_e32 v217, 16, v165
	v_and_b32_e32 v165, 0xffff0000, v165
	v_fmac_f32_e32 v26, s44, v216
	v_fmac_f32_e32 v27, s44, v164
	v_fmac_f32_e32 v28, s44, v217
	v_fmac_f32_e32 v29, s44, v165
	v_mov_b32_dpp v220, v26 quad_perm:[1,0,3,2] row_mask:0xf bank_mask:0xf
	v_mov_b32_dpp v221, v27 quad_perm:[1,0,3,2] row_mask:0xf bank_mask:0xf
	v_mov_b32_dpp v222, v28 quad_perm:[1,0,3,2] row_mask:0xf bank_mask:0xf
	v_mov_b32_dpp v223, v29 quad_perm:[1,0,3,2] row_mask:0xf bank_mask:0xf
	v_mov_b32_dpp v224, v58 quad_perm:[1,0,3,2] row_mask:0xf bank_mask:0xf
	v_mov_b32_dpp v225, v59 quad_perm:[1,0,3,2] row_mask:0xf bank_mask:0xf
	v_mov_b32_dpp v226, v60 quad_perm:[1,0,3,2] row_mask:0xf bank_mask:0xf
	v_mov_b32_dpp v227, v61 quad_perm:[1,0,3,2] row_mask:0xf bank_mask:0xf
	v_cndmask_b32_e32 v26, v224, v26, vcc
	v_cndmask_b32_e32 v27, v225, v27, vcc
	v_cndmask_b32_e32 v28, v226, v28, vcc
	v_cndmask_b32_e32 v29, v227, v29, vcc
	v_cndmask_b32_e32 v58, v58, v220, vcc
	v_cndmask_b32_e32 v59, v59, v221, vcc
	v_cndmask_b32_e32 v60, v60, v222, vcc
	v_cndmask_b32_e32 v61, v61, v223, vcc
	global_store_dwordx4 v[140:141], v[58:61], off offset:128
	global_store_dwordx4 v[142:143], v[26:29], off offset:128
	v_lshl_add_u64 v[140:141], v[140:141], 0, s[10:11]
	v_lshl_add_u64 v[142:143], v[142:143], 0, s[10:11]
	s_waitcnt vmcnt(19)
; DEVI float blo(unsigned u) { return __uint_as_float(u << 16); }
; DEVI float bhi(unsigned u) { return __uint_as_float(u & 0xffff0000u); }
;     ...
;       for (int nf = 0; nf < 4; nf++) {
;         const int col = n0 + wn * 64 + nf * 16 + quad * 4;
;         f32x4 a = acc[nf][mf];
;         if (EPI == EPI_RESID || EPI == EPI_RESID_ATOMIC) {
;           f32x4 x = a;
;           if (EPI == EPI_RESID || kpart == 0) {
;             const u32x2 xr = *(const u32x2*)((const u16*)(p.ws + WS_XB) + (size_t)row * 1024 + col);
;             x[0] += ALPHA * blo(xr[0]); x[1] += ALPHA * bhi(xr[0]); x[2] += ALPHA * blo(xr[1]); x[3] += ALPHA * bhi(xr[1]);
;           }
;           if (EPI == EPI_RESID) *(f32x4*)((float*)(p.ws + WS_XF) + (size_t)row * 1024 + col) = x;
;           else *(f32x4*)((float*)(p.ws + WS_SLAB) + ((size_t)kpart * 512 + (row - T_P)) * 1024 + col) = x;
	v_permlane16_swap_b32_e32 v166, v168
	v_permlane16_swap_b32_e32 v167, v169
	v_lshlrev_b32_e32 v216, 16, v166
	v_and_b32_e32 v166, 0xffff0000, v166
	v_lshlrev_b32_e32 v217, 16, v167
	v_and_b32_e32 v167, 0xffff0000, v167
	v_fmac_f32_e32 v118, s44, v216
	v_fmac_f32_e32 v119, s44, v166
	v_fmac_f32_e32 v120, s44, v217
	v_fmac_f32_e32 v121, s44, v167
	v_lshlrev_b32_e32 v216, 16, v168
	v_and_b32_e32 v168, 0xffff0000, v168
	v_lshlrev_b32_e32 v217, 16, v169
	v_and_b32_e32 v169, 0xffff0000, v169
	v_fmac_f32_e32 v86, s44, v216
	v_fmac_f32_e32 v87, s44, v168
	v_fmac_f32_e32 v88, s44, v217
	v_fmac_f32_e32 v89, s44, v169
	v_mov_b32_dpp v220, v86 quad_perm:[1,0,3,2] row_mask:0xf bank_mask:0xf
	v_mov_b32_dpp v221, v87 quad_perm:[1,0,3,2] row_mask:0xf bank_mask:0xf
	v_mov_b32_dpp v222, v88 quad_perm:[1,0,3,2] row_mask:0xf bank_mask:0xf
	v_mov_b32_dpp v223, v89 quad_perm:[1,0,3,2] row_mask:0xf bank_mask:0xf
	v_mov_b32_dpp v224, v118 quad_perm:[1,0,3,2] row_mask:0xf bank_mask:0xf
	v_mov_b32_dpp v225, v119 quad_perm:[1,0,3,2] row_mask:0xf bank_mask:0xf
	v_mov_b32_dpp v226, v120 quad_perm:[1,0,3,2] row_mask:0xf bank_mask:0xf
	v_mov_b32_dpp v227, v121 quad_perm:[1,0,3,2] row_mask:0xf bank_mask:0xf
	v_cndmask_b32_e32 v86, v224, v86, vcc
	v_cndmask_b32_e32 v87, v225, v87, vcc
	v_cndmask_b32_e32 v88, v226, v88, vcc
	v_cndmask_b32_e32 v89, v227, v89, vcc
	v_cndmask_b32_e32 v118, v118, v220, vcc
	v_cndmask_b32_e32 v119, v119, v221, vcc
	v_cndmask_b32_e32 v120, v120, v222, vcc
	v_cndmask_b32_e32 v121, v121, v223, vcc
	global_store_dwordx4 v[140:141], v[118:121], off
	global_store_dwordx4 v[142:143], v[86:89], off
	s_waitcnt vmcnt(20)
	v_permlane16_swap_b32_e32 v170, v172
	v_permlane16_swap_b32_e32 v171, v173
	v_lshlrev_b32_e32 v216, 16, v170
	v_and_b32_e32 v170, 0xffff0000, v170
	v_lshlrev_b32_e32 v217, 16, v171
	v_and_b32_e32 v171, 0xffff0000, v171
	v_fmac_f32_e32 v54, s44, v216
	v_fmac_f32_e32 v55, s44, v170
	v_fmac_f32_e32 v56, s44, v217
	v_fmac_f32_e32 v57, s44, v171
	v_lshlrev_b32_e32 v216, 16, v172
	v_and_b32_e32 v172, 0xffff0000, v172
	v_lshlrev_b32_e32 v217, 16, v173
	v_and_b32_e32 v173, 0xffff0000, v173
	v_fmac_f32_e32 v22, s44, v216
	v_fmac_f32_e32 v23, s44, v172
	v_fmac_f32_e32 v24, s44, v217
	v_fmac_f32_e32 v25, s44, v173
	v_mov_b32_dpp v220, v22 quad_perm:[1,0,3,2] row_mask:0xf bank_mask:0xf
	v_mov_b32_dpp v221, v23 quad_perm:[1,0,3,2] row_mask:0xf bank_mask:0xf
	v_mov_b32_dpp v222, v24 quad_perm:[1,0,3,2] row_mask:0xf bank_mask:0xf
	v_mov_b32_dpp v223, v25 quad_perm:[1,0,3,2] row_mask:0xf bank_mask:0xf
	v_mov_b32_dpp v224, v54 quad_perm:[1,0,3,2] row_mask:0xf bank_mask:0xf
	v_mov_b32_dpp v225, v55 quad_perm:[1,0,3,2] row_mask:0xf bank_mask:0xf
	v_mov_b32_dpp v226, v56 quad_perm:[1,0,3,2] row_mask:0xf bank_mask:0xf
	v_mov_b32_dpp v227, v57 quad_perm:[1,0,3,2] row_mask:0xf bank_mask:0xf
	v_cndmask_b32_e32 v22, v224, v22, vcc
	v_cndmask_b32_e32 v23, v225, v23, vcc
	v_cndmask_b32_e32 v24, v226, v24, vcc
	v_cndmask_b32_e32 v25, v227, v25, vcc
	v_cndmask_b32_e32 v54, v54, v220, vcc
	v_cndmask_b32_e32 v55, v55, v221, vcc
	v_cndmask_b32_e32 v56, v56, v222, vcc
	v_cndmask_b32_e32 v57, v57, v223, vcc
	global_store_dwordx4 v[140:141], v[54:57], off offset:128
	global_store_dwordx4 v[142:143], v[22:25], off offset:128
	v_lshl_add_u64 v[140:141], v[140:141], 0, s[10:11]
	v_lshl_add_u64 v[142:143], v[142:143], 0, s[10:11]
	s_waitcnt vmcnt(21)
	v_permlane16_swap_b32_e32 v176, v178
	v_permlane16_swap_b32_e32 v177, v179
	v_lshlrev_b32_e32 v216, 16, v176
	v_and_b32_e32 v176, 0xffff0000, v176
	v_lshlrev_b32_e32 v217, 16, v177
	v_and_b32_e32 v177, 0xffff0000, v177
	v_fmac_f32_e32 v114, s44, v216
	v_fmac_f32_e32 v115, s44, v176
	v_fmac_f32_e32 v116, s44, v217
	v_fmac_f32_e32 v117, s44, v177
	v_lshlrev_b32_e32 v216, 16, v178
	v_and_b32_e32 v178, 0xffff0000, v178
	v_lshlrev_b32_e32 v217, 16, v179
	v_and_b32_e32 v179, 0xffff0000, v179
	v_fmac_f32_e32 v82, s44, v216
	v_fmac_f32_e32 v83, s44, v178
	v_fmac_f32_e32 v84, s44, v217
	v_fmac_f32_e32 v85, s44, v179
	v_mov_b32_dpp v220, v82 quad_perm:[1,0,3,2] row_mask:0xf bank_mask:0xf
	v_mov_b32_dpp v221, v83 quad_perm:[1,0,3,2] row_mask:0xf bank_mask:0xf
	v_mov_b32_dpp v222, v84 quad_perm:[1,0,3,2] row_mask:0xf bank_mask:0xf
	v_mov_b32_dpp v223, v85 quad_perm:[1,0,3,2] row_mask:0xf bank_mask:0xf
	v_mov_b32_dpp v224, v114 quad_perm:[1,0,3,2] row_mask:0xf bank_mask:0xf
	v_mov_b32_dpp v225, v115 quad_perm:[1,0,3,2] row_mask:0xf bank_mask:0xf
	v_mov_b32_dpp v226, v116 quad_perm:[1,0,3,2] row_mask:0xf bank_mask:0xf
	v_mov_b32_dpp v227, v117 quad_perm:[1,0,3,2] row_mask:0xf bank_mask:0xf
	v_cndmask_b32_e32 v82, v224, v82, vcc
	v_cndmask_b32_e32 v83, v225, v83, vcc
	v_cndmask_b32_e32 v84, v226, v84, vcc
	v_cndmask_b32_e32 v85, v227, v85, vcc
	v_cndmask_b32_e32 v114, v114, v220, vcc
	v_cndmask_b32_e32 v115, v115, v221, vcc
	v_cndmask_b32_e32 v116, v116, v222, vcc
	v_cndmask_b32_e32 v117, v117, v223, vcc
	global_store_dwordx4 v[140:141], v[114:117], off
	global_store_dwordx4 v[142:143], v[82:85], off
	s_waitcnt vmcnt(22)
; DEVI float blo(unsigned u) { return __uint_as_float(u << 16); }
; DEVI float bhi(unsigned u) { return __uint_as_float(u & 0xffff0000u); }
;     ...
;       for (int nf = 0; nf < 4; nf++) {
;         const int col = n0 + wn * 64 + nf * 16 + quad * 4;
;         f32x4 a = acc[nf][mf];
;         if (EPI == EPI_RESID || EPI == EPI_RESID_ATOMIC) {
;           f32x4 x = a;
;           if (EPI == EPI_RESID || kpart == 0) {
;             const u32x2 xr = *(const u32x2*)((const u16*)(p.ws + WS_XB) + (size_t)row * 1024 + col);
;             x[0] += ALPHA * blo(xr[0]); x[1] += ALPHA * bhi(xr[0]); x[2] += ALPHA * blo(xr[1]); x[3] += ALPHA * bhi(xr[1]);
;           }
;           if (EPI == EPI_RESID) *(f32x4*)((float*)(p.ws + WS_XF) + (size_t)row * 1024 + col) = x;
;           else *(f32x4*)((float*)(p.ws + WS_SLAB) + ((size_t)kpart * 512 + (row - T_P)) * 1024 + col) = x;
	v_permlane16_swap_b32_e32 v180, v182
	v_permlane16_swap_b32_e32 v181, v183
	v_lshlrev_b32_e32 v216, 16, v180
	v_and_b32_e32 v180, 0xffff0000, v180
	v_lshlrev_b32_e32 v217, 16, v181
	v_and_b32_e32 v181, 0xffff0000, v181
	v_fmac_f32_e32 v50, s44, v216
	v_fmac_f32_e32 v51, s44, v180
	v_fmac_f32_e32 v52, s44, v217
	v_fmac_f32_e32 v53, s44, v181
	v_lshlrev_b32_e32 v216, 16, v182
	v_and_b32_e32 v182, 0xffff0000, v182
	v_lshlrev_b32_e32 v217, 16, v183
	v_and_b32_e32 v183, 0xffff0000, v183
	v_fmac_f32_e32 v18, s44, v216
	v_fmac_f32_e32 v19, s44, v182
	v_fmac_f32_e32 v20, s44, v217
	v_fmac_f32_e32 v21, s44, v183
	v_mov_b32_dpp v220, v18 quad_perm:[1,0,3,2] row_mask:0xf bank_mask:0xf
	v_mov_b32_dpp v221, v19 quad_perm:[1,0,3,2] row_mask:0xf bank_mask:0xf
	v_mov_b32_dpp v222, v20 quad_perm:[1,0,3,2] row_mask:0xf bank_mask:0xf
	v_mov_b32_dpp v223, v21 quad_perm:[1,0,3,2] row_mask:0xf bank_mask:0xf
	v_mov_b32_dpp v224, v50 quad_perm:[1,0,3,2] row_mask:0xf bank_mask:0xf
	v_mov_b32_dpp v225, v51 quad_perm:[1,0,3,2] row_mask:0xf bank_mask:0xf
	v_mov_b32_dpp v226, v52 quad_perm:[1,0,3,2] row_mask:0xf bank_mask:0xf
	v_mov_b32_dpp v227, v53 quad_perm:[1,0,3,2] row_mask:0xf bank_mask:0xf
	v_cndmask_b32_e32 v18, v224, v18, vcc
	v_cndmask_b32_e32 v19, v225, v19, vcc
	v_cndmask_b32_e32 v20, v226, v20, vcc
	v_cndmask_b32_e32 v21, v227, v21, vcc
	v_cndmask_b32_e32 v50, v50, v220, vcc
	v_cndmask_b32_e32 v51, v51, v221, vcc
	v_cndmask_b32_e32 v52, v52, v222, vcc
	v_cndmask_b32_e32 v53, v53, v223, vcc
	global_store_dwordx4 v[140:141], v[50:53], off offset:128
	global_store_dwordx4 v[142:143], v[18:21], off offset:128
	v_lshl_add_u64 v[140:141], v[140:141], 0, s[10:11]
	v_lshl_add_u64 v[142:143], v[142:143], 0, s[10:11]
	s_waitcnt vmcnt(23)
	v_permlane16_swap_b32_e32 v184, v186
	v_permlane16_swap_b32_e32 v185, v187
	v_lshlrev_b32_e32 v216, 16, v184
	v_and_b32_e32 v184, 0xffff0000, v184
	v_lshlrev_b32_e32 v217, 16, v185
	v_and_b32_e32 v185, 0xffff0000, v185
	v_fmac_f32_e32 v110, s44, v216
	v_fmac_f32_e32 v111, s44, v184
	v_fmac_f32_e32 v112, s44, v217
	v_fmac_f32_e32 v113, s44, v185
	v_lshlrev_b32_e32 v216, 16, v186
	v_and_b32_e32 v186, 0xffff0000, v186
	v_lshlrev_b32_e32 v217, 16, v187
	v_and_b32_e32 v187, 0xffff0000, v187
	v_fmac_f32_e32 v78, s44, v216
	v_fmac_f32_e32 v79, s44, v186
	v_fmac_f32_e32 v80, s44, v217
	v_fmac_f32_e32 v81, s44, v187
	v_mov_b32_dpp v220, v78 quad_perm:[1,0,3,2] row_mask:0xf bank_mask:0xf
	v_mov_b32_dpp v221, v79 quad_perm:[1,0,3,2] row_mask:0xf bank_mask:0xf
	v_mov_b32_dpp v222, v80 quad_perm:[1,0,3,2] row_mask:0xf bank_mask:0xf
	v_mov_b32_dpp v223, v81 quad_perm:[1,0,3,2] row_mask:0xf bank_mask:0xf
	v_mov_b32_dpp v224, v110 quad_perm:[1,0,3,2] row_mask:0xf bank_mask:0xf
	v_mov_b32_dpp v225, v111 quad_perm:[1,0,3,2] row_mask:0xf bank_mask:0xf
	v_mov_b32_dpp v226, v112 quad_perm:[1,0,3,2] row_mask:0xf bank_mask:0xf
	v_mov_b32_dpp v227, v113 quad_perm:[1,0,3,2] row_mask:0xf bank_mask:0xf
	v_cndmask_b32_e32 v78, v224, v78, vcc
	v_cndmask_b32_e32 v79, v225, v79, vcc
	v_cndmask_b32_e32 v80, v226, v80, vcc
	v_cndmask_b32_e32 v81, v227, v81, vcc
	v_cndmask_b32_e32 v110, v110, v220, vcc
	v_cndmask_b32_e32 v111, v111, v221, vcc
	v_cndmask_b32_e32 v112, v112, v222, vcc
	v_cndmask_b32_e32 v113, v113, v223, vcc
	global_store_dwordx4 v[140:141], v[110:113], off
	global_store_dwordx4 v[142:143], v[78:81], off
	s_waitcnt vmcnt(24)
	v_permlane16_swap_b32_e32 v188, v190
	v_permlane16_swap_b32_e32 v189, v191
	v_lshlrev_b32_e32 v216, 16, v188
	v_and_b32_e32 v188, 0xffff0000, v188
	v_lshlrev_b32_e32 v217, 16, v189
	v_and_b32_e32 v189, 0xffff0000, v189
	v_fmac_f32_e32 v46, s44, v216
	v_fmac_f32_e32 v47, s44, v188
	v_fmac_f32_e32 v48, s44, v217
	v_fmac_f32_e32 v49, s44, v189
	v_lshlrev_b32_e32 v216, 16, v190
	v_and_b32_e32 v190, 0xffff0000, v190
	v_lshlrev_b32_e32 v217, 16, v191
	v_and_b32_e32 v191, 0xffff0000, v191
	v_fmac_f32_e32 v14, s44, v216
	v_fmac_f32_e32 v15, s44, v190
	v_fmac_f32_e32 v16, s44, v217
	v_fmac_f32_e32 v17, s44, v191
	v_mov_b32_dpp v220, v14 quad_perm:[1,0,3,2] row_mask:0xf bank_mask:0xf
	v_mov_b32_dpp v221, v15 quad_perm:[1,0,3,2] row_mask:0xf bank_mask:0xf
	v_mov_b32_dpp v222, v16 quad_perm:[1,0,3,2] row_mask:0xf bank_mask:0xf
	v_mov_b32_dpp v223, v17 quad_perm:[1,0,3,2] row_mask:0xf bank_mask:0xf
	v_mov_b32_dpp v224, v46 quad_perm:[1,0,3,2] row_mask:0xf bank_mask:0xf
	v_mov_b32_dpp v225, v47 quad_perm:[1,0,3,2] row_mask:0xf bank_mask:0xf
	v_mov_b32_dpp v226, v48 quad_perm:[1,0,3,2] row_mask:0xf bank_mask:0xf
	v_mov_b32_dpp v227, v49 quad_perm:[1,0,3,2] row_mask:0xf bank_mask:0xf
	v_cndmask_b32_e32 v14, v224, v14, vcc
	v_cndmask_b32_e32 v15, v225, v15, vcc
	v_cndmask_b32_e32 v16, v226, v16, vcc
	v_cndmask_b32_e32 v17, v227, v17, vcc
	v_cndmask_b32_e32 v46, v46, v220, vcc
	v_cndmask_b32_e32 v47, v47, v221, vcc
	v_cndmask_b32_e32 v48, v48, v222, vcc
	v_cndmask_b32_e32 v49, v49, v223, vcc
	global_store_dwordx4 v[140:141], v[46:49], off offset:128
	global_store_dwordx4 v[142:143], v[14:17], off offset:128
	v_lshl_add_u64 v[140:141], v[140:141], 0, s[10:11]
	v_lshl_add_u64 v[142:143], v[142:143], 0, s[10:11]
	s_waitcnt vmcnt(25)
; DEVI float blo(unsigned u) { return __uint_as_float(u << 16); }
; DEVI float bhi(unsigned u) { return __uint_as_float(u & 0xffff0000u); }
;     ...
;       for (int nf = 0; nf < 4; nf++) {
;         const int col = n0 + wn * 64 + nf * 16 + quad * 4;
;         f32x4 a = acc[nf][mf];
;         if (EPI == EPI_RESID || EPI == EPI_RESID_ATOMIC) {
;           f32x4 x = a;
;           if (EPI == EPI_RESID || kpart == 0) {
;             const u32x2 xr = *(const u32x2*)((const u16*)(p.ws + WS_XB) + (size_t)row * 1024 + col);
;             x[0] += ALPHA * blo(xr[0]); x[1] += ALPHA * bhi(xr[0]); x[2] += ALPHA * blo(xr[1]); x[3] += ALPHA * bhi(xr[1]);
;           }
;           if (EPI == EPI_RESID) *(f32x4*)((float*)(p.ws + WS_XF) + (size_t)row * 1024 + col) = x;
;           else *(f32x4*)((float*)(p.ws + WS_SLAB) + ((size_t)kpart * 512 + (row - T_P)) * 1024 + col) = x;
	v_permlane16_swap_b32_e32 v192, v194
	v_permlane16_swap_b32_e32 v193, v195
	v_lshlrev_b32_e32 v216, 16, v192
	v_and_b32_e32 v192, 0xffff0000, v192
	v_lshlrev_b32_e32 v217, 16, v193
	v_and_b32_e32 v193, 0xffff0000, v193
	v_fmac_f32_e32 v106, s44, v216
	v_fmac_f32_e32 v107, s44, v192
	v_fmac_f32_e32 v108, s44, v217
	v_fmac_f32_e32 v109, s44, v193
	v_lshlrev_b32_e32 v216, 16, v194
	v_and_b32_e32 v194, 0xffff0000, v194
	v_lshlrev_b32_e32 v217, 16, v195
	v_and_b32_e32 v195, 0xffff0000, v195
	v_fmac_f32_e32 v74, s44, v216
	v_fmac_f32_e32 v75, s44, v194
	v_fmac_f32_e32 v76, s44, v217
	v_fmac_f32_e32 v77, s44, v195
	v_mov_b32_dpp v220, v74 quad_perm:[1,0,3,2] row_mask:0xf bank_mask:0xf
	v_mov_b32_dpp v221, v75 quad_perm:[1,0,3,2] row_mask:0xf bank_mask:0xf
	v_mov_b32_dpp v222, v76 quad_perm:[1,0,3,2] row_mask:0xf bank_mask:0xf
	v_mov_b32_dpp v223, v77 quad_perm:[1,0,3,2] row_mask:0xf bank_mask:0xf
	v_mov_b32_dpp v224, v106 quad_perm:[1,0,3,2] row_mask:0xf bank_mask:0xf
	v_mov_b32_dpp v225, v107 quad_perm:[1,0,3,2] row_mask:0xf bank_mask:0xf
	v_mov_b32_dpp v226, v108 quad_perm:[1,0,3,2] row_mask:0xf bank_mask:0xf
	v_mov_b32_dpp v227, v109 quad_perm:[1,0,3,2] row_mask:0xf bank_mask:0xf
	v_cndmask_b32_e32 v74, v224, v74, vcc
	v_cndmask_b32_e32 v75, v225, v75, vcc
	v_cndmask_b32_e32 v76, v226, v76, vcc
	v_cndmask_b32_e32 v77, v227, v77, vcc
	v_cndmask_b32_e32 v106, v106, v220, vcc
	v_cndmask_b32_e32 v107, v107, v221, vcc
	v_cndmask_b32_e32 v108, v108, v222, vcc
	v_cndmask_b32_e32 v109, v109, v223, vcc
	global_store_dwordx4 v[140:141], v[106:109], off
	global_store_dwordx4 v[142:143], v[74:77], off
	s_waitcnt vmcnt(26)
	v_permlane16_swap_b32_e32 v196, v198
	v_permlane16_swap_b32_e32 v197, v199
	v_lshlrev_b32_e32 v216, 16, v196
	v_and_b32_e32 v196, 0xffff0000, v196
	v_lshlrev_b32_e32 v217, 16, v197
	v_and_b32_e32 v197, 0xffff0000, v197
	v_fmac_f32_e32 v42, s44, v216
	v_fmac_f32_e32 v43, s44, v196
	v_fmac_f32_e32 v44, s44, v217
	v_fmac_f32_e32 v45, s44, v197
	v_lshlrev_b32_e32 v216, 16, v198
	v_and_b32_e32 v198, 0xffff0000, v198
	v_lshlrev_b32_e32 v217, 16, v199
	v_and_b32_e32 v199, 0xffff0000, v199
	v_fmac_f32_e32 v10, s44, v216
	v_fmac_f32_e32 v11, s44, v198
	v_fmac_f32_e32 v12, s44, v217
	v_fmac_f32_e32 v13, s44, v199
	v_mov_b32_dpp v220, v10 quad_perm:[1,0,3,2] row_mask:0xf bank_mask:0xf
	v_mov_b32_dpp v221, v11 quad_perm:[1,0,3,2] row_mask:0xf bank_mask:0xf
	v_mov_b32_dpp v222, v12 quad_perm:[1,0,3,2] row_mask:0xf bank_mask:0xf
	v_mov_b32_dpp v223, v13 quad_perm:[1,0,3,2] row_mask:0xf bank_mask:0xf
	v_mov_b32_dpp v224, v42 quad_perm:[1,0,3,2] row_mask:0xf bank_mask:0xf
	v_mov_b32_dpp v225, v43 quad_perm:[1,0,3,2] row_mask:0xf bank_mask:0xf
	v_mov_b32_dpp v226, v44 quad_perm:[1,0,3,2] row_mask:0xf bank_mask:0xf
	v_mov_b32_dpp v227, v45 quad_perm:[1,0,3,2] row_mask:0xf bank_mask:0xf
	v_cndmask_b32_e32 v10, v224, v10, vcc
	v_cndmask_b32_e32 v11, v225, v11, vcc
	v_cndmask_b32_e32 v12, v226, v12, vcc
	v_cndmask_b32_e32 v13, v227, v13, vcc
	v_cndmask_b32_e32 v42, v42, v220, vcc
	v_cndmask_b32_e32 v43, v43, v221, vcc
	v_cndmask_b32_e32 v44, v44, v222, vcc
	v_cndmask_b32_e32 v45, v45, v223, vcc
	global_store_dwordx4 v[140:141], v[42:45], off offset:128
	global_store_dwordx4 v[142:143], v[10:13], off offset:128
	v_lshl_add_u64 v[140:141], v[140:141], 0, s[10:11]
	v_lshl_add_u64 v[142:143], v[142:143], 0, s[10:11]
	s_waitcnt vmcnt(27)
	v_permlane16_swap_b32_e32 v200, v202
	v_permlane16_swap_b32_e32 v201, v203
	v_lshlrev_b32_e32 v216, 16, v200
	v_and_b32_e32 v200, 0xffff0000, v200
	v_lshlrev_b32_e32 v217, 16, v201
	v_and_b32_e32 v201, 0xffff0000, v201
	v_fmac_f32_e32 v102, s44, v216
	v_fmac_f32_e32 v103, s44, v200
	v_fmac_f32_e32 v104, s44, v217
	v_fmac_f32_e32 v105, s44, v201
	v_lshlrev_b32_e32 v216, 16, v202
	v_and_b32_e32 v202, 0xffff0000, v202
	v_lshlrev_b32_e32 v217, 16, v203
	v_and_b32_e32 v203, 0xffff0000, v203
	v_fmac_f32_e32 v70, s44, v216
	v_fmac_f32_e32 v71, s44, v202
	v_fmac_f32_e32 v72, s44, v217
	v_fmac_f32_e32 v73, s44, v203
	v_mov_b32_dpp v220, v70 quad_perm:[1,0,3,2] row_mask:0xf bank_mask:0xf
	v_mov_b32_dpp v221, v71 quad_perm:[1,0,3,2] row_mask:0xf bank_mask:0xf
	v_mov_b32_dpp v222, v72 quad_perm:[1,0,3,2] row_mask:0xf bank_mask:0xf
	v_mov_b32_dpp v223, v73 quad_perm:[1,0,3,2] row_mask:0xf bank_mask:0xf
	v_mov_b32_dpp v224, v102 quad_perm:[1,0,3,2] row_mask:0xf bank_mask:0xf
	v_mov_b32_dpp v225, v103 quad_perm:[1,0,3,2] row_mask:0xf bank_mask:0xf
	v_mov_b32_dpp v226, v104 quad_perm:[1,0,3,2] row_mask:0xf bank_mask:0xf
	v_mov_b32_dpp v227, v105 quad_perm:[1,0,3,2] row_mask:0xf bank_mask:0xf
	v_cndmask_b32_e32 v70, v224, v70, vcc
	v_cndmask_b32_e32 v71, v225, v71, vcc
	v_cndmask_b32_e32 v72, v226, v72, vcc
	v_cndmask_b32_e32 v73, v227, v73, vcc
	v_cndmask_b32_e32 v102, v102, v220, vcc
	v_cndmask_b32_e32 v103, v103, v221, vcc
	v_cndmask_b32_e32 v104, v104, v222, vcc
	v_cndmask_b32_e32 v105, v105, v223, vcc
	global_store_dwordx4 v[140:141], v[102:105], off
	global_store_dwordx4 v[142:143], v[70:73], off
	s_waitcnt vmcnt(28)
; DEVI float blo(unsigned u) { return __uint_as_float(u << 16); }
; DEVI float bhi(unsigned u) { return __uint_as_float(u & 0xffff0000u); }
; DEVI int xcd_first_tile() { return (blockIdx.x & 7) * (gridDim.x >> 3) + (blockIdx.x >> 3); }
;     ...
;       for (int nf = 0; nf < 4; nf++) {
;         const int col = n0 + wn * 64 + nf * 16 + quad * 4;
;         f32x4 a = acc[nf][mf];
;         if (EPI == EPI_RESID || EPI == EPI_RESID_ATOMIC) {
;           f32x4 x = a;
;           if (EPI == EPI_RESID || kpart == 0) {
;             const u32x2 xr = *(const u32x2*)((const u16*)(p.ws + WS_XB) + (size_t)row * 1024 + col);
;             x[0] += ALPHA * blo(xr[0]); x[1] += ALPHA * bhi(xr[0]); x[2] += ALPHA * blo(xr[1]); x[3] += ALPHA * bhi(xr[1]);
;           }
;           if (EPI == EPI_RESID) *(f32x4*)((float*)(p.ws + WS_XF) + (size_t)row * 1024 + col) = x;
;           else *(f32x4*)((float*)(p.ws + WS_SLAB) + ((size_t)kpart * 512 + (row - T_P)) * 1024 + col) = x;
; DEVI void run_phase(const Params& p, int ph, char* smem) {
;     ...
;       for (int t = xcd_first_tile(); t < 512 + 16 * 11; t += xcd_tile_step()) {
;         if (t < 512) {
;           int mt_, nt_; tile_coords(t, 64, 8, mt_, nt_);
;           gemm_tile256<EPI_RESID>(p, hb, DFF, Bt, DFF, mt_ * 256, nt_ * 128, nullptr, 0, smem);
;         } else {
;           const int u_ = t - 512, tl_ = u_ / 11, q_ = u_ - tl_ * 11;
;           gemm_tile256<EPI_RESID_ATOMIC>(p, hb, DFF, Bt, DFF, (64 + (tl_ & 1)) * 256, (tl_ >> 1) * 128, nullptr, 0, smem, q_ * 256, 8, q_);
;         }
	v_permlane16_swap_b32_e32 v204, v206
	v_permlane16_swap_b32_e32 v205, v207
	v_lshlrev_b32_e32 v216, 16, v204
	v_and_b32_e32 v204, 0xffff0000, v204
	v_lshlrev_b32_e32 v217, 16, v205
	v_and_b32_e32 v205, 0xffff0000, v205
	v_fmac_f32_e32 v38, s44, v216
	v_fmac_f32_e32 v39, s44, v204
	v_fmac_f32_e32 v40, s44, v217
	v_fmac_f32_e32 v41, s44, v205
	v_lshlrev_b32_e32 v216, 16, v206
	v_and_b32_e32 v206, 0xffff0000, v206
	v_lshlrev_b32_e32 v217, 16, v207
	v_and_b32_e32 v207, 0xffff0000, v207
	v_fmac_f32_e32 v6, s44, v216
	v_fmac_f32_e32 v7, s44, v206
	v_fmac_f32_e32 v8, s44, v217
	v_fmac_f32_e32 v9, s44, v207
	v_mov_b32_dpp v220, v6 quad_perm:[1,0,3,2] row_mask:0xf bank_mask:0xf
	v_mov_b32_dpp v221, v7 quad_perm:[1,0,3,2] row_mask:0xf bank_mask:0xf
	v_mov_b32_dpp v222, v8 quad_perm:[1,0,3,2] row_mask:0xf bank_mask:0xf
	v_mov_b32_dpp v223, v9 quad_perm:[1,0,3,2] row_mask:0xf bank_mask:0xf
	v_mov_b32_dpp v224, v38 quad_perm:[1,0,3,2] row_mask:0xf bank_mask:0xf
	v_mov_b32_dpp v225, v39 quad_perm:[1,0,3,2] row_mask:0xf bank_mask:0xf
	v_mov_b32_dpp v226, v40 quad_perm:[1,0,3,2] row_mask:0xf bank_mask:0xf
	v_mov_b32_dpp v227, v41 quad_perm:[1,0,3,2] row_mask:0xf bank_mask:0xf
	v_cndmask_b32_e32 v6, v224, v6, vcc
	v_cndmask_b32_e32 v7, v225, v7, vcc
	v_cndmask_b32_e32 v8, v226, v8, vcc
	v_cndmask_b32_e32 v9, v227, v9, vcc
	v_cndmask_b32_e32 v38, v38, v220, vcc
	v_cndmask_b32_e32 v39, v39, v221, vcc
	v_cndmask_b32_e32 v40, v40, v222, vcc
	v_cndmask_b32_e32 v41, v41, v223, vcc
	global_store_dwordx4 v[140:141], v[38:41], off offset:128
	global_store_dwordx4 v[142:143], v[6:9], off offset:128
	v_lshl_add_u64 v[140:141], v[140:141], 0, s[10:11]
	v_lshl_add_u64 v[142:143], v[142:143], 0, s[10:11]
	s_waitcnt vmcnt(29)
	v_permlane16_swap_b32_e32 v208, v210
	v_permlane16_swap_b32_e32 v209, v211
	v_lshlrev_b32_e32 v216, 16, v208
	v_and_b32_e32 v208, 0xffff0000, v208
	v_lshlrev_b32_e32 v217, 16, v209
	v_and_b32_e32 v209, 0xffff0000, v209
	v_fmac_f32_e32 v98, s44, v216
	v_fmac_f32_e32 v99, s44, v208
	v_fmac_f32_e32 v100, s44, v217
	v_fmac_f32_e32 v101, s44, v209
	v_lshlrev_b32_e32 v216, 16, v210
	v_and_b32_e32 v210, 0xffff0000, v210
	v_lshlrev_b32_e32 v217, 16, v211
	v_and_b32_e32 v211, 0xffff0000, v211
	v_fmac_f32_e32 v66, s44, v216
	v_fmac_f32_e32 v67, s44, v210
	v_fmac_f32_e32 v68, s44, v217
	v_fmac_f32_e32 v69, s44, v211
	v_mov_b32_dpp v220, v66 quad_perm:[1,0,3,2] row_mask:0xf bank_mask:0xf
	v_mov_b32_dpp v221, v67 quad_perm:[1,0,3,2] row_mask:0xf bank_mask:0xf
	v_mov_b32_dpp v222, v68 quad_perm:[1,0,3,2] row_mask:0xf bank_mask:0xf
	v_mov_b32_dpp v223, v69 quad_perm:[1,0,3,2] row_mask:0xf bank_mask:0xf
	v_mov_b32_dpp v224, v98 quad_perm:[1,0,3,2] row_mask:0xf bank_mask:0xf
	v_mov_b32_dpp v225, v99 quad_perm:[1,0,3,2] row_mask:0xf bank_mask:0xf
	v_mov_b32_dpp v226, v100 quad_perm:[1,0,3,2] row_mask:0xf bank_mask:0xf
	v_mov_b32_dpp v227, v101 quad_perm:[1,0,3,2] row_mask:0xf bank_mask:0xf
	v_cndmask_b32_e32 v66, v224, v66, vcc
	v_cndmask_b32_e32 v67, v225, v67, vcc
	v_cndmask_b32_e32 v68, v226, v68, vcc
	v_cndmask_b32_e32 v69, v227, v69, vcc
	v_cndmask_b32_e32 v98, v98, v220, vcc
	v_cndmask_b32_e32 v99, v99, v221, vcc
	v_cndmask_b32_e32 v100, v100, v222, vcc
	v_cndmask_b32_e32 v101, v101, v223, vcc
	global_store_dwordx4 v[140:141], v[98:101], off
	global_store_dwordx4 v[142:143], v[66:69], off
	s_waitcnt vmcnt(30)
	v_permlane16_swap_b32_e32 v212, v214
	v_permlane16_swap_b32_e32 v213, v215
	v_lshlrev_b32_e32 v216, 16, v212
	v_and_b32_e32 v212, 0xffff0000, v212
	v_lshlrev_b32_e32 v217, 16, v213
	v_and_b32_e32 v213, 0xffff0000, v213
	v_fmac_f32_e32 v34, s44, v216
	v_fmac_f32_e32 v35, s44, v212
	v_fmac_f32_e32 v36, s44, v217
	v_fmac_f32_e32 v37, s44, v213
	v_lshlrev_b32_e32 v216, 16, v214
	v_and_b32_e32 v214, 0xffff0000, v214
	v_lshlrev_b32_e32 v217, 16, v215
	v_and_b32_e32 v215, 0xffff0000, v215
	v_fmac_f32_e32 v2, s44, v216
	v_fmac_f32_e32 v3, s44, v214
	v_fmac_f32_e32 v4, s44, v217
	v_fmac_f32_e32 v5, s44, v215
	v_mov_b32_dpp v220, v2 quad_perm:[1,0,3,2] row_mask:0xf bank_mask:0xf
	v_mov_b32_dpp v221, v3 quad_perm:[1,0,3,2] row_mask:0xf bank_mask:0xf
	v_mov_b32_dpp v222, v4 quad_perm:[1,0,3,2] row_mask:0xf bank_mask:0xf
	v_mov_b32_dpp v223, v5 quad_perm:[1,0,3,2] row_mask:0xf bank_mask:0xf
	v_mov_b32_dpp v224, v34 quad_perm:[1,0,3,2] row_mask:0xf bank_mask:0xf
	v_mov_b32_dpp v225, v35 quad_perm:[1,0,3,2] row_mask:0xf bank_mask:0xf
	v_mov_b32_dpp v226, v36 quad_perm:[1,0,3,2] row_mask:0xf bank_mask:0xf
	v_mov_b32_dpp v227, v37 quad_perm:[1,0,3,2] row_mask:0xf bank_mask:0xf
	v_cndmask_b32_e32 v2, v224, v2, vcc
	v_cndmask_b32_e32 v3, v225, v3, vcc
	v_cndmask_b32_e32 v4, v226, v4, vcc
	v_cndmask_b32_e32 v5, v227, v5, vcc
	v_cndmask_b32_e32 v34, v34, v220, vcc
	v_cndmask_b32_e32 v35, v35, v221, vcc
	v_cndmask_b32_e32 v36, v36, v222, vcc
	v_cndmask_b32_e32 v37, v37, v223, vcc
	global_store_dwordx4 v[140:141], v[34:37], off offset:128
	global_store_dwordx4 v[142:143], v[2:5], off offset:128
	v_readlane_b32 s39, v250, 7
	s_cmpk_lg_u32 s39, 0x200
	s_cbranch_scc1 .LBB0_41
	v_readlane_b32 s40, v250, 0
	s_lshr_b32 s41, s40, 3
	s_and_b32 s40, s40, 7
	s_mul_i32 s40, s40, 22
	s_add_i32 s40, s40, s41
	s_cmp_lt_u32 s41, 22
	s_movk_i32 s38, 0x4000
	s_branch .LBB0_41

;     ...
;   __syncthreads();
;   G2_STAGE(0); G2_STAGE(1);
;   const int fsw = (0x78 >> (((r16 >> 2) & 3) * 2)) & 3;
;   const int aoff = (wm * 128 + r16) * 64 + ((quad ^ fsw) << 4);
;   const int boff = 16384 + (wn * 64 + r16) * 64 + ((quad ^ fsw) << 4);
;   for (int kt = 0; kt < nk; kt++) {
;     if (kt + 1 < nk) asm volatile("s_waitcnt vmcnt(6)" ::: "memory");
;     else asm volatile("s_waitcnt vmcnt(0)" ::: "memory");
;     __builtin_amdgcn_s_barrier();
;     asm volatile("" ::: "memory");
;     if (kt + 2 < nk) G2_STAGE(kt + 2);
;     const char* cS = smem + (kt % 3) * 24576;
;     bf16x8 xa[8], wb[4];
; #pragma unroll
;     for (int f = 0; f < 8; f++) xa[f] = *(const bf16x8*)(cS + aoff + f * 1024);
; #pragma unroll
;     for (int f = 0; f < 4; f++) wb[f] = *(const bf16x8*)(cS + boff + f * 1024);
; #pragma unroll
;     for (int nf = 0; nf < 4; nf++)
; #pragma unroll
;       for (int mf = 0; mf < 8; mf++)
;         acc[nf][mf] = __builtin_amdgcn_mfma_f32_16x16x32_bf16(wb[nf], xa[mf], acc[nf][mf], 0, 0, 0);
;   }
.Lt10_loop:
	.p2align 3
	s_waitcnt vmcnt(6) lgkmcnt(0)
	s_barrier
	s_setprio 1
	v_add_u32_e32 v144, s36, v136
	v_mfma_f32_16x16x32_bf16 v[126:129], v[184:187], v[146:149], v[126:129]
	ds_read_b128 v[200:203], v144 offset:0
	v_mfma_f32_16x16x32_bf16 v[122:125], v[184:187], v[152:155], v[122:125]
	ds_read_b128 v[204:207], v144 offset:1024
	v_mfma_f32_16x16x32_bf16 v[118:121], v[184:187], v[156:159], v[118:121]
	ds_read_b128 v[208:211], v144 offset:2048
	v_mfma_f32_16x16x32_bf16 v[114:117], v[184:187], v[162:165], v[114:117]
	ds_read_b128 v[212:215], v144 offset:3072
	v_mfma_f32_16x16x32_bf16 v[110:113], v[184:187], v[166:169], v[110:113]
	ds_read_b128 v[216:219], v144 offset:4096
	v_mfma_f32_16x16x32_bf16 v[106:109], v[184:187], v[170:173], v[106:109]
	ds_read_b128 v[220:223], v144 offset:5120
	v_mfma_f32_16x16x32_bf16 v[102:105], v[184:187], v[176:179], v[102:105]
	ds_read_b128 v[224:227], v144 offset:6144
	v_mfma_f32_16x16x32_bf16 v[98:101], v[184:187], v[180:183], v[98:101]
	ds_read_b128 v[228:231], v144 offset:7168
	v_mfma_f32_16x16x32_bf16 v[94:97], v[188:191], v[146:149], v[94:97]
	v_add_u32_e64 v144, s36, v137
	v_mfma_f32_16x16x32_bf16 v[90:93], v[188:191], v[152:155], v[90:93]
	v_mfma_f32_16x16x32_bf16 v[86:89], v[188:191], v[156:159], v[86:89]
	ds_read_b128 v[232:235], v144 offset:16384
	v_mfma_f32_16x16x32_bf16 v[82:85], v[188:191], v[162:165], v[82:85]
	ds_read_b128 v[236:239], v144 offset:17408
	v_mfma_f32_16x16x32_bf16 v[78:81], v[188:191], v[166:169], v[78:81]
	ds_read_b128 v[240:243], v144 offset:18432
	v_mfma_f32_16x16x32_bf16 v[74:77], v[188:191], v[170:173], v[74:77]
	ds_read_b128 v[244:247], v144 offset:19456
	v_mfma_f32_16x16x32_bf16 v[70:73], v[188:191], v[176:179], v[70:73]
	s_add_i32 s38, s43, s37
	s_mov_b32 m0, s38
	v_lshl_add_u64 v[142:143], v[132:133], 0, s[2:3]
	v_mfma_f32_16x16x32_bf16 v[66:69], v[188:191], v[180:183], v[66:69]
	global_load_lds_dwordx4 v[132:133], off
	s_add_i32 m0, m0, 0x1000
	v_mfma_f32_16x16x32_bf16 v[62:65], v[192:195], v[146:149], v[62:65]
	v_mfma_f32_16x16x32_bf16 v[58:61], v[192:195], v[152:155], v[58:61]
	v_mfma_f32_16x16x32_bf16 v[54:57], v[192:195], v[156:159], v[54:57]
	global_load_lds_dwordx4 v[142:143], off
	v_lshl_add_u64 v[142:143], v[142:143], 0, s[2:3]
	s_add_i32 m0, m0, 0x1000
	v_mfma_f32_16x16x32_bf16 v[50:53], v[192:195], v[162:165], v[50:53]
	v_mfma_f32_16x16x32_bf16 v[46:49], v[192:195], v[166:169], v[46:49]
	s_setprio 0
	s_nop 0
	v_mfma_f32_16x16x32_bf16 v[42:45], v[192:195], v[170:173], v[42:45]
	global_load_lds_dwordx4 v[142:143], off
	v_lshl_add_u64 v[142:143], v[142:143], 0, s[2:3]
	s_add_i32 m0, m0, 0x1000
	v_mfma_f32_16x16x32_bf16 v[38:41], v[192:195], v[176:179], v[38:41]
	v_mfma_f32_16x16x32_bf16 v[34:37], v[192:195], v[180:183], v[34:37]
	v_mfma_f32_16x16x32_bf16 v[30:33], v[196:199], v[146:149], v[30:33]
	global_load_lds_dwordx4 v[142:143], off
	s_add_i32 m0, m0, 0x1000
	v_lshl_add_u64 v[142:143], v[134:135], 0, s[2:3]
	v_mfma_f32_16x16x32_bf16 v[26:29], v[196:199], v[152:155], v[26:29]
	v_mfma_f32_16x16x32_bf16 v[22:25], v[196:199], v[156:159], v[22:25]
	v_mfma_f32_16x16x32_bf16 v[18:21], v[196:199], v[162:165], v[18:21]
	global_load_lds_dwordx4 v[134:135], off
	s_add_i32 m0, m0, 0x1000
	v_lshl_add_u64 v[132:133], v[132:133], 0, s[14:15]
	v_mfma_f32_16x16x32_bf16 v[14:17], v[196:199], v[166:169], v[14:17]
	v_mfma_f32_16x16x32_bf16 v[10:13], v[196:199], v[170:173], v[10:13]
	v_mfma_f32_16x16x32_bf16 v[6:9], v[196:199], v[176:179], v[6:9]
	global_load_lds_dwordx4 v[142:143], off
	v_lshl_add_u64 v[134:135], v[134:135], 0, s[10:11]
	v_mfma_f32_16x16x32_bf16 v[2:5], v[196:199], v[180:183], v[2:5]
	s_mov_b32 s37, s36
	s_nop 0
	s_add_i32 s36, s36, 0x6000
	s_cmp_eq_u32 s36, 0x12000
	s_cselect_b32 s36, 0, s36
	s_nop 0
	.p2align 3
	s_waitcnt vmcnt(6) lgkmcnt(0)
	s_barrier
	s_setprio 1
	v_add_u32_e32 v144, s36, v136
	v_mfma_f32_16x16x32_bf16 v[126:129], v[232:235], v[200:203], v[126:129]
	ds_read_b128 v[146:149], v144 offset:0
	v_mfma_f32_16x16x32_bf16 v[122:125], v[232:235], v[204:207], v[122:125]
	ds_read_b128 v[152:155], v144 offset:1024
	v_mfma_f32_16x16x32_bf16 v[118:121], v[232:235], v[208:211], v[118:121]
	ds_read_b128 v[156:159], v144 offset:2048
	v_mfma_f32_16x16x32_bf16 v[114:117], v[232:235], v[212:215], v[114:117]
	ds_read_b128 v[162:165], v144 offset:3072
	v_mfma_f32_16x16x32_bf16 v[110:113], v[232:235], v[216:219], v[110:113]
	ds_read_b128 v[166:169], v144 offset:4096
	v_mfma_f32_16x16x32_bf16 v[106:109], v[232:235], v[220:223], v[106:109]
	ds_read_b128 v[170:173], v144 offset:5120
	v_mfma_f32_16x16x32_bf16 v[102:105], v[232:235], v[224:227], v[102:105]
	ds_read_b128 v[176:179], v144 offset:6144
	v_mfma_f32_16x16x32_bf16 v[98:101], v[232:235], v[228:231], v[98:101]
	ds_read_b128 v[180:183], v144 offset:7168
	v_mfma_f32_16x16x32_bf16 v[94:97], v[236:239], v[200:203], v[94:97]
	v_add_u32_e64 v144, s36, v137
	v_mfma_f32_16x16x32_bf16 v[90:93], v[236:239], v[204:207], v[90:93]
	v_mfma_f32_16x16x32_bf16 v[86:89], v[236:239], v[208:211], v[86:89]
	ds_read_b128 v[184:187], v144 offset:16384
	v_mfma_f32_16x16x32_bf16 v[82:85], v[236:239], v[212:215], v[82:85]
	ds_read_b128 v[188:191], v144 offset:17408
	v_mfma_f32_16x16x32_bf16 v[78:81], v[236:239], v[216:219], v[78:81]
	ds_read_b128 v[192:195], v144 offset:18432
	v_mfma_f32_16x16x32_bf16 v[74:77], v[236:239], v[220:223], v[74:77]
	ds_read_b128 v[196:199], v144 offset:19456
	v_mfma_f32_16x16x32_bf16 v[70:73], v[236:239], v[224:227], v[70:73]
	s_add_i32 s38, s43, s37
	s_mov_b32 m0, s38
	v_lshl_add_u64 v[142:143], v[132:133], 0, s[2:3]
	v_mfma_f32_16x16x32_bf16 v[66:69], v[236:239], v[228:231], v[66:69]
;     ...
;   __syncthreads();
;   G2_STAGE(0); G2_STAGE(1);
;   const int fsw = (0x78 >> (((r16 >> 2) & 3) * 2)) & 3;
;   const int aoff = (wm * 128 + r16) * 64 + ((quad ^ fsw) << 4);
;   const int boff = 16384 + (wn * 64 + r16) * 64 + ((quad ^ fsw) << 4);
;   for (int kt = 0; kt < nk; kt++) {
;     if (kt + 1 < nk) asm volatile("s_waitcnt vmcnt(6)" ::: "memory");
;     else asm volatile("s_waitcnt vmcnt(0)" ::: "memory");
;     __builtin_amdgcn_s_barrier();
;     asm volatile("" ::: "memory");
;     if (kt + 2 < nk) G2_STAGE(kt + 2);
;     const char* cS = smem + (kt % 3) * 24576;
;     bf16x8 xa[8], wb[4];
; #pragma unroll
;     for (int f = 0; f < 8; f++) xa[f] = *(const bf16x8*)(cS + aoff + f * 1024);
; #pragma unroll
;     for (int f = 0; f < 4; f++) wb[f] = *(const bf16x8*)(cS + boff + f * 1024);
; #pragma unroll
;     for (int nf = 0; nf < 4; nf++)
; #pragma unroll
;       for (int mf = 0; mf < 8; mf++)
;         acc[nf][mf] = __builtin_amdgcn_mfma_f32_16x16x32_bf16(wb[nf], xa[mf], acc[nf][mf], 0, 0, 0);
;   }
	global_load_lds_dwordx4 v[132:133], off
	s_add_i32 m0, m0, 0x1000
	v_mfma_f32_16x16x32_bf16 v[62:65], v[240:243], v[200:203], v[62:65]
	v_mfma_f32_16x16x32_bf16 v[58:61], v[240:243], v[204:207], v[58:61]
	v_mfma_f32_16x16x32_bf16 v[54:57], v[240:243], v[208:211], v[54:57]
	global_load_lds_dwordx4 v[142:143], off
	v_lshl_add_u64 v[142:143], v[142:143], 0, s[2:3]
	s_add_i32 m0, m0, 0x1000
	v_mfma_f32_16x16x32_bf16 v[50:53], v[240:243], v[212:215], v[50:53]
	v_mfma_f32_16x16x32_bf16 v[46:49], v[240:243], v[216:219], v[46:49]
	s_setprio 0
	s_nop 0
	v_mfma_f32_16x16x32_bf16 v[42:45], v[240:243], v[220:223], v[42:45]
	global_load_lds_dwordx4 v[142:143], off
	v_lshl_add_u64 v[142:143], v[142:143], 0, s[2:3]
	s_add_i32 m0, m0, 0x1000
	v_mfma_f32_16x16x32_bf16 v[38:41], v[240:243], v[224:227], v[38:41]
	v_mfma_f32_16x16x32_bf16 v[34:37], v[240:243], v[228:231], v[34:37]
	v_mfma_f32_16x16x32_bf16 v[30:33], v[244:247], v[200:203], v[30:33]
	global_load_lds_dwordx4 v[142:143], off
	s_add_i32 m0, m0, 0x1000
	v_lshl_add_u64 v[142:143], v[134:135], 0, s[2:3]
	v_mfma_f32_16x16x32_bf16 v[26:29], v[244:247], v[204:207], v[26:29]
	v_mfma_f32_16x16x32_bf16 v[22:25], v[244:247], v[208:211], v[22:25]
	v_mfma_f32_16x16x32_bf16 v[18:21], v[244:247], v[212:215], v[18:21]
	global_load_lds_dwordx4 v[134:135], off
	s_add_i32 m0, m0, 0x1000
	v_lshl_add_u64 v[132:133], v[132:133], 0, s[14:15]
	v_mfma_f32_16x16x32_bf16 v[14:17], v[244:247], v[216:219], v[14:17]
	v_mfma_f32_16x16x32_bf16 v[10:13], v[244:247], v[220:223], v[10:13]
	v_mfma_f32_16x16x32_bf16 v[6:9], v[244:247], v[224:227], v[6:9]
	global_load_lds_dwordx4 v[142:143], off
	v_lshl_add_u64 v[134:135], v[134:135], 0, s[10:11]
	v_mfma_f32_16x16x32_bf16 v[2:5], v[244:247], v[228:231], v[2:5]
	s_mov_b32 s37, s36
	s_nop 0
	s_add_i32 s36, s36, 0x6000
	s_cmp_eq_u32 s36, 0x12000
	s_cselect_b32 s36, 0, s36
	s_nop 0
	s_sub_i32 s9, s9, 1
	s_cmp_lg_u32 s9, 0
	s_cbranch_scc1 .Lt10_loop
	.p2align 3
	s_waitcnt vmcnt(6) lgkmcnt(0)
	s_barrier
	s_setprio 1
	v_add_u32_e32 v144, s36, v136
	v_mfma_f32_16x16x32_bf16 v[126:129], v[184:187], v[146:149], v[126:129]
	ds_read_b128 v[200:203], v144 offset:0
	v_mfma_f32_16x16x32_bf16 v[122:125], v[184:187], v[152:155], v[122:125]
	ds_read_b128 v[204:207], v144 offset:1024
	v_mfma_f32_16x16x32_bf16 v[118:121], v[184:187], v[156:159], v[118:121]
	ds_read_b128 v[208:211], v144 offset:2048
	v_mfma_f32_16x16x32_bf16 v[114:117], v[184:187], v[162:165], v[114:117]
	ds_read_b128 v[212:215], v144 offset:3072
	v_mfma_f32_16x16x32_bf16 v[110:113], v[184:187], v[166:169], v[110:113]
	ds_read_b128 v[216:219], v144 offset:4096
	v_mfma_f32_16x16x32_bf16 v[106:109], v[184:187], v[170:173], v[106:109]
	ds_read_b128 v[220:223], v144 offset:5120
	v_mfma_f32_16x16x32_bf16 v[102:105], v[184:187], v[176:179], v[102:105]
	ds_read_b128 v[224:227], v144 offset:6144
	v_mfma_f32_16x16x32_bf16 v[98:101], v[184:187], v[180:183], v[98:101]
	ds_read_b128 v[228:231], v144 offset:7168
	v_mfma_f32_16x16x32_bf16 v[94:97], v[188:191], v[146:149], v[94:97]
	v_add_u32_e64 v144, s36, v137
	v_mfma_f32_16x16x32_bf16 v[90:93], v[188:191], v[152:155], v[90:93]
	v_mfma_f32_16x16x32_bf16 v[86:89], v[188:191], v[156:159], v[86:89]
	ds_read_b128 v[232:235], v144 offset:16384
	v_mfma_f32_16x16x32_bf16 v[82:85], v[188:191], v[162:165], v[82:85]
	ds_read_b128 v[236:239], v144 offset:17408
	v_mfma_f32_16x16x32_bf16 v[78:81], v[188:191], v[166:169], v[78:81]
	ds_read_b128 v[240:243], v144 offset:18432
	v_mfma_f32_16x16x32_bf16 v[74:77], v[188:191], v[170:173], v[74:77]
	ds_read_b128 v[244:247], v144 offset:19456
	v_mfma_f32_16x16x32_bf16 v[70:73], v[188:191], v[176:179], v[70:73]
	s_add_i32 s38, s43, s37
	s_mov_b32 m0, s38
	v_lshl_add_u64 v[142:143], v[132:133], 0, s[2:3]
	v_mfma_f32_16x16x32_bf16 v[66:69], v[188:191], v[180:183], v[66:69]
	global_load_lds_dwordx4 v[132:133], off
	s_add_i32 m0, m0, 0x1000
	v_mfma_f32_16x16x32_bf16 v[62:65], v[192:195], v[146:149], v[62:65]
	v_mfma_f32_16x16x32_bf16 v[58:61], v[192:195], v[152:155], v[58:61]
	v_mfma_f32_16x16x32_bf16 v[54:57], v[192:195], v[156:159], v[54:57]
	global_load_lds_dwordx4 v[142:143], off
	v_lshl_add_u64 v[142:143], v[142:143], 0, s[2:3]
	s_add_i32 m0, m0, 0x1000
	v_mfma_f32_16x16x32_bf16 v[50:53], v[192:195], v[162:165], v[50:53]
	v_mfma_f32_16x16x32_bf16 v[46:49], v[192:195], v[166:169], v[46:49]
	s_setprio 0
	s_nop 0
	v_mfma_f32_16x16x32_bf16 v[42:45], v[192:195], v[170:173], v[42:45]
	global_load_lds_dwordx4 v[142:143], off
	v_lshl_add_u64 v[142:143], v[142:143], 0, s[2:3]
	s_add_i32 m0, m0, 0x1000
	v_mfma_f32_16x16x32_bf16 v[38:41], v[192:195], v[176:179], v[38:41]
	v_mfma_f32_16x16x32_bf16 v[34:37], v[192:195], v[180:183], v[34:37]
	v_mfma_f32_16x16x32_bf16 v[30:33], v[196:199], v[146:149], v[30:33]
	global_load_lds_dwordx4 v[142:143], off
	s_add_i32 m0, m0, 0x1000
	v_lshl_add_u64 v[142:143], v[134:135], 0, s[2:3]
	v_mfma_f32_16x16x32_bf16 v[26:29], v[196:199], v[152:155], v[26:29]
	v_mfma_f32_16x16x32_bf16 v[22:25], v[196:199], v[156:159], v[22:25]
	v_mfma_f32_16x16x32_bf16 v[18:21], v[196:199], v[162:165], v[18:21]
	global_load_lds_dwordx4 v[134:135], off
	s_add_i32 m0, m0, 0x1000
	v_lshl_add_u64 v[132:133], v[132:133], 0, s[14:15]
	v_mfma_f32_16x16x32_bf16 v[14:17], v[196:199], v[166:169], v[14:17]
	v_mfma_f32_16x16x32_bf16 v[10:13], v[196:199], v[170:173], v[10:13]
	v_mfma_f32_16x16x32_bf16 v[6:9], v[196:199], v[176:179], v[6:9]
	global_load_lds_dwordx4 v[142:143], off
	v_lshl_add_u64 v[134:135], v[134:135], 0, s[10:11]
	v_mfma_f32_16x16x32_bf16 v[2:5], v[196:199], v[180:183], v[2:5]
	s_mov_b32 s37, s36
	s_nop 0
	s_add_i32 s36, s36, 0x6000
	s_cmp_eq_u32 s36, 0x12000
	s_cselect_b32 s36, 0, s36
	s_nop 0
	.p2align 3
	s_waitcnt vmcnt(6) lgkmcnt(0)
	s_barrier
;     ...
;   for (int kt = 0; kt < nk; kt++) {
;     if (kt + 1 < nk) asm volatile("s_waitcnt vmcnt(6)" ::: "memory");
;     else asm volatile("s_waitcnt vmcnt(0)" ::: "memory");
;     __builtin_amdgcn_s_barrier();
;     asm volatile("" ::: "memory");
;     if (kt + 2 < nk) G2_STAGE(kt + 2);
;     const char* cS = smem + (kt % 3) * 24576;
;     bf16x8 xa[8], wb[4];
; #pragma unroll
;     for (int f = 0; f < 8; f++) xa[f] = *(const bf16x8*)(cS + aoff + f * 1024);
; #pragma unroll
;     for (int f = 0; f < 4; f++) wb[f] = *(const bf16x8*)(cS + boff + f * 1024);
; #pragma unroll
;     for (int nf = 0; nf < 4; nf++)
; #pragma unroll
;       for (int mf = 0; mf < 8; mf++)
;         acc[nf][mf] = __builtin_amdgcn_mfma_f32_16x16x32_bf16(wb[nf], xa[mf], acc[nf][mf], 0, 0, 0);
;   }
	s_setprio 1
	v_add_u32_e32 v144, s36, v136
	v_mfma_f32_16x16x32_bf16 v[126:129], v[232:235], v[200:203], v[126:129]
	ds_read_b128 v[146:149], v144 offset:0
	v_mfma_f32_16x16x32_bf16 v[122:125], v[232:235], v[204:207], v[122:125]
	ds_read_b128 v[152:155], v144 offset:1024
	v_mfma_f32_16x16x32_bf16 v[118:121], v[232:235], v[208:211], v[118:121]
	ds_read_b128 v[156:159], v144 offset:2048
	v_mfma_f32_16x16x32_bf16 v[114:117], v[232:235], v[212:215], v[114:117]
	ds_read_b128 v[162:165], v144 offset:3072
	v_mfma_f32_16x16x32_bf16 v[110:113], v[232:235], v[216:219], v[110:113]
	ds_read_b128 v[166:169], v144 offset:4096
	v_mfma_f32_16x16x32_bf16 v[106:109], v[232:235], v[220:223], v[106:109]
	ds_read_b128 v[170:173], v144 offset:5120
	v_mfma_f32_16x16x32_bf16 v[102:105], v[232:235], v[224:227], v[102:105]
	ds_read_b128 v[176:179], v144 offset:6144
	v_mfma_f32_16x16x32_bf16 v[98:101], v[232:235], v[228:231], v[98:101]
	ds_read_b128 v[180:183], v144 offset:7168
	v_mfma_f32_16x16x32_bf16 v[94:97], v[236:239], v[200:203], v[94:97]
	v_add_u32_e64 v144, s36, v137
	v_mfma_f32_16x16x32_bf16 v[90:93], v[236:239], v[204:207], v[90:93]
	v_mfma_f32_16x16x32_bf16 v[86:89], v[236:239], v[208:211], v[86:89]
	ds_read_b128 v[184:187], v144 offset:16384
	v_mfma_f32_16x16x32_bf16 v[82:85], v[236:239], v[212:215], v[82:85]
	ds_read_b128 v[188:191], v144 offset:17408
	v_mfma_f32_16x16x32_bf16 v[78:81], v[236:239], v[216:219], v[78:81]
	ds_read_b128 v[192:195], v144 offset:18432
	v_mfma_f32_16x16x32_bf16 v[74:77], v[236:239], v[220:223], v[74:77]
	ds_read_b128 v[196:199], v144 offset:19456
	v_mfma_f32_16x16x32_bf16 v[70:73], v[236:239], v[224:227], v[70:73]
	v_mfma_f32_16x16x32_bf16 v[66:69], v[236:239], v[228:231], v[66:69]
	v_mfma_f32_16x16x32_bf16 v[62:65], v[240:243], v[200:203], v[62:65]
	v_mfma_f32_16x16x32_bf16 v[58:61], v[240:243], v[204:207], v[58:61]
	v_mfma_f32_16x16x32_bf16 v[54:57], v[240:243], v[208:211], v[54:57]
	v_mfma_f32_16x16x32_bf16 v[50:53], v[240:243], v[212:215], v[50:53]
	v_mfma_f32_16x16x32_bf16 v[46:49], v[240:243], v[216:219], v[46:49]
	s_setprio 0
	s_nop 0
	v_mfma_f32_16x16x32_bf16 v[42:45], v[240:243], v[220:223], v[42:45]
	v_mfma_f32_16x16x32_bf16 v[38:41], v[240:243], v[224:227], v[38:41]
	v_mfma_f32_16x16x32_bf16 v[34:37], v[240:243], v[228:231], v[34:37]
	v_mfma_f32_16x16x32_bf16 v[30:33], v[244:247], v[200:203], v[30:33]
	v_mfma_f32_16x16x32_bf16 v[26:29], v[244:247], v[204:207], v[26:29]
	v_mfma_f32_16x16x32_bf16 v[22:25], v[244:247], v[208:211], v[22:25]
	v_mfma_f32_16x16x32_bf16 v[18:21], v[244:247], v[212:215], v[18:21]
	v_mfma_f32_16x16x32_bf16 v[14:17], v[244:247], v[216:219], v[14:17]
	v_mfma_f32_16x16x32_bf16 v[10:13], v[244:247], v[220:223], v[10:13]
	v_mfma_f32_16x16x32_bf16 v[6:9], v[244:247], v[224:227], v[6:9]
	v_mfma_f32_16x16x32_bf16 v[2:5], v[244:247], v[228:231], v[2:5]
	s_mov_b32 s37, s36
	s_nop 0
	s_add_i32 s36, s36, 0x6000
	s_cmp_eq_u32 s36, 0x12000
	s_cselect_b32 s36, 0, s36
	s_nop 0
	.p2align 3
	s_waitcnt vmcnt(0) lgkmcnt(0)
	s_barrier
	s_setprio 1
	v_add_u32_e32 v144, s36, v136
	v_mfma_f32_16x16x32_bf16 v[126:129], v[184:187], v[146:149], v[126:129]
	ds_read_b128 v[200:203], v144 offset:0
	v_mfma_f32_16x16x32_bf16 v[122:125], v[184:187], v[152:155], v[122:125]
	ds_read_b128 v[204:207], v144 offset:1024
	v_mfma_f32_16x16x32_bf16 v[118:121], v[184:187], v[156:159], v[118:121]
	ds_read_b128 v[208:211], v144 offset:2048
	v_mfma_f32_16x16x32_bf16 v[114:117], v[184:187], v[162:165], v[114:117]
	ds_read_b128 v[212:215], v144 offset:3072
	v_mfma_f32_16x16x32_bf16 v[110:113], v[184:187], v[166:169], v[110:113]
	ds_read_b128 v[216:219], v144 offset:4096
	v_mfma_f32_16x16x32_bf16 v[106:109], v[184:187], v[170:173], v[106:109]
	ds_read_b128 v[220:223], v144 offset:5120
	v_mfma_f32_16x16x32_bf16 v[102:105], v[184:187], v[176:179], v[102:105]
	ds_read_b128 v[224:227], v144 offset:6144
	v_mfma_f32_16x16x32_bf16 v[98:101], v[184:187], v[180:183], v[98:101]
	ds_read_b128 v[228:231], v144 offset:7168
	v_mfma_f32_16x16x32_bf16 v[94:97], v[188:191], v[146:149], v[94:97]
	v_add_u32_e64 v144, s36, v137
	v_mfma_f32_16x16x32_bf16 v[90:93], v[188:191], v[152:155], v[90:93]
	v_mfma_f32_16x16x32_bf16 v[86:89], v[188:191], v[156:159], v[86:89]
	ds_read_b128 v[232:235], v144 offset:16384
	v_mfma_f32_16x16x32_bf16 v[82:85], v[188:191], v[162:165], v[82:85]
	ds_read_b128 v[236:239], v144 offset:17408
	v_mfma_f32_16x16x32_bf16 v[78:81], v[188:191], v[166:169], v[78:81]
	ds_read_b128 v[240:243], v144 offset:18432
	v_mfma_f32_16x16x32_bf16 v[74:77], v[188:191], v[170:173], v[74:77]
	ds_read_b128 v[244:247], v144 offset:19456
	v_mfma_f32_16x16x32_bf16 v[70:73], v[188:191], v[176:179], v[70:73]
	v_mfma_f32_16x16x32_bf16 v[66:69], v[188:191], v[180:183], v[66:69]
	v_mfma_f32_16x16x32_bf16 v[62:65], v[192:195], v[146:149], v[62:65]
	v_mfma_f32_16x16x32_bf16 v[58:61], v[192:195], v[152:155], v[58:61]
	v_mfma_f32_16x16x32_bf16 v[54:57], v[192:195], v[156:159], v[54:57]
	v_mfma_f32_16x16x32_bf16 v[50:53], v[192:195], v[162:165], v[50:53]
	v_mfma_f32_16x16x32_bf16 v[46:49], v[192:195], v[166:169], v[46:49]
	s_setprio 0
	s_nop 0
	v_mfma_f32_16x16x32_bf16 v[42:45], v[192:195], v[170:173], v[42:45]
	v_mfma_f32_16x16x32_bf16 v[38:41], v[192:195], v[176:179], v[38:41]
	v_mfma_f32_16x16x32_bf16 v[34:37], v[192:195], v[180:183], v[34:37]
	v_mfma_f32_16x16x32_bf16 v[30:33], v[196:199], v[146:149], v[30:33]
	v_mfma_f32_16x16x32_bf16 v[26:29], v[196:199], v[152:155], v[26:29]
	v_mfma_f32_16x16x32_bf16 v[22:25], v[196:199], v[156:159], v[22:25]
	v_mfma_f32_16x16x32_bf16 v[18:21], v[196:199], v[162:165], v[18:21]
	v_mfma_f32_16x16x32_bf16 v[14:17], v[196:199], v[166:169], v[14:17]
	v_mfma_f32_16x16x32_bf16 v[10:13], v[196:199], v[170:173], v[10:13]
	v_mfma_f32_16x16x32_bf16 v[6:9], v[196:199], v[176:179], v[6:9]
	v_mfma_f32_16x16x32_bf16 v[2:5], v[196:199], v[180:183], v[2:5]
	s_mov_b32 s37, s36
	s_nop 0
	s_add_i32 s36, s36, 0x6000
	s_cmp_eq_u32 s36, 0x12000
	s_cselect_b32 s36, 0, s36
	s_nop 0
	.p2align 3
	s_waitcnt lgkmcnt(0)
; DEVI unsigned pack2(float a, float b) { return __builtin_bit_cast(unsigned, __builtin_convertvector((f32x2_t){a, b}, bf16x2_t)); }
; DEVI float siluf_(float x) { return x * __builtin_amdgcn_rcpf(1.f + __expf(-x)); }
;     ...
;     for (int nf = 0; nf < 4; nf++)
; #pragma unroll
;       for (int mf = 0; mf < 8; mf++)
;         acc[nf][mf] = __builtin_amdgcn_mfma_f32_16x16x32_bf16(wb[nf], xa[mf], acc[nf][mf], 0, 0, 0);
;   }
;     ...
; #pragma unroll
;   for (int mf = 0; mf < 8; mf++) {
;     const int row = m0 + wm * 128 + mf * 16 + r16;
;     if (EPI == EPI_SWIGLU) {
; #pragma unroll
;       for (int nf = 0; nf < 2; nf++) {
;         const int hcol = (n0 >> 1) + wn * 32 + nf * 16 + quad * 4;
;         f32x4 g = acc[nf][mf], u = acc[nf + 2][mf];
;         u32x2 pk;
;         pk[0] = pack2(siluf_(g[0]) * u[0], siluf_(g[1]) * u[1]);
;         pk[1] = pack2(siluf_(g[2]) * u[2], siluf_(g[3]) * u[3]);
;         *(u32x2*)(outb + (size_t)row * DFF + hcol) = pk;
;       }
	s_nop 0
	v_mfma_f32_16x16x32_bf16 v[126:129], v[232:235], v[200:203], v[126:129]
	v_mfma_f32_16x16x32_bf16 v[122:125], v[232:235], v[204:207], v[122:125]
	v_mfma_f32_16x16x32_bf16 v[118:121], v[232:235], v[208:211], v[118:121]
	v_mfma_f32_16x16x32_bf16 v[114:117], v[232:235], v[212:215], v[114:117]
	v_mfma_f32_16x16x32_bf16 v[110:113], v[232:235], v[216:219], v[110:113]
	v_mfma_f32_16x16x32_bf16 v[106:109], v[232:235], v[220:223], v[106:109]
	v_mfma_f32_16x16x32_bf16 v[102:105], v[232:235], v[224:227], v[102:105]
	v_mfma_f32_16x16x32_bf16 v[98:101], v[232:235], v[228:231], v[98:101]
	v_mfma_f32_16x16x32_bf16 v[94:97], v[236:239], v[200:203], v[94:97]
	v_mfma_f32_16x16x32_bf16 v[90:93], v[236:239], v[204:207], v[90:93]
	v_mfma_f32_16x16x32_bf16 v[86:89], v[236:239], v[208:211], v[86:89]
	v_mfma_f32_16x16x32_bf16 v[82:85], v[236:239], v[212:215], v[82:85]
	v_mfma_f32_16x16x32_bf16 v[78:81], v[236:239], v[216:219], v[78:81]
	v_mfma_f32_16x16x32_bf16 v[74:77], v[236:239], v[220:223], v[74:77]
	v_mfma_f32_16x16x32_bf16 v[70:73], v[236:239], v[224:227], v[70:73]
	v_mfma_f32_16x16x32_bf16 v[66:69], v[236:239], v[228:231], v[66:69]
	v_mfma_f32_16x16x32_bf16 v[62:65], v[240:243], v[200:203], v[62:65]
	v_mfma_f32_16x16x32_bf16 v[58:61], v[240:243], v[204:207], v[58:61]
	v_mfma_f32_16x16x32_bf16 v[54:57], v[240:243], v[208:211], v[54:57]
	v_mfma_f32_16x16x32_bf16 v[50:53], v[240:243], v[212:215], v[50:53]
	v_mfma_f32_16x16x32_bf16 v[46:49], v[240:243], v[216:219], v[46:49]
	v_mfma_f32_16x16x32_bf16 v[42:45], v[240:243], v[220:223], v[42:45]
	v_mfma_f32_16x16x32_bf16 v[38:41], v[240:243], v[224:227], v[38:41]
	v_mfma_f32_16x16x32_bf16 v[34:37], v[240:243], v[228:231], v[34:37]
	v_mfma_f32_16x16x32_bf16 v[30:33], v[244:247], v[200:203], v[30:33]
	v_mfma_f32_16x16x32_bf16 v[26:29], v[244:247], v[204:207], v[26:29]
	v_mfma_f32_16x16x32_bf16 v[22:25], v[244:247], v[208:211], v[22:25]
	v_mfma_f32_16x16x32_bf16 v[18:21], v[244:247], v[212:215], v[18:21]
	v_mfma_f32_16x16x32_bf16 v[14:17], v[244:247], v[216:219], v[14:17]
	v_mfma_f32_16x16x32_bf16 v[10:13], v[244:247], v[220:223], v[10:13]
	v_mfma_f32_16x16x32_bf16 v[6:9], v[244:247], v[224:227], v[6:9]
	v_mfma_f32_16x16x32_bf16 v[2:5], v[244:247], v[228:231], v[2:5]
	s_mov_b32 m0, s39
	s_mov_b32 s10, 0x16000
	s_mov_b32 s11, 0
	s_mov_b32 s40, 0xbfb8aa3b
	s_nop 7
	v_mov_b32_e32 v224, s40
	v_mov_b32_e32 v225, s40
	v_mov_b32_e32 v226, 1.0
	v_mov_b32_e32 v227, 1.0
	v_pk_mul_f32 v[216:217], v[126:127], v[224:225]
	v_pk_mul_f32 v[218:219], v[128:129], v[224:225]
	v_exp_f32_e32 v216, v216
	v_exp_f32_e32 v217, v217
	v_exp_f32_e32 v218, v218
	v_exp_f32_e32 v219, v219
	v_pk_add_f32 v[216:217], v[216:217], v[226:227]
	v_pk_add_f32 v[218:219], v[218:219], v[226:227]
	v_rcp_f32_e32 v216, v216
	v_rcp_f32_e32 v217, v217
	v_rcp_f32_e32 v218, v218
	v_rcp_f32_e32 v219, v219
	v_pk_mul_f32 v[126:127], v[126:127], v[216:217]
	v_pk_mul_f32 v[128:129], v[128:129], v[218:219]
	v_pk_mul_f32 v[126:127], v[126:127], v[62:63]
	v_pk_mul_f32 v[128:129], v[128:129], v[64:65]
	v_pk_mul_f32 v[220:221], v[94:95], v[224:225]
	v_pk_mul_f32 v[222:223], v[96:97], v[224:225]
	v_exp_f32_e32 v220, v220
	v_exp_f32_e32 v221, v221
	v_exp_f32_e32 v222, v222
	v_exp_f32_e32 v223, v223
	v_pk_add_f32 v[220:221], v[220:221], v[226:227]
	v_pk_add_f32 v[222:223], v[222:223], v[226:227]
	v_rcp_f32_e32 v220, v220
	v_rcp_f32_e32 v221, v221
	v_rcp_f32_e32 v222, v222
	v_rcp_f32_e32 v223, v223
	v_pk_mul_f32 v[94:95], v[94:95], v[220:221]
	v_pk_mul_f32 v[96:97], v[96:97], v[222:223]
	v_pk_mul_f32 v[94:95], v[94:95], v[30:31]
	v_pk_mul_f32 v[96:97], v[96:97], v[32:33]
	v_cvt_pk_bf16_f32 v126, v126, v127
	v_cvt_pk_bf16_f32 v127, v128, v129
	v_cvt_pk_bf16_f32 v128, v94, v95
	v_cvt_pk_bf16_f32 v129, v96, v97
	s_nop 1
	v_permlane16_swap_b32_e32 v126, v128
	v_permlane16_swap_b32_e32 v127, v129
	global_store_dwordx4 v[140:141], v[126:129], off
	v_lshl_add_u64 v[140:141], v[140:141], 0, s[10:11]
	v_pk_mul_f32 v[216:217], v[122:123], v[224:225]
	v_pk_mul_f32 v[218:219], v[124:125], v[224:225]
	v_exp_f32_e32 v216, v216
	v_exp_f32_e32 v217, v217
	v_exp_f32_e32 v218, v218
	v_exp_f32_e32 v219, v219
	v_pk_add_f32 v[216:217], v[216:217], v[226:227]
	v_pk_add_f32 v[218:219], v[218:219], v[226:227]
	v_rcp_f32_e32 v216, v216
	v_rcp_f32_e32 v217, v217
	v_rcp_f32_e32 v218, v218
	v_rcp_f32_e32 v219, v219
	v_pk_mul_f32 v[122:123], v[122:123], v[216:217]
	v_pk_mul_f32 v[124:125], v[124:125], v[218:219]
	v_pk_mul_f32 v[122:123], v[122:123], v[58:59]
	v_pk_mul_f32 v[124:125], v[124:125], v[60:61]
	v_pk_mul_f32 v[220:221], v[90:91], v[224:225]
	v_pk_mul_f32 v[222:223], v[92:93], v[224:225]
	v_exp_f32_e32 v220, v220
	v_exp_f32_e32 v221, v221
	v_exp_f32_e32 v222, v222
	v_exp_f32_e32 v223, v223
	v_pk_add_f32 v[220:221], v[220:221], v[226:227]
	v_pk_add_f32 v[222:223], v[222:223], v[226:227]
	v_rcp_f32_e32 v220, v220
	v_rcp_f32_e32 v221, v221
	v_rcp_f32_e32 v222, v222
	v_rcp_f32_e32 v223, v223
	v_pk_mul_f32 v[90:91], v[90:91], v[220:221]
	v_pk_mul_f32 v[92:93], v[92:93], v[222:223]
	v_pk_mul_f32 v[90:91], v[90:91], v[26:27]
	v_pk_mul_f32 v[92:93], v[92:93], v[28:29]
	v_cvt_pk_bf16_f32 v122, v122, v123
	v_cvt_pk_bf16_f32 v123, v124, v125
	v_cvt_pk_bf16_f32 v124, v90, v91
	v_cvt_pk_bf16_f32 v125, v92, v93
	s_nop 1
	v_permlane16_swap_b32_e32 v122, v124
	v_permlane16_swap_b32_e32 v123, v125
	global_store_dwordx4 v[140:141], v[122:125], off
	v_lshl_add_u64 v[140:141], v[140:141], 0, s[10:11]
	v_pk_mul_f32 v[216:217], v[118:119], v[224:225]
	v_pk_mul_f32 v[218:219], v[120:121], v[224:225]
	v_exp_f32_e32 v216, v216
	v_exp_f32_e32 v217, v217
	v_exp_f32_e32 v218, v218
	v_exp_f32_e32 v219, v219
; DEVI unsigned pack2(float a, float b) { return __builtin_bit_cast(unsigned, __builtin_convertvector((f32x2_t){a, b}, bf16x2_t)); }
; DEVI float siluf_(float x) { return x * __builtin_amdgcn_rcpf(1.f + __expf(-x)); }
;     ...
;   for (int mf = 0; mf < 8; mf++) {
;     const int row = m0 + wm * 128 + mf * 16 + r16;
;     if (EPI == EPI_SWIGLU) {
; #pragma unroll
;       for (int nf = 0; nf < 2; nf++) {
;         const int hcol = (n0 >> 1) + wn * 32 + nf * 16 + quad * 4;
;         f32x4 g = acc[nf][mf], u = acc[nf + 2][mf];
;         u32x2 pk;
;         pk[0] = pack2(siluf_(g[0]) * u[0], siluf_(g[1]) * u[1]);
;         pk[1] = pack2(siluf_(g[2]) * u[2], siluf_(g[3]) * u[3]);
;         *(u32x2*)(outb + (size_t)row * DFF + hcol) = pk;
;       }
	v_pk_add_f32 v[216:217], v[216:217], v[226:227]
	v_pk_add_f32 v[218:219], v[218:219], v[226:227]
	v_rcp_f32_e32 v216, v216
	v_rcp_f32_e32 v217, v217
	v_rcp_f32_e32 v218, v218
	v_rcp_f32_e32 v219, v219
	v_pk_mul_f32 v[118:119], v[118:119], v[216:217]
	v_pk_mul_f32 v[120:121], v[120:121], v[218:219]
	v_pk_mul_f32 v[118:119], v[118:119], v[54:55]
	v_pk_mul_f32 v[120:121], v[120:121], v[56:57]
	v_pk_mul_f32 v[220:221], v[86:87], v[224:225]
	v_pk_mul_f32 v[222:223], v[88:89], v[224:225]
	v_exp_f32_e32 v220, v220
	v_exp_f32_e32 v221, v221
	v_exp_f32_e32 v222, v222
	v_exp_f32_e32 v223, v223
	v_pk_add_f32 v[220:221], v[220:221], v[226:227]
	v_pk_add_f32 v[222:223], v[222:223], v[226:227]
	v_rcp_f32_e32 v220, v220
	v_rcp_f32_e32 v221, v221
	v_rcp_f32_e32 v222, v222
	v_rcp_f32_e32 v223, v223
	v_pk_mul_f32 v[86:87], v[86:87], v[220:221]
	v_pk_mul_f32 v[88:89], v[88:89], v[222:223]
	v_pk_mul_f32 v[86:87], v[86:87], v[22:23]
	v_pk_mul_f32 v[88:89], v[88:89], v[24:25]
	v_cvt_pk_bf16_f32 v118, v118, v119
	v_cvt_pk_bf16_f32 v119, v120, v121
	v_cvt_pk_bf16_f32 v120, v86, v87
	v_cvt_pk_bf16_f32 v121, v88, v89
	s_nop 1
	v_permlane16_swap_b32_e32 v118, v120
	v_permlane16_swap_b32_e32 v119, v121
	global_store_dwordx4 v[140:141], v[118:121], off
	v_lshl_add_u64 v[140:141], v[140:141], 0, s[10:11]
	v_pk_mul_f32 v[216:217], v[114:115], v[224:225]
	v_pk_mul_f32 v[218:219], v[116:117], v[224:225]
	v_exp_f32_e32 v216, v216
	v_exp_f32_e32 v217, v217
	v_exp_f32_e32 v218, v218
	v_exp_f32_e32 v219, v219
	v_pk_add_f32 v[216:217], v[216:217], v[226:227]
	v_pk_add_f32 v[218:219], v[218:219], v[226:227]
	v_rcp_f32_e32 v216, v216
	v_rcp_f32_e32 v217, v217
	v_rcp_f32_e32 v218, v218
	v_rcp_f32_e32 v219, v219
	v_pk_mul_f32 v[114:115], v[114:115], v[216:217]
	v_pk_mul_f32 v[116:117], v[116:117], v[218:219]
	v_pk_mul_f32 v[114:115], v[114:115], v[50:51]
	v_pk_mul_f32 v[116:117], v[116:117], v[52:53]
	v_pk_mul_f32 v[220:221], v[82:83], v[224:225]
	v_pk_mul_f32 v[222:223], v[84:85], v[224:225]
	v_exp_f32_e32 v220, v220
	v_exp_f32_e32 v221, v221
	v_exp_f32_e32 v222, v222
	v_exp_f32_e32 v223, v223
	v_pk_add_f32 v[220:221], v[220:221], v[226:227]
	v_pk_add_f32 v[222:223], v[222:223], v[226:227]
	v_rcp_f32_e32 v220, v220
	v_rcp_f32_e32 v221, v221
	v_rcp_f32_e32 v222, v222
	v_rcp_f32_e32 v223, v223
	v_pk_mul_f32 v[82:83], v[82:83], v[220:221]
	v_pk_mul_f32 v[84:85], v[84:85], v[222:223]
	v_pk_mul_f32 v[82:83], v[82:83], v[18:19]
	v_pk_mul_f32 v[84:85], v[84:85], v[20:21]
	v_cvt_pk_bf16_f32 v114, v114, v115
	v_cvt_pk_bf16_f32 v115, v116, v117
	v_cvt_pk_bf16_f32 v116, v82, v83
	v_cvt_pk_bf16_f32 v117, v84, v85
	s_nop 1
	v_permlane16_swap_b32_e32 v114, v116
	v_permlane16_swap_b32_e32 v115, v117
	global_store_dwordx4 v[140:141], v[114:117], off
	v_lshl_add_u64 v[140:141], v[140:141], 0, s[10:11]
	v_pk_mul_f32 v[216:217], v[110:111], v[224:225]
	v_pk_mul_f32 v[218:219], v[112:113], v[224:225]
	v_exp_f32_e32 v216, v216
	v_exp_f32_e32 v217, v217
	v_exp_f32_e32 v218, v218
	v_exp_f32_e32 v219, v219
	v_pk_add_f32 v[216:217], v[216:217], v[226:227]
	v_pk_add_f32 v[218:219], v[218:219], v[226:227]
	v_rcp_f32_e32 v216, v216
	v_rcp_f32_e32 v217, v217
	v_rcp_f32_e32 v218, v218
	v_rcp_f32_e32 v219, v219
	v_pk_mul_f32 v[110:111], v[110:111], v[216:217]
	v_pk_mul_f32 v[112:113], v[112:113], v[218:219]
	v_pk_mul_f32 v[110:111], v[110:111], v[46:47]
	v_pk_mul_f32 v[112:113], v[112:113], v[48:49]
	v_pk_mul_f32 v[220:221], v[78:79], v[224:225]
	v_pk_mul_f32 v[222:223], v[80:81], v[224:225]
	v_exp_f32_e32 v220, v220
	v_exp_f32_e32 v221, v221
	v_exp_f32_e32 v222, v222
	v_exp_f32_e32 v223, v223
	v_pk_add_f32 v[220:221], v[220:221], v[226:227]
	v_pk_add_f32 v[222:223], v[222:223], v[226:227]
	v_rcp_f32_e32 v220, v220
	v_rcp_f32_e32 v221, v221
	v_rcp_f32_e32 v222, v222
	v_rcp_f32_e32 v223, v223
	v_pk_mul_f32 v[78:79], v[78:79], v[220:221]
	v_pk_mul_f32 v[80:81], v[80:81], v[222:223]
	v_pk_mul_f32 v[78:79], v[78:79], v[14:15]
	v_pk_mul_f32 v[80:81], v[80:81], v[16:17]
	v_cvt_pk_bf16_f32 v110, v110, v111
	v_cvt_pk_bf16_f32 v111, v112, v113
	v_cvt_pk_bf16_f32 v112, v78, v79
	v_cvt_pk_bf16_f32 v113, v80, v81
	s_nop 1
	v_permlane16_swap_b32_e32 v110, v112
	v_permlane16_swap_b32_e32 v111, v113
	global_store_dwordx4 v[140:141], v[110:113], off
	v_lshl_add_u64 v[140:141], v[140:141], 0, s[10:11]
	v_pk_mul_f32 v[216:217], v[106:107], v[224:225]
	v_pk_mul_f32 v[218:219], v[108:109], v[224:225]
	v_exp_f32_e32 v216, v216
; DEVI unsigned pack2(float a, float b) { return __builtin_bit_cast(unsigned, __builtin_convertvector((f32x2_t){a, b}, bf16x2_t)); }
; DEVI float siluf_(float x) { return x * __builtin_amdgcn_rcpf(1.f + __expf(-x)); }
; DEVI int xcd_first_tile() { return (blockIdx.x & 7) * (gridDim.x >> 3) + (blockIdx.x >> 3); }
;     ...
;   for (int mf = 0; mf < 8; mf++) {
;     const int row = m0 + wm * 128 + mf * 16 + r16;
;     if (EPI == EPI_SWIGLU) {
; #pragma unroll
;       for (int nf = 0; nf < 2; nf++) {
;         const int hcol = (n0 >> 1) + wn * 32 + nf * 16 + quad * 4;
;         f32x4 g = acc[nf][mf], u = acc[nf + 2][mf];
;         u32x2 pk;
;         pk[0] = pack2(siluf_(g[0]) * u[0], siluf_(g[1]) * u[1]);
;         pk[1] = pack2(siluf_(g[2]) * u[2], siluf_(g[3]) * u[3]);
;         *(u32x2*)(outb + (size_t)row * DFF + hcol) = pk;
;       }
; DEVI void run_phase(const Params& p, int ph, char* smem) {
;     ...
;       for (int t = xcd_first_tile(); t < 66 * 44; t += xcd_tile_step()) {
;         int mt_, nt_; tile_coords(t, 66, 44, mt_, nt_);
;         gemm_tile256<EPI_SWIGLU>(p, xb, 1024, Bt, 1024, mt_ * 256, nt_ * 128, hb, DFF, smem);
;       }
	v_exp_f32_e32 v217, v217
	v_exp_f32_e32 v218, v218
	v_exp_f32_e32 v219, v219
	v_pk_add_f32 v[216:217], v[216:217], v[226:227]
	v_pk_add_f32 v[218:219], v[218:219], v[226:227]
	v_rcp_f32_e32 v216, v216
	v_rcp_f32_e32 v217, v217
	v_rcp_f32_e32 v218, v218
	v_rcp_f32_e32 v219, v219
	v_pk_mul_f32 v[106:107], v[106:107], v[216:217]
	v_pk_mul_f32 v[108:109], v[108:109], v[218:219]
	v_pk_mul_f32 v[106:107], v[106:107], v[42:43]
	v_pk_mul_f32 v[108:109], v[108:109], v[44:45]
	v_pk_mul_f32 v[220:221], v[74:75], v[224:225]
	v_pk_mul_f32 v[222:223], v[76:77], v[224:225]
	v_exp_f32_e32 v220, v220
	v_exp_f32_e32 v221, v221
	v_exp_f32_e32 v222, v222
	v_exp_f32_e32 v223, v223
	v_pk_add_f32 v[220:221], v[220:221], v[226:227]
	v_pk_add_f32 v[222:223], v[222:223], v[226:227]
	v_rcp_f32_e32 v220, v220
	v_rcp_f32_e32 v221, v221
	v_rcp_f32_e32 v222, v222
	v_rcp_f32_e32 v223, v223
	v_pk_mul_f32 v[74:75], v[74:75], v[220:221]
	v_pk_mul_f32 v[76:77], v[76:77], v[222:223]
	v_pk_mul_f32 v[74:75], v[74:75], v[10:11]
	v_pk_mul_f32 v[76:77], v[76:77], v[12:13]
	v_cvt_pk_bf16_f32 v106, v106, v107
	v_cvt_pk_bf16_f32 v107, v108, v109
	v_cvt_pk_bf16_f32 v108, v74, v75
	v_cvt_pk_bf16_f32 v109, v76, v77
	s_nop 1
	v_permlane16_swap_b32_e32 v106, v108
	v_permlane16_swap_b32_e32 v107, v109
	global_store_dwordx4 v[140:141], v[106:109], off
	v_lshl_add_u64 v[140:141], v[140:141], 0, s[10:11]
	v_pk_mul_f32 v[216:217], v[102:103], v[224:225]
	v_pk_mul_f32 v[218:219], v[104:105], v[224:225]
	v_exp_f32_e32 v216, v216
	v_exp_f32_e32 v217, v217
	v_exp_f32_e32 v218, v218
	v_exp_f32_e32 v219, v219
	v_pk_add_f32 v[216:217], v[216:217], v[226:227]
	v_pk_add_f32 v[218:219], v[218:219], v[226:227]
	v_rcp_f32_e32 v216, v216
	v_rcp_f32_e32 v217, v217
	v_rcp_f32_e32 v218, v218
	v_rcp_f32_e32 v219, v219
	v_pk_mul_f32 v[102:103], v[102:103], v[216:217]
	v_pk_mul_f32 v[104:105], v[104:105], v[218:219]
	v_pk_mul_f32 v[102:103], v[102:103], v[38:39]
	v_pk_mul_f32 v[104:105], v[104:105], v[40:41]
	v_pk_mul_f32 v[220:221], v[70:71], v[224:225]
	v_pk_mul_f32 v[222:223], v[72:73], v[224:225]
	v_exp_f32_e32 v220, v220
	v_exp_f32_e32 v221, v221
	v_exp_f32_e32 v222, v222
	v_exp_f32_e32 v223, v223
	v_pk_add_f32 v[220:221], v[220:221], v[226:227]
	v_pk_add_f32 v[222:223], v[222:223], v[226:227]
	v_rcp_f32_e32 v220, v220
	v_rcp_f32_e32 v221, v221
	v_rcp_f32_e32 v222, v222
	v_rcp_f32_e32 v223, v223
	v_pk_mul_f32 v[70:71], v[70:71], v[220:221]
	v_pk_mul_f32 v[72:73], v[72:73], v[222:223]
	v_pk_mul_f32 v[70:71], v[70:71], v[6:7]
	v_pk_mul_f32 v[72:73], v[72:73], v[8:9]
	v_cvt_pk_bf16_f32 v102, v102, v103
	v_cvt_pk_bf16_f32 v103, v104, v105
	v_cvt_pk_bf16_f32 v104, v70, v71
	v_cvt_pk_bf16_f32 v105, v72, v73
	s_nop 1
	v_permlane16_swap_b32_e32 v102, v104
	v_permlane16_swap_b32_e32 v103, v105
	global_store_dwordx4 v[140:141], v[102:105], off
	v_lshl_add_u64 v[140:141], v[140:141], 0, s[10:11]
	v_pk_mul_f32 v[216:217], v[98:99], v[224:225]
	v_pk_mul_f32 v[218:219], v[100:101], v[224:225]
	v_exp_f32_e32 v216, v216
	v_exp_f32_e32 v217, v217
	v_exp_f32_e32 v218, v218
	v_exp_f32_e32 v219, v219
	v_pk_add_f32 v[216:217], v[216:217], v[226:227]
	v_pk_add_f32 v[218:219], v[218:219], v[226:227]
	v_rcp_f32_e32 v216, v216
	v_rcp_f32_e32 v217, v217
	v_rcp_f32_e32 v218, v218
	v_rcp_f32_e32 v219, v219
	v_pk_mul_f32 v[98:99], v[98:99], v[216:217]
	v_pk_mul_f32 v[100:101], v[100:101], v[218:219]
	v_pk_mul_f32 v[98:99], v[98:99], v[34:35]
	v_pk_mul_f32 v[100:101], v[100:101], v[36:37]
	v_pk_mul_f32 v[220:221], v[66:67], v[224:225]
	v_pk_mul_f32 v[222:223], v[68:69], v[224:225]
	v_exp_f32_e32 v220, v220
	v_exp_f32_e32 v221, v221
	v_exp_f32_e32 v222, v222
	v_exp_f32_e32 v223, v223
	v_pk_add_f32 v[220:221], v[220:221], v[226:227]
	v_pk_add_f32 v[222:223], v[222:223], v[226:227]
	v_rcp_f32_e32 v220, v220
	v_rcp_f32_e32 v221, v221
	v_rcp_f32_e32 v222, v222
	v_rcp_f32_e32 v223, v223
	v_pk_mul_f32 v[66:67], v[66:67], v[220:221]
	v_pk_mul_f32 v[68:69], v[68:69], v[222:223]
	v_pk_mul_f32 v[66:67], v[66:67], v[2:3]
	v_pk_mul_f32 v[68:69], v[68:69], v[4:5]
	v_cvt_pk_bf16_f32 v98, v98, v99
	v_cvt_pk_bf16_f32 v99, v100, v101
	v_cvt_pk_bf16_f32 v100, v66, v67
	v_cvt_pk_bf16_f32 v101, v68, v69
	s_nop 1
	v_permlane16_swap_b32_e32 v98, v100
	v_permlane16_swap_b32_e32 v99, v101
	global_store_dwordx4 v[140:141], v[98:101], off
	v_readlane_b32 s42, v250, 7
	s_add_i32 s8, s8, s42
	s_cmpk_gt_i32 s8, 0xb57
	s_cbranch_scc0 .LBB0_124
	s_branch .LBB0_131

; #define LAS __attribute__((address_space(3)))
;     ...
;   f32x4 acc[4][8];
; #pragma unroll
;   for (int i = 0; i < 4; i++)
; #pragma unroll
;     for (int j = 0; j < 8; j++) acc[i][j] = (f32x4){0.f, 0.f, 0.f, 0.f};
;   const int nk = (nk_part < 0) ? (K >> 5) : nk_part;
;   const int lrow = tid >> 2, lpc = tid & 3;
;   const int lch = lpc ^ ((0x78 >> (((lrow >> 2) & 3) * 2)) & 3);
;   const u16* ga = A + (size_t)(m0 + lrow) * lda + kbeg + lch * 8;
;   const u16* gb = Bt + (size_t)(n0 + lrow) * K + kbeg + lch * 8;
;   const size_t ga1 = (size_t)64 * lda, gb1 = (size_t)64 * K;
;   const unsigned lds0 = (unsigned)(uintptr_t)(LAS char*)smem + (unsigned)__builtin_amdgcn_readfirstlane(wid) * 1024u;
;     ...
;   __syncthreads();
;   G2_STAGE(0); G2_STAGE(1);
; DEVI void run_phase(const Params& p, int ph, char* smem) {
;     ...
;           const int u_ = t - 512, tl_ = u_ / 2, q_ = u_ - tl_ * 2;
;           gemm_tile256<EPI_RESID_ATOMIC>(p, ox, 256, Bt, 256, (64 + (tl_ & 1)) * 256, (tl_ >> 1) * 128, nullptr, 0, smem, q_ * 128, 4, q_);
.LBB0_147:
	s_cmpk_gt_i32 s38, 0x1ff
	s_mov_b64 s[2:3], -1
	s_cbranch_scc0 .LBB0_208
	s_setprio 2
	s_sub_i32 s98, s38, 512
	s_lshr_b32 s41, s98, 1
	s_and_b32 s99, s98, 1
	s_lshr_b32 s13, s41, 1
	s_and_b32 s41, s41, 1
	s_add_i32 s41, s41, 64
	v_readlane_b32 s2, v250, 5
	v_readlane_b32 s3, v250, 6
	v_readlane_b32 s98, v254, 62
	s_mul_i32 s1, s41, 0x20000
	s_add_u32 s4, s2, s1
	s_addc_u32 s5, s3, 0
	s_add_u32 s4, s4, 0xe700000
	s_addc_u32 s5, s5, 0
	s_mul_i32 s1, s98, 0x80000
	s_mul_i32 s12, s13, 0x10000
	s_add_i32 s1, s1, s12
	s_add_u32 s8, s2, s1
	s_addc_u32 s9, s3, 0
	s_add_u32 s8, s8, 0x16c00000
	s_addc_u32 s9, s9, 0
	s_mul_i32 s1, s99, 256
	s_add_u32 s4, s4, s1
	s_addc_u32 s5, s5, 0
	s_mul_i32 s1, s99, 512
	s_add_u32 s8, s8, s1
	s_addc_u32 s9, s9, 0
	s_movk_i32 s0, 0x78
	v_lshrrev_b32_e32 v0, 2, v145
	v_and_b32_e32 v131, 3, v145
	v_bfe_u32 v136, v145, 4, 2
	v_lshlrev_b32_e32 v136, 1, v136
	v_lshrrev_b32_e64 v136, v136, s0
	v_and_b32_e32 v136, 3, v136
	v_xor_b32_e32 v131, v131, v136
	v_lshlrev_b32_e32 v131, 4, v131
	s_movk_i32 s12, 0x200
	v_mad_u32_u24 v0, v0, s12, v131
	v_bfe_u32 v137, v145, 2, 1
	s_movk_i32 s12, 0x1c0
	v_mul_u32_u24_e32 v136, s12, v137
	v_sub_u32_e32 v136, v0, v136
	v_mov_b32_e32 v137, 0
	v_lshl_add_u64 v[134:135], s[8:9], 0, v[136:137]
	v_bfe_u32 v137, v145, 2, 1
	s_mov_b32 s10, 64
	s_mov_b32 s11, 0
	v_lshl_add_u64 v[132:133], s[4:5], 0, v[0:1]
	v_bfe_u32 v136, v145, 2, 2
	v_lshlrev_b32_e32 v136, 1, v136
	v_lshrrev_b32_e64 v136, v136, s0
	v_and_b32_e32 v136, 3, v136
	v_bfe_u32 v137, v145, 4, 2
	v_xor_b32_e32 v136, v136, v137
	v_lshlrev_b32_e32 v136, 4, v136
	v_and_b32_e32 v131, 15, v145
	v_lshl_or_b32 v136, v131, 6, v136
	v_bfe_u32 v137, v145, 6, 1
	v_lshl_or_b32 v137, v137, 12, v136
	v_lshrrev_b32_e32 v0, 7, v145
	v_lshl_or_b32 v136, v0, 13, v136
	v_and_b32_e32 v140, 1, v131
	v_lshl_or_b32 v131, v0, 7, v131
	v_bfe_u32 v0, v145, 4, 2
	v_lshlrev_b32_e32 v0, 3, v0
	v_bfe_u32 v141, v145, 6, 1
	s_lshl_b32 s1, s41, 19
	s_lshl_b32 s12, s13, 8
	s_add_i32 s1, s1, s12
	s_add_u32 s4, s2, s1
	s_addc_u32 s5, s3, 0
	s_add_u32 s4, s4, 0x4200000
	s_addc_u32 s5, s5, 0
	v_lshlrev_b32_e32 v138, 11, v131
	v_lshl_add_u32 v138, v141, 7, v138
	v_bfe_u32 v139, v145, 4, 1
	v_lshl_add_u32 v138, v139, 5, v138
	v_bfe_u32 v139, v145, 5, 1
	v_lshl_add_u32 v138, v139, 4, v138
	v_mov_b32_e32 v139, 0
	v_lshl_add_u64 v[138:139], s[4:5], 0, v[138:139]
	s_and_b32 s1, s41, 1
	s_lshl_b32 s1, s1, 20
	s_lshl_b32 s12, s99, 21
	s_add_i32 s1, s1, s12
	s_lshl_b32 s12, s13, 9
	s_add_i32 s1, s1, s12
	s_add_u32 s8, s2, s1
	s_addc_u32 s9, s3, 0
	s_add_u32 s8, s8, 0x1dcc0000
	s_addc_u32 s9, s9, 0
	v_lshlrev_b32_e32 v140, 12, v131
	v_lshl_add_u32 v140, v141, 8, v140
	v_lshl_add_u32 v140, v0, 1, v140
	v_mov_b32_e32 v141, 0
	v_lshl_add_u64 v[140:141], s[8:9], 0, v[140:141]
	s_mov_b32 s2, 0x8000
	s_mov_b32 s3, 0
	v_lshrrev_b32_e32 v0, 6, v145
	v_lshlrev_b32_e32 v0, 10, v0
	s_nop 0
	v_readfirstlane_b32 s98, v0
	s_mov_b32 s39, m0
	s_mov_b32 s4, 128
	s_mov_b32 s5, 0
	s_barrier
	s_add_i32 s13, s98, 0x0
	s_mov_b32 m0, s13
	v_lshl_add_u64 v[142:143], v[132:133], 0, s[2:3]
	global_load_lds_dwordx4 v[132:133], off
	s_add_i32 m0, m0, 0x1000
	s_nop 0
	global_load_lds_dwordx4 v[142:143], off
	v_lshl_add_u64 v[142:143], v[142:143], 0, s[2:3]
	s_add_i32 m0, m0, 0x1000
	s_nop 0
	global_load_lds_dwordx4 v[142:143], off
	v_lshl_add_u64 v[142:143], v[142:143], 0, s[2:3]
	s_add_i32 m0, m0, 0x1000
	s_nop 0
	global_load_lds_dwordx4 v[142:143], off
	s_add_i32 m0, m0, 0x1000
	v_lshl_add_u64 v[142:143], v[134:135], 0, s[2:3]
	s_nop 0
	global_load_lds_dwordx4 v[134:135], off
	s_add_i32 m0, m0, 0x1000
	v_lshl_add_u64 v[132:133], v[132:133], 0, s[10:11]
	s_nop 0
	global_load_lds_dwordx4 v[142:143], off
	v_lshl_add_u64 v[134:135], v[134:135], 0, s[4:5]
	s_nop 0
	s_add_i32 s13, s98, 0x6000
	s_mov_b32 m0, s13
	v_lshl_add_u64 v[142:143], v[132:133], 0, s[2:3]
	global_load_lds_dwordx4 v[132:133], off
	s_add_i32 m0, m0, 0x1000
	s_nop 0
	global_load_lds_dwordx4 v[142:143], off
	v_lshl_add_u64 v[142:143], v[142:143], 0, s[2:3]
	s_add_i32 m0, m0, 0x1000
	s_nop 0
	global_load_lds_dwordx4 v[142:143], off
	v_lshl_add_u64 v[142:143], v[142:143], 0, s[2:3]
	s_add_i32 m0, m0, 0x1000
	s_nop 0
	global_load_lds_dwordx4 v[142:143], off
	s_add_i32 m0, m0, 0x1000
	v_lshl_add_u64 v[142:143], v[134:135], 0, s[2:3]
	s_nop 0
	global_load_lds_dwordx4 v[134:135], off
	s_add_i32 m0, m0, 0x1000
	v_lshl_add_u64 v[132:133], v[132:133], 0, s[10:11]
	s_nop 0
	global_load_lds_dwordx4 v[142:143], off
	v_lshl_add_u64 v[134:135], v[134:135], 0, s[4:5]
	s_nop 0
	s_add_i32 s13, s98, 0xc000
	s_mov_b32 m0, s13
	v_lshl_add_u64 v[142:143], v[132:133], 0, s[2:3]
	global_load_lds_dwordx4 v[132:133], off
	s_add_i32 m0, m0, 0x1000
	s_nop 0
	global_load_lds_dwordx4 v[142:143], off
	v_lshl_add_u64 v[142:143], v[142:143], 0, s[2:3]
	s_add_i32 m0, m0, 0x1000
	s_nop 0
	global_load_lds_dwordx4 v[142:143], off
	v_lshl_add_u64 v[142:143], v[142:143], 0, s[2:3]
	s_add_i32 m0, m0, 0x1000
	s_nop 0
	global_load_lds_dwordx4 v[142:143], off
	s_add_i32 m0, m0, 0x1000
	v_lshl_add_u64 v[142:143], v[134:135], 0, s[2:3]
	s_nop 0
	global_load_lds_dwordx4 v[134:135], off
	s_add_i32 m0, m0, 0x1000
	v_lshl_add_u64 v[132:133], v[132:133], 0, s[10:11]
	s_nop 0
	global_load_lds_dwordx4 v[142:143], off
	v_lshl_add_u64 v[134:135], v[134:135], 0, s[4:5]
	s_nop 0
	v_mov_b32_e32 v2, 0
	v_mov_b32_e32 v3, 0
	v_mov_b32_e32 v4, 0
	v_mov_b32_e32 v5, 0
	v_mov_b32_e32 v6, 0
	v_mov_b32_e32 v7, 0
	v_mov_b32_e32 v8, 0
	v_mov_b32_e32 v9, 0
	v_mov_b32_e32 v10, 0
	v_mov_b32_e32 v11, 0
	v_mov_b32_e32 v12, 0
	v_mov_b32_e32 v13, 0
	v_mov_b32_e32 v14, 0
	v_mov_b32_e32 v15, 0
; #define LAS __attribute__((address_space(3)))
;     ...
;   f32x4 acc[4][8];
; #pragma unroll
;   for (int i = 0; i < 4; i++)
; #pragma unroll
;     for (int j = 0; j < 8; j++) acc[i][j] = (f32x4){0.f, 0.f, 0.f, 0.f};
;   const int nk = (nk_part < 0) ? (K >> 5) : nk_part;
;   const int lrow = tid >> 2, lpc = tid & 3;
;   const int lch = lpc ^ ((0x78 >> (((lrow >> 2) & 3) * 2)) & 3);
;   const u16* ga = A + (size_t)(m0 + lrow) * lda + kbeg + lch * 8;
;   const u16* gb = Bt + (size_t)(n0 + lrow) * K + kbeg + lch * 8;
;   const size_t ga1 = (size_t)64 * lda, gb1 = (size_t)64 * K;
;   const unsigned lds0 = (unsigned)(uintptr_t)(LAS char*)smem + (unsigned)__builtin_amdgcn_readfirstlane(wid) * 1024u;
;     ...
;   __syncthreads();
;   G2_STAGE(0); G2_STAGE(1);
;   const int fsw = (0x78 >> (((r16 >> 2) & 3) * 2)) & 3;
;   const int aoff = (wm * 128 + r16) * 64 + ((quad ^ fsw) << 4);
;   const int boff = 16384 + (wn * 64 + r16) * 64 + ((quad ^ fsw) << 4);
;   for (int kt = 0; kt < nk; kt++) {
;     if (kt + 1 < nk) asm volatile("s_waitcnt vmcnt(6)" ::: "memory");
;     else asm volatile("s_waitcnt vmcnt(0)" ::: "memory");
;     __builtin_amdgcn_s_barrier();
;     asm volatile("" ::: "memory");
;     if (kt + 2 < nk) G2_STAGE(kt + 2);
;     const char* cS = smem + (kt % 3) * 24576;
;     bf16x8 xa[8], wb[4];
; #pragma unroll
;     for (int f = 0; f < 8; f++) xa[f] = *(const bf16x8*)(cS + aoff + f * 1024);
; #pragma unroll
;     for (int f = 0; f < 4; f++) wb[f] = *(const bf16x8*)(cS + boff + f * 1024);
; #pragma unroll
;     for (int nf = 0; nf < 4; nf++)
; #pragma unroll
;       for (int mf = 0; mf < 8; mf++)
;         acc[nf][mf] = __builtin_amdgcn_mfma_f32_16x16x32_bf16(wb[nf], xa[mf], acc[nf][mf], 0, 0, 0);
;   }
	v_mov_b32_e32 v16, 0
	v_mov_b32_e32 v17, 0
	v_mov_b32_e32 v18, 0
	v_mov_b32_e32 v19, 0
	v_mov_b32_e32 v20, 0
	v_mov_b32_e32 v21, 0
	v_mov_b32_e32 v22, 0
	v_mov_b32_e32 v23, 0
	v_mov_b32_e32 v24, 0
	v_mov_b32_e32 v25, 0
	v_mov_b32_e32 v26, 0
	v_mov_b32_e32 v27, 0
	v_mov_b32_e32 v28, 0
	v_mov_b32_e32 v29, 0
	v_mov_b32_e32 v30, 0
	v_mov_b32_e32 v31, 0
	v_mov_b32_e32 v32, 0
	v_mov_b32_e32 v33, 0
	v_mov_b32_e32 v34, 0
	v_mov_b32_e32 v35, 0
	v_mov_b32_e32 v36, 0
	v_mov_b32_e32 v37, 0
	v_mov_b32_e32 v38, 0
	v_mov_b32_e32 v39, 0
	v_mov_b32_e32 v40, 0
	v_mov_b32_e32 v41, 0
	v_mov_b32_e32 v42, 0
	v_mov_b32_e32 v43, 0
	v_mov_b32_e32 v44, 0
	v_mov_b32_e32 v45, 0
	v_mov_b32_e32 v46, 0
	v_mov_b32_e32 v47, 0
	v_mov_b32_e32 v48, 0
	v_mov_b32_e32 v49, 0
	v_mov_b32_e32 v50, 0
	v_mov_b32_e32 v51, 0
	v_mov_b32_e32 v52, 0
	v_mov_b32_e32 v53, 0
	v_mov_b32_e32 v54, 0
	v_mov_b32_e32 v55, 0
	v_mov_b32_e32 v56, 0
	v_mov_b32_e32 v57, 0
	v_mov_b32_e32 v58, 0
	v_mov_b32_e32 v59, 0
	v_mov_b32_e32 v60, 0
	v_mov_b32_e32 v61, 0
	v_mov_b32_e32 v62, 0
	v_mov_b32_e32 v63, 0
	v_mov_b32_e32 v64, 0
	v_mov_b32_e32 v65, 0
	v_mov_b32_e32 v66, 0
	v_mov_b32_e32 v67, 0
	v_mov_b32_e32 v68, 0
	v_mov_b32_e32 v69, 0
	v_mov_b32_e32 v70, 0
	v_mov_b32_e32 v71, 0
	v_mov_b32_e32 v72, 0
	v_mov_b32_e32 v73, 0
	v_mov_b32_e32 v74, 0
	v_mov_b32_e32 v75, 0
	v_mov_b32_e32 v76, 0
	v_mov_b32_e32 v77, 0
	v_mov_b32_e32 v78, 0
	v_mov_b32_e32 v79, 0
	v_mov_b32_e32 v80, 0
	v_mov_b32_e32 v81, 0
	v_mov_b32_e32 v82, 0
	v_mov_b32_e32 v83, 0
	v_mov_b32_e32 v84, 0
	v_mov_b32_e32 v85, 0
	v_mov_b32_e32 v86, 0
	v_mov_b32_e32 v87, 0
	v_mov_b32_e32 v88, 0
	v_mov_b32_e32 v89, 0
	v_mov_b32_e32 v90, 0
	v_mov_b32_e32 v91, 0
	v_mov_b32_e32 v92, 0
	v_mov_b32_e32 v93, 0
	v_mov_b32_e32 v94, 0
	v_mov_b32_e32 v95, 0
	v_mov_b32_e32 v96, 0
	v_mov_b32_e32 v97, 0
	v_mov_b32_e32 v98, 0
	v_mov_b32_e32 v99, 0
	v_mov_b32_e32 v100, 0
	v_mov_b32_e32 v101, 0
	v_mov_b32_e32 v102, 0
	v_mov_b32_e32 v103, 0
	v_mov_b32_e32 v104, 0
	v_mov_b32_e32 v105, 0
	v_mov_b32_e32 v106, 0
	v_mov_b32_e32 v107, 0
	v_mov_b32_e32 v108, 0
	v_mov_b32_e32 v109, 0
	v_mov_b32_e32 v110, 0
	v_mov_b32_e32 v111, 0
	v_mov_b32_e32 v112, 0
	v_mov_b32_e32 v113, 0
	v_mov_b32_e32 v114, 0
	v_mov_b32_e32 v115, 0
	v_mov_b32_e32 v116, 0
	v_mov_b32_e32 v117, 0
	v_mov_b32_e32 v118, 0
	v_mov_b32_e32 v119, 0
	v_mov_b32_e32 v120, 0
	v_mov_b32_e32 v121, 0
	v_mov_b32_e32 v122, 0
	v_mov_b32_e32 v123, 0
	v_mov_b32_e32 v124, 0
	v_mov_b32_e32 v125, 0
	v_mov_b32_e32 v126, 0
	v_mov_b32_e32 v127, 0
	v_mov_b32_e32 v128, 0
	v_mov_b32_e32 v129, 0
	s_setprio 0
	s_waitcnt vmcnt(12)
	s_barrier
	ds_read_b128 v[146:149], v136 offset:0
	ds_read_b128 v[152:155], v136 offset:1024
	ds_read_b128 v[156:159], v136 offset:2048
	ds_read_b128 v[162:165], v136 offset:3072
	ds_read_b128 v[166:169], v136 offset:4096
	ds_read_b128 v[170:173], v136 offset:5120
	ds_read_b128 v[176:179], v136 offset:6144
	ds_read_b128 v[180:183], v136 offset:7168
	ds_read_b128 v[184:187], v137 offset:16384
	ds_read_b128 v[188:191], v137 offset:17408
	ds_read_b128 v[192:195], v137 offset:18432
	ds_read_b128 v[196:199], v137 offset:19456
	s_movk_i32 s1, 0x6000
	s_mov_b32 s12, 0
	.p2align 3
	s_waitcnt vmcnt(6) lgkmcnt(0)
	s_barrier
	s_setprio 1
	v_add_u32_e32 v144, s1, v136
	v_mfma_f32_16x16x32_bf16 v[126:129], v[184:187], v[146:149], v[126:129]
	ds_read_b128 v[200:203], v144 offset:0
	v_mfma_f32_16x16x32_bf16 v[122:125], v[184:187], v[152:155], v[122:125]
	ds_read_b128 v[204:207], v144 offset:1024
	v_mfma_f32_16x16x32_bf16 v[118:121], v[184:187], v[156:159], v[118:121]
	ds_read_b128 v[208:211], v144 offset:2048
	v_mfma_f32_16x16x32_bf16 v[114:117], v[184:187], v[162:165], v[114:117]
	ds_read_b128 v[212:215], v144 offset:3072
	v_mfma_f32_16x16x32_bf16 v[110:113], v[184:187], v[166:169], v[110:113]
	ds_read_b128 v[216:219], v144 offset:4096
	v_mfma_f32_16x16x32_bf16 v[106:109], v[184:187], v[170:173], v[106:109]
	ds_read_b128 v[220:223], v144 offset:5120
	v_mfma_f32_16x16x32_bf16 v[102:105], v[184:187], v[176:179], v[102:105]
	ds_read_b128 v[224:227], v144 offset:6144
	v_mfma_f32_16x16x32_bf16 v[98:101], v[184:187], v[180:183], v[98:101]
	ds_read_b128 v[228:231], v144 offset:7168
	v_mfma_f32_16x16x32_bf16 v[94:97], v[188:191], v[146:149], v[94:97]
	v_add_u32_e64 v144, s1, v137
	v_mfma_f32_16x16x32_bf16 v[90:93], v[188:191], v[152:155], v[90:93]
	v_mfma_f32_16x16x32_bf16 v[86:89], v[188:191], v[156:159], v[86:89]
	ds_read_b128 v[232:235], v144 offset:16384
	v_mfma_f32_16x16x32_bf16 v[82:85], v[188:191], v[162:165], v[82:85]
	ds_read_b128 v[236:239], v144 offset:17408
	v_mfma_f32_16x16x32_bf16 v[78:81], v[188:191], v[166:169], v[78:81]
	ds_read_b128 v[240:243], v144 offset:18432
	v_mfma_f32_16x16x32_bf16 v[74:77], v[188:191], v[170:173], v[74:77]
	ds_read_b128 v[244:247], v144 offset:19456
	v_mfma_f32_16x16x32_bf16 v[70:73], v[188:191], v[176:179], v[70:73]
	s_add_i32 s13, s98, s12
	s_mov_b32 m0, s13
	v_lshl_add_u64 v[142:143], v[132:133], 0, s[2:3]
	v_mfma_f32_16x16x32_bf16 v[66:69], v[188:191], v[180:183], v[66:69]
	global_load_lds_dwordx4 v[132:133], off
	s_add_i32 m0, m0, 0x1000
	v_mfma_f32_16x16x32_bf16 v[62:65], v[192:195], v[146:149], v[62:65]
	v_mfma_f32_16x16x32_bf16 v[58:61], v[192:195], v[152:155], v[58:61]
	v_mfma_f32_16x16x32_bf16 v[54:57], v[192:195], v[156:159], v[54:57]
	global_load_lds_dwordx4 v[142:143], off
	v_lshl_add_u64 v[142:143], v[142:143], 0, s[2:3]
	s_add_i32 m0, m0, 0x1000
	v_mfma_f32_16x16x32_bf16 v[50:53], v[192:195], v[162:165], v[50:53]
	v_mfma_f32_16x16x32_bf16 v[46:49], v[192:195], v[166:169], v[46:49]
	s_setprio 0
	s_nop 0
	v_mfma_f32_16x16x32_bf16 v[42:45], v[192:195], v[170:173], v[42:45]
	global_load_lds_dwordx4 v[142:143], off
	v_lshl_add_u64 v[142:143], v[142:143], 0, s[2:3]
	s_add_i32 m0, m0, 0x1000
	v_mfma_f32_16x16x32_bf16 v[38:41], v[192:195], v[176:179], v[38:41]
	v_mfma_f32_16x16x32_bf16 v[34:37], v[192:195], v[180:183], v[34:37]
	v_mfma_f32_16x16x32_bf16 v[30:33], v[196:199], v[146:149], v[30:33]
	global_load_lds_dwordx4 v[142:143], off
	s_add_i32 m0, m0, 0x1000
	v_lshl_add_u64 v[142:143], v[134:135], 0, s[2:3]
	v_mfma_f32_16x16x32_bf16 v[26:29], v[196:199], v[152:155], v[26:29]
	v_mfma_f32_16x16x32_bf16 v[22:25], v[196:199], v[156:159], v[22:25]
	v_mfma_f32_16x16x32_bf16 v[18:21], v[196:199], v[162:165], v[18:21]
	global_load_lds_dwordx4 v[134:135], off
	s_add_i32 m0, m0, 0x1000
	v_lshl_add_u64 v[132:133], v[132:133], 0, s[10:11]
	v_mfma_f32_16x16x32_bf16 v[14:17], v[196:199], v[166:169], v[14:17]
	v_mfma_f32_16x16x32_bf16 v[10:13], v[196:199], v[170:173], v[10:13]
	v_mfma_f32_16x16x32_bf16 v[6:9], v[196:199], v[176:179], v[6:9]
	global_load_lds_dwordx4 v[142:143], off
	v_lshl_add_u64 v[134:135], v[134:135], 0, s[4:5]
	v_mfma_f32_16x16x32_bf16 v[2:5], v[196:199], v[180:183], v[2:5]
	s_mov_b32 s12, s1
	s_nop 0
	s_add_i32 s1, s1, 0x6000
	s_cmp_eq_u32 s1, 0x12000
	s_cselect_b32 s1, 0, s1
	s_nop 0
	.p2align 3
	s_waitcnt vmcnt(6) lgkmcnt(0)
	s_barrier
;     ...
;   for (int kt = 0; kt < nk; kt++) {
;     if (kt + 1 < nk) asm volatile("s_waitcnt vmcnt(6)" ::: "memory");
;     else asm volatile("s_waitcnt vmcnt(0)" ::: "memory");
;     __builtin_amdgcn_s_barrier();
;     asm volatile("" ::: "memory");
;     if (kt + 2 < nk) G2_STAGE(kt + 2);
;     const char* cS = smem + (kt % 3) * 24576;
;     bf16x8 xa[8], wb[4];
; #pragma unroll
;     for (int f = 0; f < 8; f++) xa[f] = *(const bf16x8*)(cS + aoff + f * 1024);
; #pragma unroll
;     for (int f = 0; f < 4; f++) wb[f] = *(const bf16x8*)(cS + boff + f * 1024);
; #pragma unroll
;     for (int nf = 0; nf < 4; nf++)
; #pragma unroll
;       for (int mf = 0; mf < 8; mf++)
;         acc[nf][mf] = __builtin_amdgcn_mfma_f32_16x16x32_bf16(wb[nf], xa[mf], acc[nf][mf], 0, 0, 0);
;   }
	s_setprio 1
	v_add_u32_e32 v144, s1, v136
	v_mfma_f32_16x16x32_bf16 v[126:129], v[232:235], v[200:203], v[126:129]
	ds_read_b128 v[146:149], v144 offset:0
	v_mfma_f32_16x16x32_bf16 v[122:125], v[232:235], v[204:207], v[122:125]
	ds_read_b128 v[152:155], v144 offset:1024
	v_mfma_f32_16x16x32_bf16 v[118:121], v[232:235], v[208:211], v[118:121]
	ds_read_b128 v[156:159], v144 offset:2048
	v_mfma_f32_16x16x32_bf16 v[114:117], v[232:235], v[212:215], v[114:117]
	ds_read_b128 v[162:165], v144 offset:3072
	v_mfma_f32_16x16x32_bf16 v[110:113], v[232:235], v[216:219], v[110:113]
	ds_read_b128 v[166:169], v144 offset:4096
	v_mfma_f32_16x16x32_bf16 v[106:109], v[232:235], v[220:223], v[106:109]
	ds_read_b128 v[170:173], v144 offset:5120
	v_mfma_f32_16x16x32_bf16 v[102:105], v[232:235], v[224:227], v[102:105]
	ds_read_b128 v[176:179], v144 offset:6144
	v_mfma_f32_16x16x32_bf16 v[98:101], v[232:235], v[228:231], v[98:101]
	ds_read_b128 v[180:183], v144 offset:7168
	v_mfma_f32_16x16x32_bf16 v[94:97], v[236:239], v[200:203], v[94:97]
	v_add_u32_e64 v144, s1, v137
	v_mfma_f32_16x16x32_bf16 v[90:93], v[236:239], v[204:207], v[90:93]
	v_mfma_f32_16x16x32_bf16 v[86:89], v[236:239], v[208:211], v[86:89]
	ds_read_b128 v[184:187], v144 offset:16384
	v_mfma_f32_16x16x32_bf16 v[82:85], v[236:239], v[212:215], v[82:85]
	ds_read_b128 v[188:191], v144 offset:17408
	v_mfma_f32_16x16x32_bf16 v[78:81], v[236:239], v[216:219], v[78:81]
	ds_read_b128 v[192:195], v144 offset:18432
	v_mfma_f32_16x16x32_bf16 v[74:77], v[236:239], v[220:223], v[74:77]
	ds_read_b128 v[196:199], v144 offset:19456
	v_mfma_f32_16x16x32_bf16 v[70:73], v[236:239], v[224:227], v[70:73]
	v_mfma_f32_16x16x32_bf16 v[66:69], v[236:239], v[228:231], v[66:69]
	v_mfma_f32_16x16x32_bf16 v[62:65], v[240:243], v[200:203], v[62:65]
	v_mfma_f32_16x16x32_bf16 v[58:61], v[240:243], v[204:207], v[58:61]
	v_mfma_f32_16x16x32_bf16 v[54:57], v[240:243], v[208:211], v[54:57]
	v_mfma_f32_16x16x32_bf16 v[50:53], v[240:243], v[212:215], v[50:53]
	v_mfma_f32_16x16x32_bf16 v[46:49], v[240:243], v[216:219], v[46:49]
	s_setprio 0
	s_nop 0
	v_mfma_f32_16x16x32_bf16 v[42:45], v[240:243], v[220:223], v[42:45]
	v_mfma_f32_16x16x32_bf16 v[38:41], v[240:243], v[224:227], v[38:41]
	v_mfma_f32_16x16x32_bf16 v[34:37], v[240:243], v[228:231], v[34:37]
	v_mfma_f32_16x16x32_bf16 v[30:33], v[244:247], v[200:203], v[30:33]
	v_mfma_f32_16x16x32_bf16 v[26:29], v[244:247], v[204:207], v[26:29]
	v_mfma_f32_16x16x32_bf16 v[22:25], v[244:247], v[208:211], v[22:25]
	v_mfma_f32_16x16x32_bf16 v[18:21], v[244:247], v[212:215], v[18:21]
	v_mfma_f32_16x16x32_bf16 v[14:17], v[244:247], v[216:219], v[14:17]
	v_mfma_f32_16x16x32_bf16 v[10:13], v[244:247], v[220:223], v[10:13]
	v_mfma_f32_16x16x32_bf16 v[6:9], v[244:247], v[224:227], v[6:9]
	v_mfma_f32_16x16x32_bf16 v[2:5], v[244:247], v[228:231], v[2:5]
	s_mov_b32 s12, s1
	s_nop 0
	s_add_i32 s1, s1, 0x6000
	s_cmp_eq_u32 s1, 0x12000
	s_cselect_b32 s1, 0, s1
	s_nop 0
	.p2align 3
	s_waitcnt vmcnt(0) lgkmcnt(0)
	s_barrier
	s_setprio 1
	v_add_u32_e32 v144, s1, v136
	v_mfma_f32_16x16x32_bf16 v[126:129], v[184:187], v[146:149], v[126:129]
	ds_read_b128 v[200:203], v144 offset:0
	v_mfma_f32_16x16x32_bf16 v[122:125], v[184:187], v[152:155], v[122:125]
	ds_read_b128 v[204:207], v144 offset:1024
	v_mfma_f32_16x16x32_bf16 v[118:121], v[184:187], v[156:159], v[118:121]
	ds_read_b128 v[208:211], v144 offset:2048
	v_mfma_f32_16x16x32_bf16 v[114:117], v[184:187], v[162:165], v[114:117]
	ds_read_b128 v[212:215], v144 offset:3072
	v_mfma_f32_16x16x32_bf16 v[110:113], v[184:187], v[166:169], v[110:113]
	ds_read_b128 v[216:219], v144 offset:4096
	v_mfma_f32_16x16x32_bf16 v[106:109], v[184:187], v[170:173], v[106:109]
	ds_read_b128 v[220:223], v144 offset:5120
	v_mfma_f32_16x16x32_bf16 v[102:105], v[184:187], v[176:179], v[102:105]
	ds_read_b128 v[224:227], v144 offset:6144
	v_mfma_f32_16x16x32_bf16 v[98:101], v[184:187], v[180:183], v[98:101]
	ds_read_b128 v[228:231], v144 offset:7168
	v_mfma_f32_16x16x32_bf16 v[94:97], v[188:191], v[146:149], v[94:97]
	v_add_u32_e64 v144, s1, v137
	v_mfma_f32_16x16x32_bf16 v[90:93], v[188:191], v[152:155], v[90:93]
	v_mfma_f32_16x16x32_bf16 v[86:89], v[188:191], v[156:159], v[86:89]
	ds_read_b128 v[232:235], v144 offset:16384
	v_mfma_f32_16x16x32_bf16 v[82:85], v[188:191], v[162:165], v[82:85]
	ds_read_b128 v[236:239], v144 offset:17408
	v_mfma_f32_16x16x32_bf16 v[78:81], v[188:191], v[166:169], v[78:81]
	ds_read_b128 v[240:243], v144 offset:18432
	v_mfma_f32_16x16x32_bf16 v[74:77], v[188:191], v[170:173], v[74:77]
	ds_read_b128 v[244:247], v144 offset:19456
	v_mfma_f32_16x16x32_bf16 v[70:73], v[188:191], v[176:179], v[70:73]
	v_mfma_f32_16x16x32_bf16 v[66:69], v[188:191], v[180:183], v[66:69]
	v_mfma_f32_16x16x32_bf16 v[62:65], v[192:195], v[146:149], v[62:65]
	v_mfma_f32_16x16x32_bf16 v[58:61], v[192:195], v[152:155], v[58:61]
	v_mfma_f32_16x16x32_bf16 v[54:57], v[192:195], v[156:159], v[54:57]
	v_mfma_f32_16x16x32_bf16 v[50:53], v[192:195], v[162:165], v[50:53]
	v_mfma_f32_16x16x32_bf16 v[46:49], v[192:195], v[166:169], v[46:49]
	s_setprio 0
	s_nop 0
	v_mfma_f32_16x16x32_bf16 v[42:45], v[192:195], v[170:173], v[42:45]
	v_mfma_f32_16x16x32_bf16 v[38:41], v[192:195], v[176:179], v[38:41]
	v_mfma_f32_16x16x32_bf16 v[34:37], v[192:195], v[180:183], v[34:37]
	v_mfma_f32_16x16x32_bf16 v[30:33], v[196:199], v[146:149], v[30:33]
	v_mfma_f32_16x16x32_bf16 v[26:29], v[196:199], v[152:155], v[26:29]
	v_mfma_f32_16x16x32_bf16 v[22:25], v[196:199], v[156:159], v[22:25]
	v_mfma_f32_16x16x32_bf16 v[18:21], v[196:199], v[162:165], v[18:21]
	v_mfma_f32_16x16x32_bf16 v[14:17], v[196:199], v[166:169], v[14:17]
	v_mfma_f32_16x16x32_bf16 v[10:13], v[196:199], v[170:173], v[10:13]
	v_mfma_f32_16x16x32_bf16 v[6:9], v[196:199], v[176:179], v[6:9]
	v_mfma_f32_16x16x32_bf16 v[2:5], v[196:199], v[180:183], v[2:5]
	s_mov_b32 s12, s1
	s_nop 0
	s_add_i32 s1, s1, 0x6000
	s_cmp_eq_u32 s1, 0x12000
	s_cselect_b32 s1, 0, s1
	s_nop 0
	s_mov_b32 s4, 0x8000
	s_mov_b32 s5, 0
	s_mov_b32 s8, 0x10000
	s_mov_b32 s9, 0
	s_mov_b32 s40, 0x3fd744fd
	.p2align 3
	s_waitcnt lgkmcnt(0)
; DEVI unsigned pack2(float a, float b) { return __builtin_bit_cast(unsigned, __builtin_convertvector((f32x2_t){a, b}, bf16x2_t)); }
; DEVI float blo(unsigned u) { return __uint_as_float(u << 16); }
; DEVI float bhi(unsigned u) { return __uint_as_float(u & 0xffff0000u); }
; DEVI float siluf_(float x) { return x * __builtin_amdgcn_rcpf(1.f + __expf(-x)); }
;     ...
;     for (int nf = 0; nf < 4; nf++)
; #pragma unroll
;       for (int mf = 0; mf < 8; mf++)
;         acc[nf][mf] = __builtin_amdgcn_mfma_f32_16x16x32_bf16(wb[nf], xa[mf], acc[nf][mf], 0, 0, 0);
;   }
;     ...
; #pragma unroll
;   for (int mf = 0; mf < 8; mf++) {
;     const int row = m0 + wm * 128 + mf * 16 + r16;
;     if (EPI == EPI_SWIGLU) {
; #pragma unroll
;       for (int nf = 0; nf < 2; nf++) {
;         const int hcol = (n0 >> 1) + wn * 32 + nf * 16 + quad * 4;
;         f32x4 g = acc[nf][mf], u = acc[nf + 2][mf];
;         u32x2 pk;
;         pk[0] = pack2(siluf_(g[0]) * u[0], siluf_(g[1]) * u[1]);
;         pk[1] = pack2(siluf_(g[2]) * u[2], siluf_(g[3]) * u[3]);
;         *(u32x2*)(outb + (size_t)row * DFF + hcol) = pk;
;       }
;     } else {
; #pragma unroll
;       for (int nf = 0; nf < 4; nf++) {
;         const int col = n0 + wn * 64 + nf * 16 + quad * 4;
;         f32x4 a = acc[nf][mf];
;         if (EPI == EPI_RESID || EPI == EPI_RESID_ATOMIC) {
;           f32x4 x = a;
;           if (EPI == EPI_RESID || kpart == 0) {
;             const u32x2 xr = *(const u32x2*)((const u16*)(p.ws + WS_XB) + (size_t)row * 1024 + col);
;             x[0] += ALPHA * blo(xr[0]); x[1] += ALPHA * bhi(xr[0]); x[2] += ALPHA * blo(xr[1]); x[3] += ALPHA * bhi(xr[1]);
;           }
;           if (EPI == EPI_RESID) *(f32x4*)((float*)(p.ws + WS_XF) + (size_t)row * 1024 + col) = x;
;           else *(f32x4*)((float*)(p.ws + WS_SLAB) + ((size_t)kpart * 512 + (row - T_P)) * 1024 + col) = x;
; DEVI void run_phase(const Params& p, int ph, char* smem) {
;     ...
;           const int u_ = t - 512, tl_ = u_ / 2, q_ = u_ - tl_ * 2;
;           gemm_tile256<EPI_RESID_ATOMIC>(p, ox, 256, Bt, 256, (64 + (tl_ & 1)) * 256, (tl_ >> 1) * 128, nullptr, 0, smem, q_ * 128, 4, q_);
;         }
	s_nop 0
	v_mfma_f32_16x16x32_bf16 v[126:129], v[232:235], v[200:203], v[126:129]
	v_mfma_f32_16x16x32_bf16 v[122:125], v[232:235], v[204:207], v[122:125]
	v_mfma_f32_16x16x32_bf16 v[118:121], v[232:235], v[208:211], v[118:121]
	v_mfma_f32_16x16x32_bf16 v[114:117], v[232:235], v[212:215], v[114:117]
	v_mfma_f32_16x16x32_bf16 v[110:113], v[232:235], v[216:219], v[110:113]
	v_mfma_f32_16x16x32_bf16 v[106:109], v[232:235], v[220:223], v[106:109]
	v_mfma_f32_16x16x32_bf16 v[102:105], v[232:235], v[224:227], v[102:105]
	v_mfma_f32_16x16x32_bf16 v[98:101], v[232:235], v[228:231], v[98:101]
	v_mfma_f32_16x16x32_bf16 v[94:97], v[236:239], v[200:203], v[94:97]
	v_mfma_f32_16x16x32_bf16 v[90:93], v[236:239], v[204:207], v[90:93]
	v_mfma_f32_16x16x32_bf16 v[86:89], v[236:239], v[208:211], v[86:89]
	v_mfma_f32_16x16x32_bf16 v[82:85], v[236:239], v[212:215], v[82:85]
	v_mfma_f32_16x16x32_bf16 v[78:81], v[236:239], v[216:219], v[78:81]
	v_mfma_f32_16x16x32_bf16 v[74:77], v[236:239], v[220:223], v[74:77]
	v_mfma_f32_16x16x32_bf16 v[70:73], v[236:239], v[224:227], v[70:73]
	v_mfma_f32_16x16x32_bf16 v[66:69], v[236:239], v[228:231], v[66:69]
	v_mfma_f32_16x16x32_bf16 v[62:65], v[240:243], v[200:203], v[62:65]
	v_mfma_f32_16x16x32_bf16 v[58:61], v[240:243], v[204:207], v[58:61]
	v_mfma_f32_16x16x32_bf16 v[54:57], v[240:243], v[208:211], v[54:57]
	v_mfma_f32_16x16x32_bf16 v[50:53], v[240:243], v[212:215], v[50:53]
	v_mfma_f32_16x16x32_bf16 v[46:49], v[240:243], v[216:219], v[46:49]
	v_mfma_f32_16x16x32_bf16 v[42:45], v[240:243], v[220:223], v[42:45]
	v_mfma_f32_16x16x32_bf16 v[38:41], v[240:243], v[224:227], v[38:41]
	v_mfma_f32_16x16x32_bf16 v[34:37], v[240:243], v[228:231], v[34:37]
	v_mfma_f32_16x16x32_bf16 v[30:33], v[244:247], v[200:203], v[30:33]
	v_mfma_f32_16x16x32_bf16 v[26:29], v[244:247], v[204:207], v[26:29]
	v_mfma_f32_16x16x32_bf16 v[22:25], v[244:247], v[208:211], v[22:25]
	v_mfma_f32_16x16x32_bf16 v[18:21], v[244:247], v[212:215], v[18:21]
	v_mfma_f32_16x16x32_bf16 v[14:17], v[244:247], v[216:219], v[14:17]
	v_mfma_f32_16x16x32_bf16 v[10:13], v[244:247], v[220:223], v[10:13]
	v_mfma_f32_16x16x32_bf16 v[6:9], v[244:247], v[224:227], v[6:9]
	v_mfma_f32_16x16x32_bf16 v[2:5], v[244:247], v[228:231], v[2:5]
	s_mov_b32 m0, s39
	s_cmp_eq_u32 s99, 0
	s_cbranch_scc1 .Lta8_first
	s_nop 7
	global_store_dwordx4 v[140:141], v[126:129], off offset:0
	global_store_dwordx4 v[140:141], v[94:97], off offset:64
	global_store_dwordx4 v[140:141], v[62:65], off offset:128
	global_store_dwordx4 v[140:141], v[30:33], off offset:192
	v_lshl_add_u64 v[140:141], v[140:141], 0, s[8:9]
	global_store_dwordx4 v[140:141], v[122:125], off offset:0
	global_store_dwordx4 v[140:141], v[90:93], off offset:64
	global_store_dwordx4 v[140:141], v[58:61], off offset:128
	global_store_dwordx4 v[140:141], v[26:29], off offset:192
	v_lshl_add_u64 v[140:141], v[140:141], 0, s[8:9]
	global_store_dwordx4 v[140:141], v[118:121], off offset:0
	global_store_dwordx4 v[140:141], v[86:89], off offset:64
	global_store_dwordx4 v[140:141], v[54:57], off offset:128
	global_store_dwordx4 v[140:141], v[22:25], off offset:192
	v_lshl_add_u64 v[140:141], v[140:141], 0, s[8:9]
	global_store_dwordx4 v[140:141], v[114:117], off offset:0
	global_store_dwordx4 v[140:141], v[82:85], off offset:64
	global_store_dwordx4 v[140:141], v[50:53], off offset:128
	global_store_dwordx4 v[140:141], v[18:21], off offset:192
	v_lshl_add_u64 v[140:141], v[140:141], 0, s[8:9]
	global_store_dwordx4 v[140:141], v[110:113], off offset:0
	global_store_dwordx4 v[140:141], v[78:81], off offset:64
	global_store_dwordx4 v[140:141], v[46:49], off offset:128
	global_store_dwordx4 v[140:141], v[14:17], off offset:192
	v_lshl_add_u64 v[140:141], v[140:141], 0, s[8:9]
	global_store_dwordx4 v[140:141], v[106:109], off offset:0
	global_store_dwordx4 v[140:141], v[74:77], off offset:64
	global_store_dwordx4 v[140:141], v[42:45], off offset:128
	global_store_dwordx4 v[140:141], v[10:13], off offset:192
	v_lshl_add_u64 v[140:141], v[140:141], 0, s[8:9]
	global_store_dwordx4 v[140:141], v[102:105], off offset:0
	global_store_dwordx4 v[140:141], v[70:73], off offset:64
	global_store_dwordx4 v[140:141], v[38:41], off offset:128
	global_store_dwordx4 v[140:141], v[6:9], off offset:192
	v_lshl_add_u64 v[140:141], v[140:141], 0, s[8:9]
	global_store_dwordx4 v[140:141], v[98:101], off offset:0
	global_store_dwordx4 v[140:141], v[66:69], off offset:64
	global_store_dwordx4 v[140:141], v[34:37], off offset:128
	global_store_dwordx4 v[140:141], v[2:5], off offset:192
	v_readlane_b32 s0, v250, 7
	s_cmpk_lg_u32 s0, 0x200
	s_cbranch_scc1 .Lta8_ar1
	s_mov_b32 s0, 1
	v_writelane_b32 v255, s0, 41
	v_readlane_b32 s1, v250, 0
	s_lshr_b32 s12, s1, 3
	s_and_b32 s1, s1, 7
	s_lshl_b32 s1, s1, 6
	s_add_i32 s1, s1, s12
	s_sub_i32 s38, s1, 0x200

;     ...
;   __syncthreads();
;   G2_STAGE(0); G2_STAGE(1);
;   const int fsw = (0x78 >> (((r16 >> 2) & 3) * 2)) & 3;
;   const int aoff = (wm * 128 + r16) * 64 + ((quad ^ fsw) << 4);
;   const int boff = 16384 + (wn * 64 + r16) * 64 + ((quad ^ fsw) << 4);
;   for (int kt = 0; kt < nk; kt++) {
;     if (kt + 1 < nk) asm volatile("s_waitcnt vmcnt(6)" ::: "memory");
;     else asm volatile("s_waitcnt vmcnt(0)" ::: "memory");
;     __builtin_amdgcn_s_barrier();
;     asm volatile("" ::: "memory");
;     if (kt + 2 < nk) G2_STAGE(kt + 2);
;     const char* cS = smem + (kt % 3) * 24576;
;     bf16x8 xa[8], wb[4];
; #pragma unroll
;     for (int f = 0; f < 8; f++) xa[f] = *(const bf16x8*)(cS + aoff + f * 1024);
; #pragma unroll
;     for (int f = 0; f < 4; f++) wb[f] = *(const bf16x8*)(cS + boff + f * 1024);
; #pragma unroll
;     for (int nf = 0; nf < 4; nf++)
; #pragma unroll
;       for (int mf = 0; mf < 8; mf++)
;         acc[nf][mf] = __builtin_amdgcn_mfma_f32_16x16x32_bf16(wb[nf], xa[mf], acc[nf][mf], 0, 0, 0);
;   }
.Lt8_loop:
	.p2align 3
	s_waitcnt vmcnt(6) lgkmcnt(0)
	s_barrier
	s_setprio 1
	v_add_u32_e32 v144, s40, v136
	v_mfma_f32_16x16x32_bf16 v[126:129], v[184:187], v[146:149], v[126:129]
	ds_read_b128 v[200:203], v144 offset:0
	v_mfma_f32_16x16x32_bf16 v[122:125], v[184:187], v[152:155], v[122:125]
	ds_read_b128 v[204:207], v144 offset:1024
	v_mfma_f32_16x16x32_bf16 v[118:121], v[184:187], v[156:159], v[118:121]
	ds_read_b128 v[208:211], v144 offset:2048
	v_mfma_f32_16x16x32_bf16 v[114:117], v[184:187], v[162:165], v[114:117]
	ds_read_b128 v[212:215], v144 offset:3072
	v_mfma_f32_16x16x32_bf16 v[110:113], v[184:187], v[166:169], v[110:113]
	ds_read_b128 v[216:219], v144 offset:4096
	v_mfma_f32_16x16x32_bf16 v[106:109], v[184:187], v[170:173], v[106:109]
	ds_read_b128 v[220:223], v144 offset:5120
	v_mfma_f32_16x16x32_bf16 v[102:105], v[184:187], v[176:179], v[102:105]
	ds_read_b128 v[224:227], v144 offset:6144
	v_mfma_f32_16x16x32_bf16 v[98:101], v[184:187], v[180:183], v[98:101]
	ds_read_b128 v[228:231], v144 offset:7168
	v_mfma_f32_16x16x32_bf16 v[94:97], v[188:191], v[146:149], v[94:97]
	v_add_u32_e64 v144, s40, v137
	v_mfma_f32_16x16x32_bf16 v[90:93], v[188:191], v[152:155], v[90:93]
	v_mfma_f32_16x16x32_bf16 v[86:89], v[188:191], v[156:159], v[86:89]
	ds_read_b128 v[232:235], v144 offset:16384
	v_mfma_f32_16x16x32_bf16 v[82:85], v[188:191], v[162:165], v[82:85]
	ds_read_b128 v[236:239], v144 offset:17408
	v_mfma_f32_16x16x32_bf16 v[78:81], v[188:191], v[166:169], v[78:81]
	ds_read_b128 v[240:243], v144 offset:18432
	v_mfma_f32_16x16x32_bf16 v[74:77], v[188:191], v[170:173], v[74:77]
	ds_read_b128 v[244:247], v144 offset:19456
	v_mfma_f32_16x16x32_bf16 v[70:73], v[188:191], v[176:179], v[70:73]
	s_add_i32 s42, s46, s41
	s_mov_b32 m0, s42
	v_lshl_add_u64 v[142:143], v[132:133], 0, s[2:3]
	v_mfma_f32_16x16x32_bf16 v[66:69], v[188:191], v[180:183], v[66:69]
	global_load_lds_dwordx4 v[132:133], off
	s_add_i32 m0, m0, 0x1000
	v_mfma_f32_16x16x32_bf16 v[62:65], v[192:195], v[146:149], v[62:65]
	v_mfma_f32_16x16x32_bf16 v[58:61], v[192:195], v[152:155], v[58:61]
	v_mfma_f32_16x16x32_bf16 v[54:57], v[192:195], v[156:159], v[54:57]
	global_load_lds_dwordx4 v[142:143], off
	v_lshl_add_u64 v[142:143], v[142:143], 0, s[2:3]
	s_add_i32 m0, m0, 0x1000
	v_mfma_f32_16x16x32_bf16 v[50:53], v[192:195], v[162:165], v[50:53]
	v_mfma_f32_16x16x32_bf16 v[46:49], v[192:195], v[166:169], v[46:49]
	s_setprio 0
	s_nop 0
	v_mfma_f32_16x16x32_bf16 v[42:45], v[192:195], v[170:173], v[42:45]
	global_load_lds_dwordx4 v[142:143], off
	v_lshl_add_u64 v[142:143], v[142:143], 0, s[2:3]
	s_add_i32 m0, m0, 0x1000
	v_mfma_f32_16x16x32_bf16 v[38:41], v[192:195], v[176:179], v[38:41]
	v_mfma_f32_16x16x32_bf16 v[34:37], v[192:195], v[180:183], v[34:37]
	v_mfma_f32_16x16x32_bf16 v[30:33], v[196:199], v[146:149], v[30:33]
	global_load_lds_dwordx4 v[142:143], off
	s_add_i32 m0, m0, 0x1000
	v_lshl_add_u64 v[142:143], v[134:135], 0, s[2:3]
	v_mfma_f32_16x16x32_bf16 v[26:29], v[196:199], v[152:155], v[26:29]
	v_mfma_f32_16x16x32_bf16 v[22:25], v[196:199], v[156:159], v[22:25]
	v_mfma_f32_16x16x32_bf16 v[18:21], v[196:199], v[162:165], v[18:21]
	global_load_lds_dwordx4 v[134:135], off
	s_add_i32 m0, m0, 0x1000
	v_lshl_add_u64 v[132:133], v[132:133], 0, s[12:13]
	v_mfma_f32_16x16x32_bf16 v[14:17], v[196:199], v[166:169], v[14:17]
	v_mfma_f32_16x16x32_bf16 v[10:13], v[196:199], v[170:173], v[10:13]
	v_mfma_f32_16x16x32_bf16 v[6:9], v[196:199], v[176:179], v[6:9]
	global_load_lds_dwordx4 v[142:143], off
	v_lshl_add_u64 v[134:135], v[134:135], 0, s[4:5]
	v_mfma_f32_16x16x32_bf16 v[2:5], v[196:199], v[180:183], v[2:5]
	s_mov_b32 s41, s40
	s_nop 0
	s_add_i32 s40, s40, 0x6000
	s_cmp_eq_u32 s40, 0x12000
	s_cselect_b32 s40, 0, s40
	s_nop 0
	.p2align 3
	s_waitcnt vmcnt(6) lgkmcnt(0)
	s_barrier
	s_setprio 1
	v_add_u32_e32 v144, s40, v136
	v_mfma_f32_16x16x32_bf16 v[126:129], v[232:235], v[200:203], v[126:129]
	ds_read_b128 v[146:149], v144 offset:0
	v_mfma_f32_16x16x32_bf16 v[122:125], v[232:235], v[204:207], v[122:125]
	ds_read_b128 v[152:155], v144 offset:1024
	v_mfma_f32_16x16x32_bf16 v[118:121], v[232:235], v[208:211], v[118:121]
	ds_read_b128 v[156:159], v144 offset:2048
	v_mfma_f32_16x16x32_bf16 v[114:117], v[232:235], v[212:215], v[114:117]
	ds_read_b128 v[162:165], v144 offset:3072
	v_mfma_f32_16x16x32_bf16 v[110:113], v[232:235], v[216:219], v[110:113]
	ds_read_b128 v[166:169], v144 offset:4096
	v_mfma_f32_16x16x32_bf16 v[106:109], v[232:235], v[220:223], v[106:109]
	ds_read_b128 v[170:173], v144 offset:5120
	v_mfma_f32_16x16x32_bf16 v[102:105], v[232:235], v[224:227], v[102:105]
	ds_read_b128 v[176:179], v144 offset:6144
	v_mfma_f32_16x16x32_bf16 v[98:101], v[232:235], v[228:231], v[98:101]
	ds_read_b128 v[180:183], v144 offset:7168
	v_mfma_f32_16x16x32_bf16 v[94:97], v[236:239], v[200:203], v[94:97]
	v_add_u32_e64 v144, s40, v137
	v_mfma_f32_16x16x32_bf16 v[90:93], v[236:239], v[204:207], v[90:93]
	v_mfma_f32_16x16x32_bf16 v[86:89], v[236:239], v[208:211], v[86:89]
	ds_read_b128 v[184:187], v144 offset:16384
	v_mfma_f32_16x16x32_bf16 v[82:85], v[236:239], v[212:215], v[82:85]
	ds_read_b128 v[188:191], v144 offset:17408
	v_mfma_f32_16x16x32_bf16 v[78:81], v[236:239], v[216:219], v[78:81]
	ds_read_b128 v[192:195], v144 offset:18432
	v_mfma_f32_16x16x32_bf16 v[74:77], v[236:239], v[220:223], v[74:77]
	ds_read_b128 v[196:199], v144 offset:19456
	v_mfma_f32_16x16x32_bf16 v[70:73], v[236:239], v[224:227], v[70:73]
	s_add_i32 s42, s46, s41
	s_mov_b32 m0, s42
	v_lshl_add_u64 v[142:143], v[132:133], 0, s[2:3]
	v_mfma_f32_16x16x32_bf16 v[66:69], v[236:239], v[228:231], v[66:69]
;     ...
;   __syncthreads();
;   G2_STAGE(0); G2_STAGE(1);
;   const int fsw = (0x78 >> (((r16 >> 2) & 3) * 2)) & 3;
;   const int aoff = (wm * 128 + r16) * 64 + ((quad ^ fsw) << 4);
;   const int boff = 16384 + (wn * 64 + r16) * 64 + ((quad ^ fsw) << 4);
;   for (int kt = 0; kt < nk; kt++) {
;     if (kt + 1 < nk) asm volatile("s_waitcnt vmcnt(6)" ::: "memory");
;     else asm volatile("s_waitcnt vmcnt(0)" ::: "memory");
;     __builtin_amdgcn_s_barrier();
;     asm volatile("" ::: "memory");
;     if (kt + 2 < nk) G2_STAGE(kt + 2);
;     const char* cS = smem + (kt % 3) * 24576;
;     bf16x8 xa[8], wb[4];
; #pragma unroll
;     for (int f = 0; f < 8; f++) xa[f] = *(const bf16x8*)(cS + aoff + f * 1024);
; #pragma unroll
;     for (int f = 0; f < 4; f++) wb[f] = *(const bf16x8*)(cS + boff + f * 1024);
; #pragma unroll
;     for (int nf = 0; nf < 4; nf++)
; #pragma unroll
;       for (int mf = 0; mf < 8; mf++)
;         acc[nf][mf] = __builtin_amdgcn_mfma_f32_16x16x32_bf16(wb[nf], xa[mf], acc[nf][mf], 0, 0, 0);
;   }
	global_load_lds_dwordx4 v[132:133], off
	s_add_i32 m0, m0, 0x1000
	v_mfma_f32_16x16x32_bf16 v[62:65], v[240:243], v[200:203], v[62:65]
	v_mfma_f32_16x16x32_bf16 v[58:61], v[240:243], v[204:207], v[58:61]
	v_mfma_f32_16x16x32_bf16 v[54:57], v[240:243], v[208:211], v[54:57]
	global_load_lds_dwordx4 v[142:143], off
	v_lshl_add_u64 v[142:143], v[142:143], 0, s[2:3]
	s_add_i32 m0, m0, 0x1000
	v_mfma_f32_16x16x32_bf16 v[50:53], v[240:243], v[212:215], v[50:53]
	v_mfma_f32_16x16x32_bf16 v[46:49], v[240:243], v[216:219], v[46:49]
	s_setprio 0
	s_nop 0
	v_mfma_f32_16x16x32_bf16 v[42:45], v[240:243], v[220:223], v[42:45]
	global_load_lds_dwordx4 v[142:143], off
	v_lshl_add_u64 v[142:143], v[142:143], 0, s[2:3]
	s_add_i32 m0, m0, 0x1000
	v_mfma_f32_16x16x32_bf16 v[38:41], v[240:243], v[224:227], v[38:41]
	v_mfma_f32_16x16x32_bf16 v[34:37], v[240:243], v[228:231], v[34:37]
	v_mfma_f32_16x16x32_bf16 v[30:33], v[244:247], v[200:203], v[30:33]
	global_load_lds_dwordx4 v[142:143], off
	s_add_i32 m0, m0, 0x1000
	v_lshl_add_u64 v[142:143], v[134:135], 0, s[2:3]
	v_mfma_f32_16x16x32_bf16 v[26:29], v[244:247], v[204:207], v[26:29]
	v_mfma_f32_16x16x32_bf16 v[22:25], v[244:247], v[208:211], v[22:25]
	v_mfma_f32_16x16x32_bf16 v[18:21], v[244:247], v[212:215], v[18:21]
	global_load_lds_dwordx4 v[134:135], off
	s_add_i32 m0, m0, 0x1000
	v_lshl_add_u64 v[132:133], v[132:133], 0, s[12:13]
	v_mfma_f32_16x16x32_bf16 v[14:17], v[244:247], v[216:219], v[14:17]
	v_mfma_f32_16x16x32_bf16 v[10:13], v[244:247], v[220:223], v[10:13]
	v_mfma_f32_16x16x32_bf16 v[6:9], v[244:247], v[224:227], v[6:9]
	global_load_lds_dwordx4 v[142:143], off
	v_lshl_add_u64 v[134:135], v[134:135], 0, s[4:5]
	v_mfma_f32_16x16x32_bf16 v[2:5], v[244:247], v[228:231], v[2:5]
	s_mov_b32 s41, s40
	s_nop 0
	s_add_i32 s40, s40, 0x6000
	s_cmp_eq_u32 s40, 0x12000
	s_cselect_b32 s40, 0, s40
	s_nop 0
	s_sub_i32 s39, s39, 1
	s_cmp_lg_u32 s39, 0
	s_cbranch_scc1 .Lt8_loop
	.p2align 3
	s_waitcnt vmcnt(6) lgkmcnt(0)
	s_barrier
	s_setprio 1
	v_add_u32_e32 v144, s40, v136
	v_mfma_f32_16x16x32_bf16 v[126:129], v[184:187], v[146:149], v[126:129]
	ds_read_b128 v[200:203], v144 offset:0
	v_mfma_f32_16x16x32_bf16 v[122:125], v[184:187], v[152:155], v[122:125]
	ds_read_b128 v[204:207], v144 offset:1024
	v_mfma_f32_16x16x32_bf16 v[118:121], v[184:187], v[156:159], v[118:121]
	ds_read_b128 v[208:211], v144 offset:2048
	v_mfma_f32_16x16x32_bf16 v[114:117], v[184:187], v[162:165], v[114:117]
	ds_read_b128 v[212:215], v144 offset:3072
	v_mfma_f32_16x16x32_bf16 v[110:113], v[184:187], v[166:169], v[110:113]
	ds_read_b128 v[216:219], v144 offset:4096
	v_mfma_f32_16x16x32_bf16 v[106:109], v[184:187], v[170:173], v[106:109]
	ds_read_b128 v[220:223], v144 offset:5120
	v_mfma_f32_16x16x32_bf16 v[102:105], v[184:187], v[176:179], v[102:105]
	ds_read_b128 v[224:227], v144 offset:6144
	v_mfma_f32_16x16x32_bf16 v[98:101], v[184:187], v[180:183], v[98:101]
	ds_read_b128 v[228:231], v144 offset:7168
	v_mfma_f32_16x16x32_bf16 v[94:97], v[188:191], v[146:149], v[94:97]
	v_add_u32_e64 v144, s40, v137
	v_mfma_f32_16x16x32_bf16 v[90:93], v[188:191], v[152:155], v[90:93]
	v_mfma_f32_16x16x32_bf16 v[86:89], v[188:191], v[156:159], v[86:89]
	ds_read_b128 v[232:235], v144 offset:16384
	v_mfma_f32_16x16x32_bf16 v[82:85], v[188:191], v[162:165], v[82:85]
	ds_read_b128 v[236:239], v144 offset:17408
	v_mfma_f32_16x16x32_bf16 v[78:81], v[188:191], v[166:169], v[78:81]
	ds_read_b128 v[240:243], v144 offset:18432
	v_mfma_f32_16x16x32_bf16 v[74:77], v[188:191], v[170:173], v[74:77]
	ds_read_b128 v[244:247], v144 offset:19456
	v_mfma_f32_16x16x32_bf16 v[70:73], v[188:191], v[176:179], v[70:73]
	s_add_i32 s42, s46, s41
	s_mov_b32 m0, s42
	v_lshl_add_u64 v[142:143], v[132:133], 0, s[2:3]
	v_mfma_f32_16x16x32_bf16 v[66:69], v[188:191], v[180:183], v[66:69]
	global_load_lds_dwordx4 v[132:133], off
	s_add_i32 m0, m0, 0x1000
	v_mfma_f32_16x16x32_bf16 v[62:65], v[192:195], v[146:149], v[62:65]
	v_mfma_f32_16x16x32_bf16 v[58:61], v[192:195], v[152:155], v[58:61]
	v_mfma_f32_16x16x32_bf16 v[54:57], v[192:195], v[156:159], v[54:57]
	global_load_lds_dwordx4 v[142:143], off
	v_lshl_add_u64 v[142:143], v[142:143], 0, s[2:3]
	s_add_i32 m0, m0, 0x1000
	v_mfma_f32_16x16x32_bf16 v[50:53], v[192:195], v[162:165], v[50:53]
	v_mfma_f32_16x16x32_bf16 v[46:49], v[192:195], v[166:169], v[46:49]
	s_setprio 0
	s_nop 0
	v_mfma_f32_16x16x32_bf16 v[42:45], v[192:195], v[170:173], v[42:45]
	global_load_lds_dwordx4 v[142:143], off
	v_lshl_add_u64 v[142:143], v[142:143], 0, s[2:3]
	s_add_i32 m0, m0, 0x1000
	v_mfma_f32_16x16x32_bf16 v[38:41], v[192:195], v[176:179], v[38:41]
	v_mfma_f32_16x16x32_bf16 v[34:37], v[192:195], v[180:183], v[34:37]
	v_mfma_f32_16x16x32_bf16 v[30:33], v[196:199], v[146:149], v[30:33]
	global_load_lds_dwordx4 v[142:143], off
	s_add_i32 m0, m0, 0x1000
	v_lshl_add_u64 v[142:143], v[134:135], 0, s[2:3]
	v_mfma_f32_16x16x32_bf16 v[26:29], v[196:199], v[152:155], v[26:29]
	v_mfma_f32_16x16x32_bf16 v[22:25], v[196:199], v[156:159], v[22:25]
	v_mfma_f32_16x16x32_bf16 v[18:21], v[196:199], v[162:165], v[18:21]
	global_load_lds_dwordx4 v[134:135], off
	s_add_i32 m0, m0, 0x1000
	v_lshl_add_u64 v[132:133], v[132:133], 0, s[12:13]
	v_mfma_f32_16x16x32_bf16 v[14:17], v[196:199], v[166:169], v[14:17]
	v_mfma_f32_16x16x32_bf16 v[10:13], v[196:199], v[170:173], v[10:13]
	v_mfma_f32_16x16x32_bf16 v[6:9], v[196:199], v[176:179], v[6:9]
	global_load_lds_dwordx4 v[142:143], off
	v_lshl_add_u64 v[134:135], v[134:135], 0, s[4:5]
	v_mfma_f32_16x16x32_bf16 v[2:5], v[196:199], v[180:183], v[2:5]
	s_mov_b32 s41, s40
	s_nop 0
	s_add_i32 s40, s40, 0x6000
	s_cmp_eq_u32 s40, 0x12000
	s_cselect_b32 s40, 0, s40
	s_nop 0
	.p2align 3
	s_waitcnt vmcnt(6) lgkmcnt(0)
	s_barrier
;     ...
;   for (int kt = 0; kt < nk; kt++) {
;     if (kt + 1 < nk) asm volatile("s_waitcnt vmcnt(6)" ::: "memory");
;     else asm volatile("s_waitcnt vmcnt(0)" ::: "memory");
;     __builtin_amdgcn_s_barrier();
;     asm volatile("" ::: "memory");
;     if (kt + 2 < nk) G2_STAGE(kt + 2);
;     const char* cS = smem + (kt % 3) * 24576;
;     bf16x8 xa[8], wb[4];
; #pragma unroll
;     for (int f = 0; f < 8; f++) xa[f] = *(const bf16x8*)(cS + aoff + f * 1024);
; #pragma unroll
;     for (int f = 0; f < 4; f++) wb[f] = *(const bf16x8*)(cS + boff + f * 1024);
; #pragma unroll
;     for (int nf = 0; nf < 4; nf++)
; #pragma unroll
;       for (int mf = 0; mf < 8; mf++)
;         acc[nf][mf] = __builtin_amdgcn_mfma_f32_16x16x32_bf16(wb[nf], xa[mf], acc[nf][mf], 0, 0, 0);
;   }
	s_setprio 1
	v_add_u32_e32 v144, s40, v136
	v_mfma_f32_16x16x32_bf16 v[126:129], v[232:235], v[200:203], v[126:129]
	ds_read_b128 v[146:149], v144 offset:0
	v_mfma_f32_16x16x32_bf16 v[122:125], v[232:235], v[204:207], v[122:125]
	ds_read_b128 v[152:155], v144 offset:1024
	v_mfma_f32_16x16x32_bf16 v[118:121], v[232:235], v[208:211], v[118:121]
	ds_read_b128 v[156:159], v144 offset:2048
	v_mfma_f32_16x16x32_bf16 v[114:117], v[232:235], v[212:215], v[114:117]
	ds_read_b128 v[162:165], v144 offset:3072
	v_mfma_f32_16x16x32_bf16 v[110:113], v[232:235], v[216:219], v[110:113]
	ds_read_b128 v[166:169], v144 offset:4096
	v_mfma_f32_16x16x32_bf16 v[106:109], v[232:235], v[220:223], v[106:109]
	ds_read_b128 v[170:173], v144 offset:5120
	v_mfma_f32_16x16x32_bf16 v[102:105], v[232:235], v[224:227], v[102:105]
	ds_read_b128 v[176:179], v144 offset:6144
	v_mfma_f32_16x16x32_bf16 v[98:101], v[232:235], v[228:231], v[98:101]
	ds_read_b128 v[180:183], v144 offset:7168
	v_mfma_f32_16x16x32_bf16 v[94:97], v[236:239], v[200:203], v[94:97]
	v_add_u32_e64 v144, s40, v137
	v_mfma_f32_16x16x32_bf16 v[90:93], v[236:239], v[204:207], v[90:93]
	v_mfma_f32_16x16x32_bf16 v[86:89], v[236:239], v[208:211], v[86:89]
	ds_read_b128 v[184:187], v144 offset:16384
	v_mfma_f32_16x16x32_bf16 v[82:85], v[236:239], v[212:215], v[82:85]
	ds_read_b128 v[188:191], v144 offset:17408
	v_mfma_f32_16x16x32_bf16 v[78:81], v[236:239], v[216:219], v[78:81]
	ds_read_b128 v[192:195], v144 offset:18432
	v_mfma_f32_16x16x32_bf16 v[74:77], v[236:239], v[220:223], v[74:77]
	ds_read_b128 v[196:199], v144 offset:19456
	v_mfma_f32_16x16x32_bf16 v[70:73], v[236:239], v[224:227], v[70:73]
	v_mfma_f32_16x16x32_bf16 v[66:69], v[236:239], v[228:231], v[66:69]
	v_mfma_f32_16x16x32_bf16 v[62:65], v[240:243], v[200:203], v[62:65]
	v_mfma_f32_16x16x32_bf16 v[58:61], v[240:243], v[204:207], v[58:61]
	v_mfma_f32_16x16x32_bf16 v[54:57], v[240:243], v[208:211], v[54:57]
	v_mfma_f32_16x16x32_bf16 v[50:53], v[240:243], v[212:215], v[50:53]
	v_mfma_f32_16x16x32_bf16 v[46:49], v[240:243], v[216:219], v[46:49]
	s_setprio 0
	s_nop 0
	v_mfma_f32_16x16x32_bf16 v[42:45], v[240:243], v[220:223], v[42:45]
	v_mfma_f32_16x16x32_bf16 v[38:41], v[240:243], v[224:227], v[38:41]
	v_mfma_f32_16x16x32_bf16 v[34:37], v[240:243], v[228:231], v[34:37]
	v_mfma_f32_16x16x32_bf16 v[30:33], v[244:247], v[200:203], v[30:33]
	v_mfma_f32_16x16x32_bf16 v[26:29], v[244:247], v[204:207], v[26:29]
	v_mfma_f32_16x16x32_bf16 v[22:25], v[244:247], v[208:211], v[22:25]
	v_mfma_f32_16x16x32_bf16 v[18:21], v[244:247], v[212:215], v[18:21]
	v_mfma_f32_16x16x32_bf16 v[14:17], v[244:247], v[216:219], v[14:17]
	v_mfma_f32_16x16x32_bf16 v[10:13], v[244:247], v[220:223], v[10:13]
	v_mfma_f32_16x16x32_bf16 v[6:9], v[244:247], v[224:227], v[6:9]
	v_mfma_f32_16x16x32_bf16 v[2:5], v[244:247], v[228:231], v[2:5]
	s_mov_b32 s41, s40
	s_nop 0
	s_add_i32 s40, s40, 0x6000
	s_cmp_eq_u32 s40, 0x12000
	s_cselect_b32 s40, 0, s40
	s_nop 0
	.p2align 3
	s_waitcnt vmcnt(0) lgkmcnt(0)
	s_barrier
	s_setprio 1
	v_add_u32_e32 v144, s40, v136
	v_mfma_f32_16x16x32_bf16 v[126:129], v[184:187], v[146:149], v[126:129]
	ds_read_b128 v[200:203], v144 offset:0
	v_mfma_f32_16x16x32_bf16 v[122:125], v[184:187], v[152:155], v[122:125]
	ds_read_b128 v[204:207], v144 offset:1024
	v_mfma_f32_16x16x32_bf16 v[118:121], v[184:187], v[156:159], v[118:121]
	ds_read_b128 v[208:211], v144 offset:2048
	v_mfma_f32_16x16x32_bf16 v[114:117], v[184:187], v[162:165], v[114:117]
	ds_read_b128 v[212:215], v144 offset:3072
	v_mfma_f32_16x16x32_bf16 v[110:113], v[184:187], v[166:169], v[110:113]
	ds_read_b128 v[216:219], v144 offset:4096
	v_mfma_f32_16x16x32_bf16 v[106:109], v[184:187], v[170:173], v[106:109]
	ds_read_b128 v[220:223], v144 offset:5120
	v_mfma_f32_16x16x32_bf16 v[102:105], v[184:187], v[176:179], v[102:105]
	ds_read_b128 v[224:227], v144 offset:6144
	v_mfma_f32_16x16x32_bf16 v[98:101], v[184:187], v[180:183], v[98:101]
	ds_read_b128 v[228:231], v144 offset:7168
	v_mfma_f32_16x16x32_bf16 v[94:97], v[188:191], v[146:149], v[94:97]
	v_add_u32_e64 v144, s40, v137
	v_mfma_f32_16x16x32_bf16 v[90:93], v[188:191], v[152:155], v[90:93]
	v_mfma_f32_16x16x32_bf16 v[86:89], v[188:191], v[156:159], v[86:89]
	ds_read_b128 v[232:235], v144 offset:16384
	v_mfma_f32_16x16x32_bf16 v[82:85], v[188:191], v[162:165], v[82:85]
	ds_read_b128 v[236:239], v144 offset:17408
	v_mfma_f32_16x16x32_bf16 v[78:81], v[188:191], v[166:169], v[78:81]
	ds_read_b128 v[240:243], v144 offset:18432
	v_mfma_f32_16x16x32_bf16 v[74:77], v[188:191], v[170:173], v[74:77]
	ds_read_b128 v[244:247], v144 offset:19456
	v_mfma_f32_16x16x32_bf16 v[70:73], v[188:191], v[176:179], v[70:73]
	v_mfma_f32_16x16x32_bf16 v[66:69], v[188:191], v[180:183], v[66:69]
	v_mfma_f32_16x16x32_bf16 v[62:65], v[192:195], v[146:149], v[62:65]
	v_mfma_f32_16x16x32_bf16 v[58:61], v[192:195], v[152:155], v[58:61]
	v_mfma_f32_16x16x32_bf16 v[54:57], v[192:195], v[156:159], v[54:57]
	v_mfma_f32_16x16x32_bf16 v[50:53], v[192:195], v[162:165], v[50:53]
	v_mfma_f32_16x16x32_bf16 v[46:49], v[192:195], v[166:169], v[46:49]
	s_setprio 0
	s_nop 0
	v_mfma_f32_16x16x32_bf16 v[42:45], v[192:195], v[170:173], v[42:45]
	v_mfma_f32_16x16x32_bf16 v[38:41], v[192:195], v[176:179], v[38:41]
	v_mfma_f32_16x16x32_bf16 v[34:37], v[192:195], v[180:183], v[34:37]
	v_mfma_f32_16x16x32_bf16 v[30:33], v[196:199], v[146:149], v[30:33]
	v_mfma_f32_16x16x32_bf16 v[26:29], v[196:199], v[152:155], v[26:29]
	v_mfma_f32_16x16x32_bf16 v[22:25], v[196:199], v[156:159], v[22:25]
	v_mfma_f32_16x16x32_bf16 v[18:21], v[196:199], v[162:165], v[18:21]
	v_mfma_f32_16x16x32_bf16 v[14:17], v[196:199], v[166:169], v[14:17]
	v_mfma_f32_16x16x32_bf16 v[10:13], v[196:199], v[170:173], v[10:13]
	v_mfma_f32_16x16x32_bf16 v[6:9], v[196:199], v[176:179], v[6:9]
	v_mfma_f32_16x16x32_bf16 v[2:5], v[196:199], v[180:183], v[2:5]
	s_mov_b32 s41, s40
	s_nop 0
	s_add_i32 s40, s40, 0x6000
	s_cmp_eq_u32 s40, 0x12000
	s_cselect_b32 s40, 0, s40
	s_nop 0
	s_mov_b32 s4, 0x8000
	s_mov_b32 s5, 0
	s_mov_b32 s10, 0x10000
	s_mov_b32 s11, 0
	s_mov_b32 s44, 0x3fd744fd
	.p2align 3
	s_waitcnt lgkmcnt(0)
; DEVI float blo(unsigned u) { return __uint_as_float(u << 16); }
; DEVI float bhi(unsigned u) { return __uint_as_float(u & 0xffff0000u); }
;     ...
;     for (int nf = 0; nf < 4; nf++)
; #pragma unroll
;       for (int mf = 0; mf < 8; mf++)
;         acc[nf][mf] = __builtin_amdgcn_mfma_f32_16x16x32_bf16(wb[nf], xa[mf], acc[nf][mf], 0, 0, 0);
;     ...
;         if (EPI == EPI_RESID || EPI == EPI_RESID_ATOMIC) {
;           f32x4 x = a;
;           if (EPI == EPI_RESID || kpart == 0) {
;             const u32x2 xr = *(const u32x2*)((const u16*)(p.ws + WS_XB) + (size_t)row * 1024 + col);
;             x[0] += ALPHA * blo(xr[0]); x[1] += ALPHA * bhi(xr[0]); x[2] += ALPHA * blo(xr[1]); x[3] += ALPHA * bhi(xr[1]);
;           }
;           if (EPI == EPI_RESID) *(f32x4*)((float*)(p.ws + WS_XF) + (size_t)row * 1024 + col) = x;
;           else *(f32x4*)((float*)(p.ws + WS_SLAB) + ((size_t)kpart * 512 + (row - T_P)) * 1024 + col) = x;
	s_nop 0
	v_mfma_f32_16x16x32_bf16 v[126:129], v[232:235], v[200:203], v[126:129]
	v_mfma_f32_16x16x32_bf16 v[122:125], v[232:235], v[204:207], v[122:125]
	v_mfma_f32_16x16x32_bf16 v[118:121], v[232:235], v[208:211], v[118:121]
	v_mfma_f32_16x16x32_bf16 v[114:117], v[232:235], v[212:215], v[114:117]
	v_mfma_f32_16x16x32_bf16 v[110:113], v[232:235], v[216:219], v[110:113]
	global_load_dwordx4 v[146:149], v[138:139], off offset:0
	v_mfma_f32_16x16x32_bf16 v[106:109], v[232:235], v[220:223], v[106:109]
	v_mfma_f32_16x16x32_bf16 v[102:105], v[232:235], v[224:227], v[102:105]
	global_load_dwordx4 v[152:155], v[138:139], off offset:64
	v_mfma_f32_16x16x32_bf16 v[98:101], v[232:235], v[228:231], v[98:101]
	v_lshl_add_u64 v[138:139], v[138:139], 0, s[4:5]
	v_mfma_f32_16x16x32_bf16 v[94:97], v[236:239], v[200:203], v[94:97]
	global_load_dwordx4 v[156:159], v[138:139], off offset:0
	v_mfma_f32_16x16x32_bf16 v[90:93], v[236:239], v[204:207], v[90:93]
	v_mfma_f32_16x16x32_bf16 v[86:89], v[236:239], v[208:211], v[86:89]
	global_load_dwordx4 v[162:165], v[138:139], off offset:64
	v_mfma_f32_16x16x32_bf16 v[82:85], v[236:239], v[212:215], v[82:85]
	v_lshl_add_u64 v[138:139], v[138:139], 0, s[4:5]
	v_mfma_f32_16x16x32_bf16 v[78:81], v[236:239], v[216:219], v[78:81]
	global_load_dwordx4 v[166:169], v[138:139], off offset:0
	v_mfma_f32_16x16x32_bf16 v[74:77], v[236:239], v[220:223], v[74:77]
	v_mfma_f32_16x16x32_bf16 v[70:73], v[236:239], v[224:227], v[70:73]
	global_load_dwordx4 v[170:173], v[138:139], off offset:64
	v_mfma_f32_16x16x32_bf16 v[66:69], v[236:239], v[228:231], v[66:69]
	v_lshl_add_u64 v[138:139], v[138:139], 0, s[4:5]
	v_mfma_f32_16x16x32_bf16 v[62:65], v[240:243], v[200:203], v[62:65]
	global_load_dwordx4 v[176:179], v[138:139], off offset:0
	v_mfma_f32_16x16x32_bf16 v[58:61], v[240:243], v[204:207], v[58:61]
	v_mfma_f32_16x16x32_bf16 v[54:57], v[240:243], v[208:211], v[54:57]
	global_load_dwordx4 v[180:183], v[138:139], off offset:64
	v_mfma_f32_16x16x32_bf16 v[50:53], v[240:243], v[212:215], v[50:53]
	v_lshl_add_u64 v[138:139], v[138:139], 0, s[4:5]
	v_mfma_f32_16x16x32_bf16 v[46:49], v[240:243], v[216:219], v[46:49]
	global_load_dwordx4 v[184:187], v[138:139], off offset:0
	v_mfma_f32_16x16x32_bf16 v[42:45], v[240:243], v[220:223], v[42:45]
	v_mfma_f32_16x16x32_bf16 v[38:41], v[240:243], v[224:227], v[38:41]
	global_load_dwordx4 v[188:191], v[138:139], off offset:64
	v_mfma_f32_16x16x32_bf16 v[34:37], v[240:243], v[228:231], v[34:37]
	v_lshl_add_u64 v[138:139], v[138:139], 0, s[4:5]
	v_mfma_f32_16x16x32_bf16 v[30:33], v[244:247], v[200:203], v[30:33]
	global_load_dwordx4 v[192:195], v[138:139], off offset:0
	v_mfma_f32_16x16x32_bf16 v[26:29], v[244:247], v[204:207], v[26:29]
	v_mfma_f32_16x16x32_bf16 v[22:25], v[244:247], v[208:211], v[22:25]
	global_load_dwordx4 v[196:199], v[138:139], off offset:64
	v_mfma_f32_16x16x32_bf16 v[18:21], v[244:247], v[212:215], v[18:21]
	v_lshl_add_u64 v[138:139], v[138:139], 0, s[4:5]
	v_mfma_f32_16x16x32_bf16 v[14:17], v[244:247], v[216:219], v[14:17]
	v_mfma_f32_16x16x32_bf16 v[10:13], v[244:247], v[220:223], v[10:13]
	v_mfma_f32_16x16x32_bf16 v[6:9], v[244:247], v[224:227], v[6:9]
	v_mfma_f32_16x16x32_bf16 v[2:5], v[244:247], v[228:231], v[2:5]
	s_mov_b32 m0, s43
	global_load_dwordx4 v[200:203], v[138:139], off offset:0
	global_load_dwordx4 v[204:207], v[138:139], off offset:64
	v_lshl_add_u64 v[138:139], v[138:139], 0, s[4:5]
	global_load_dwordx4 v[208:211], v[138:139], off offset:0
	global_load_dwordx4 v[212:215], v[138:139], off offset:64
	v_lshl_add_u64 v[138:139], v[138:139], 0, s[4:5]
	s_nop 7
	v_and_b32_e32 v228, 1, v145
	v_cmp_ne_u32_e32 vcc, 0, v228
	v_mov_b32_e32 v229, 0xfffff040
	v_cndmask_b32_e32 v230, 0, v229, vcc
	v_ashrrev_i32_e32 v231, 31, v230
	v_lshl_add_u64 v[140:141], v[140:141], 0, v[230:231]
	v_add_co_u32_e32 v142, vcc, 0x1000, v140
	s_nop 0
	v_addc_co_u32_e32 v143, vcc, 0, v141, vcc
	v_cmp_ne_u32_e32 vcc, 0, v228
	s_waitcnt vmcnt(15)
	v_permlane16_swap_b32_e32 v146, v148
	v_permlane16_swap_b32_e32 v147, v149
	v_lshlrev_b32_e32 v216, 16, v146
	v_and_b32_e32 v146, 0xffff0000, v146
	v_lshlrev_b32_e32 v217, 16, v147
	v_and_b32_e32 v147, 0xffff0000, v147
	v_fmac_f32_e32 v126, s44, v216
	v_fmac_f32_e32 v127, s44, v146
	v_fmac_f32_e32 v128, s44, v217
	v_fmac_f32_e32 v129, s44, v147
	v_lshlrev_b32_e32 v216, 16, v148
	v_and_b32_e32 v148, 0xffff0000, v148
	v_lshlrev_b32_e32 v217, 16, v149
	v_and_b32_e32 v149, 0xffff0000, v149
	v_fmac_f32_e32 v94, s44, v216
	v_fmac_f32_e32 v95, s44, v148
	v_fmac_f32_e32 v96, s44, v217
	v_fmac_f32_e32 v97, s44, v149
	v_mov_b32_dpp v220, v94 quad_perm:[1,0,3,2] row_mask:0xf bank_mask:0xf
	v_mov_b32_dpp v221, v95 quad_perm:[1,0,3,2] row_mask:0xf bank_mask:0xf
	v_mov_b32_dpp v222, v96 quad_perm:[1,0,3,2] row_mask:0xf bank_mask:0xf
	v_mov_b32_dpp v223, v97 quad_perm:[1,0,3,2] row_mask:0xf bank_mask:0xf
	v_mov_b32_dpp v224, v126 quad_perm:[1,0,3,2] row_mask:0xf bank_mask:0xf
	v_mov_b32_dpp v225, v127 quad_perm:[1,0,3,2] row_mask:0xf bank_mask:0xf
	v_mov_b32_dpp v226, v128 quad_perm:[1,0,3,2] row_mask:0xf bank_mask:0xf
	v_mov_b32_dpp v227, v129 quad_perm:[1,0,3,2] row_mask:0xf bank_mask:0xf
	v_cndmask_b32_e32 v94, v224, v94, vcc
	v_cndmask_b32_e32 v95, v225, v95, vcc
	v_cndmask_b32_e32 v96, v226, v96, vcc
	v_cndmask_b32_e32 v97, v227, v97, vcc
	v_cndmask_b32_e32 v126, v126, v220, vcc
	v_cndmask_b32_e32 v127, v127, v221, vcc
	v_cndmask_b32_e32 v128, v128, v222, vcc
	v_cndmask_b32_e32 v129, v129, v223, vcc
	global_store_dwordx4 v[140:141], v[126:129], off
	global_store_dwordx4 v[142:143], v[94:97], off
	s_waitcnt vmcnt(16)
; DEVI float blo(unsigned u) { return __uint_as_float(u << 16); }
; DEVI float bhi(unsigned u) { return __uint_as_float(u & 0xffff0000u); }
;     ...
;         if (EPI == EPI_RESID || EPI == EPI_RESID_ATOMIC) {
;           f32x4 x = a;
;           if (EPI == EPI_RESID || kpart == 0) {
;             const u32x2 xr = *(const u32x2*)((const u16*)(p.ws + WS_XB) + (size_t)row * 1024 + col);
;             x[0] += ALPHA * blo(xr[0]); x[1] += ALPHA * bhi(xr[0]); x[2] += ALPHA * blo(xr[1]); x[3] += ALPHA * bhi(xr[1]);
;           }
;           if (EPI == EPI_RESID) *(f32x4*)((float*)(p.ws + WS_XF) + (size_t)row * 1024 + col) = x;
;           else *(f32x4*)((float*)(p.ws + WS_SLAB) + ((size_t)kpart * 512 + (row - T_P)) * 1024 + col) = x;
	v_permlane16_swap_b32_e32 v152, v154
	v_permlane16_swap_b32_e32 v153, v155
	v_lshlrev_b32_e32 v216, 16, v152
	v_and_b32_e32 v152, 0xffff0000, v152
	v_lshlrev_b32_e32 v217, 16, v153
	v_and_b32_e32 v153, 0xffff0000, v153
	v_fmac_f32_e32 v62, s44, v216
	v_fmac_f32_e32 v63, s44, v152
	v_fmac_f32_e32 v64, s44, v217
	v_fmac_f32_e32 v65, s44, v153
	v_lshlrev_b32_e32 v216, 16, v154
	v_and_b32_e32 v154, 0xffff0000, v154
	v_lshlrev_b32_e32 v217, 16, v155
	v_and_b32_e32 v155, 0xffff0000, v155
	v_fmac_f32_e32 v30, s44, v216
	v_fmac_f32_e32 v31, s44, v154
	v_fmac_f32_e32 v32, s44, v217
	v_fmac_f32_e32 v33, s44, v155
	v_mov_b32_dpp v220, v30 quad_perm:[1,0,3,2] row_mask:0xf bank_mask:0xf
	v_mov_b32_dpp v221, v31 quad_perm:[1,0,3,2] row_mask:0xf bank_mask:0xf
	v_mov_b32_dpp v222, v32 quad_perm:[1,0,3,2] row_mask:0xf bank_mask:0xf
	v_mov_b32_dpp v223, v33 quad_perm:[1,0,3,2] row_mask:0xf bank_mask:0xf
	v_mov_b32_dpp v224, v62 quad_perm:[1,0,3,2] row_mask:0xf bank_mask:0xf
	v_mov_b32_dpp v225, v63 quad_perm:[1,0,3,2] row_mask:0xf bank_mask:0xf
	v_mov_b32_dpp v226, v64 quad_perm:[1,0,3,2] row_mask:0xf bank_mask:0xf
	v_mov_b32_dpp v227, v65 quad_perm:[1,0,3,2] row_mask:0xf bank_mask:0xf
	v_cndmask_b32_e32 v30, v224, v30, vcc
	v_cndmask_b32_e32 v31, v225, v31, vcc
	v_cndmask_b32_e32 v32, v226, v32, vcc
	v_cndmask_b32_e32 v33, v227, v33, vcc
	v_cndmask_b32_e32 v62, v62, v220, vcc
	v_cndmask_b32_e32 v63, v63, v221, vcc
	v_cndmask_b32_e32 v64, v64, v222, vcc
	v_cndmask_b32_e32 v65, v65, v223, vcc
	global_store_dwordx4 v[140:141], v[62:65], off offset:128
	global_store_dwordx4 v[142:143], v[30:33], off offset:128
	v_lshl_add_u64 v[140:141], v[140:141], 0, s[10:11]
	v_lshl_add_u64 v[142:143], v[142:143], 0, s[10:11]
	s_waitcnt vmcnt(17)
	v_permlane16_swap_b32_e32 v156, v158
	v_permlane16_swap_b32_e32 v157, v159
	v_lshlrev_b32_e32 v216, 16, v156
	v_and_b32_e32 v156, 0xffff0000, v156
	v_lshlrev_b32_e32 v217, 16, v157
	v_and_b32_e32 v157, 0xffff0000, v157
	v_fmac_f32_e32 v122, s44, v216
	v_fmac_f32_e32 v123, s44, v156
	v_fmac_f32_e32 v124, s44, v217
	v_fmac_f32_e32 v125, s44, v157
	v_lshlrev_b32_e32 v216, 16, v158
	v_and_b32_e32 v158, 0xffff0000, v158
	v_lshlrev_b32_e32 v217, 16, v159
	v_and_b32_e32 v159, 0xffff0000, v159
	v_fmac_f32_e32 v90, s44, v216
	v_fmac_f32_e32 v91, s44, v158
	v_fmac_f32_e32 v92, s44, v217
	v_fmac_f32_e32 v93, s44, v159
	v_mov_b32_dpp v220, v90 quad_perm:[1,0,3,2] row_mask:0xf bank_mask:0xf
	v_mov_b32_dpp v221, v91 quad_perm:[1,0,3,2] row_mask:0xf bank_mask:0xf
	v_mov_b32_dpp v222, v92 quad_perm:[1,0,3,2] row_mask:0xf bank_mask:0xf
	v_mov_b32_dpp v223, v93 quad_perm:[1,0,3,2] row_mask:0xf bank_mask:0xf
	v_mov_b32_dpp v224, v122 quad_perm:[1,0,3,2] row_mask:0xf bank_mask:0xf
	v_mov_b32_dpp v225, v123 quad_perm:[1,0,3,2] row_mask:0xf bank_mask:0xf
	v_mov_b32_dpp v226, v124 quad_perm:[1,0,3,2] row_mask:0xf bank_mask:0xf
	v_mov_b32_dpp v227, v125 quad_perm:[1,0,3,2] row_mask:0xf bank_mask:0xf
	v_cndmask_b32_e32 v90, v224, v90, vcc
	v_cndmask_b32_e32 v91, v225, v91, vcc
	v_cndmask_b32_e32 v92, v226, v92, vcc
	v_cndmask_b32_e32 v93, v227, v93, vcc
	v_cndmask_b32_e32 v122, v122, v220, vcc
	v_cndmask_b32_e32 v123, v123, v221, vcc
	v_cndmask_b32_e32 v124, v124, v222, vcc
	v_cndmask_b32_e32 v125, v125, v223, vcc
	global_store_dwordx4 v[140:141], v[122:125], off
	global_store_dwordx4 v[142:143], v[90:93], off
	s_waitcnt vmcnt(18)
	v_permlane16_swap_b32_e32 v162, v164
	v_permlane16_swap_b32_e32 v163, v165
	v_lshlrev_b32_e32 v216, 16, v162
	v_and_b32_e32 v162, 0xffff0000, v162
	v_lshlrev_b32_e32 v217, 16, v163
	v_and_b32_e32 v163, 0xffff0000, v163
	v_fmac_f32_e32 v58, s44, v216
	v_fmac_f32_e32 v59, s44, v162
	v_fmac_f32_e32 v60, s44, v217
	v_fmac_f32_e32 v61, s44, v163
	v_lshlrev_b32_e32 v216, 16, v164
	v_and_b32_e32 v164, 0xffff0000, v164
	v_lshlrev_b32_e32 v217, 16, v165
	v_and_b32_e32 v165, 0xffff0000, v165
	v_fmac_f32_e32 v26, s44, v216
	v_fmac_f32_e32 v27, s44, v164
	v_fmac_f32_e32 v28, s44, v217
	v_fmac_f32_e32 v29, s44, v165
	v_mov_b32_dpp v220, v26 quad_perm:[1,0,3,2] row_mask:0xf bank_mask:0xf
	v_mov_b32_dpp v221, v27 quad_perm:[1,0,3,2] row_mask:0xf bank_mask:0xf
	v_mov_b32_dpp v222, v28 quad_perm:[1,0,3,2] row_mask:0xf bank_mask:0xf
	v_mov_b32_dpp v223, v29 quad_perm:[1,0,3,2] row_mask:0xf bank_mask:0xf
	v_mov_b32_dpp v224, v58 quad_perm:[1,0,3,2] row_mask:0xf bank_mask:0xf
	v_mov_b32_dpp v225, v59 quad_perm:[1,0,3,2] row_mask:0xf bank_mask:0xf
	v_mov_b32_dpp v226, v60 quad_perm:[1,0,3,2] row_mask:0xf bank_mask:0xf
	v_mov_b32_dpp v227, v61 quad_perm:[1,0,3,2] row_mask:0xf bank_mask:0xf
	v_cndmask_b32_e32 v26, v224, v26, vcc
	v_cndmask_b32_e32 v27, v225, v27, vcc
	v_cndmask_b32_e32 v28, v226, v28, vcc
	v_cndmask_b32_e32 v29, v227, v29, vcc
	v_cndmask_b32_e32 v58, v58, v220, vcc
	v_cndmask_b32_e32 v59, v59, v221, vcc
	v_cndmask_b32_e32 v60, v60, v222, vcc
	v_cndmask_b32_e32 v61, v61, v223, vcc
	global_store_dwordx4 v[140:141], v[58:61], off offset:128
	global_store_dwordx4 v[142:143], v[26:29], off offset:128
	v_lshl_add_u64 v[140:141], v[140:141], 0, s[10:11]
	v_lshl_add_u64 v[142:143], v[142:143], 0, s[10:11]
	s_waitcnt vmcnt(19)
; DEVI float blo(unsigned u) { return __uint_as_float(u << 16); }
; DEVI float bhi(unsigned u) { return __uint_as_float(u & 0xffff0000u); }
;     ...
;         if (EPI == EPI_RESID || EPI == EPI_RESID_ATOMIC) {
;           f32x4 x = a;
;           if (EPI == EPI_RESID || kpart == 0) {
;             const u32x2 xr = *(const u32x2*)((const u16*)(p.ws + WS_XB) + (size_t)row * 1024 + col);
;             x[0] += ALPHA * blo(xr[0]); x[1] += ALPHA * bhi(xr[0]); x[2] += ALPHA * blo(xr[1]); x[3] += ALPHA * bhi(xr[1]);
;           }
;           if (EPI == EPI_RESID) *(f32x4*)((float*)(p.ws + WS_XF) + (size_t)row * 1024 + col) = x;
;           else *(f32x4*)((float*)(p.ws + WS_SLAB) + ((size_t)kpart * 512 + (row - T_P)) * 1024 + col) = x;
	v_permlane16_swap_b32_e32 v166, v168
	v_permlane16_swap_b32_e32 v167, v169
	v_lshlrev_b32_e32 v216, 16, v166
	v_and_b32_e32 v166, 0xffff0000, v166
	v_lshlrev_b32_e32 v217, 16, v167
	v_and_b32_e32 v167, 0xffff0000, v167
	v_fmac_f32_e32 v118, s44, v216
	v_fmac_f32_e32 v119, s44, v166
	v_fmac_f32_e32 v120, s44, v217
	v_fmac_f32_e32 v121, s44, v167
	v_lshlrev_b32_e32 v216, 16, v168
	v_and_b32_e32 v168, 0xffff0000, v168
	v_lshlrev_b32_e32 v217, 16, v169
	v_and_b32_e32 v169, 0xffff0000, v169
	v_fmac_f32_e32 v86, s44, v216
	v_fmac_f32_e32 v87, s44, v168
	v_fmac_f32_e32 v88, s44, v217
	v_fmac_f32_e32 v89, s44, v169
	v_mov_b32_dpp v220, v86 quad_perm:[1,0,3,2] row_mask:0xf bank_mask:0xf
	v_mov_b32_dpp v221, v87 quad_perm:[1,0,3,2] row_mask:0xf bank_mask:0xf
	v_mov_b32_dpp v222, v88 quad_perm:[1,0,3,2] row_mask:0xf bank_mask:0xf
	v_mov_b32_dpp v223, v89 quad_perm:[1,0,3,2] row_mask:0xf bank_mask:0xf
	v_mov_b32_dpp v224, v118 quad_perm:[1,0,3,2] row_mask:0xf bank_mask:0xf
	v_mov_b32_dpp v225, v119 quad_perm:[1,0,3,2] row_mask:0xf bank_mask:0xf
	v_mov_b32_dpp v226, v120 quad_perm:[1,0,3,2] row_mask:0xf bank_mask:0xf
	v_mov_b32_dpp v227, v121 quad_perm:[1,0,3,2] row_mask:0xf bank_mask:0xf
	v_cndmask_b32_e32 v86, v224, v86, vcc
	v_cndmask_b32_e32 v87, v225, v87, vcc
	v_cndmask_b32_e32 v88, v226, v88, vcc
	v_cndmask_b32_e32 v89, v227, v89, vcc
	v_cndmask_b32_e32 v118, v118, v220, vcc
	v_cndmask_b32_e32 v119, v119, v221, vcc
	v_cndmask_b32_e32 v120, v120, v222, vcc
	v_cndmask_b32_e32 v121, v121, v223, vcc
	global_store_dwordx4 v[140:141], v[118:121], off
	global_store_dwordx4 v[142:143], v[86:89], off
	s_waitcnt vmcnt(20)
	v_permlane16_swap_b32_e32 v170, v172
	v_permlane16_swap_b32_e32 v171, v173
	v_lshlrev_b32_e32 v216, 16, v170
	v_and_b32_e32 v170, 0xffff0000, v170
	v_lshlrev_b32_e32 v217, 16, v171
	v_and_b32_e32 v171, 0xffff0000, v171
	v_fmac_f32_e32 v54, s44, v216
	v_fmac_f32_e32 v55, s44, v170
	v_fmac_f32_e32 v56, s44, v217
	v_fmac_f32_e32 v57, s44, v171
	v_lshlrev_b32_e32 v216, 16, v172
	v_and_b32_e32 v172, 0xffff0000, v172
	v_lshlrev_b32_e32 v217, 16, v173
	v_and_b32_e32 v173, 0xffff0000, v173
	v_fmac_f32_e32 v22, s44, v216
	v_fmac_f32_e32 v23, s44, v172
	v_fmac_f32_e32 v24, s44, v217
	v_fmac_f32_e32 v25, s44, v173
	v_mov_b32_dpp v220, v22 quad_perm:[1,0,3,2] row_mask:0xf bank_mask:0xf
	v_mov_b32_dpp v221, v23 quad_perm:[1,0,3,2] row_mask:0xf bank_mask:0xf
	v_mov_b32_dpp v222, v24 quad_perm:[1,0,3,2] row_mask:0xf bank_mask:0xf
	v_mov_b32_dpp v223, v25 quad_perm:[1,0,3,2] row_mask:0xf bank_mask:0xf
	v_mov_b32_dpp v224, v54 quad_perm:[1,0,3,2] row_mask:0xf bank_mask:0xf
	v_mov_b32_dpp v225, v55 quad_perm:[1,0,3,2] row_mask:0xf bank_mask:0xf
	v_mov_b32_dpp v226, v56 quad_perm:[1,0,3,2] row_mask:0xf bank_mask:0xf
	v_mov_b32_dpp v227, v57 quad_perm:[1,0,3,2] row_mask:0xf bank_mask:0xf
	v_cndmask_b32_e32 v22, v224, v22, vcc
	v_cndmask_b32_e32 v23, v225, v23, vcc
	v_cndmask_b32_e32 v24, v226, v24, vcc
	v_cndmask_b32_e32 v25, v227, v25, vcc
	v_cndmask_b32_e32 v54, v54, v220, vcc
	v_cndmask_b32_e32 v55, v55, v221, vcc
	v_cndmask_b32_e32 v56, v56, v222, vcc
	v_cndmask_b32_e32 v57, v57, v223, vcc
	global_store_dwordx4 v[140:141], v[54:57], off offset:128
	global_store_dwordx4 v[142:143], v[22:25], off offset:128
	v_lshl_add_u64 v[140:141], v[140:141], 0, s[10:11]
	v_lshl_add_u64 v[142:143], v[142:143], 0, s[10:11]
	s_waitcnt vmcnt(21)
	v_permlane16_swap_b32_e32 v176, v178
	v_permlane16_swap_b32_e32 v177, v179
	v_lshlrev_b32_e32 v216, 16, v176
	v_and_b32_e32 v176, 0xffff0000, v176
	v_lshlrev_b32_e32 v217, 16, v177
	v_and_b32_e32 v177, 0xffff0000, v177
	v_fmac_f32_e32 v114, s44, v216
	v_fmac_f32_e32 v115, s44, v176
	v_fmac_f32_e32 v116, s44, v217
	v_fmac_f32_e32 v117, s44, v177
	v_lshlrev_b32_e32 v216, 16, v178
	v_and_b32_e32 v178, 0xffff0000, v178
	v_lshlrev_b32_e32 v217, 16, v179
	v_and_b32_e32 v179, 0xffff0000, v179
	v_fmac_f32_e32 v82, s44, v216
	v_fmac_f32_e32 v83, s44, v178
	v_fmac_f32_e32 v84, s44, v217
	v_fmac_f32_e32 v85, s44, v179
	v_mov_b32_dpp v220, v82 quad_perm:[1,0,3,2] row_mask:0xf bank_mask:0xf
	v_mov_b32_dpp v221, v83 quad_perm:[1,0,3,2] row_mask:0xf bank_mask:0xf
	v_mov_b32_dpp v222, v84 quad_perm:[1,0,3,2] row_mask:0xf bank_mask:0xf
	v_mov_b32_dpp v223, v85 quad_perm:[1,0,3,2] row_mask:0xf bank_mask:0xf
	v_mov_b32_dpp v224, v114 quad_perm:[1,0,3,2] row_mask:0xf bank_mask:0xf
	v_mov_b32_dpp v225, v115 quad_perm:[1,0,3,2] row_mask:0xf bank_mask:0xf
	v_mov_b32_dpp v226, v116 quad_perm:[1,0,3,2] row_mask:0xf bank_mask:0xf
	v_mov_b32_dpp v227, v117 quad_perm:[1,0,3,2] row_mask:0xf bank_mask:0xf
	v_cndmask_b32_e32 v82, v224, v82, vcc
	v_cndmask_b32_e32 v83, v225, v83, vcc
	v_cndmask_b32_e32 v84, v226, v84, vcc
	v_cndmask_b32_e32 v85, v227, v85, vcc
	v_cndmask_b32_e32 v114, v114, v220, vcc
	v_cndmask_b32_e32 v115, v115, v221, vcc
	v_cndmask_b32_e32 v116, v116, v222, vcc
	v_cndmask_b32_e32 v117, v117, v223, vcc
	global_store_dwordx4 v[140:141], v[114:117], off
	global_store_dwordx4 v[142:143], v[82:85], off
	s_waitcnt vmcnt(22)
; DEVI float blo(unsigned u) { return __uint_as_float(u << 16); }
; DEVI float bhi(unsigned u) { return __uint_as_float(u & 0xffff0000u); }
;     ...
;         if (EPI == EPI_RESID || EPI == EPI_RESID_ATOMIC) {
;           f32x4 x = a;
;           if (EPI == EPI_RESID || kpart == 0) {
;             const u32x2 xr = *(const u32x2*)((const u16*)(p.ws + WS_XB) + (size_t)row * 1024 + col);
;             x[0] += ALPHA * blo(xr[0]); x[1] += ALPHA * bhi(xr[0]); x[2] += ALPHA * blo(xr[1]); x[3] += ALPHA * bhi(xr[1]);
;           }
;           if (EPI == EPI_RESID) *(f32x4*)((float*)(p.ws + WS_XF) + (size_t)row * 1024 + col) = x;
;           else *(f32x4*)((float*)(p.ws + WS_SLAB) + ((size_t)kpart * 512 + (row - T_P)) * 1024 + col) = x;
	v_permlane16_swap_b32_e32 v180, v182
	v_permlane16_swap_b32_e32 v181, v183
	v_lshlrev_b32_e32 v216, 16, v180
	v_and_b32_e32 v180, 0xffff0000, v180
	v_lshlrev_b32_e32 v217, 16, v181
	v_and_b32_e32 v181, 0xffff0000, v181
	v_fmac_f32_e32 v50, s44, v216
	v_fmac_f32_e32 v51, s44, v180
	v_fmac_f32_e32 v52, s44, v217
	v_fmac_f32_e32 v53, s44, v181
	v_lshlrev_b32_e32 v216, 16, v182
	v_and_b32_e32 v182, 0xffff0000, v182
	v_lshlrev_b32_e32 v217, 16, v183
	v_and_b32_e32 v183, 0xffff0000, v183
	v_fmac_f32_e32 v18, s44, v216
	v_fmac_f32_e32 v19, s44, v182
	v_fmac_f32_e32 v20, s44, v217
	v_fmac_f32_e32 v21, s44, v183
	v_mov_b32_dpp v220, v18 quad_perm:[1,0,3,2] row_mask:0xf bank_mask:0xf
	v_mov_b32_dpp v221, v19 quad_perm:[1,0,3,2] row_mask:0xf bank_mask:0xf
	v_mov_b32_dpp v222, v20 quad_perm:[1,0,3,2] row_mask:0xf bank_mask:0xf
	v_mov_b32_dpp v223, v21 quad_perm:[1,0,3,2] row_mask:0xf bank_mask:0xf
	v_mov_b32_dpp v224, v50 quad_perm:[1,0,3,2] row_mask:0xf bank_mask:0xf
	v_mov_b32_dpp v225, v51 quad_perm:[1,0,3,2] row_mask:0xf bank_mask:0xf
	v_mov_b32_dpp v226, v52 quad_perm:[1,0,3,2] row_mask:0xf bank_mask:0xf
	v_mov_b32_dpp v227, v53 quad_perm:[1,0,3,2] row_mask:0xf bank_mask:0xf
	v_cndmask_b32_e32 v18, v224, v18, vcc
	v_cndmask_b32_e32 v19, v225, v19, vcc
	v_cndmask_b32_e32 v20, v226, v20, vcc
	v_cndmask_b32_e32 v21, v227, v21, vcc
	v_cndmask_b32_e32 v50, v50, v220, vcc
	v_cndmask_b32_e32 v51, v51, v221, vcc
	v_cndmask_b32_e32 v52, v52, v222, vcc
	v_cndmask_b32_e32 v53, v53, v223, vcc
	global_store_dwordx4 v[140:141], v[50:53], off offset:128
	global_store_dwordx4 v[142:143], v[18:21], off offset:128
	v_lshl_add_u64 v[140:141], v[140:141], 0, s[10:11]
	v_lshl_add_u64 v[142:143], v[142:143], 0, s[10:11]
	s_waitcnt vmcnt(23)
	v_permlane16_swap_b32_e32 v184, v186
	v_permlane16_swap_b32_e32 v185, v187
	v_lshlrev_b32_e32 v216, 16, v184
	v_and_b32_e32 v184, 0xffff0000, v184
	v_lshlrev_b32_e32 v217, 16, v185
	v_and_b32_e32 v185, 0xffff0000, v185
	v_fmac_f32_e32 v110, s44, v216
	v_fmac_f32_e32 v111, s44, v184
	v_fmac_f32_e32 v112, s44, v217
	v_fmac_f32_e32 v113, s44, v185
	v_lshlrev_b32_e32 v216, 16, v186
	v_and_b32_e32 v186, 0xffff0000, v186
	v_lshlrev_b32_e32 v217, 16, v187
	v_and_b32_e32 v187, 0xffff0000, v187
	v_fmac_f32_e32 v78, s44, v216
	v_fmac_f32_e32 v79, s44, v186
	v_fmac_f32_e32 v80, s44, v217
	v_fmac_f32_e32 v81, s44, v187
	v_mov_b32_dpp v220, v78 quad_perm:[1,0,3,2] row_mask:0xf bank_mask:0xf
	v_mov_b32_dpp v221, v79 quad_perm:[1,0,3,2] row_mask:0xf bank_mask:0xf
	v_mov_b32_dpp v222, v80 quad_perm:[1,0,3,2] row_mask:0xf bank_mask:0xf
	v_mov_b32_dpp v223, v81 quad_perm:[1,0,3,2] row_mask:0xf bank_mask:0xf
	v_mov_b32_dpp v224, v110 quad_perm:[1,0,3,2] row_mask:0xf bank_mask:0xf
	v_mov_b32_dpp v225, v111 quad_perm:[1,0,3,2] row_mask:0xf bank_mask:0xf
	v_mov_b32_dpp v226, v112 quad_perm:[1,0,3,2] row_mask:0xf bank_mask:0xf
	v_mov_b32_dpp v227, v113 quad_perm:[1,0,3,2] row_mask:0xf bank_mask:0xf
	v_cndmask_b32_e32 v78, v224, v78, vcc
	v_cndmask_b32_e32 v79, v225, v79, vcc
	v_cndmask_b32_e32 v80, v226, v80, vcc
	v_cndmask_b32_e32 v81, v227, v81, vcc
	v_cndmask_b32_e32 v110, v110, v220, vcc
	v_cndmask_b32_e32 v111, v111, v221, vcc
	v_cndmask_b32_e32 v112, v112, v222, vcc
	v_cndmask_b32_e32 v113, v113, v223, vcc
	global_store_dwordx4 v[140:141], v[110:113], off
	global_store_dwordx4 v[142:143], v[78:81], off
	s_waitcnt vmcnt(24)
	v_permlane16_swap_b32_e32 v188, v190
	v_permlane16_swap_b32_e32 v189, v191
	v_lshlrev_b32_e32 v216, 16, v188
	v_and_b32_e32 v188, 0xffff0000, v188
	v_lshlrev_b32_e32 v217, 16, v189
	v_and_b32_e32 v189, 0xffff0000, v189
	v_fmac_f32_e32 v46, s44, v216
	v_fmac_f32_e32 v47, s44, v188
	v_fmac_f32_e32 v48, s44, v217
	v_fmac_f32_e32 v49, s44, v189
	v_lshlrev_b32_e32 v216, 16, v190
	v_and_b32_e32 v190, 0xffff0000, v190
	v_lshlrev_b32_e32 v217, 16, v191
	v_and_b32_e32 v191, 0xffff0000, v191
	v_fmac_f32_e32 v14, s44, v216
	v_fmac_f32_e32 v15, s44, v190
	v_fmac_f32_e32 v16, s44, v217
	v_fmac_f32_e32 v17, s44, v191
	v_mov_b32_dpp v220, v14 quad_perm:[1,0,3,2] row_mask:0xf bank_mask:0xf
	v_mov_b32_dpp v221, v15 quad_perm:[1,0,3,2] row_mask:0xf bank_mask:0xf
	v_mov_b32_dpp v222, v16 quad_perm:[1,0,3,2] row_mask:0xf bank_mask:0xf
	v_mov_b32_dpp v223, v17 quad_perm:[1,0,3,2] row_mask:0xf bank_mask:0xf
	v_mov_b32_dpp v224, v46 quad_perm:[1,0,3,2] row_mask:0xf bank_mask:0xf
	v_mov_b32_dpp v225, v47 quad_perm:[1,0,3,2] row_mask:0xf bank_mask:0xf
	v_mov_b32_dpp v226, v48 quad_perm:[1,0,3,2] row_mask:0xf bank_mask:0xf
	v_mov_b32_dpp v227, v49 quad_perm:[1,0,3,2] row_mask:0xf bank_mask:0xf
	v_cndmask_b32_e32 v14, v224, v14, vcc
	v_cndmask_b32_e32 v15, v225, v15, vcc
	v_cndmask_b32_e32 v16, v226, v16, vcc
	v_cndmask_b32_e32 v17, v227, v17, vcc
	v_cndmask_b32_e32 v46, v46, v220, vcc
	v_cndmask_b32_e32 v47, v47, v221, vcc
	v_cndmask_b32_e32 v48, v48, v222, vcc
	v_cndmask_b32_e32 v49, v49, v223, vcc
	global_store_dwordx4 v[140:141], v[46:49], off offset:128
	global_store_dwordx4 v[142:143], v[14:17], off offset:128
	v_lshl_add_u64 v[140:141], v[140:141], 0, s[10:11]
	v_lshl_add_u64 v[142:143], v[142:143], 0, s[10:11]
	s_waitcnt vmcnt(25)
; DEVI float blo(unsigned u) { return __uint_as_float(u << 16); }
; DEVI float bhi(unsigned u) { return __uint_as_float(u & 0xffff0000u); }
;     ...
;         if (EPI == EPI_RESID || EPI == EPI_RESID_ATOMIC) {
;           f32x4 x = a;
;           if (EPI == EPI_RESID || kpart == 0) {
;             const u32x2 xr = *(const u32x2*)((const u16*)(p.ws + WS_XB) + (size_t)row * 1024 + col);
;             x[0] += ALPHA * blo(xr[0]); x[1] += ALPHA * bhi(xr[0]); x[2] += ALPHA * blo(xr[1]); x[3] += ALPHA * bhi(xr[1]);
;           }
;           if (EPI == EPI_RESID) *(f32x4*)((float*)(p.ws + WS_XF) + (size_t)row * 1024 + col) = x;
;           else *(f32x4*)((float*)(p.ws + WS_SLAB) + ((size_t)kpart * 512 + (row - T_P)) * 1024 + col) = x;
	v_permlane16_swap_b32_e32 v192, v194
	v_permlane16_swap_b32_e32 v193, v195
	v_lshlrev_b32_e32 v216, 16, v192
	v_and_b32_e32 v192, 0xffff0000, v192
	v_lshlrev_b32_e32 v217, 16, v193
	v_and_b32_e32 v193, 0xffff0000, v193
	v_fmac_f32_e32 v106, s44, v216
	v_fmac_f32_e32 v107, s44, v192
	v_fmac_f32_e32 v108, s44, v217
	v_fmac_f32_e32 v109, s44, v193
	v_lshlrev_b32_e32 v216, 16, v194
	v_and_b32_e32 v194, 0xffff0000, v194
	v_lshlrev_b32_e32 v217, 16, v195
	v_and_b32_e32 v195, 0xffff0000, v195
	v_fmac_f32_e32 v74, s44, v216
	v_fmac_f32_e32 v75, s44, v194
	v_fmac_f32_e32 v76, s44, v217
	v_fmac_f32_e32 v77, s44, v195
	v_mov_b32_dpp v220, v74 quad_perm:[1,0,3,2] row_mask:0xf bank_mask:0xf
	v_mov_b32_dpp v221, v75 quad_perm:[1,0,3,2] row_mask:0xf bank_mask:0xf
	v_mov_b32_dpp v222, v76 quad_perm:[1,0,3,2] row_mask:0xf bank_mask:0xf
	v_mov_b32_dpp v223, v77 quad_perm:[1,0,3,2] row_mask:0xf bank_mask:0xf
	v_mov_b32_dpp v224, v106 quad_perm:[1,0,3,2] row_mask:0xf bank_mask:0xf
	v_mov_b32_dpp v225, v107 quad_perm:[1,0,3,2] row_mask:0xf bank_mask:0xf
	v_mov_b32_dpp v226, v108 quad_perm:[1,0,3,2] row_mask:0xf bank_mask:0xf
	v_mov_b32_dpp v227, v109 quad_perm:[1,0,3,2] row_mask:0xf bank_mask:0xf
	v_cndmask_b32_e32 v74, v224, v74, vcc
	v_cndmask_b32_e32 v75, v225, v75, vcc
	v_cndmask_b32_e32 v76, v226, v76, vcc
	v_cndmask_b32_e32 v77, v227, v77, vcc
	v_cndmask_b32_e32 v106, v106, v220, vcc
	v_cndmask_b32_e32 v107, v107, v221, vcc
	v_cndmask_b32_e32 v108, v108, v222, vcc
	v_cndmask_b32_e32 v109, v109, v223, vcc
	global_store_dwordx4 v[140:141], v[106:109], off
	global_store_dwordx4 v[142:143], v[74:77], off
	s_waitcnt vmcnt(26)
	v_permlane16_swap_b32_e32 v196, v198
	v_permlane16_swap_b32_e32 v197, v199
	v_lshlrev_b32_e32 v216, 16, v196
	v_and_b32_e32 v196, 0xffff0000, v196
	v_lshlrev_b32_e32 v217, 16, v197
	v_and_b32_e32 v197, 0xffff0000, v197
	v_fmac_f32_e32 v42, s44, v216
	v_fmac_f32_e32 v43, s44, v196
	v_fmac_f32_e32 v44, s44, v217
	v_fmac_f32_e32 v45, s44, v197
	v_lshlrev_b32_e32 v216, 16, v198
	v_and_b32_e32 v198, 0xffff0000, v198
	v_lshlrev_b32_e32 v217, 16, v199
	v_and_b32_e32 v199, 0xffff0000, v199
	v_fmac_f32_e32 v10, s44, v216
	v_fmac_f32_e32 v11, s44, v198
	v_fmac_f32_e32 v12, s44, v217
	v_fmac_f32_e32 v13, s44, v199
	v_mov_b32_dpp v220, v10 quad_perm:[1,0,3,2] row_mask:0xf bank_mask:0xf
	v_mov_b32_dpp v221, v11 quad_perm:[1,0,3,2] row_mask:0xf bank_mask:0xf
	v_mov_b32_dpp v222, v12 quad_perm:[1,0,3,2] row_mask:0xf bank_mask:0xf
	v_mov_b32_dpp v223, v13 quad_perm:[1,0,3,2] row_mask:0xf bank_mask:0xf
	v_mov_b32_dpp v224, v42 quad_perm:[1,0,3,2] row_mask:0xf bank_mask:0xf
	v_mov_b32_dpp v225, v43 quad_perm:[1,0,3,2] row_mask:0xf bank_mask:0xf
	v_mov_b32_dpp v226, v44 quad_perm:[1,0,3,2] row_mask:0xf bank_mask:0xf
	v_mov_b32_dpp v227, v45 quad_perm:[1,0,3,2] row_mask:0xf bank_mask:0xf
	v_cndmask_b32_e32 v10, v224, v10, vcc
	v_cndmask_b32_e32 v11, v225, v11, vcc
	v_cndmask_b32_e32 v12, v226, v12, vcc
	v_cndmask_b32_e32 v13, v227, v13, vcc
	v_cndmask_b32_e32 v42, v42, v220, vcc
	v_cndmask_b32_e32 v43, v43, v221, vcc
	v_cndmask_b32_e32 v44, v44, v222, vcc
	v_cndmask_b32_e32 v45, v45, v223, vcc
	global_store_dwordx4 v[140:141], v[42:45], off offset:128
	global_store_dwordx4 v[142:143], v[10:13], off offset:128
	v_lshl_add_u64 v[140:141], v[140:141], 0, s[10:11]
	v_lshl_add_u64 v[142:143], v[142:143], 0, s[10:11]
	s_waitcnt vmcnt(27)
	v_permlane16_swap_b32_e32 v200, v202
	v_permlane16_swap_b32_e32 v201, v203
	v_lshlrev_b32_e32 v216, 16, v200
	v_and_b32_e32 v200, 0xffff0000, v200
	v_lshlrev_b32_e32 v217, 16, v201
	v_and_b32_e32 v201, 0xffff0000, v201
	v_fmac_f32_e32 v102, s44, v216
	v_fmac_f32_e32 v103, s44, v200
	v_fmac_f32_e32 v104, s44, v217
	v_fmac_f32_e32 v105, s44, v201
	v_lshlrev_b32_e32 v216, 16, v202
	v_and_b32_e32 v202, 0xffff0000, v202
	v_lshlrev_b32_e32 v217, 16, v203
	v_and_b32_e32 v203, 0xffff0000, v203
	v_fmac_f32_e32 v70, s44, v216
	v_fmac_f32_e32 v71, s44, v202
	v_fmac_f32_e32 v72, s44, v217
	v_fmac_f32_e32 v73, s44, v203
	v_mov_b32_dpp v220, v70 quad_perm:[1,0,3,2] row_mask:0xf bank_mask:0xf
	v_mov_b32_dpp v221, v71 quad_perm:[1,0,3,2] row_mask:0xf bank_mask:0xf
	v_mov_b32_dpp v222, v72 quad_perm:[1,0,3,2] row_mask:0xf bank_mask:0xf
	v_mov_b32_dpp v223, v73 quad_perm:[1,0,3,2] row_mask:0xf bank_mask:0xf
	v_mov_b32_dpp v224, v102 quad_perm:[1,0,3,2] row_mask:0xf bank_mask:0xf
	v_mov_b32_dpp v225, v103 quad_perm:[1,0,3,2] row_mask:0xf bank_mask:0xf
	v_mov_b32_dpp v226, v104 quad_perm:[1,0,3,2] row_mask:0xf bank_mask:0xf
	v_mov_b32_dpp v227, v105 quad_perm:[1,0,3,2] row_mask:0xf bank_mask:0xf
	v_cndmask_b32_e32 v70, v224, v70, vcc
	v_cndmask_b32_e32 v71, v225, v71, vcc
	v_cndmask_b32_e32 v72, v226, v72, vcc
	v_cndmask_b32_e32 v73, v227, v73, vcc
	v_cndmask_b32_e32 v102, v102, v220, vcc
	v_cndmask_b32_e32 v103, v103, v221, vcc
	v_cndmask_b32_e32 v104, v104, v222, vcc
	v_cndmask_b32_e32 v105, v105, v223, vcc
	global_store_dwordx4 v[140:141], v[102:105], off
	global_store_dwordx4 v[142:143], v[70:73], off
	s_waitcnt vmcnt(28)
; DEVI float blo(unsigned u) { return __uint_as_float(u << 16); }
; DEVI float bhi(unsigned u) { return __uint_as_float(u & 0xffff0000u); }
;     ...
;         if (EPI == EPI_RESID || EPI == EPI_RESID_ATOMIC) {
;           f32x4 x = a;
;           if (EPI == EPI_RESID || kpart == 0) {
;             const u32x2 xr = *(const u32x2*)((const u16*)(p.ws + WS_XB) + (size_t)row * 1024 + col);
;             x[0] += ALPHA * blo(xr[0]); x[1] += ALPHA * bhi(xr[0]); x[2] += ALPHA * blo(xr[1]); x[3] += ALPHA * bhi(xr[1]);
;           }
;           if (EPI == EPI_RESID) *(f32x4*)((float*)(p.ws + WS_XF) + (size_t)row * 1024 + col) = x;
;           else *(f32x4*)((float*)(p.ws + WS_SLAB) + ((size_t)kpart * 512 + (row - T_P)) * 1024 + col) = x;
	v_permlane16_swap_b32_e32 v204, v206
	v_permlane16_swap_b32_e32 v205, v207
	v_lshlrev_b32_e32 v216, 16, v204
	v_and_b32_e32 v204, 0xffff0000, v204
	v_lshlrev_b32_e32 v217, 16, v205
	v_and_b32_e32 v205, 0xffff0000, v205
	v_fmac_f32_e32 v38, s44, v216
	v_fmac_f32_e32 v39, s44, v204
	v_fmac_f32_e32 v40, s44, v217
	v_fmac_f32_e32 v41, s44, v205
	v_lshlrev_b32_e32 v216, 16, v206
	v_and_b32_e32 v206, 0xffff0000, v206
	v_lshlrev_b32_e32 v217, 16, v207
	v_and_b32_e32 v207, 0xffff0000, v207
	v_fmac_f32_e32 v6, s44, v216
	v_fmac_f32_e32 v7, s44, v206
	v_fmac_f32_e32 v8, s44, v217
	v_fmac_f32_e32 v9, s44, v207
	v_mov_b32_dpp v220, v6 quad_perm:[1,0,3,2] row_mask:0xf bank_mask:0xf
	v_mov_b32_dpp v221, v7 quad_perm:[1,0,3,2] row_mask:0xf bank_mask:0xf
	v_mov_b32_dpp v222, v8 quad_perm:[1,0,3,2] row_mask:0xf bank_mask:0xf
	v_mov_b32_dpp v223, v9 quad_perm:[1,0,3,2] row_mask:0xf bank_mask:0xf
	v_mov_b32_dpp v224, v38 quad_perm:[1,0,3,2] row_mask:0xf bank_mask:0xf
	v_mov_b32_dpp v225, v39 quad_perm:[1,0,3,2] row_mask:0xf bank_mask:0xf
	v_mov_b32_dpp v226, v40 quad_perm:[1,0,3,2] row_mask:0xf bank_mask:0xf
	v_mov_b32_dpp v227, v41 quad_perm:[1,0,3,2] row_mask:0xf bank_mask:0xf
	v_cndmask_b32_e32 v6, v224, v6, vcc
	v_cndmask_b32_e32 v7, v225, v7, vcc
	v_cndmask_b32_e32 v8, v226, v8, vcc
	v_cndmask_b32_e32 v9, v227, v9, vcc
	v_cndmask_b32_e32 v38, v38, v220, vcc
	v_cndmask_b32_e32 v39, v39, v221, vcc
	v_cndmask_b32_e32 v40, v40, v222, vcc
	v_cndmask_b32_e32 v41, v41, v223, vcc
	global_store_dwordx4 v[140:141], v[38:41], off offset:128
	global_store_dwordx4 v[142:143], v[6:9], off offset:128
	v_lshl_add_u64 v[140:141], v[140:141], 0, s[10:11]
	v_lshl_add_u64 v[142:143], v[142:143], 0, s[10:11]
	s_waitcnt vmcnt(29)
	v_permlane16_swap_b32_e32 v208, v210
	v_permlane16_swap_b32_e32 v209, v211
	v_lshlrev_b32_e32 v216, 16, v208
	v_and_b32_e32 v208, 0xffff0000, v208
	v_lshlrev_b32_e32 v217, 16, v209
	v_and_b32_e32 v209, 0xffff0000, v209
	v_fmac_f32_e32 v98, s44, v216
	v_fmac_f32_e32 v99, s44, v208
	v_fmac_f32_e32 v100, s44, v217
	v_fmac_f32_e32 v101, s44, v209
	v_lshlrev_b32_e32 v216, 16, v210
	v_and_b32_e32 v210, 0xffff0000, v210
	v_lshlrev_b32_e32 v217, 16, v211
	v_and_b32_e32 v211, 0xffff0000, v211
	v_fmac_f32_e32 v66, s44, v216
	v_fmac_f32_e32 v67, s44, v210
	v_fmac_f32_e32 v68, s44, v217
	v_fmac_f32_e32 v69, s44, v211
	v_mov_b32_dpp v220, v66 quad_perm:[1,0,3,2] row_mask:0xf bank_mask:0xf
	v_mov_b32_dpp v221, v67 quad_perm:[1,0,3,2] row_mask:0xf bank_mask:0xf
	v_mov_b32_dpp v222, v68 quad_perm:[1,0,3,2] row_mask:0xf bank_mask:0xf
	v_mov_b32_dpp v223, v69 quad_perm:[1,0,3,2] row_mask:0xf bank_mask:0xf
	v_mov_b32_dpp v224, v98 quad_perm:[1,0,3,2] row_mask:0xf bank_mask:0xf
	v_mov_b32_dpp v225, v99 quad_perm:[1,0,3,2] row_mask:0xf bank_mask:0xf
	v_mov_b32_dpp v226, v100 quad_perm:[1,0,3,2] row_mask:0xf bank_mask:0xf
	v_mov_b32_dpp v227, v101 quad_perm:[1,0,3,2] row_mask:0xf bank_mask:0xf
	v_cndmask_b32_e32 v66, v224, v66, vcc
	v_cndmask_b32_e32 v67, v225, v67, vcc
	v_cndmask_b32_e32 v68, v226, v68, vcc
	v_cndmask_b32_e32 v69, v227, v69, vcc
	v_cndmask_b32_e32 v98, v98, v220, vcc
	v_cndmask_b32_e32 v99, v99, v221, vcc
	v_cndmask_b32_e32 v100, v100, v222, vcc
	v_cndmask_b32_e32 v101, v101, v223, vcc
	global_store_dwordx4 v[140:141], v[98:101], off
	global_store_dwordx4 v[142:143], v[66:69], off
	s_waitcnt vmcnt(30)
	v_permlane16_swap_b32_e32 v212, v214
	v_permlane16_swap_b32_e32 v213, v215
	v_lshlrev_b32_e32 v216, 16, v212
	v_and_b32_e32 v212, 0xffff0000, v212
	v_lshlrev_b32_e32 v217, 16, v213
	v_and_b32_e32 v213, 0xffff0000, v213
	v_fmac_f32_e32 v34, s44, v216
	v_fmac_f32_e32 v35, s44, v212
	v_fmac_f32_e32 v36, s44, v217
	v_fmac_f32_e32 v37, s44, v213
	v_lshlrev_b32_e32 v216, 16, v214
	v_and_b32_e32 v214, 0xffff0000, v214
	v_lshlrev_b32_e32 v217, 16, v215
	v_and_b32_e32 v215, 0xffff0000, v215
	v_fmac_f32_e32 v2, s44, v216
	v_fmac_f32_e32 v3, s44, v214
	v_fmac_f32_e32 v4, s44, v217
	v_fmac_f32_e32 v5, s44, v215
	v_mov_b32_dpp v220, v2 quad_perm:[1,0,3,2] row_mask:0xf bank_mask:0xf
	v_mov_b32_dpp v221, v3 quad_perm:[1,0,3,2] row_mask:0xf bank_mask:0xf
	v_mov_b32_dpp v222, v4 quad_perm:[1,0,3,2] row_mask:0xf bank_mask:0xf
	v_mov_b32_dpp v223, v5 quad_perm:[1,0,3,2] row_mask:0xf bank_mask:0xf
	v_mov_b32_dpp v224, v34 quad_perm:[1,0,3,2] row_mask:0xf bank_mask:0xf
	v_mov_b32_dpp v225, v35 quad_perm:[1,0,3,2] row_mask:0xf bank_mask:0xf
	v_mov_b32_dpp v226, v36 quad_perm:[1,0,3,2] row_mask:0xf bank_mask:0xf
	v_mov_b32_dpp v227, v37 quad_perm:[1,0,3,2] row_mask:0xf bank_mask:0xf
	v_cndmask_b32_e32 v2, v224, v2, vcc
	v_cndmask_b32_e32 v3, v225, v3, vcc
	v_cndmask_b32_e32 v4, v226, v4, vcc
	v_cndmask_b32_e32 v5, v227, v5, vcc
	v_cndmask_b32_e32 v34, v34, v220, vcc
	v_cndmask_b32_e32 v35, v35, v221, vcc
	v_cndmask_b32_e32 v36, v36, v222, vcc
	v_cndmask_b32_e32 v37, v37, v223, vcc
	global_store_dwordx4 v[140:141], v[34:37], off offset:128
	global_store_dwordx4 v[142:143], v[2:5], off offset:128
	v_readlane_b32 s39, v250, 7
	s_cmpk_lg_u32 s39, 0x200
	s_cbranch_scc1 .LBB0_146
	v_readlane_b32 s40, v250, 0
	s_lshr_b32 s41, s40, 3
	s_and_b32 s40, s40, 7
	s_mul_i32 s40, s40, 4
	s_add_i32 s40, s40, s41
	s_cmp_lt_u32 s41, 4
	s_movk_i32 s38, 0x4000
	s_branch .LBB0_146

; #define LAS __attribute__((address_space(3)))
; DEVI int tidx() { int t = threadIdx.x; asm volatile("" : "+v"(t)); return t; }
;   const int tid = tidx(), lane = tid & 63, wid = tid >> 6;
;   const int wm = wid >> 1, wn = wid & 1, r16 = lane & 15, quad = lane >> 4;
;   f32x4 acc[4][8];
; #pragma unroll
;   for (int i = 0; i < 4; i++)
; #pragma unroll
;     for (int j = 0; j < 8; j++) acc[i][j] = (f32x4){0.f, 0.f, 0.f, 0.f};
;   const int nk = (nk_part < 0) ? (K >> 5) : nk_part;
;   const int lrow = tid >> 2, lpc = tid & 3;
;   const int lch = lpc ^ ((0x78 >> (((lrow >> 2) & 3) * 2)) & 3);
;   const u16* ga = A + (size_t)(m0 + lrow) * lda + kbeg + lch * 8;
;   const u16* gb = Bt + (size_t)(n0 + lrow) * K + kbeg + lch * 8;
;   const size_t ga1 = (size_t)64 * lda, gb1 = (size_t)64 * K;
;   const unsigned lds0 = (unsigned)(uintptr_t)(LAS char*)smem + (unsigned)__builtin_amdgcn_readfirstlane(wid) * 1024u;
;     ...
;   __syncthreads();
;   G2_STAGE(0); G2_STAGE(1);
; DEVI void run_phase(const Params& p, int ph, char* smem) {
;     ...
;           const int u_ = t - 512, tl_ = u_ / 8, q_ = u_ - tl_ * 8;
;           gemm_tile256<EPI_RESID_ATOMIC>(p, mix, 1024, Bt, 1024, (64 + (tl_ & 1)) * 256, (tl_ >> 1) * 128, nullptr, 0, smem, q_ * 128, 4, q_);
.LBB0_758:
	s_cmpk_gt_i32 s39, 0x1ff
	s_mov_b64 s[2:3], -1
	s_cbranch_scc0 .LBB0_812
	s_setprio 2
	s_sub_i32 s43, s39, 512
	s_lshr_b32 s42, s43, 3
	s_and_b32 s98, s43, 7
	s_lshr_b32 s15, s42, 1
	s_and_b32 s42, s42, 1
	s_add_i32 s42, s42, 64
	v_readlane_b32 s2, v250, 5
	v_readlane_b32 s3, v250, 6
	v_readlane_b32 s43, v254, 62
	s_mul_i32 s1, s42, 0x80000
	s_add_u32 s4, s2, s1
	s_addc_u32 s5, s3, 0
	s_add_u32 s4, s4, 0xb580000
	s_addc_u32 s5, s5, 0
	s_mul_i32 s1, s43, 0x200000
	s_mul_i32 s14, s15, 0x40000
	s_add_i32 s1, s1, s14
	s_add_u32 s10, s2, s1
	s_addc_u32 s11, s3, 0
	s_add_u32 s10, s10, 0x15e00000
	s_addc_u32 s11, s11, 0
	s_mul_i32 s1, s98, 256
	s_add_u32 s4, s4, s1
	s_addc_u32 s5, s5, 0
	s_mul_i32 s1, s98, 512
	s_add_u32 s10, s10, s1
	s_addc_u32 s11, s11, 0
	s_movk_i32 s0, 0x78
	v_lshrrev_b32_e32 v0, 2, v145
	v_and_b32_e32 v131, 3, v145
	v_bfe_u32 v136, v145, 4, 2
	v_lshlrev_b32_e32 v136, 1, v136
	v_lshrrev_b32_e64 v136, v136, s0
	v_and_b32_e32 v136, 3, v136
	v_xor_b32_e32 v131, v131, v136
	v_lshlrev_b32_e32 v131, 4, v131
	s_movk_i32 s14, 0x800
	v_mad_u32_u24 v0, v0, s14, v131
	v_bfe_u32 v137, v145, 2, 1
	s_movk_i32 s14, 0x7c0
	v_mul_u32_u24_e32 v136, s14, v137
	v_sub_u32_e32 v136, v0, v136
	v_mov_b32_e32 v137, 0
	v_lshl_add_u64 v[134:135], s[10:11], 0, v[136:137]
	v_bfe_u32 v137, v145, 2, 1
	s_mov_b32 s12, 64
	s_mov_b32 s13, 0
	v_lshl_add_u64 v[132:133], s[4:5], 0, v[0:1]
	v_bfe_u32 v136, v145, 2, 2
	v_lshlrev_b32_e32 v136, 1, v136
	v_lshrrev_b32_e64 v136, v136, s0
	v_and_b32_e32 v136, 3, v136
	v_bfe_u32 v137, v145, 4, 2
	v_xor_b32_e32 v136, v136, v137
	v_lshlrev_b32_e32 v136, 4, v136
	v_and_b32_e32 v131, 15, v145
	v_lshl_or_b32 v136, v131, 6, v136
	v_bfe_u32 v137, v145, 6, 1
	v_lshl_or_b32 v137, v137, 12, v136
	v_lshrrev_b32_e32 v0, 7, v145
	v_lshl_or_b32 v136, v0, 13, v136
	v_and_b32_e32 v140, 1, v131
	v_lshl_or_b32 v131, v0, 7, v131
	v_bfe_u32 v0, v145, 4, 2
	v_lshlrev_b32_e32 v0, 3, v0
	v_bfe_u32 v141, v145, 6, 1
	s_lshl_b32 s1, s42, 19
	s_lshl_b32 s14, s15, 8
	s_add_i32 s1, s1, s14
	s_add_u32 s4, s2, s1
	s_addc_u32 s5, s3, 0
	s_add_u32 s4, s4, 0x4200000
	s_addc_u32 s5, s5, 0
	v_lshlrev_b32_e32 v138, 11, v131
	v_lshl_add_u32 v138, v141, 7, v138
	v_bfe_u32 v139, v145, 4, 1
	v_lshl_add_u32 v138, v139, 5, v138
	v_bfe_u32 v139, v145, 5, 1
	v_lshl_add_u32 v138, v139, 4, v138
	v_mov_b32_e32 v139, 0
	v_lshl_add_u64 v[138:139], s[4:5], 0, v[138:139]
	s_and_b32 s1, s42, 1
	s_lshl_b32 s1, s1, 20
	s_lshl_b32 s14, s98, 21
	s_add_i32 s1, s1, s14
	s_lshl_b32 s14, s15, 9
	s_add_i32 s1, s1, s14
	s_add_u32 s10, s2, s1
	s_addc_u32 s11, s3, 0
	s_add_u32 s10, s10, 0x1dcc0000
	s_addc_u32 s11, s11, 0
	v_lshlrev_b32_e32 v140, 12, v131
	v_lshl_add_u32 v140, v141, 8, v140
	v_lshl_add_u32 v140, v0, 1, v140
	v_mov_b32_e32 v141, 0
	v_lshl_add_u64 v[140:141], s[10:11], 0, v[140:141]
	s_mov_b32 s2, 0x20000
	s_mov_b32 s3, 0
	v_lshrrev_b32_e32 v0, 6, v145
	v_lshlrev_b32_e32 v0, 10, v0
	s_nop 0
	v_readfirstlane_b32 s43, v0
	s_mov_b32 s40, m0
	s_mov_b32 s4, 128
	s_mov_b32 s5, 0
	s_barrier
	s_add_i32 s15, s43, 0x0
	s_mov_b32 m0, s15
	v_lshl_add_u64 v[142:143], v[132:133], 0, s[2:3]
	global_load_lds_dwordx4 v[132:133], off
	s_add_i32 m0, m0, 0x1000
	s_nop 0
	global_load_lds_dwordx4 v[142:143], off
	v_lshl_add_u64 v[142:143], v[142:143], 0, s[2:3]
	s_add_i32 m0, m0, 0x1000
	s_nop 0
	global_load_lds_dwordx4 v[142:143], off
	v_lshl_add_u64 v[142:143], v[142:143], 0, s[2:3]
	s_add_i32 m0, m0, 0x1000
	s_nop 0
	global_load_lds_dwordx4 v[142:143], off
	s_add_i32 m0, m0, 0x1000
	v_lshl_add_u64 v[142:143], v[134:135], 0, s[2:3]
	s_nop 0
	global_load_lds_dwordx4 v[134:135], off
	s_add_i32 m0, m0, 0x1000
	v_lshl_add_u64 v[132:133], v[132:133], 0, s[12:13]
	s_nop 0
	global_load_lds_dwordx4 v[142:143], off
	v_lshl_add_u64 v[134:135], v[134:135], 0, s[4:5]
	s_nop 0
	s_add_i32 s15, s43, 0x6000
	s_mov_b32 m0, s15
	v_lshl_add_u64 v[142:143], v[132:133], 0, s[2:3]
	global_load_lds_dwordx4 v[132:133], off
	s_add_i32 m0, m0, 0x1000
	s_nop 0
	global_load_lds_dwordx4 v[142:143], off
	v_lshl_add_u64 v[142:143], v[142:143], 0, s[2:3]
	s_add_i32 m0, m0, 0x1000
	s_nop 0
	global_load_lds_dwordx4 v[142:143], off
	v_lshl_add_u64 v[142:143], v[142:143], 0, s[2:3]
	s_add_i32 m0, m0, 0x1000
	s_nop 0
	global_load_lds_dwordx4 v[142:143], off
	s_add_i32 m0, m0, 0x1000
	v_lshl_add_u64 v[142:143], v[134:135], 0, s[2:3]
	s_nop 0
	global_load_lds_dwordx4 v[134:135], off
	s_add_i32 m0, m0, 0x1000
	v_lshl_add_u64 v[132:133], v[132:133], 0, s[12:13]
	s_nop 0
	global_load_lds_dwordx4 v[142:143], off
	v_lshl_add_u64 v[134:135], v[134:135], 0, s[4:5]
	s_nop 0
	s_add_i32 s15, s43, 0xc000
	s_mov_b32 m0, s15
	v_lshl_add_u64 v[142:143], v[132:133], 0, s[2:3]
	global_load_lds_dwordx4 v[132:133], off
	s_add_i32 m0, m0, 0x1000
	s_nop 0
	global_load_lds_dwordx4 v[142:143], off
	v_lshl_add_u64 v[142:143], v[142:143], 0, s[2:3]
	s_add_i32 m0, m0, 0x1000
	s_nop 0
	global_load_lds_dwordx4 v[142:143], off
	v_lshl_add_u64 v[142:143], v[142:143], 0, s[2:3]
	s_add_i32 m0, m0, 0x1000
	s_nop 0
	global_load_lds_dwordx4 v[142:143], off
	s_add_i32 m0, m0, 0x1000
	v_lshl_add_u64 v[142:143], v[134:135], 0, s[2:3]
	s_nop 0
	global_load_lds_dwordx4 v[134:135], off
	s_add_i32 m0, m0, 0x1000
	v_lshl_add_u64 v[132:133], v[132:133], 0, s[12:13]
	s_nop 0
	global_load_lds_dwordx4 v[142:143], off
	v_lshl_add_u64 v[134:135], v[134:135], 0, s[4:5]
	s_nop 0
	v_mov_b32_e32 v2, 0
	v_mov_b32_e32 v3, 0
	v_mov_b32_e32 v4, 0
	v_mov_b32_e32 v5, 0
	v_mov_b32_e32 v6, 0
	v_mov_b32_e32 v7, 0
	v_mov_b32_e32 v8, 0
	v_mov_b32_e32 v9, 0
	v_mov_b32_e32 v10, 0
	v_mov_b32_e32 v11, 0
	v_mov_b32_e32 v12, 0
	v_mov_b32_e32 v13, 0
	v_mov_b32_e32 v14, 0
; #define LAS __attribute__((address_space(3)))
;     ...
;   f32x4 acc[4][8];
; #pragma unroll
;   for (int i = 0; i < 4; i++)
; #pragma unroll
;     for (int j = 0; j < 8; j++) acc[i][j] = (f32x4){0.f, 0.f, 0.f, 0.f};
;   const int nk = (nk_part < 0) ? (K >> 5) : nk_part;
;   const int lrow = tid >> 2, lpc = tid & 3;
;   const int lch = lpc ^ ((0x78 >> (((lrow >> 2) & 3) * 2)) & 3);
;   const u16* ga = A + (size_t)(m0 + lrow) * lda + kbeg + lch * 8;
;   const u16* gb = Bt + (size_t)(n0 + lrow) * K + kbeg + lch * 8;
;   const size_t ga1 = (size_t)64 * lda, gb1 = (size_t)64 * K;
;   const unsigned lds0 = (unsigned)(uintptr_t)(LAS char*)smem + (unsigned)__builtin_amdgcn_readfirstlane(wid) * 1024u;
;     ...
;   __syncthreads();
;   G2_STAGE(0); G2_STAGE(1);
;   const int fsw = (0x78 >> (((r16 >> 2) & 3) * 2)) & 3;
;   const int aoff = (wm * 128 + r16) * 64 + ((quad ^ fsw) << 4);
;   const int boff = 16384 + (wn * 64 + r16) * 64 + ((quad ^ fsw) << 4);
;   for (int kt = 0; kt < nk; kt++) {
;     if (kt + 1 < nk) asm volatile("s_waitcnt vmcnt(6)" ::: "memory");
;     else asm volatile("s_waitcnt vmcnt(0)" ::: "memory");
;     __builtin_amdgcn_s_barrier();
;     asm volatile("" ::: "memory");
;     if (kt + 2 < nk) G2_STAGE(kt + 2);
;     const char* cS = smem + (kt % 3) * 24576;
;     bf16x8 xa[8], wb[4];
; #pragma unroll
;     for (int f = 0; f < 8; f++) xa[f] = *(const bf16x8*)(cS + aoff + f * 1024);
; #pragma unroll
;     for (int f = 0; f < 4; f++) wb[f] = *(const bf16x8*)(cS + boff + f * 1024);
; #pragma unroll
;     for (int nf = 0; nf < 4; nf++)
; #pragma unroll
;       for (int mf = 0; mf < 8; mf++)
;         acc[nf][mf] = __builtin_amdgcn_mfma_f32_16x16x32_bf16(wb[nf], xa[mf], acc[nf][mf], 0, 0, 0);
	v_mov_b32_e32 v15, 0
	v_mov_b32_e32 v16, 0
	v_mov_b32_e32 v17, 0
	v_mov_b32_e32 v18, 0
	v_mov_b32_e32 v19, 0
	v_mov_b32_e32 v20, 0
	v_mov_b32_e32 v21, 0
	v_mov_b32_e32 v22, 0
	v_mov_b32_e32 v23, 0
	v_mov_b32_e32 v24, 0
	v_mov_b32_e32 v25, 0
	v_mov_b32_e32 v26, 0
	v_mov_b32_e32 v27, 0
	v_mov_b32_e32 v28, 0
	v_mov_b32_e32 v29, 0
	v_mov_b32_e32 v30, 0
	v_mov_b32_e32 v31, 0
	v_mov_b32_e32 v32, 0
	v_mov_b32_e32 v33, 0
	v_mov_b32_e32 v34, 0
	v_mov_b32_e32 v35, 0
	v_mov_b32_e32 v36, 0
	v_mov_b32_e32 v37, 0
	v_mov_b32_e32 v38, 0
	v_mov_b32_e32 v39, 0
	v_mov_b32_e32 v40, 0
	v_mov_b32_e32 v41, 0
	v_mov_b32_e32 v42, 0
	v_mov_b32_e32 v43, 0
	v_mov_b32_e32 v44, 0
	v_mov_b32_e32 v45, 0
	v_mov_b32_e32 v46, 0
	v_mov_b32_e32 v47, 0
	v_mov_b32_e32 v48, 0
	v_mov_b32_e32 v49, 0
	v_mov_b32_e32 v50, 0
	v_mov_b32_e32 v51, 0
	v_mov_b32_e32 v52, 0
	v_mov_b32_e32 v53, 0
	v_mov_b32_e32 v54, 0
	v_mov_b32_e32 v55, 0
	v_mov_b32_e32 v56, 0
	v_mov_b32_e32 v57, 0
	v_mov_b32_e32 v58, 0
	v_mov_b32_e32 v59, 0
	v_mov_b32_e32 v60, 0
	v_mov_b32_e32 v61, 0
	v_mov_b32_e32 v62, 0
	v_mov_b32_e32 v63, 0
	v_mov_b32_e32 v64, 0
	v_mov_b32_e32 v65, 0
	v_mov_b32_e32 v66, 0
	v_mov_b32_e32 v67, 0
	v_mov_b32_e32 v68, 0
	v_mov_b32_e32 v69, 0
	v_mov_b32_e32 v70, 0
	v_mov_b32_e32 v71, 0
	v_mov_b32_e32 v72, 0
	v_mov_b32_e32 v73, 0
	v_mov_b32_e32 v74, 0
	v_mov_b32_e32 v75, 0
	v_mov_b32_e32 v76, 0
	v_mov_b32_e32 v77, 0
	v_mov_b32_e32 v78, 0
	v_mov_b32_e32 v79, 0
	v_mov_b32_e32 v80, 0
	v_mov_b32_e32 v81, 0
	v_mov_b32_e32 v82, 0
	v_mov_b32_e32 v83, 0
	v_mov_b32_e32 v84, 0
	v_mov_b32_e32 v85, 0
	v_mov_b32_e32 v86, 0
	v_mov_b32_e32 v87, 0
	v_mov_b32_e32 v88, 0
	v_mov_b32_e32 v89, 0
	v_mov_b32_e32 v90, 0
	v_mov_b32_e32 v91, 0
	v_mov_b32_e32 v92, 0
	v_mov_b32_e32 v93, 0
	v_mov_b32_e32 v94, 0
	v_mov_b32_e32 v95, 0
	v_mov_b32_e32 v96, 0
	v_mov_b32_e32 v97, 0
	v_mov_b32_e32 v98, 0
	v_mov_b32_e32 v99, 0
	v_mov_b32_e32 v100, 0
	v_mov_b32_e32 v101, 0
	v_mov_b32_e32 v102, 0
	v_mov_b32_e32 v103, 0
	v_mov_b32_e32 v104, 0
	v_mov_b32_e32 v105, 0
	v_mov_b32_e32 v106, 0
	v_mov_b32_e32 v107, 0
	v_mov_b32_e32 v108, 0
	v_mov_b32_e32 v109, 0
	v_mov_b32_e32 v110, 0
	v_mov_b32_e32 v111, 0
	v_mov_b32_e32 v112, 0
	v_mov_b32_e32 v113, 0
	v_mov_b32_e32 v114, 0
	v_mov_b32_e32 v115, 0
	v_mov_b32_e32 v116, 0
	v_mov_b32_e32 v117, 0
	v_mov_b32_e32 v118, 0
	v_mov_b32_e32 v119, 0
	v_mov_b32_e32 v120, 0
	v_mov_b32_e32 v121, 0
	v_mov_b32_e32 v122, 0
	v_mov_b32_e32 v123, 0
	v_mov_b32_e32 v124, 0
	v_mov_b32_e32 v125, 0
	v_mov_b32_e32 v126, 0
	v_mov_b32_e32 v127, 0
	v_mov_b32_e32 v128, 0
	v_mov_b32_e32 v129, 0
	s_setprio 0
	s_waitcnt vmcnt(12)
	s_barrier
	ds_read_b128 v[146:149], v136 offset:0
	ds_read_b128 v[152:155], v136 offset:1024
	ds_read_b128 v[156:159], v136 offset:2048
	ds_read_b128 v[162:165], v136 offset:3072
	ds_read_b128 v[166:169], v136 offset:4096
	ds_read_b128 v[170:173], v136 offset:5120
	ds_read_b128 v[176:179], v136 offset:6144
	ds_read_b128 v[180:183], v136 offset:7168
	ds_read_b128 v[184:187], v137 offset:16384
	ds_read_b128 v[188:191], v137 offset:17408
	ds_read_b128 v[192:195], v137 offset:18432
	ds_read_b128 v[196:199], v137 offset:19456
	s_movk_i32 s1, 0x6000
	s_mov_b32 s14, 0
	.p2align 3
	s_waitcnt vmcnt(6) lgkmcnt(0)
	s_barrier
	s_setprio 1
	v_add_u32_e32 v144, s1, v136
	v_mfma_f32_16x16x32_bf16 v[126:129], v[184:187], v[146:149], v[126:129]
	ds_read_b128 v[200:203], v144 offset:0
	v_mfma_f32_16x16x32_bf16 v[122:125], v[184:187], v[152:155], v[122:125]
	ds_read_b128 v[204:207], v144 offset:1024
	v_mfma_f32_16x16x32_bf16 v[118:121], v[184:187], v[156:159], v[118:121]
	ds_read_b128 v[208:211], v144 offset:2048
	v_mfma_f32_16x16x32_bf16 v[114:117], v[184:187], v[162:165], v[114:117]
	ds_read_b128 v[212:215], v144 offset:3072
	v_mfma_f32_16x16x32_bf16 v[110:113], v[184:187], v[166:169], v[110:113]
	ds_read_b128 v[216:219], v144 offset:4096
	v_mfma_f32_16x16x32_bf16 v[106:109], v[184:187], v[170:173], v[106:109]
	ds_read_b128 v[220:223], v144 offset:5120
	v_mfma_f32_16x16x32_bf16 v[102:105], v[184:187], v[176:179], v[102:105]
	ds_read_b128 v[224:227], v144 offset:6144
	v_mfma_f32_16x16x32_bf16 v[98:101], v[184:187], v[180:183], v[98:101]
	ds_read_b128 v[228:231], v144 offset:7168
	v_mfma_f32_16x16x32_bf16 v[94:97], v[188:191], v[146:149], v[94:97]
	v_add_u32_e64 v144, s1, v137
	v_mfma_f32_16x16x32_bf16 v[90:93], v[188:191], v[152:155], v[90:93]
	v_mfma_f32_16x16x32_bf16 v[86:89], v[188:191], v[156:159], v[86:89]
	ds_read_b128 v[232:235], v144 offset:16384
	v_mfma_f32_16x16x32_bf16 v[82:85], v[188:191], v[162:165], v[82:85]
	ds_read_b128 v[236:239], v144 offset:17408
	v_mfma_f32_16x16x32_bf16 v[78:81], v[188:191], v[166:169], v[78:81]
	ds_read_b128 v[240:243], v144 offset:18432
	v_mfma_f32_16x16x32_bf16 v[74:77], v[188:191], v[170:173], v[74:77]
	ds_read_b128 v[244:247], v144 offset:19456
	v_mfma_f32_16x16x32_bf16 v[70:73], v[188:191], v[176:179], v[70:73]
	s_add_i32 s15, s43, s14
	s_mov_b32 m0, s15
	v_lshl_add_u64 v[142:143], v[132:133], 0, s[2:3]
	v_mfma_f32_16x16x32_bf16 v[66:69], v[188:191], v[180:183], v[66:69]
	global_load_lds_dwordx4 v[132:133], off
	s_add_i32 m0, m0, 0x1000
	v_mfma_f32_16x16x32_bf16 v[62:65], v[192:195], v[146:149], v[62:65]
	v_mfma_f32_16x16x32_bf16 v[58:61], v[192:195], v[152:155], v[58:61]
	v_mfma_f32_16x16x32_bf16 v[54:57], v[192:195], v[156:159], v[54:57]
	global_load_lds_dwordx4 v[142:143], off
	v_lshl_add_u64 v[142:143], v[142:143], 0, s[2:3]
	s_add_i32 m0, m0, 0x1000
	v_mfma_f32_16x16x32_bf16 v[50:53], v[192:195], v[162:165], v[50:53]
	v_mfma_f32_16x16x32_bf16 v[46:49], v[192:195], v[166:169], v[46:49]
	s_setprio 0
	s_nop 0
	v_mfma_f32_16x16x32_bf16 v[42:45], v[192:195], v[170:173], v[42:45]
	global_load_lds_dwordx4 v[142:143], off
	v_lshl_add_u64 v[142:143], v[142:143], 0, s[2:3]
	s_add_i32 m0, m0, 0x1000
	v_mfma_f32_16x16x32_bf16 v[38:41], v[192:195], v[176:179], v[38:41]
	v_mfma_f32_16x16x32_bf16 v[34:37], v[192:195], v[180:183], v[34:37]
	v_mfma_f32_16x16x32_bf16 v[30:33], v[196:199], v[146:149], v[30:33]
	global_load_lds_dwordx4 v[142:143], off
	s_add_i32 m0, m0, 0x1000
	v_lshl_add_u64 v[142:143], v[134:135], 0, s[2:3]
	v_mfma_f32_16x16x32_bf16 v[26:29], v[196:199], v[152:155], v[26:29]
	v_mfma_f32_16x16x32_bf16 v[22:25], v[196:199], v[156:159], v[22:25]
	v_mfma_f32_16x16x32_bf16 v[18:21], v[196:199], v[162:165], v[18:21]
	global_load_lds_dwordx4 v[134:135], off
	s_add_i32 m0, m0, 0x1000
	v_lshl_add_u64 v[132:133], v[132:133], 0, s[12:13]
	v_mfma_f32_16x16x32_bf16 v[14:17], v[196:199], v[166:169], v[14:17]
	v_mfma_f32_16x16x32_bf16 v[10:13], v[196:199], v[170:173], v[10:13]
	v_mfma_f32_16x16x32_bf16 v[6:9], v[196:199], v[176:179], v[6:9]
	global_load_lds_dwordx4 v[142:143], off
	v_lshl_add_u64 v[134:135], v[134:135], 0, s[4:5]
	v_mfma_f32_16x16x32_bf16 v[2:5], v[196:199], v[180:183], v[2:5]
	s_mov_b32 s14, s1
	s_nop 0
	s_add_i32 s1, s1, 0x6000
	s_cmp_eq_u32 s1, 0x12000
	s_cselect_b32 s1, 0, s1
	s_nop 0
	.p2align 3
	s_waitcnt vmcnt(6) lgkmcnt(0)
	s_barrier
;     ...
;   for (int kt = 0; kt < nk; kt++) {
;     if (kt + 1 < nk) asm volatile("s_waitcnt vmcnt(6)" ::: "memory");
;     else asm volatile("s_waitcnt vmcnt(0)" ::: "memory");
;     __builtin_amdgcn_s_barrier();
;     asm volatile("" ::: "memory");
;     if (kt + 2 < nk) G2_STAGE(kt + 2);
;     const char* cS = smem + (kt % 3) * 24576;
;     bf16x8 xa[8], wb[4];
; #pragma unroll
;     for (int f = 0; f < 8; f++) xa[f] = *(const bf16x8*)(cS + aoff + f * 1024);
; #pragma unroll
;     for (int f = 0; f < 4; f++) wb[f] = *(const bf16x8*)(cS + boff + f * 1024);
; #pragma unroll
;     for (int nf = 0; nf < 4; nf++)
; #pragma unroll
;       for (int mf = 0; mf < 8; mf++)
;         acc[nf][mf] = __builtin_amdgcn_mfma_f32_16x16x32_bf16(wb[nf], xa[mf], acc[nf][mf], 0, 0, 0);
	s_setprio 1
	v_add_u32_e32 v144, s1, v136
	v_mfma_f32_16x16x32_bf16 v[126:129], v[232:235], v[200:203], v[126:129]
	ds_read_b128 v[146:149], v144 offset:0
	v_mfma_f32_16x16x32_bf16 v[122:125], v[232:235], v[204:207], v[122:125]
	ds_read_b128 v[152:155], v144 offset:1024
	v_mfma_f32_16x16x32_bf16 v[118:121], v[232:235], v[208:211], v[118:121]
	ds_read_b128 v[156:159], v144 offset:2048
	v_mfma_f32_16x16x32_bf16 v[114:117], v[232:235], v[212:215], v[114:117]
	ds_read_b128 v[162:165], v144 offset:3072
	v_mfma_f32_16x16x32_bf16 v[110:113], v[232:235], v[216:219], v[110:113]
	ds_read_b128 v[166:169], v144 offset:4096
	v_mfma_f32_16x16x32_bf16 v[106:109], v[232:235], v[220:223], v[106:109]
	ds_read_b128 v[170:173], v144 offset:5120
	v_mfma_f32_16x16x32_bf16 v[102:105], v[232:235], v[224:227], v[102:105]
	ds_read_b128 v[176:179], v144 offset:6144
	v_mfma_f32_16x16x32_bf16 v[98:101], v[232:235], v[228:231], v[98:101]
	ds_read_b128 v[180:183], v144 offset:7168
	v_mfma_f32_16x16x32_bf16 v[94:97], v[236:239], v[200:203], v[94:97]
	v_add_u32_e64 v144, s1, v137
	v_mfma_f32_16x16x32_bf16 v[90:93], v[236:239], v[204:207], v[90:93]
	v_mfma_f32_16x16x32_bf16 v[86:89], v[236:239], v[208:211], v[86:89]
	ds_read_b128 v[184:187], v144 offset:16384
	v_mfma_f32_16x16x32_bf16 v[82:85], v[236:239], v[212:215], v[82:85]
	ds_read_b128 v[188:191], v144 offset:17408
	v_mfma_f32_16x16x32_bf16 v[78:81], v[236:239], v[216:219], v[78:81]
	ds_read_b128 v[192:195], v144 offset:18432
	v_mfma_f32_16x16x32_bf16 v[74:77], v[236:239], v[220:223], v[74:77]
	ds_read_b128 v[196:199], v144 offset:19456
	v_mfma_f32_16x16x32_bf16 v[70:73], v[236:239], v[224:227], v[70:73]
	v_mfma_f32_16x16x32_bf16 v[66:69], v[236:239], v[228:231], v[66:69]
	v_mfma_f32_16x16x32_bf16 v[62:65], v[240:243], v[200:203], v[62:65]
	v_mfma_f32_16x16x32_bf16 v[58:61], v[240:243], v[204:207], v[58:61]
	v_mfma_f32_16x16x32_bf16 v[54:57], v[240:243], v[208:211], v[54:57]
	v_mfma_f32_16x16x32_bf16 v[50:53], v[240:243], v[212:215], v[50:53]
	v_mfma_f32_16x16x32_bf16 v[46:49], v[240:243], v[216:219], v[46:49]
	s_setprio 0
	s_nop 0
	v_mfma_f32_16x16x32_bf16 v[42:45], v[240:243], v[220:223], v[42:45]
	v_mfma_f32_16x16x32_bf16 v[38:41], v[240:243], v[224:227], v[38:41]
	v_mfma_f32_16x16x32_bf16 v[34:37], v[240:243], v[228:231], v[34:37]
	v_mfma_f32_16x16x32_bf16 v[30:33], v[244:247], v[200:203], v[30:33]
	v_mfma_f32_16x16x32_bf16 v[26:29], v[244:247], v[204:207], v[26:29]
	v_mfma_f32_16x16x32_bf16 v[22:25], v[244:247], v[208:211], v[22:25]
	v_mfma_f32_16x16x32_bf16 v[18:21], v[244:247], v[212:215], v[18:21]
	v_mfma_f32_16x16x32_bf16 v[14:17], v[244:247], v[216:219], v[14:17]
	v_mfma_f32_16x16x32_bf16 v[10:13], v[244:247], v[220:223], v[10:13]
	v_mfma_f32_16x16x32_bf16 v[6:9], v[244:247], v[224:227], v[6:9]
	v_mfma_f32_16x16x32_bf16 v[2:5], v[244:247], v[228:231], v[2:5]
	s_mov_b32 s14, s1
	s_nop 0
	s_add_i32 s1, s1, 0x6000
	s_cmp_eq_u32 s1, 0x12000
	s_cselect_b32 s1, 0, s1
	s_nop 0
	.p2align 3
	s_waitcnt vmcnt(0) lgkmcnt(0)
	s_barrier
	s_setprio 1
	v_add_u32_e32 v144, s1, v136
	v_mfma_f32_16x16x32_bf16 v[126:129], v[184:187], v[146:149], v[126:129]
	ds_read_b128 v[200:203], v144 offset:0
	v_mfma_f32_16x16x32_bf16 v[122:125], v[184:187], v[152:155], v[122:125]
	ds_read_b128 v[204:207], v144 offset:1024
	v_mfma_f32_16x16x32_bf16 v[118:121], v[184:187], v[156:159], v[118:121]
	ds_read_b128 v[208:211], v144 offset:2048
	v_mfma_f32_16x16x32_bf16 v[114:117], v[184:187], v[162:165], v[114:117]
	ds_read_b128 v[212:215], v144 offset:3072
	v_mfma_f32_16x16x32_bf16 v[110:113], v[184:187], v[166:169], v[110:113]
	ds_read_b128 v[216:219], v144 offset:4096
	v_mfma_f32_16x16x32_bf16 v[106:109], v[184:187], v[170:173], v[106:109]
	ds_read_b128 v[220:223], v144 offset:5120
	v_mfma_f32_16x16x32_bf16 v[102:105], v[184:187], v[176:179], v[102:105]
	ds_read_b128 v[224:227], v144 offset:6144
	v_mfma_f32_16x16x32_bf16 v[98:101], v[184:187], v[180:183], v[98:101]
	ds_read_b128 v[228:231], v144 offset:7168
	v_mfma_f32_16x16x32_bf16 v[94:97], v[188:191], v[146:149], v[94:97]
	v_add_u32_e64 v144, s1, v137
	v_mfma_f32_16x16x32_bf16 v[90:93], v[188:191], v[152:155], v[90:93]
	v_mfma_f32_16x16x32_bf16 v[86:89], v[188:191], v[156:159], v[86:89]
	ds_read_b128 v[232:235], v144 offset:16384
	v_mfma_f32_16x16x32_bf16 v[82:85], v[188:191], v[162:165], v[82:85]
	ds_read_b128 v[236:239], v144 offset:17408
	v_mfma_f32_16x16x32_bf16 v[78:81], v[188:191], v[166:169], v[78:81]
	ds_read_b128 v[240:243], v144 offset:18432
	v_mfma_f32_16x16x32_bf16 v[74:77], v[188:191], v[170:173], v[74:77]
	ds_read_b128 v[244:247], v144 offset:19456
	v_mfma_f32_16x16x32_bf16 v[70:73], v[188:191], v[176:179], v[70:73]
	v_mfma_f32_16x16x32_bf16 v[66:69], v[188:191], v[180:183], v[66:69]
	v_mfma_f32_16x16x32_bf16 v[62:65], v[192:195], v[146:149], v[62:65]
	v_mfma_f32_16x16x32_bf16 v[58:61], v[192:195], v[152:155], v[58:61]
	v_mfma_f32_16x16x32_bf16 v[54:57], v[192:195], v[156:159], v[54:57]
	v_mfma_f32_16x16x32_bf16 v[50:53], v[192:195], v[162:165], v[50:53]
	v_mfma_f32_16x16x32_bf16 v[46:49], v[192:195], v[166:169], v[46:49]
	s_setprio 0
	s_nop 0
	v_mfma_f32_16x16x32_bf16 v[42:45], v[192:195], v[170:173], v[42:45]
	v_mfma_f32_16x16x32_bf16 v[38:41], v[192:195], v[176:179], v[38:41]
	v_mfma_f32_16x16x32_bf16 v[34:37], v[192:195], v[180:183], v[34:37]
	v_mfma_f32_16x16x32_bf16 v[30:33], v[196:199], v[146:149], v[30:33]
	v_mfma_f32_16x16x32_bf16 v[26:29], v[196:199], v[152:155], v[26:29]
	v_mfma_f32_16x16x32_bf16 v[22:25], v[196:199], v[156:159], v[22:25]
	v_mfma_f32_16x16x32_bf16 v[18:21], v[196:199], v[162:165], v[18:21]
	v_mfma_f32_16x16x32_bf16 v[14:17], v[196:199], v[166:169], v[14:17]
	v_mfma_f32_16x16x32_bf16 v[10:13], v[196:199], v[170:173], v[10:13]
	v_mfma_f32_16x16x32_bf16 v[6:9], v[196:199], v[176:179], v[6:9]
	v_mfma_f32_16x16x32_bf16 v[2:5], v[196:199], v[180:183], v[2:5]
	s_mov_b32 s14, s1
	s_nop 0
	s_add_i32 s1, s1, 0x6000
	s_cmp_eq_u32 s1, 0x12000
	s_cselect_b32 s1, 0, s1
	s_nop 0
	s_mov_b32 s4, 0x8000
	s_mov_b32 s5, 0
	s_mov_b32 s10, 0x10000
	s_mov_b32 s11, 0
	s_mov_b32 s41, 0x3fd744fd
	.p2align 3
	s_waitcnt lgkmcnt(0)
; DEVI float blo(unsigned u) { return __uint_as_float(u << 16); }
; DEVI float bhi(unsigned u) { return __uint_as_float(u & 0xffff0000u); }
;     ...
;     for (int nf = 0; nf < 4; nf++)
; #pragma unroll
;       for (int mf = 0; mf < 8; mf++)
;         acc[nf][mf] = __builtin_amdgcn_mfma_f32_16x16x32_bf16(wb[nf], xa[mf], acc[nf][mf], 0, 0, 0);
;     ...
;         if (EPI == EPI_RESID || EPI == EPI_RESID_ATOMIC) {
;           f32x4 x = a;
;           if (EPI == EPI_RESID || kpart == 0) {
;             const u32x2 xr = *(const u32x2*)((const u16*)(p.ws + WS_XB) + (size_t)row * 1024 + col);
;             x[0] += ALPHA * blo(xr[0]); x[1] += ALPHA * bhi(xr[0]); x[2] += ALPHA * blo(xr[1]); x[3] += ALPHA * bhi(xr[1]);
;           }
;           if (EPI == EPI_RESID) *(f32x4*)((float*)(p.ws + WS_XF) + (size_t)row * 1024 + col) = x;
;           else *(f32x4*)((float*)(p.ws + WS_SLAB) + ((size_t)kpart * 512 + (row - T_P)) * 1024 + col) = x;
	s_nop 0
	v_mfma_f32_16x16x32_bf16 v[126:129], v[232:235], v[200:203], v[126:129]
	v_mfma_f32_16x16x32_bf16 v[122:125], v[232:235], v[204:207], v[122:125]
	v_mfma_f32_16x16x32_bf16 v[118:121], v[232:235], v[208:211], v[118:121]
	v_mfma_f32_16x16x32_bf16 v[114:117], v[232:235], v[212:215], v[114:117]
	v_mfma_f32_16x16x32_bf16 v[110:113], v[232:235], v[216:219], v[110:113]
	v_mfma_f32_16x16x32_bf16 v[106:109], v[232:235], v[220:223], v[106:109]
	v_mfma_f32_16x16x32_bf16 v[102:105], v[232:235], v[224:227], v[102:105]
	v_mfma_f32_16x16x32_bf16 v[98:101], v[232:235], v[228:231], v[98:101]
	v_mfma_f32_16x16x32_bf16 v[94:97], v[236:239], v[200:203], v[94:97]
	v_mfma_f32_16x16x32_bf16 v[90:93], v[236:239], v[204:207], v[90:93]
	v_mfma_f32_16x16x32_bf16 v[86:89], v[236:239], v[208:211], v[86:89]
	v_mfma_f32_16x16x32_bf16 v[82:85], v[236:239], v[212:215], v[82:85]
	v_mfma_f32_16x16x32_bf16 v[78:81], v[236:239], v[216:219], v[78:81]
	v_mfma_f32_16x16x32_bf16 v[74:77], v[236:239], v[220:223], v[74:77]
	v_mfma_f32_16x16x32_bf16 v[70:73], v[236:239], v[224:227], v[70:73]
	v_mfma_f32_16x16x32_bf16 v[66:69], v[236:239], v[228:231], v[66:69]
	v_mfma_f32_16x16x32_bf16 v[62:65], v[240:243], v[200:203], v[62:65]
	v_mfma_f32_16x16x32_bf16 v[58:61], v[240:243], v[204:207], v[58:61]
	v_mfma_f32_16x16x32_bf16 v[54:57], v[240:243], v[208:211], v[54:57]
	v_mfma_f32_16x16x32_bf16 v[50:53], v[240:243], v[212:215], v[50:53]
	v_mfma_f32_16x16x32_bf16 v[46:49], v[240:243], v[216:219], v[46:49]
	v_mfma_f32_16x16x32_bf16 v[42:45], v[240:243], v[220:223], v[42:45]
	v_mfma_f32_16x16x32_bf16 v[38:41], v[240:243], v[224:227], v[38:41]
	v_mfma_f32_16x16x32_bf16 v[34:37], v[240:243], v[228:231], v[34:37]
	v_mfma_f32_16x16x32_bf16 v[30:33], v[244:247], v[200:203], v[30:33]
	v_mfma_f32_16x16x32_bf16 v[26:29], v[244:247], v[204:207], v[26:29]
	v_mfma_f32_16x16x32_bf16 v[22:25], v[244:247], v[208:211], v[22:25]
	v_mfma_f32_16x16x32_bf16 v[18:21], v[244:247], v[212:215], v[18:21]
	v_mfma_f32_16x16x32_bf16 v[14:17], v[244:247], v[216:219], v[14:17]
	v_mfma_f32_16x16x32_bf16 v[10:13], v[244:247], v[220:223], v[10:13]
	v_mfma_f32_16x16x32_bf16 v[6:9], v[244:247], v[224:227], v[6:9]
	v_mfma_f32_16x16x32_bf16 v[2:5], v[244:247], v[228:231], v[2:5]
	s_mov_b32 m0, s40
	s_cmp_eq_u32 s98, 0
	s_cbranch_scc1 .Lta4_first
	s_nop 7
	global_store_dwordx4 v[140:141], v[126:129], off offset:0
	global_store_dwordx4 v[140:141], v[94:97], off offset:64
	global_store_dwordx4 v[140:141], v[62:65], off offset:128
	global_store_dwordx4 v[140:141], v[30:33], off offset:192
	v_lshl_add_u64 v[140:141], v[140:141], 0, s[10:11]
	global_store_dwordx4 v[140:141], v[122:125], off offset:0
	global_store_dwordx4 v[140:141], v[90:93], off offset:64
	global_store_dwordx4 v[140:141], v[58:61], off offset:128
	global_store_dwordx4 v[140:141], v[26:29], off offset:192
	v_lshl_add_u64 v[140:141], v[140:141], 0, s[10:11]
	global_store_dwordx4 v[140:141], v[118:121], off offset:0
	global_store_dwordx4 v[140:141], v[86:89], off offset:64
	global_store_dwordx4 v[140:141], v[54:57], off offset:128
	global_store_dwordx4 v[140:141], v[22:25], off offset:192
	v_lshl_add_u64 v[140:141], v[140:141], 0, s[10:11]
	global_store_dwordx4 v[140:141], v[114:117], off offset:0
	global_store_dwordx4 v[140:141], v[82:85], off offset:64
	global_store_dwordx4 v[140:141], v[50:53], off offset:128
	global_store_dwordx4 v[140:141], v[18:21], off offset:192
	v_lshl_add_u64 v[140:141], v[140:141], 0, s[10:11]
	global_store_dwordx4 v[140:141], v[110:113], off offset:0
	global_store_dwordx4 v[140:141], v[78:81], off offset:64
	global_store_dwordx4 v[140:141], v[46:49], off offset:128
	global_store_dwordx4 v[140:141], v[14:17], off offset:192
	v_lshl_add_u64 v[140:141], v[140:141], 0, s[10:11]
	global_store_dwordx4 v[140:141], v[106:109], off offset:0
	global_store_dwordx4 v[140:141], v[74:77], off offset:64
	global_store_dwordx4 v[140:141], v[42:45], off offset:128
	global_store_dwordx4 v[140:141], v[10:13], off offset:192
	v_lshl_add_u64 v[140:141], v[140:141], 0, s[10:11]
	global_store_dwordx4 v[140:141], v[102:105], off offset:0
	global_store_dwordx4 v[140:141], v[70:73], off offset:64
	global_store_dwordx4 v[140:141], v[38:41], off offset:128
	global_store_dwordx4 v[140:141], v[6:9], off offset:192
	v_lshl_add_u64 v[140:141], v[140:141], 0, s[10:11]
	global_store_dwordx4 v[140:141], v[98:101], off offset:0
	global_store_dwordx4 v[140:141], v[66:69], off offset:64
	global_store_dwordx4 v[140:141], v[34:37], off offset:128
	global_store_dwordx4 v[140:141], v[2:5], off offset:192
	v_readlane_b32 s0, v250, 7
	s_cmpk_lg_u32 s0, 0x200
	s_cbranch_scc1 .Lta4_ar1
	s_mov_b32 s0, 1
	v_writelane_b32 v255, s0, 41
	v_readlane_b32 s1, v250, 0
	s_lshr_b32 s14, s1, 3
	s_and_b32 s1, s1, 7
	s_lshl_b32 s1, s1, 6
	s_add_i32 s1, s1, s14
	s_sub_i32 s39, s1, 0x200

;     ...
;   for (int kt = 0; kt < nk; kt++) {
;     if (kt + 1 < nk) asm volatile("s_waitcnt vmcnt(6)" ::: "memory");
;     else asm volatile("s_waitcnt vmcnt(0)" ::: "memory");
;     __builtin_amdgcn_s_barrier();
;     asm volatile("" ::: "memory");
;     if (kt + 2 < nk) G2_STAGE(kt + 2);
;     const char* cS = smem + (kt % 3) * 24576;
;     bf16x8 xa[8], wb[4];
; #pragma unroll
;     for (int f = 0; f < 8; f++) xa[f] = *(const bf16x8*)(cS + aoff + f * 1024);
; #pragma unroll
;     for (int f = 0; f < 4; f++) wb[f] = *(const bf16x8*)(cS + boff + f * 1024);
; #pragma unroll
;     for (int nf = 0; nf < 4; nf++)
; #pragma unroll
;       for (int mf = 0; mf < 8; mf++)
;         acc[nf][mf] = __builtin_amdgcn_mfma_f32_16x16x32_bf16(wb[nf], xa[mf], acc[nf][mf], 0, 0, 0);
.Lt4_loop:
	.p2align 3
	s_waitcnt vmcnt(6) lgkmcnt(0)
	s_barrier
	s_setprio 1
	v_add_u32_e32 v144, s41, v136
	v_mfma_f32_16x16x32_bf16 v[126:129], v[184:187], v[146:149], v[126:129]
	ds_read_b128 v[200:203], v144 offset:0
	v_mfma_f32_16x16x32_bf16 v[122:125], v[184:187], v[152:155], v[122:125]
	ds_read_b128 v[204:207], v144 offset:1024
	v_mfma_f32_16x16x32_bf16 v[118:121], v[184:187], v[156:159], v[118:121]
	ds_read_b128 v[208:211], v144 offset:2048
	v_mfma_f32_16x16x32_bf16 v[114:117], v[184:187], v[162:165], v[114:117]
	ds_read_b128 v[212:215], v144 offset:3072
	v_mfma_f32_16x16x32_bf16 v[110:113], v[184:187], v[166:169], v[110:113]
	ds_read_b128 v[216:219], v144 offset:4096
	v_mfma_f32_16x16x32_bf16 v[106:109], v[184:187], v[170:173], v[106:109]
	ds_read_b128 v[220:223], v144 offset:5120
	v_mfma_f32_16x16x32_bf16 v[102:105], v[184:187], v[176:179], v[102:105]
	ds_read_b128 v[224:227], v144 offset:6144
	v_mfma_f32_16x16x32_bf16 v[98:101], v[184:187], v[180:183], v[98:101]
	ds_read_b128 v[228:231], v144 offset:7168
	v_mfma_f32_16x16x32_bf16 v[94:97], v[188:191], v[146:149], v[94:97]
	v_add_u32_e64 v144, s41, v137
	v_mfma_f32_16x16x32_bf16 v[90:93], v[188:191], v[152:155], v[90:93]
	v_mfma_f32_16x16x32_bf16 v[86:89], v[188:191], v[156:159], v[86:89]
	ds_read_b128 v[232:235], v144 offset:16384
	v_mfma_f32_16x16x32_bf16 v[82:85], v[188:191], v[162:165], v[82:85]
	ds_read_b128 v[236:239], v144 offset:17408
	v_mfma_f32_16x16x32_bf16 v[78:81], v[188:191], v[166:169], v[78:81]
	ds_read_b128 v[240:243], v144 offset:18432
	v_mfma_f32_16x16x32_bf16 v[74:77], v[188:191], v[170:173], v[74:77]
	ds_read_b128 v[244:247], v144 offset:19456
	v_mfma_f32_16x16x32_bf16 v[70:73], v[188:191], v[176:179], v[70:73]
	s_add_i32 s43, s47, s42
	s_mov_b32 m0, s43
	v_lshl_add_u64 v[142:143], v[132:133], 0, s[2:3]
	v_mfma_f32_16x16x32_bf16 v[66:69], v[188:191], v[180:183], v[66:69]
	global_load_lds_dwordx4 v[132:133], off
	s_add_i32 m0, m0, 0x1000
	v_mfma_f32_16x16x32_bf16 v[62:65], v[192:195], v[146:149], v[62:65]
	v_mfma_f32_16x16x32_bf16 v[58:61], v[192:195], v[152:155], v[58:61]
	v_mfma_f32_16x16x32_bf16 v[54:57], v[192:195], v[156:159], v[54:57]
	global_load_lds_dwordx4 v[142:143], off
	v_lshl_add_u64 v[142:143], v[142:143], 0, s[2:3]
	s_add_i32 m0, m0, 0x1000
	v_mfma_f32_16x16x32_bf16 v[50:53], v[192:195], v[162:165], v[50:53]
	v_mfma_f32_16x16x32_bf16 v[46:49], v[192:195], v[166:169], v[46:49]
	s_setprio 0
	s_nop 0
	v_mfma_f32_16x16x32_bf16 v[42:45], v[192:195], v[170:173], v[42:45]
	global_load_lds_dwordx4 v[142:143], off
	v_lshl_add_u64 v[142:143], v[142:143], 0, s[2:3]
	s_add_i32 m0, m0, 0x1000
	v_mfma_f32_16x16x32_bf16 v[38:41], v[192:195], v[176:179], v[38:41]
	v_mfma_f32_16x16x32_bf16 v[34:37], v[192:195], v[180:183], v[34:37]
	v_mfma_f32_16x16x32_bf16 v[30:33], v[196:199], v[146:149], v[30:33]
	global_load_lds_dwordx4 v[142:143], off
	s_add_i32 m0, m0, 0x1000
	v_lshl_add_u64 v[142:143], v[134:135], 0, s[2:3]
	v_mfma_f32_16x16x32_bf16 v[26:29], v[196:199], v[152:155], v[26:29]
	v_mfma_f32_16x16x32_bf16 v[22:25], v[196:199], v[156:159], v[22:25]
	v_mfma_f32_16x16x32_bf16 v[18:21], v[196:199], v[162:165], v[18:21]
	global_load_lds_dwordx4 v[134:135], off
	s_add_i32 m0, m0, 0x1000
	v_lshl_add_u64 v[132:133], v[132:133], 0, s[12:13]
	v_mfma_f32_16x16x32_bf16 v[14:17], v[196:199], v[166:169], v[14:17]
	v_mfma_f32_16x16x32_bf16 v[10:13], v[196:199], v[170:173], v[10:13]
	v_mfma_f32_16x16x32_bf16 v[6:9], v[196:199], v[176:179], v[6:9]
	global_load_lds_dwordx4 v[142:143], off
	v_lshl_add_u64 v[134:135], v[134:135], 0, s[4:5]
	v_mfma_f32_16x16x32_bf16 v[2:5], v[196:199], v[180:183], v[2:5]
	s_mov_b32 s42, s41
	s_nop 0
	s_add_i32 s41, s41, 0x6000
	s_cmp_eq_u32 s41, 0x12000
	s_cselect_b32 s41, 0, s41
	s_nop 0
	.p2align 3
	s_waitcnt vmcnt(6) lgkmcnt(0)
	s_barrier
	s_setprio 1
	v_add_u32_e32 v144, s41, v136
	v_mfma_f32_16x16x32_bf16 v[126:129], v[232:235], v[200:203], v[126:129]
	ds_read_b128 v[146:149], v144 offset:0
	v_mfma_f32_16x16x32_bf16 v[122:125], v[232:235], v[204:207], v[122:125]
	ds_read_b128 v[152:155], v144 offset:1024
	v_mfma_f32_16x16x32_bf16 v[118:121], v[232:235], v[208:211], v[118:121]
	ds_read_b128 v[156:159], v144 offset:2048
	v_mfma_f32_16x16x32_bf16 v[114:117], v[232:235], v[212:215], v[114:117]
	ds_read_b128 v[162:165], v144 offset:3072
	v_mfma_f32_16x16x32_bf16 v[110:113], v[232:235], v[216:219], v[110:113]
	ds_read_b128 v[166:169], v144 offset:4096
	v_mfma_f32_16x16x32_bf16 v[106:109], v[232:235], v[220:223], v[106:109]
	ds_read_b128 v[170:173], v144 offset:5120
	v_mfma_f32_16x16x32_bf16 v[102:105], v[232:235], v[224:227], v[102:105]
	ds_read_b128 v[176:179], v144 offset:6144
	v_mfma_f32_16x16x32_bf16 v[98:101], v[232:235], v[228:231], v[98:101]
	ds_read_b128 v[180:183], v144 offset:7168
	v_mfma_f32_16x16x32_bf16 v[94:97], v[236:239], v[200:203], v[94:97]
	v_add_u32_e64 v144, s41, v137
	v_mfma_f32_16x16x32_bf16 v[90:93], v[236:239], v[204:207], v[90:93]
	v_mfma_f32_16x16x32_bf16 v[86:89], v[236:239], v[208:211], v[86:89]
	ds_read_b128 v[184:187], v144 offset:16384
	v_mfma_f32_16x16x32_bf16 v[82:85], v[236:239], v[212:215], v[82:85]
	ds_read_b128 v[188:191], v144 offset:17408
	v_mfma_f32_16x16x32_bf16 v[78:81], v[236:239], v[216:219], v[78:81]
	ds_read_b128 v[192:195], v144 offset:18432
	v_mfma_f32_16x16x32_bf16 v[74:77], v[236:239], v[220:223], v[74:77]
	ds_read_b128 v[196:199], v144 offset:19456
	v_mfma_f32_16x16x32_bf16 v[70:73], v[236:239], v[224:227], v[70:73]
	s_add_i32 s43, s47, s42
	s_mov_b32 m0, s43
	v_lshl_add_u64 v[142:143], v[132:133], 0, s[2:3]
	v_mfma_f32_16x16x32_bf16 v[66:69], v[236:239], v[228:231], v[66:69]
;     ...
;   for (int kt = 0; kt < nk; kt++) {
;     if (kt + 1 < nk) asm volatile("s_waitcnt vmcnt(6)" ::: "memory");
;     else asm volatile("s_waitcnt vmcnt(0)" ::: "memory");
;     __builtin_amdgcn_s_barrier();
;     asm volatile("" ::: "memory");
;     if (kt + 2 < nk) G2_STAGE(kt + 2);
;     const char* cS = smem + (kt % 3) * 24576;
;     bf16x8 xa[8], wb[4];
; #pragma unroll
;     for (int f = 0; f < 8; f++) xa[f] = *(const bf16x8*)(cS + aoff + f * 1024);
; #pragma unroll
;     for (int f = 0; f < 4; f++) wb[f] = *(const bf16x8*)(cS + boff + f * 1024);
; #pragma unroll
;     for (int nf = 0; nf < 4; nf++)
; #pragma unroll
;       for (int mf = 0; mf < 8; mf++)
;         acc[nf][mf] = __builtin_amdgcn_mfma_f32_16x16x32_bf16(wb[nf], xa[mf], acc[nf][mf], 0, 0, 0);
	global_load_lds_dwordx4 v[132:133], off
	s_add_i32 m0, m0, 0x1000
	v_mfma_f32_16x16x32_bf16 v[62:65], v[240:243], v[200:203], v[62:65]
	v_mfma_f32_16x16x32_bf16 v[58:61], v[240:243], v[204:207], v[58:61]
	v_mfma_f32_16x16x32_bf16 v[54:57], v[240:243], v[208:211], v[54:57]
	global_load_lds_dwordx4 v[142:143], off
	v_lshl_add_u64 v[142:143], v[142:143], 0, s[2:3]
	s_add_i32 m0, m0, 0x1000
	v_mfma_f32_16x16x32_bf16 v[50:53], v[240:243], v[212:215], v[50:53]
	v_mfma_f32_16x16x32_bf16 v[46:49], v[240:243], v[216:219], v[46:49]
	s_setprio 0
	s_nop 0
	v_mfma_f32_16x16x32_bf16 v[42:45], v[240:243], v[220:223], v[42:45]
	global_load_lds_dwordx4 v[142:143], off
	v_lshl_add_u64 v[142:143], v[142:143], 0, s[2:3]
	s_add_i32 m0, m0, 0x1000
	v_mfma_f32_16x16x32_bf16 v[38:41], v[240:243], v[224:227], v[38:41]
	v_mfma_f32_16x16x32_bf16 v[34:37], v[240:243], v[228:231], v[34:37]
	v_mfma_f32_16x16x32_bf16 v[30:33], v[244:247], v[200:203], v[30:33]
	global_load_lds_dwordx4 v[142:143], off
	s_add_i32 m0, m0, 0x1000
	v_lshl_add_u64 v[142:143], v[134:135], 0, s[2:3]
	v_mfma_f32_16x16x32_bf16 v[26:29], v[244:247], v[204:207], v[26:29]
	v_mfma_f32_16x16x32_bf16 v[22:25], v[244:247], v[208:211], v[22:25]
	v_mfma_f32_16x16x32_bf16 v[18:21], v[244:247], v[212:215], v[18:21]
	global_load_lds_dwordx4 v[134:135], off
	s_add_i32 m0, m0, 0x1000
	v_lshl_add_u64 v[132:133], v[132:133], 0, s[12:13]
	v_mfma_f32_16x16x32_bf16 v[14:17], v[244:247], v[216:219], v[14:17]
	v_mfma_f32_16x16x32_bf16 v[10:13], v[244:247], v[220:223], v[10:13]
	v_mfma_f32_16x16x32_bf16 v[6:9], v[244:247], v[224:227], v[6:9]
	global_load_lds_dwordx4 v[142:143], off
	v_lshl_add_u64 v[134:135], v[134:135], 0, s[4:5]
	v_mfma_f32_16x16x32_bf16 v[2:5], v[244:247], v[228:231], v[2:5]
	s_mov_b32 s42, s41
	s_nop 0
	s_add_i32 s41, s41, 0x6000
	s_cmp_eq_u32 s41, 0x12000
	s_cselect_b32 s41, 0, s41
	s_nop 0
	s_sub_i32 s40, s40, 1
	s_cmp_lg_u32 s40, 0
	s_cbranch_scc1 .Lt4_loop
	.p2align 3
	s_waitcnt vmcnt(6) lgkmcnt(0)
	s_barrier
	s_setprio 1
	v_add_u32_e32 v144, s41, v136
	v_mfma_f32_16x16x32_bf16 v[126:129], v[184:187], v[146:149], v[126:129]
	ds_read_b128 v[200:203], v144 offset:0
	v_mfma_f32_16x16x32_bf16 v[122:125], v[184:187], v[152:155], v[122:125]
	ds_read_b128 v[204:207], v144 offset:1024
	v_mfma_f32_16x16x32_bf16 v[118:121], v[184:187], v[156:159], v[118:121]
	ds_read_b128 v[208:211], v144 offset:2048
	v_mfma_f32_16x16x32_bf16 v[114:117], v[184:187], v[162:165], v[114:117]
	ds_read_b128 v[212:215], v144 offset:3072
	v_mfma_f32_16x16x32_bf16 v[110:113], v[184:187], v[166:169], v[110:113]
	ds_read_b128 v[216:219], v144 offset:4096
	v_mfma_f32_16x16x32_bf16 v[106:109], v[184:187], v[170:173], v[106:109]
	ds_read_b128 v[220:223], v144 offset:5120
	v_mfma_f32_16x16x32_bf16 v[102:105], v[184:187], v[176:179], v[102:105]
	ds_read_b128 v[224:227], v144 offset:6144
	v_mfma_f32_16x16x32_bf16 v[98:101], v[184:187], v[180:183], v[98:101]
	ds_read_b128 v[228:231], v144 offset:7168
	v_mfma_f32_16x16x32_bf16 v[94:97], v[188:191], v[146:149], v[94:97]
	v_add_u32_e64 v144, s41, v137
	v_mfma_f32_16x16x32_bf16 v[90:93], v[188:191], v[152:155], v[90:93]
	v_mfma_f32_16x16x32_bf16 v[86:89], v[188:191], v[156:159], v[86:89]
	ds_read_b128 v[232:235], v144 offset:16384
	v_mfma_f32_16x16x32_bf16 v[82:85], v[188:191], v[162:165], v[82:85]
	ds_read_b128 v[236:239], v144 offset:17408
	v_mfma_f32_16x16x32_bf16 v[78:81], v[188:191], v[166:169], v[78:81]
	ds_read_b128 v[240:243], v144 offset:18432
	v_mfma_f32_16x16x32_bf16 v[74:77], v[188:191], v[170:173], v[74:77]
	ds_read_b128 v[244:247], v144 offset:19456
	v_mfma_f32_16x16x32_bf16 v[70:73], v[188:191], v[176:179], v[70:73]
	s_add_i32 s43, s47, s42
	s_mov_b32 m0, s43
	v_lshl_add_u64 v[142:143], v[132:133], 0, s[2:3]
	v_mfma_f32_16x16x32_bf16 v[66:69], v[188:191], v[180:183], v[66:69]
	global_load_lds_dwordx4 v[132:133], off
	s_add_i32 m0, m0, 0x1000
	v_mfma_f32_16x16x32_bf16 v[62:65], v[192:195], v[146:149], v[62:65]
	v_mfma_f32_16x16x32_bf16 v[58:61], v[192:195], v[152:155], v[58:61]
	v_mfma_f32_16x16x32_bf16 v[54:57], v[192:195], v[156:159], v[54:57]
	global_load_lds_dwordx4 v[142:143], off
	v_lshl_add_u64 v[142:143], v[142:143], 0, s[2:3]
	s_add_i32 m0, m0, 0x1000
	v_mfma_f32_16x16x32_bf16 v[50:53], v[192:195], v[162:165], v[50:53]
	v_mfma_f32_16x16x32_bf16 v[46:49], v[192:195], v[166:169], v[46:49]
	s_setprio 0
	s_nop 0
	v_mfma_f32_16x16x32_bf16 v[42:45], v[192:195], v[170:173], v[42:45]
	global_load_lds_dwordx4 v[142:143], off
	v_lshl_add_u64 v[142:143], v[142:143], 0, s[2:3]
	s_add_i32 m0, m0, 0x1000
	v_mfma_f32_16x16x32_bf16 v[38:41], v[192:195], v[176:179], v[38:41]
	v_mfma_f32_16x16x32_bf16 v[34:37], v[192:195], v[180:183], v[34:37]
	v_mfma_f32_16x16x32_bf16 v[30:33], v[196:199], v[146:149], v[30:33]
	global_load_lds_dwordx4 v[142:143], off
	s_add_i32 m0, m0, 0x1000
	v_lshl_add_u64 v[142:143], v[134:135], 0, s[2:3]
	v_mfma_f32_16x16x32_bf16 v[26:29], v[196:199], v[152:155], v[26:29]
	v_mfma_f32_16x16x32_bf16 v[22:25], v[196:199], v[156:159], v[22:25]
	v_mfma_f32_16x16x32_bf16 v[18:21], v[196:199], v[162:165], v[18:21]
	global_load_lds_dwordx4 v[134:135], off
	s_add_i32 m0, m0, 0x1000
	v_lshl_add_u64 v[132:133], v[132:133], 0, s[12:13]
	v_mfma_f32_16x16x32_bf16 v[14:17], v[196:199], v[166:169], v[14:17]
	v_mfma_f32_16x16x32_bf16 v[10:13], v[196:199], v[170:173], v[10:13]
	v_mfma_f32_16x16x32_bf16 v[6:9], v[196:199], v[176:179], v[6:9]
	global_load_lds_dwordx4 v[142:143], off
	v_lshl_add_u64 v[134:135], v[134:135], 0, s[4:5]
	v_mfma_f32_16x16x32_bf16 v[2:5], v[196:199], v[180:183], v[2:5]
	s_mov_b32 s42, s41
	s_nop 0
	s_add_i32 s41, s41, 0x6000
	s_cmp_eq_u32 s41, 0x12000
	s_cselect_b32 s41, 0, s41
	s_nop 0
	.p2align 3
	s_waitcnt vmcnt(6) lgkmcnt(0)
	s_barrier
;     ...
;   for (int kt = 0; kt < nk; kt++) {
;     if (kt + 1 < nk) asm volatile("s_waitcnt vmcnt(6)" ::: "memory");
;     else asm volatile("s_waitcnt vmcnt(0)" ::: "memory");
;     __builtin_amdgcn_s_barrier();
;     asm volatile("" ::: "memory");
;     if (kt + 2 < nk) G2_STAGE(kt + 2);
;     const char* cS = smem + (kt % 3) * 24576;
;     bf16x8 xa[8], wb[4];
; #pragma unroll
;     for (int f = 0; f < 8; f++) xa[f] = *(const bf16x8*)(cS + aoff + f * 1024);
; #pragma unroll
;     for (int f = 0; f < 4; f++) wb[f] = *(const bf16x8*)(cS + boff + f * 1024);
; #pragma unroll
;     for (int nf = 0; nf < 4; nf++)
; #pragma unroll
;       for (int mf = 0; mf < 8; mf++)
;         acc[nf][mf] = __builtin_amdgcn_mfma_f32_16x16x32_bf16(wb[nf], xa[mf], acc[nf][mf], 0, 0, 0);
	s_setprio 1
	v_add_u32_e32 v144, s41, v136
	v_mfma_f32_16x16x32_bf16 v[126:129], v[232:235], v[200:203], v[126:129]
	ds_read_b128 v[146:149], v144 offset:0
	v_mfma_f32_16x16x32_bf16 v[122:125], v[232:235], v[204:207], v[122:125]
	ds_read_b128 v[152:155], v144 offset:1024
	v_mfma_f32_16x16x32_bf16 v[118:121], v[232:235], v[208:211], v[118:121]
	ds_read_b128 v[156:159], v144 offset:2048
	v_mfma_f32_16x16x32_bf16 v[114:117], v[232:235], v[212:215], v[114:117]
	ds_read_b128 v[162:165], v144 offset:3072
	v_mfma_f32_16x16x32_bf16 v[110:113], v[232:235], v[216:219], v[110:113]
	ds_read_b128 v[166:169], v144 offset:4096
	v_mfma_f32_16x16x32_bf16 v[106:109], v[232:235], v[220:223], v[106:109]
	ds_read_b128 v[170:173], v144 offset:5120
	v_mfma_f32_16x16x32_bf16 v[102:105], v[232:235], v[224:227], v[102:105]
	ds_read_b128 v[176:179], v144 offset:6144
	v_mfma_f32_16x16x32_bf16 v[98:101], v[232:235], v[228:231], v[98:101]
	ds_read_b128 v[180:183], v144 offset:7168
	v_mfma_f32_16x16x32_bf16 v[94:97], v[236:239], v[200:203], v[94:97]
	v_add_u32_e64 v144, s41, v137
	v_mfma_f32_16x16x32_bf16 v[90:93], v[236:239], v[204:207], v[90:93]
	v_mfma_f32_16x16x32_bf16 v[86:89], v[236:239], v[208:211], v[86:89]
	ds_read_b128 v[184:187], v144 offset:16384
	v_mfma_f32_16x16x32_bf16 v[82:85], v[236:239], v[212:215], v[82:85]
	ds_read_b128 v[188:191], v144 offset:17408
	v_mfma_f32_16x16x32_bf16 v[78:81], v[236:239], v[216:219], v[78:81]
	ds_read_b128 v[192:195], v144 offset:18432
	v_mfma_f32_16x16x32_bf16 v[74:77], v[236:239], v[220:223], v[74:77]
	ds_read_b128 v[196:199], v144 offset:19456
	v_mfma_f32_16x16x32_bf16 v[70:73], v[236:239], v[224:227], v[70:73]
	v_mfma_f32_16x16x32_bf16 v[66:69], v[236:239], v[228:231], v[66:69]
	v_mfma_f32_16x16x32_bf16 v[62:65], v[240:243], v[200:203], v[62:65]
	v_mfma_f32_16x16x32_bf16 v[58:61], v[240:243], v[204:207], v[58:61]
	v_mfma_f32_16x16x32_bf16 v[54:57], v[240:243], v[208:211], v[54:57]
	v_mfma_f32_16x16x32_bf16 v[50:53], v[240:243], v[212:215], v[50:53]
	v_mfma_f32_16x16x32_bf16 v[46:49], v[240:243], v[216:219], v[46:49]
	s_setprio 0
	s_nop 0
	v_mfma_f32_16x16x32_bf16 v[42:45], v[240:243], v[220:223], v[42:45]
	v_mfma_f32_16x16x32_bf16 v[38:41], v[240:243], v[224:227], v[38:41]
	v_mfma_f32_16x16x32_bf16 v[34:37], v[240:243], v[228:231], v[34:37]
	v_mfma_f32_16x16x32_bf16 v[30:33], v[244:247], v[200:203], v[30:33]
	v_mfma_f32_16x16x32_bf16 v[26:29], v[244:247], v[204:207], v[26:29]
	v_mfma_f32_16x16x32_bf16 v[22:25], v[244:247], v[208:211], v[22:25]
	v_mfma_f32_16x16x32_bf16 v[18:21], v[244:247], v[212:215], v[18:21]
	v_mfma_f32_16x16x32_bf16 v[14:17], v[244:247], v[216:219], v[14:17]
	v_mfma_f32_16x16x32_bf16 v[10:13], v[244:247], v[220:223], v[10:13]
	v_mfma_f32_16x16x32_bf16 v[6:9], v[244:247], v[224:227], v[6:9]
	v_mfma_f32_16x16x32_bf16 v[2:5], v[244:247], v[228:231], v[2:5]
	s_mov_b32 s42, s41
	s_nop 0
	s_add_i32 s41, s41, 0x6000
	s_cmp_eq_u32 s41, 0x12000
	s_cselect_b32 s41, 0, s41
	s_nop 0
	.p2align 3
	s_waitcnt vmcnt(0) lgkmcnt(0)
	s_barrier
	s_setprio 1
	v_add_u32_e32 v144, s41, v136
	v_mfma_f32_16x16x32_bf16 v[126:129], v[184:187], v[146:149], v[126:129]
	ds_read_b128 v[200:203], v144 offset:0
	v_mfma_f32_16x16x32_bf16 v[122:125], v[184:187], v[152:155], v[122:125]
	ds_read_b128 v[204:207], v144 offset:1024
	v_mfma_f32_16x16x32_bf16 v[118:121], v[184:187], v[156:159], v[118:121]
	ds_read_b128 v[208:211], v144 offset:2048
	v_mfma_f32_16x16x32_bf16 v[114:117], v[184:187], v[162:165], v[114:117]
	ds_read_b128 v[212:215], v144 offset:3072
	v_mfma_f32_16x16x32_bf16 v[110:113], v[184:187], v[166:169], v[110:113]
	ds_read_b128 v[216:219], v144 offset:4096
	v_mfma_f32_16x16x32_bf16 v[106:109], v[184:187], v[170:173], v[106:109]
	ds_read_b128 v[220:223], v144 offset:5120
	v_mfma_f32_16x16x32_bf16 v[102:105], v[184:187], v[176:179], v[102:105]
	ds_read_b128 v[224:227], v144 offset:6144
	v_mfma_f32_16x16x32_bf16 v[98:101], v[184:187], v[180:183], v[98:101]
	ds_read_b128 v[228:231], v144 offset:7168
	v_mfma_f32_16x16x32_bf16 v[94:97], v[188:191], v[146:149], v[94:97]
	v_add_u32_e64 v144, s41, v137
	v_mfma_f32_16x16x32_bf16 v[90:93], v[188:191], v[152:155], v[90:93]
	v_mfma_f32_16x16x32_bf16 v[86:89], v[188:191], v[156:159], v[86:89]
	ds_read_b128 v[232:235], v144 offset:16384
	v_mfma_f32_16x16x32_bf16 v[82:85], v[188:191], v[162:165], v[82:85]
	ds_read_b128 v[236:239], v144 offset:17408
	v_mfma_f32_16x16x32_bf16 v[78:81], v[188:191], v[166:169], v[78:81]
	ds_read_b128 v[240:243], v144 offset:18432
	v_mfma_f32_16x16x32_bf16 v[74:77], v[188:191], v[170:173], v[74:77]
	ds_read_b128 v[244:247], v144 offset:19456
	v_mfma_f32_16x16x32_bf16 v[70:73], v[188:191], v[176:179], v[70:73]
	v_mfma_f32_16x16x32_bf16 v[66:69], v[188:191], v[180:183], v[66:69]
	v_mfma_f32_16x16x32_bf16 v[62:65], v[192:195], v[146:149], v[62:65]
	v_mfma_f32_16x16x32_bf16 v[58:61], v[192:195], v[152:155], v[58:61]
	v_mfma_f32_16x16x32_bf16 v[54:57], v[192:195], v[156:159], v[54:57]
	v_mfma_f32_16x16x32_bf16 v[50:53], v[192:195], v[162:165], v[50:53]
	v_mfma_f32_16x16x32_bf16 v[46:49], v[192:195], v[166:169], v[46:49]
	s_setprio 0
	s_nop 0
	v_mfma_f32_16x16x32_bf16 v[42:45], v[192:195], v[170:173], v[42:45]
	v_mfma_f32_16x16x32_bf16 v[38:41], v[192:195], v[176:179], v[38:41]
	v_mfma_f32_16x16x32_bf16 v[34:37], v[192:195], v[180:183], v[34:37]
	v_mfma_f32_16x16x32_bf16 v[30:33], v[196:199], v[146:149], v[30:33]
	v_mfma_f32_16x16x32_bf16 v[26:29], v[196:199], v[152:155], v[26:29]
	v_mfma_f32_16x16x32_bf16 v[22:25], v[196:199], v[156:159], v[22:25]
	v_mfma_f32_16x16x32_bf16 v[18:21], v[196:199], v[162:165], v[18:21]
	v_mfma_f32_16x16x32_bf16 v[14:17], v[196:199], v[166:169], v[14:17]
	v_mfma_f32_16x16x32_bf16 v[10:13], v[196:199], v[170:173], v[10:13]
	v_mfma_f32_16x16x32_bf16 v[6:9], v[196:199], v[176:179], v[6:9]
	v_mfma_f32_16x16x32_bf16 v[2:5], v[196:199], v[180:183], v[2:5]
	s_mov_b32 s42, s41
	s_nop 0
	s_add_i32 s41, s41, 0x6000
	s_cmp_eq_u32 s41, 0x12000
	s_cselect_b32 s41, 0, s41
	s_nop 0
	s_mov_b32 s4, 0x8000
	s_mov_b32 s5, 0
	s_mov_b32 s10, 0x10000
	s_mov_b32 s11, 0
	s_mov_b32 s45, 0x3fd744fd
	.p2align 3
	s_waitcnt lgkmcnt(0)
; DEVI float blo(unsigned u) { return __uint_as_float(u << 16); }
; DEVI float bhi(unsigned u) { return __uint_as_float(u & 0xffff0000u); }
;     ...
;     for (int nf = 0; nf < 4; nf++)
; #pragma unroll
;       for (int mf = 0; mf < 8; mf++)
;         acc[nf][mf] = __builtin_amdgcn_mfma_f32_16x16x32_bf16(wb[nf], xa[mf], acc[nf][mf], 0, 0, 0);
;     ...
;         if (EPI == EPI_RESID || EPI == EPI_RESID_ATOMIC) {
;           f32x4 x = a;
;           if (EPI == EPI_RESID || kpart == 0) {
;             const u32x2 xr = *(const u32x2*)((const u16*)(p.ws + WS_XB) + (size_t)row * 1024 + col);
;             x[0] += ALPHA * blo(xr[0]); x[1] += ALPHA * bhi(xr[0]); x[2] += ALPHA * blo(xr[1]); x[3] += ALPHA * bhi(xr[1]);
;           }
;           if (EPI == EPI_RESID) *(f32x4*)((float*)(p.ws + WS_XF) + (size_t)row * 1024 + col) = x;
;           else *(f32x4*)((float*)(p.ws + WS_SLAB) + ((size_t)kpart * 512 + (row - T_P)) * 1024 + col) = x;
	s_nop 0
	v_mfma_f32_16x16x32_bf16 v[126:129], v[232:235], v[200:203], v[126:129]
	v_mfma_f32_16x16x32_bf16 v[122:125], v[232:235], v[204:207], v[122:125]
	v_mfma_f32_16x16x32_bf16 v[118:121], v[232:235], v[208:211], v[118:121]
	v_mfma_f32_16x16x32_bf16 v[114:117], v[232:235], v[212:215], v[114:117]
	v_mfma_f32_16x16x32_bf16 v[110:113], v[232:235], v[216:219], v[110:113]
	global_load_dwordx4 v[146:149], v[138:139], off offset:0
	v_mfma_f32_16x16x32_bf16 v[106:109], v[232:235], v[220:223], v[106:109]
	v_mfma_f32_16x16x32_bf16 v[102:105], v[232:235], v[224:227], v[102:105]
	global_load_dwordx4 v[152:155], v[138:139], off offset:128
	v_mfma_f32_16x16x32_bf16 v[98:101], v[232:235], v[228:231], v[98:101]
	v_lshl_add_u64 v[138:139], v[138:139], 0, s[4:5]
	v_mfma_f32_16x16x32_bf16 v[94:97], v[236:239], v[200:203], v[94:97]
	global_load_dwordx4 v[156:159], v[138:139], off offset:0
	v_mfma_f32_16x16x32_bf16 v[90:93], v[236:239], v[204:207], v[90:93]
	v_mfma_f32_16x16x32_bf16 v[86:89], v[236:239], v[208:211], v[86:89]
	global_load_dwordx4 v[162:165], v[138:139], off offset:128
	v_mfma_f32_16x16x32_bf16 v[82:85], v[236:239], v[212:215], v[82:85]
	v_lshl_add_u64 v[138:139], v[138:139], 0, s[4:5]
	v_mfma_f32_16x16x32_bf16 v[78:81], v[236:239], v[216:219], v[78:81]
	global_load_dwordx4 v[166:169], v[138:139], off offset:0
	v_mfma_f32_16x16x32_bf16 v[74:77], v[236:239], v[220:223], v[74:77]
	v_mfma_f32_16x16x32_bf16 v[70:73], v[236:239], v[224:227], v[70:73]
	global_load_dwordx4 v[170:173], v[138:139], off offset:128
	v_mfma_f32_16x16x32_bf16 v[66:69], v[236:239], v[228:231], v[66:69]
	v_lshl_add_u64 v[138:139], v[138:139], 0, s[4:5]
	v_mfma_f32_16x16x32_bf16 v[62:65], v[240:243], v[200:203], v[62:65]
	global_load_dwordx4 v[176:179], v[138:139], off offset:0
	v_mfma_f32_16x16x32_bf16 v[58:61], v[240:243], v[204:207], v[58:61]
	v_mfma_f32_16x16x32_bf16 v[54:57], v[240:243], v[208:211], v[54:57]
	global_load_dwordx4 v[180:183], v[138:139], off offset:128
	v_mfma_f32_16x16x32_bf16 v[50:53], v[240:243], v[212:215], v[50:53]
	v_lshl_add_u64 v[138:139], v[138:139], 0, s[4:5]
	v_mfma_f32_16x16x32_bf16 v[46:49], v[240:243], v[216:219], v[46:49]
	global_load_dwordx4 v[184:187], v[138:139], off offset:0
	v_mfma_f32_16x16x32_bf16 v[42:45], v[240:243], v[220:223], v[42:45]
	v_mfma_f32_16x16x32_bf16 v[38:41], v[240:243], v[224:227], v[38:41]
	global_load_dwordx4 v[188:191], v[138:139], off offset:128
	v_mfma_f32_16x16x32_bf16 v[34:37], v[240:243], v[228:231], v[34:37]
	v_lshl_add_u64 v[138:139], v[138:139], 0, s[4:5]
	v_mfma_f32_16x16x32_bf16 v[30:33], v[244:247], v[200:203], v[30:33]
	global_load_dwordx4 v[192:195], v[138:139], off offset:0
	v_mfma_f32_16x16x32_bf16 v[26:29], v[244:247], v[204:207], v[26:29]
	v_mfma_f32_16x16x32_bf16 v[22:25], v[244:247], v[208:211], v[22:25]
	global_load_dwordx4 v[196:199], v[138:139], off offset:128
	v_mfma_f32_16x16x32_bf16 v[18:21], v[244:247], v[212:215], v[18:21]
	v_lshl_add_u64 v[138:139], v[138:139], 0, s[4:5]
	v_mfma_f32_16x16x32_bf16 v[14:17], v[244:247], v[216:219], v[14:17]
	v_mfma_f32_16x16x32_bf16 v[10:13], v[244:247], v[220:223], v[10:13]
	v_mfma_f32_16x16x32_bf16 v[6:9], v[244:247], v[224:227], v[6:9]
	v_mfma_f32_16x16x32_bf16 v[2:5], v[244:247], v[228:231], v[2:5]
	s_mov_b32 m0, s44
	global_load_dwordx4 v[200:203], v[138:139], off offset:0
	global_load_dwordx4 v[204:207], v[138:139], off offset:128
	v_lshl_add_u64 v[138:139], v[138:139], 0, s[4:5]
	global_load_dwordx4 v[208:211], v[138:139], off offset:0
	global_load_dwordx4 v[212:215], v[138:139], off offset:128
	v_lshl_add_u64 v[138:139], v[138:139], 0, s[4:5]
	s_nop 7
	v_and_b32_e32 v228, 1, v145
	v_cmp_ne_u32_e32 vcc, 0, v228
	v_mov_b32_e32 v229, 0xfffff040
	v_cndmask_b32_e32 v230, 0, v229, vcc
	v_ashrrev_i32_e32 v231, 31, v230
	v_lshl_add_u64 v[140:141], v[140:141], 0, v[230:231]
	v_add_co_u32_e32 v142, vcc, 0x1000, v140
	s_nop 0
	v_addc_co_u32_e32 v143, vcc, 0, v141, vcc
	v_cmp_ne_u32_e32 vcc, 0, v228
	s_waitcnt vmcnt(15)
	v_permlane16_swap_b32_e32 v146, v148
	v_permlane16_swap_b32_e32 v147, v149
	v_lshlrev_b32_e32 v216, 16, v146
	v_and_b32_e32 v146, 0xffff0000, v146
	v_lshlrev_b32_e32 v217, 16, v147
	v_and_b32_e32 v147, 0xffff0000, v147
	v_fmac_f32_e32 v126, s45, v216
	v_fmac_f32_e32 v127, s45, v146
	v_fmac_f32_e32 v128, s45, v217
	v_fmac_f32_e32 v129, s45, v147
	v_lshlrev_b32_e32 v216, 16, v148
	v_and_b32_e32 v148, 0xffff0000, v148
	v_lshlrev_b32_e32 v217, 16, v149
	v_and_b32_e32 v149, 0xffff0000, v149
	v_fmac_f32_e32 v94, s45, v216
	v_fmac_f32_e32 v95, s45, v148
	v_fmac_f32_e32 v96, s45, v217
	v_fmac_f32_e32 v97, s45, v149
	v_mov_b32_dpp v220, v94 quad_perm:[1,0,3,2] row_mask:0xf bank_mask:0xf
	v_mov_b32_dpp v221, v95 quad_perm:[1,0,3,2] row_mask:0xf bank_mask:0xf
	v_mov_b32_dpp v222, v96 quad_perm:[1,0,3,2] row_mask:0xf bank_mask:0xf
	v_mov_b32_dpp v223, v97 quad_perm:[1,0,3,2] row_mask:0xf bank_mask:0xf
	v_mov_b32_dpp v224, v126 quad_perm:[1,0,3,2] row_mask:0xf bank_mask:0xf
	v_mov_b32_dpp v225, v127 quad_perm:[1,0,3,2] row_mask:0xf bank_mask:0xf
	v_mov_b32_dpp v226, v128 quad_perm:[1,0,3,2] row_mask:0xf bank_mask:0xf
	v_mov_b32_dpp v227, v129 quad_perm:[1,0,3,2] row_mask:0xf bank_mask:0xf
	v_cndmask_b32_e32 v94, v224, v94, vcc
	v_cndmask_b32_e32 v95, v225, v95, vcc
	v_cndmask_b32_e32 v96, v226, v96, vcc
	v_cndmask_b32_e32 v97, v227, v97, vcc
	v_cndmask_b32_e32 v126, v126, v220, vcc
	v_cndmask_b32_e32 v127, v127, v221, vcc
	v_cndmask_b32_e32 v128, v128, v222, vcc
	v_cndmask_b32_e32 v129, v129, v223, vcc
	global_store_dwordx4 v[140:141], v[126:129], off
	global_store_dwordx4 v[142:143], v[94:97], off
	s_waitcnt vmcnt(16)
; DEVI float blo(unsigned u) { return __uint_as_float(u << 16); }
; DEVI float bhi(unsigned u) { return __uint_as_float(u & 0xffff0000u); }
;     ...
;         if (EPI == EPI_RESID || EPI == EPI_RESID_ATOMIC) {
;           f32x4 x = a;
;           if (EPI == EPI_RESID || kpart == 0) {
;             const u32x2 xr = *(const u32x2*)((const u16*)(p.ws + WS_XB) + (size_t)row * 1024 + col);
;             x[0] += ALPHA * blo(xr[0]); x[1] += ALPHA * bhi(xr[0]); x[2] += ALPHA * blo(xr[1]); x[3] += ALPHA * bhi(xr[1]);
;           }
;           if (EPI == EPI_RESID) *(f32x4*)((float*)(p.ws + WS_XF) + (size_t)row * 1024 + col) = x;
;           else *(f32x4*)((float*)(p.ws + WS_SLAB) + ((size_t)kpart * 512 + (row - T_P)) * 1024 + col) = x;
	v_permlane16_swap_b32_e32 v152, v154
	v_permlane16_swap_b32_e32 v153, v155
	v_lshlrev_b32_e32 v216, 16, v152
	v_and_b32_e32 v152, 0xffff0000, v152
	v_lshlrev_b32_e32 v217, 16, v153
	v_and_b32_e32 v153, 0xffff0000, v153
	v_fmac_f32_e32 v62, s45, v216
	v_fmac_f32_e32 v63, s45, v152
	v_fmac_f32_e32 v64, s45, v217
	v_fmac_f32_e32 v65, s45, v153
	v_lshlrev_b32_e32 v216, 16, v154
	v_and_b32_e32 v154, 0xffff0000, v154
	v_lshlrev_b32_e32 v217, 16, v155
	v_and_b32_e32 v155, 0xffff0000, v155
	v_fmac_f32_e32 v30, s45, v216
	v_fmac_f32_e32 v31, s45, v154
	v_fmac_f32_e32 v32, s45, v217
	v_fmac_f32_e32 v33, s45, v155
	v_mov_b32_dpp v220, v30 quad_perm:[1,0,3,2] row_mask:0xf bank_mask:0xf
	v_mov_b32_dpp v221, v31 quad_perm:[1,0,3,2] row_mask:0xf bank_mask:0xf
	v_mov_b32_dpp v222, v32 quad_perm:[1,0,3,2] row_mask:0xf bank_mask:0xf
	v_mov_b32_dpp v223, v33 quad_perm:[1,0,3,2] row_mask:0xf bank_mask:0xf
	v_mov_b32_dpp v224, v62 quad_perm:[1,0,3,2] row_mask:0xf bank_mask:0xf
	v_mov_b32_dpp v225, v63 quad_perm:[1,0,3,2] row_mask:0xf bank_mask:0xf
	v_mov_b32_dpp v226, v64 quad_perm:[1,0,3,2] row_mask:0xf bank_mask:0xf
	v_mov_b32_dpp v227, v65 quad_perm:[1,0,3,2] row_mask:0xf bank_mask:0xf
	v_cndmask_b32_e32 v30, v224, v30, vcc
	v_cndmask_b32_e32 v31, v225, v31, vcc
	v_cndmask_b32_e32 v32, v226, v32, vcc
	v_cndmask_b32_e32 v33, v227, v33, vcc
	v_cndmask_b32_e32 v62, v62, v220, vcc
	v_cndmask_b32_e32 v63, v63, v221, vcc
	v_cndmask_b32_e32 v64, v64, v222, vcc
	v_cndmask_b32_e32 v65, v65, v223, vcc
	global_store_dwordx4 v[140:141], v[62:65], off offset:128
	global_store_dwordx4 v[142:143], v[30:33], off offset:128
	v_lshl_add_u64 v[140:141], v[140:141], 0, s[10:11]
	v_lshl_add_u64 v[142:143], v[142:143], 0, s[10:11]
	s_waitcnt vmcnt(17)
	v_permlane16_swap_b32_e32 v156, v158
	v_permlane16_swap_b32_e32 v157, v159
	v_lshlrev_b32_e32 v216, 16, v156
	v_and_b32_e32 v156, 0xffff0000, v156
	v_lshlrev_b32_e32 v217, 16, v157
	v_and_b32_e32 v157, 0xffff0000, v157
	v_fmac_f32_e32 v122, s45, v216
	v_fmac_f32_e32 v123, s45, v156
	v_fmac_f32_e32 v124, s45, v217
	v_fmac_f32_e32 v125, s45, v157
	v_lshlrev_b32_e32 v216, 16, v158
	v_and_b32_e32 v158, 0xffff0000, v158
	v_lshlrev_b32_e32 v217, 16, v159
	v_and_b32_e32 v159, 0xffff0000, v159
	v_fmac_f32_e32 v90, s45, v216
	v_fmac_f32_e32 v91, s45, v158
	v_fmac_f32_e32 v92, s45, v217
	v_fmac_f32_e32 v93, s45, v159
	v_mov_b32_dpp v220, v90 quad_perm:[1,0,3,2] row_mask:0xf bank_mask:0xf
	v_mov_b32_dpp v221, v91 quad_perm:[1,0,3,2] row_mask:0xf bank_mask:0xf
	v_mov_b32_dpp v222, v92 quad_perm:[1,0,3,2] row_mask:0xf bank_mask:0xf
	v_mov_b32_dpp v223, v93 quad_perm:[1,0,3,2] row_mask:0xf bank_mask:0xf
	v_mov_b32_dpp v224, v122 quad_perm:[1,0,3,2] row_mask:0xf bank_mask:0xf
	v_mov_b32_dpp v225, v123 quad_perm:[1,0,3,2] row_mask:0xf bank_mask:0xf
	v_mov_b32_dpp v226, v124 quad_perm:[1,0,3,2] row_mask:0xf bank_mask:0xf
	v_mov_b32_dpp v227, v125 quad_perm:[1,0,3,2] row_mask:0xf bank_mask:0xf
	v_cndmask_b32_e32 v90, v224, v90, vcc
	v_cndmask_b32_e32 v91, v225, v91, vcc
	v_cndmask_b32_e32 v92, v226, v92, vcc
	v_cndmask_b32_e32 v93, v227, v93, vcc
	v_cndmask_b32_e32 v122, v122, v220, vcc
	v_cndmask_b32_e32 v123, v123, v221, vcc
	v_cndmask_b32_e32 v124, v124, v222, vcc
	v_cndmask_b32_e32 v125, v125, v223, vcc
	global_store_dwordx4 v[140:141], v[122:125], off
	global_store_dwordx4 v[142:143], v[90:93], off
	s_waitcnt vmcnt(18)
	v_permlane16_swap_b32_e32 v162, v164
	v_permlane16_swap_b32_e32 v163, v165
	v_lshlrev_b32_e32 v216, 16, v162
	v_and_b32_e32 v162, 0xffff0000, v162
	v_lshlrev_b32_e32 v217, 16, v163
	v_and_b32_e32 v163, 0xffff0000, v163
	v_fmac_f32_e32 v58, s45, v216
	v_fmac_f32_e32 v59, s45, v162
	v_fmac_f32_e32 v60, s45, v217
	v_fmac_f32_e32 v61, s45, v163
	v_lshlrev_b32_e32 v216, 16, v164
	v_and_b32_e32 v164, 0xffff0000, v164
	v_lshlrev_b32_e32 v217, 16, v165
	v_and_b32_e32 v165, 0xffff0000, v165
	v_fmac_f32_e32 v26, s45, v216
	v_fmac_f32_e32 v27, s45, v164
	v_fmac_f32_e32 v28, s45, v217
	v_fmac_f32_e32 v29, s45, v165
	v_mov_b32_dpp v220, v26 quad_perm:[1,0,3,2] row_mask:0xf bank_mask:0xf
	v_mov_b32_dpp v221, v27 quad_perm:[1,0,3,2] row_mask:0xf bank_mask:0xf
	v_mov_b32_dpp v222, v28 quad_perm:[1,0,3,2] row_mask:0xf bank_mask:0xf
	v_mov_b32_dpp v223, v29 quad_perm:[1,0,3,2] row_mask:0xf bank_mask:0xf
	v_mov_b32_dpp v224, v58 quad_perm:[1,0,3,2] row_mask:0xf bank_mask:0xf
	v_mov_b32_dpp v225, v59 quad_perm:[1,0,3,2] row_mask:0xf bank_mask:0xf
	v_mov_b32_dpp v226, v60 quad_perm:[1,0,3,2] row_mask:0xf bank_mask:0xf
	v_mov_b32_dpp v227, v61 quad_perm:[1,0,3,2] row_mask:0xf bank_mask:0xf
	v_cndmask_b32_e32 v26, v224, v26, vcc
	v_cndmask_b32_e32 v27, v225, v27, vcc
	v_cndmask_b32_e32 v28, v226, v28, vcc
	v_cndmask_b32_e32 v29, v227, v29, vcc
	v_cndmask_b32_e32 v58, v58, v220, vcc
	v_cndmask_b32_e32 v59, v59, v221, vcc
	v_cndmask_b32_e32 v60, v60, v222, vcc
	v_cndmask_b32_e32 v61, v61, v223, vcc
	global_store_dwordx4 v[140:141], v[58:61], off offset:128
	global_store_dwordx4 v[142:143], v[26:29], off offset:128
	v_lshl_add_u64 v[140:141], v[140:141], 0, s[10:11]
	v_lshl_add_u64 v[142:143], v[142:143], 0, s[10:11]
	s_waitcnt vmcnt(19)
; DEVI float blo(unsigned u) { return __uint_as_float(u << 16); }
; DEVI float bhi(unsigned u) { return __uint_as_float(u & 0xffff0000u); }
;     ...
;         if (EPI == EPI_RESID || EPI == EPI_RESID_ATOMIC) {
;           f32x4 x = a;
;           if (EPI == EPI_RESID || kpart == 0) {
;             const u32x2 xr = *(const u32x2*)((const u16*)(p.ws + WS_XB) + (size_t)row * 1024 + col);
;             x[0] += ALPHA * blo(xr[0]); x[1] += ALPHA * bhi(xr[0]); x[2] += ALPHA * blo(xr[1]); x[3] += ALPHA * bhi(xr[1]);
;           }
;           if (EPI == EPI_RESID) *(f32x4*)((float*)(p.ws + WS_XF) + (size_t)row * 1024 + col) = x;
;           else *(f32x4*)((float*)(p.ws + WS_SLAB) + ((size_t)kpart * 512 + (row - T_P)) * 1024 + col) = x;
	v_permlane16_swap_b32_e32 v166, v168
	v_permlane16_swap_b32_e32 v167, v169
	v_lshlrev_b32_e32 v216, 16, v166
	v_and_b32_e32 v166, 0xffff0000, v166
	v_lshlrev_b32_e32 v217, 16, v167
	v_and_b32_e32 v167, 0xffff0000, v167
	v_fmac_f32_e32 v118, s45, v216
	v_fmac_f32_e32 v119, s45, v166
	v_fmac_f32_e32 v120, s45, v217
	v_fmac_f32_e32 v121, s45, v167
	v_lshlrev_b32_e32 v216, 16, v168
	v_and_b32_e32 v168, 0xffff0000, v168
	v_lshlrev_b32_e32 v217, 16, v169
	v_and_b32_e32 v169, 0xffff0000, v169
	v_fmac_f32_e32 v86, s45, v216
	v_fmac_f32_e32 v87, s45, v168
	v_fmac_f32_e32 v88, s45, v217
	v_fmac_f32_e32 v89, s45, v169
	v_mov_b32_dpp v220, v86 quad_perm:[1,0,3,2] row_mask:0xf bank_mask:0xf
	v_mov_b32_dpp v221, v87 quad_perm:[1,0,3,2] row_mask:0xf bank_mask:0xf
	v_mov_b32_dpp v222, v88 quad_perm:[1,0,3,2] row_mask:0xf bank_mask:0xf
	v_mov_b32_dpp v223, v89 quad_perm:[1,0,3,2] row_mask:0xf bank_mask:0xf
	v_mov_b32_dpp v224, v118 quad_perm:[1,0,3,2] row_mask:0xf bank_mask:0xf
	v_mov_b32_dpp v225, v119 quad_perm:[1,0,3,2] row_mask:0xf bank_mask:0xf
	v_mov_b32_dpp v226, v120 quad_perm:[1,0,3,2] row_mask:0xf bank_mask:0xf
	v_mov_b32_dpp v227, v121 quad_perm:[1,0,3,2] row_mask:0xf bank_mask:0xf
	v_cndmask_b32_e32 v86, v224, v86, vcc
	v_cndmask_b32_e32 v87, v225, v87, vcc
	v_cndmask_b32_e32 v88, v226, v88, vcc
	v_cndmask_b32_e32 v89, v227, v89, vcc
	v_cndmask_b32_e32 v118, v118, v220, vcc
	v_cndmask_b32_e32 v119, v119, v221, vcc
	v_cndmask_b32_e32 v120, v120, v222, vcc
	v_cndmask_b32_e32 v121, v121, v223, vcc
	global_store_dwordx4 v[140:141], v[118:121], off
	global_store_dwordx4 v[142:143], v[86:89], off
	s_waitcnt vmcnt(20)
	v_permlane16_swap_b32_e32 v170, v172
	v_permlane16_swap_b32_e32 v171, v173
	v_lshlrev_b32_e32 v216, 16, v170
	v_and_b32_e32 v170, 0xffff0000, v170
	v_lshlrev_b32_e32 v217, 16, v171
	v_and_b32_e32 v171, 0xffff0000, v171
	v_fmac_f32_e32 v54, s45, v216
	v_fmac_f32_e32 v55, s45, v170
	v_fmac_f32_e32 v56, s45, v217
	v_fmac_f32_e32 v57, s45, v171
	v_lshlrev_b32_e32 v216, 16, v172
	v_and_b32_e32 v172, 0xffff0000, v172
	v_lshlrev_b32_e32 v217, 16, v173
	v_and_b32_e32 v173, 0xffff0000, v173
	v_fmac_f32_e32 v22, s45, v216
	v_fmac_f32_e32 v23, s45, v172
	v_fmac_f32_e32 v24, s45, v217
	v_fmac_f32_e32 v25, s45, v173
	v_mov_b32_dpp v220, v22 quad_perm:[1,0,3,2] row_mask:0xf bank_mask:0xf
	v_mov_b32_dpp v221, v23 quad_perm:[1,0,3,2] row_mask:0xf bank_mask:0xf
	v_mov_b32_dpp v222, v24 quad_perm:[1,0,3,2] row_mask:0xf bank_mask:0xf
	v_mov_b32_dpp v223, v25 quad_perm:[1,0,3,2] row_mask:0xf bank_mask:0xf
	v_mov_b32_dpp v224, v54 quad_perm:[1,0,3,2] row_mask:0xf bank_mask:0xf
	v_mov_b32_dpp v225, v55 quad_perm:[1,0,3,2] row_mask:0xf bank_mask:0xf
	v_mov_b32_dpp v226, v56 quad_perm:[1,0,3,2] row_mask:0xf bank_mask:0xf
	v_mov_b32_dpp v227, v57 quad_perm:[1,0,3,2] row_mask:0xf bank_mask:0xf
	v_cndmask_b32_e32 v22, v224, v22, vcc
	v_cndmask_b32_e32 v23, v225, v23, vcc
	v_cndmask_b32_e32 v24, v226, v24, vcc
	v_cndmask_b32_e32 v25, v227, v25, vcc
	v_cndmask_b32_e32 v54, v54, v220, vcc
	v_cndmask_b32_e32 v55, v55, v221, vcc
	v_cndmask_b32_e32 v56, v56, v222, vcc
	v_cndmask_b32_e32 v57, v57, v223, vcc
	global_store_dwordx4 v[140:141], v[54:57], off offset:128
	global_store_dwordx4 v[142:143], v[22:25], off offset:128
	v_lshl_add_u64 v[140:141], v[140:141], 0, s[10:11]
	v_lshl_add_u64 v[142:143], v[142:143], 0, s[10:11]
	s_waitcnt vmcnt(21)
	v_permlane16_swap_b32_e32 v176, v178
	v_permlane16_swap_b32_e32 v177, v179
	v_lshlrev_b32_e32 v216, 16, v176
	v_and_b32_e32 v176, 0xffff0000, v176
	v_lshlrev_b32_e32 v217, 16, v177
	v_and_b32_e32 v177, 0xffff0000, v177
	v_fmac_f32_e32 v114, s45, v216
	v_fmac_f32_e32 v115, s45, v176
	v_fmac_f32_e32 v116, s45, v217
	v_fmac_f32_e32 v117, s45, v177
	v_lshlrev_b32_e32 v216, 16, v178
	v_and_b32_e32 v178, 0xffff0000, v178
	v_lshlrev_b32_e32 v217, 16, v179
	v_and_b32_e32 v179, 0xffff0000, v179
	v_fmac_f32_e32 v82, s45, v216
	v_fmac_f32_e32 v83, s45, v178
	v_fmac_f32_e32 v84, s45, v217
	v_fmac_f32_e32 v85, s45, v179
	v_mov_b32_dpp v220, v82 quad_perm:[1,0,3,2] row_mask:0xf bank_mask:0xf
	v_mov_b32_dpp v221, v83 quad_perm:[1,0,3,2] row_mask:0xf bank_mask:0xf
	v_mov_b32_dpp v222, v84 quad_perm:[1,0,3,2] row_mask:0xf bank_mask:0xf
	v_mov_b32_dpp v223, v85 quad_perm:[1,0,3,2] row_mask:0xf bank_mask:0xf
	v_mov_b32_dpp v224, v114 quad_perm:[1,0,3,2] row_mask:0xf bank_mask:0xf
	v_mov_b32_dpp v225, v115 quad_perm:[1,0,3,2] row_mask:0xf bank_mask:0xf
	v_mov_b32_dpp v226, v116 quad_perm:[1,0,3,2] row_mask:0xf bank_mask:0xf
	v_mov_b32_dpp v227, v117 quad_perm:[1,0,3,2] row_mask:0xf bank_mask:0xf
	v_cndmask_b32_e32 v82, v224, v82, vcc
	v_cndmask_b32_e32 v83, v225, v83, vcc
	v_cndmask_b32_e32 v84, v226, v84, vcc
	v_cndmask_b32_e32 v85, v227, v85, vcc
	v_cndmask_b32_e32 v114, v114, v220, vcc
	v_cndmask_b32_e32 v115, v115, v221, vcc
	v_cndmask_b32_e32 v116, v116, v222, vcc
	v_cndmask_b32_e32 v117, v117, v223, vcc
	global_store_dwordx4 v[140:141], v[114:117], off
	global_store_dwordx4 v[142:143], v[82:85], off
	s_waitcnt vmcnt(22)
; DEVI float blo(unsigned u) { return __uint_as_float(u << 16); }
; DEVI float bhi(unsigned u) { return __uint_as_float(u & 0xffff0000u); }
;     ...
;         if (EPI == EPI_RESID || EPI == EPI_RESID_ATOMIC) {
;           f32x4 x = a;
;           if (EPI == EPI_RESID || kpart == 0) {
;             const u32x2 xr = *(const u32x2*)((const u16*)(p.ws + WS_XB) + (size_t)row * 1024 + col);
;             x[0] += ALPHA * blo(xr[0]); x[1] += ALPHA * bhi(xr[0]); x[2] += ALPHA * blo(xr[1]); x[3] += ALPHA * bhi(xr[1]);
;           }
;           if (EPI == EPI_RESID) *(f32x4*)((float*)(p.ws + WS_XF) + (size_t)row * 1024 + col) = x;
;           else *(f32x4*)((float*)(p.ws + WS_SLAB) + ((size_t)kpart * 512 + (row - T_P)) * 1024 + col) = x;
	v_permlane16_swap_b32_e32 v180, v182
	v_permlane16_swap_b32_e32 v181, v183
	v_lshlrev_b32_e32 v216, 16, v180
	v_and_b32_e32 v180, 0xffff0000, v180
	v_lshlrev_b32_e32 v217, 16, v181
	v_and_b32_e32 v181, 0xffff0000, v181
	v_fmac_f32_e32 v50, s45, v216
	v_fmac_f32_e32 v51, s45, v180
	v_fmac_f32_e32 v52, s45, v217
	v_fmac_f32_e32 v53, s45, v181
	v_lshlrev_b32_e32 v216, 16, v182
	v_and_b32_e32 v182, 0xffff0000, v182
	v_lshlrev_b32_e32 v217, 16, v183
	v_and_b32_e32 v183, 0xffff0000, v183
	v_fmac_f32_e32 v18, s45, v216
	v_fmac_f32_e32 v19, s45, v182
	v_fmac_f32_e32 v20, s45, v217
	v_fmac_f32_e32 v21, s45, v183
	v_mov_b32_dpp v220, v18 quad_perm:[1,0,3,2] row_mask:0xf bank_mask:0xf
	v_mov_b32_dpp v221, v19 quad_perm:[1,0,3,2] row_mask:0xf bank_mask:0xf
	v_mov_b32_dpp v222, v20 quad_perm:[1,0,3,2] row_mask:0xf bank_mask:0xf
	v_mov_b32_dpp v223, v21 quad_perm:[1,0,3,2] row_mask:0xf bank_mask:0xf
	v_mov_b32_dpp v224, v50 quad_perm:[1,0,3,2] row_mask:0xf bank_mask:0xf
	v_mov_b32_dpp v225, v51 quad_perm:[1,0,3,2] row_mask:0xf bank_mask:0xf
	v_mov_b32_dpp v226, v52 quad_perm:[1,0,3,2] row_mask:0xf bank_mask:0xf
	v_mov_b32_dpp v227, v53 quad_perm:[1,0,3,2] row_mask:0xf bank_mask:0xf
	v_cndmask_b32_e32 v18, v224, v18, vcc
	v_cndmask_b32_e32 v19, v225, v19, vcc
	v_cndmask_b32_e32 v20, v226, v20, vcc
	v_cndmask_b32_e32 v21, v227, v21, vcc
	v_cndmask_b32_e32 v50, v50, v220, vcc
	v_cndmask_b32_e32 v51, v51, v221, vcc
	v_cndmask_b32_e32 v52, v52, v222, vcc
	v_cndmask_b32_e32 v53, v53, v223, vcc
	global_store_dwordx4 v[140:141], v[50:53], off offset:128
	global_store_dwordx4 v[142:143], v[18:21], off offset:128
	v_lshl_add_u64 v[140:141], v[140:141], 0, s[10:11]
	v_lshl_add_u64 v[142:143], v[142:143], 0, s[10:11]
	s_waitcnt vmcnt(23)
	v_permlane16_swap_b32_e32 v184, v186
	v_permlane16_swap_b32_e32 v185, v187
	v_lshlrev_b32_e32 v216, 16, v184
	v_and_b32_e32 v184, 0xffff0000, v184
	v_lshlrev_b32_e32 v217, 16, v185
	v_and_b32_e32 v185, 0xffff0000, v185
	v_fmac_f32_e32 v110, s45, v216
	v_fmac_f32_e32 v111, s45, v184
	v_fmac_f32_e32 v112, s45, v217
	v_fmac_f32_e32 v113, s45, v185
	v_lshlrev_b32_e32 v216, 16, v186
	v_and_b32_e32 v186, 0xffff0000, v186
	v_lshlrev_b32_e32 v217, 16, v187
	v_and_b32_e32 v187, 0xffff0000, v187
	v_fmac_f32_e32 v78, s45, v216
	v_fmac_f32_e32 v79, s45, v186
	v_fmac_f32_e32 v80, s45, v217
	v_fmac_f32_e32 v81, s45, v187
	v_mov_b32_dpp v220, v78 quad_perm:[1,0,3,2] row_mask:0xf bank_mask:0xf
	v_mov_b32_dpp v221, v79 quad_perm:[1,0,3,2] row_mask:0xf bank_mask:0xf
	v_mov_b32_dpp v222, v80 quad_perm:[1,0,3,2] row_mask:0xf bank_mask:0xf
	v_mov_b32_dpp v223, v81 quad_perm:[1,0,3,2] row_mask:0xf bank_mask:0xf
	v_mov_b32_dpp v224, v110 quad_perm:[1,0,3,2] row_mask:0xf bank_mask:0xf
	v_mov_b32_dpp v225, v111 quad_perm:[1,0,3,2] row_mask:0xf bank_mask:0xf
	v_mov_b32_dpp v226, v112 quad_perm:[1,0,3,2] row_mask:0xf bank_mask:0xf
	v_mov_b32_dpp v227, v113 quad_perm:[1,0,3,2] row_mask:0xf bank_mask:0xf
	v_cndmask_b32_e32 v78, v224, v78, vcc
	v_cndmask_b32_e32 v79, v225, v79, vcc
	v_cndmask_b32_e32 v80, v226, v80, vcc
	v_cndmask_b32_e32 v81, v227, v81, vcc
	v_cndmask_b32_e32 v110, v110, v220, vcc
	v_cndmask_b32_e32 v111, v111, v221, vcc
	v_cndmask_b32_e32 v112, v112, v222, vcc
	v_cndmask_b32_e32 v113, v113, v223, vcc
	global_store_dwordx4 v[140:141], v[110:113], off
	global_store_dwordx4 v[142:143], v[78:81], off
	s_waitcnt vmcnt(24)
	v_permlane16_swap_b32_e32 v188, v190
	v_permlane16_swap_b32_e32 v189, v191
	v_lshlrev_b32_e32 v216, 16, v188
	v_and_b32_e32 v188, 0xffff0000, v188
	v_lshlrev_b32_e32 v217, 16, v189
	v_and_b32_e32 v189, 0xffff0000, v189
	v_fmac_f32_e32 v46, s45, v216
	v_fmac_f32_e32 v47, s45, v188
	v_fmac_f32_e32 v48, s45, v217
	v_fmac_f32_e32 v49, s45, v189
	v_lshlrev_b32_e32 v216, 16, v190
	v_and_b32_e32 v190, 0xffff0000, v190
	v_lshlrev_b32_e32 v217, 16, v191
	v_and_b32_e32 v191, 0xffff0000, v191
	v_fmac_f32_e32 v14, s45, v216
	v_fmac_f32_e32 v15, s45, v190
	v_fmac_f32_e32 v16, s45, v217
	v_fmac_f32_e32 v17, s45, v191
	v_mov_b32_dpp v220, v14 quad_perm:[1,0,3,2] row_mask:0xf bank_mask:0xf
	v_mov_b32_dpp v221, v15 quad_perm:[1,0,3,2] row_mask:0xf bank_mask:0xf
	v_mov_b32_dpp v222, v16 quad_perm:[1,0,3,2] row_mask:0xf bank_mask:0xf
	v_mov_b32_dpp v223, v17 quad_perm:[1,0,3,2] row_mask:0xf bank_mask:0xf
	v_mov_b32_dpp v224, v46 quad_perm:[1,0,3,2] row_mask:0xf bank_mask:0xf
	v_mov_b32_dpp v225, v47 quad_perm:[1,0,3,2] row_mask:0xf bank_mask:0xf
	v_mov_b32_dpp v226, v48 quad_perm:[1,0,3,2] row_mask:0xf bank_mask:0xf
	v_mov_b32_dpp v227, v49 quad_perm:[1,0,3,2] row_mask:0xf bank_mask:0xf
	v_cndmask_b32_e32 v14, v224, v14, vcc
	v_cndmask_b32_e32 v15, v225, v15, vcc
	v_cndmask_b32_e32 v16, v226, v16, vcc
	v_cndmask_b32_e32 v17, v227, v17, vcc
	v_cndmask_b32_e32 v46, v46, v220, vcc
	v_cndmask_b32_e32 v47, v47, v221, vcc
	v_cndmask_b32_e32 v48, v48, v222, vcc
	v_cndmask_b32_e32 v49, v49, v223, vcc
	global_store_dwordx4 v[140:141], v[46:49], off offset:128
	global_store_dwordx4 v[142:143], v[14:17], off offset:128
	v_lshl_add_u64 v[140:141], v[140:141], 0, s[10:11]
	v_lshl_add_u64 v[142:143], v[142:143], 0, s[10:11]
	s_waitcnt vmcnt(25)
; DEVI float blo(unsigned u) { return __uint_as_float(u << 16); }
; DEVI float bhi(unsigned u) { return __uint_as_float(u & 0xffff0000u); }
;     ...
;         if (EPI == EPI_RESID || EPI == EPI_RESID_ATOMIC) {
;           f32x4 x = a;
;           if (EPI == EPI_RESID || kpart == 0) {
;             const u32x2 xr = *(const u32x2*)((const u16*)(p.ws + WS_XB) + (size_t)row * 1024 + col);
;             x[0] += ALPHA * blo(xr[0]); x[1] += ALPHA * bhi(xr[0]); x[2] += ALPHA * blo(xr[1]); x[3] += ALPHA * bhi(xr[1]);
;           }
;           if (EPI == EPI_RESID) *(f32x4*)((float*)(p.ws + WS_XF) + (size_t)row * 1024 + col) = x;
;           else *(f32x4*)((float*)(p.ws + WS_SLAB) + ((size_t)kpart * 512 + (row - T_P)) * 1024 + col) = x;
	v_permlane16_swap_b32_e32 v192, v194
	v_permlane16_swap_b32_e32 v193, v195
	v_lshlrev_b32_e32 v216, 16, v192
	v_and_b32_e32 v192, 0xffff0000, v192
	v_lshlrev_b32_e32 v217, 16, v193
	v_and_b32_e32 v193, 0xffff0000, v193
	v_fmac_f32_e32 v106, s45, v216
	v_fmac_f32_e32 v107, s45, v192
	v_fmac_f32_e32 v108, s45, v217
	v_fmac_f32_e32 v109, s45, v193
	v_lshlrev_b32_e32 v216, 16, v194
	v_and_b32_e32 v194, 0xffff0000, v194
	v_lshlrev_b32_e32 v217, 16, v195
	v_and_b32_e32 v195, 0xffff0000, v195
	v_fmac_f32_e32 v74, s45, v216
	v_fmac_f32_e32 v75, s45, v194
	v_fmac_f32_e32 v76, s45, v217
	v_fmac_f32_e32 v77, s45, v195
	v_mov_b32_dpp v220, v74 quad_perm:[1,0,3,2] row_mask:0xf bank_mask:0xf
	v_mov_b32_dpp v221, v75 quad_perm:[1,0,3,2] row_mask:0xf bank_mask:0xf
	v_mov_b32_dpp v222, v76 quad_perm:[1,0,3,2] row_mask:0xf bank_mask:0xf
	v_mov_b32_dpp v223, v77 quad_perm:[1,0,3,2] row_mask:0xf bank_mask:0xf
	v_mov_b32_dpp v224, v106 quad_perm:[1,0,3,2] row_mask:0xf bank_mask:0xf
	v_mov_b32_dpp v225, v107 quad_perm:[1,0,3,2] row_mask:0xf bank_mask:0xf
	v_mov_b32_dpp v226, v108 quad_perm:[1,0,3,2] row_mask:0xf bank_mask:0xf
	v_mov_b32_dpp v227, v109 quad_perm:[1,0,3,2] row_mask:0xf bank_mask:0xf
	v_cndmask_b32_e32 v74, v224, v74, vcc
	v_cndmask_b32_e32 v75, v225, v75, vcc
	v_cndmask_b32_e32 v76, v226, v76, vcc
	v_cndmask_b32_e32 v77, v227, v77, vcc
	v_cndmask_b32_e32 v106, v106, v220, vcc
	v_cndmask_b32_e32 v107, v107, v221, vcc
	v_cndmask_b32_e32 v108, v108, v222, vcc
	v_cndmask_b32_e32 v109, v109, v223, vcc
	global_store_dwordx4 v[140:141], v[106:109], off
	global_store_dwordx4 v[142:143], v[74:77], off
	s_waitcnt vmcnt(26)
	v_permlane16_swap_b32_e32 v196, v198
	v_permlane16_swap_b32_e32 v197, v199
	v_lshlrev_b32_e32 v216, 16, v196
	v_and_b32_e32 v196, 0xffff0000, v196
	v_lshlrev_b32_e32 v217, 16, v197
	v_and_b32_e32 v197, 0xffff0000, v197
	v_fmac_f32_e32 v42, s45, v216
	v_fmac_f32_e32 v43, s45, v196
	v_fmac_f32_e32 v44, s45, v217
	v_fmac_f32_e32 v45, s45, v197
	v_lshlrev_b32_e32 v216, 16, v198
	v_and_b32_e32 v198, 0xffff0000, v198
	v_lshlrev_b32_e32 v217, 16, v199
	v_and_b32_e32 v199, 0xffff0000, v199
	v_fmac_f32_e32 v10, s45, v216
	v_fmac_f32_e32 v11, s45, v198
	v_fmac_f32_e32 v12, s45, v217
	v_fmac_f32_e32 v13, s45, v199
	v_mov_b32_dpp v220, v10 quad_perm:[1,0,3,2] row_mask:0xf bank_mask:0xf
	v_mov_b32_dpp v221, v11 quad_perm:[1,0,3,2] row_mask:0xf bank_mask:0xf
	v_mov_b32_dpp v222, v12 quad_perm:[1,0,3,2] row_mask:0xf bank_mask:0xf
	v_mov_b32_dpp v223, v13 quad_perm:[1,0,3,2] row_mask:0xf bank_mask:0xf
	v_mov_b32_dpp v224, v42 quad_perm:[1,0,3,2] row_mask:0xf bank_mask:0xf
	v_mov_b32_dpp v225, v43 quad_perm:[1,0,3,2] row_mask:0xf bank_mask:0xf
	v_mov_b32_dpp v226, v44 quad_perm:[1,0,3,2] row_mask:0xf bank_mask:0xf
	v_mov_b32_dpp v227, v45 quad_perm:[1,0,3,2] row_mask:0xf bank_mask:0xf
	v_cndmask_b32_e32 v10, v224, v10, vcc
	v_cndmask_b32_e32 v11, v225, v11, vcc
	v_cndmask_b32_e32 v12, v226, v12, vcc
	v_cndmask_b32_e32 v13, v227, v13, vcc
	v_cndmask_b32_e32 v42, v42, v220, vcc
	v_cndmask_b32_e32 v43, v43, v221, vcc
	v_cndmask_b32_e32 v44, v44, v222, vcc
	v_cndmask_b32_e32 v45, v45, v223, vcc
	global_store_dwordx4 v[140:141], v[42:45], off offset:128
	global_store_dwordx4 v[142:143], v[10:13], off offset:128
	v_lshl_add_u64 v[140:141], v[140:141], 0, s[10:11]
	v_lshl_add_u64 v[142:143], v[142:143], 0, s[10:11]
	s_waitcnt vmcnt(27)
	v_permlane16_swap_b32_e32 v200, v202
	v_permlane16_swap_b32_e32 v201, v203
	v_lshlrev_b32_e32 v216, 16, v200
	v_and_b32_e32 v200, 0xffff0000, v200
	v_lshlrev_b32_e32 v217, 16, v201
	v_and_b32_e32 v201, 0xffff0000, v201
	v_fmac_f32_e32 v102, s45, v216
	v_fmac_f32_e32 v103, s45, v200
	v_fmac_f32_e32 v104, s45, v217
	v_fmac_f32_e32 v105, s45, v201
	v_lshlrev_b32_e32 v216, 16, v202
	v_and_b32_e32 v202, 0xffff0000, v202
	v_lshlrev_b32_e32 v217, 16, v203
	v_and_b32_e32 v203, 0xffff0000, v203
	v_fmac_f32_e32 v70, s45, v216
	v_fmac_f32_e32 v71, s45, v202
	v_fmac_f32_e32 v72, s45, v217
	v_fmac_f32_e32 v73, s45, v203
	v_mov_b32_dpp v220, v70 quad_perm:[1,0,3,2] row_mask:0xf bank_mask:0xf
	v_mov_b32_dpp v221, v71 quad_perm:[1,0,3,2] row_mask:0xf bank_mask:0xf
	v_mov_b32_dpp v222, v72 quad_perm:[1,0,3,2] row_mask:0xf bank_mask:0xf
	v_mov_b32_dpp v223, v73 quad_perm:[1,0,3,2] row_mask:0xf bank_mask:0xf
	v_mov_b32_dpp v224, v102 quad_perm:[1,0,3,2] row_mask:0xf bank_mask:0xf
	v_mov_b32_dpp v225, v103 quad_perm:[1,0,3,2] row_mask:0xf bank_mask:0xf
	v_mov_b32_dpp v226, v104 quad_perm:[1,0,3,2] row_mask:0xf bank_mask:0xf
	v_mov_b32_dpp v227, v105 quad_perm:[1,0,3,2] row_mask:0xf bank_mask:0xf
	v_cndmask_b32_e32 v70, v224, v70, vcc
	v_cndmask_b32_e32 v71, v225, v71, vcc
	v_cndmask_b32_e32 v72, v226, v72, vcc
	v_cndmask_b32_e32 v73, v227, v73, vcc
	v_cndmask_b32_e32 v102, v102, v220, vcc
	v_cndmask_b32_e32 v103, v103, v221, vcc
	v_cndmask_b32_e32 v104, v104, v222, vcc
	v_cndmask_b32_e32 v105, v105, v223, vcc
	global_store_dwordx4 v[140:141], v[102:105], off
	global_store_dwordx4 v[142:143], v[70:73], off
	s_waitcnt vmcnt(28)
; DEVI float blo(unsigned u) { return __uint_as_float(u << 16); }
; DEVI float bhi(unsigned u) { return __uint_as_float(u & 0xffff0000u); }
;     ...
;         if (EPI == EPI_RESID || EPI == EPI_RESID_ATOMIC) {
;           f32x4 x = a;
;           if (EPI == EPI_RESID || kpart == 0) {
;             const u32x2 xr = *(const u32x2*)((const u16*)(p.ws + WS_XB) + (size_t)row * 1024 + col);
;             x[0] += ALPHA * blo(xr[0]); x[1] += ALPHA * bhi(xr[0]); x[2] += ALPHA * blo(xr[1]); x[3] += ALPHA * bhi(xr[1]);
;           }
;           if (EPI == EPI_RESID) *(f32x4*)((float*)(p.ws + WS_XF) + (size_t)row * 1024 + col) = x;
;           else *(f32x4*)((float*)(p.ws + WS_SLAB) + ((size_t)kpart * 512 + (row - T_P)) * 1024 + col) = x;
	v_permlane16_swap_b32_e32 v204, v206
	v_permlane16_swap_b32_e32 v205, v207
	v_lshlrev_b32_e32 v216, 16, v204
	v_and_b32_e32 v204, 0xffff0000, v204
	v_lshlrev_b32_e32 v217, 16, v205
	v_and_b32_e32 v205, 0xffff0000, v205
	v_fmac_f32_e32 v38, s45, v216
	v_fmac_f32_e32 v39, s45, v204
	v_fmac_f32_e32 v40, s45, v217
	v_fmac_f32_e32 v41, s45, v205
	v_lshlrev_b32_e32 v216, 16, v206
	v_and_b32_e32 v206, 0xffff0000, v206
	v_lshlrev_b32_e32 v217, 16, v207
	v_and_b32_e32 v207, 0xffff0000, v207
	v_fmac_f32_e32 v6, s45, v216
	v_fmac_f32_e32 v7, s45, v206
	v_fmac_f32_e32 v8, s45, v217
	v_fmac_f32_e32 v9, s45, v207
	v_mov_b32_dpp v220, v6 quad_perm:[1,0,3,2] row_mask:0xf bank_mask:0xf
	v_mov_b32_dpp v221, v7 quad_perm:[1,0,3,2] row_mask:0xf bank_mask:0xf
	v_mov_b32_dpp v222, v8 quad_perm:[1,0,3,2] row_mask:0xf bank_mask:0xf
	v_mov_b32_dpp v223, v9 quad_perm:[1,0,3,2] row_mask:0xf bank_mask:0xf
	v_mov_b32_dpp v224, v38 quad_perm:[1,0,3,2] row_mask:0xf bank_mask:0xf
	v_mov_b32_dpp v225, v39 quad_perm:[1,0,3,2] row_mask:0xf bank_mask:0xf
	v_mov_b32_dpp v226, v40 quad_perm:[1,0,3,2] row_mask:0xf bank_mask:0xf
	v_mov_b32_dpp v227, v41 quad_perm:[1,0,3,2] row_mask:0xf bank_mask:0xf
	v_cndmask_b32_e32 v6, v224, v6, vcc
	v_cndmask_b32_e32 v7, v225, v7, vcc
	v_cndmask_b32_e32 v8, v226, v8, vcc
	v_cndmask_b32_e32 v9, v227, v9, vcc
	v_cndmask_b32_e32 v38, v38, v220, vcc
	v_cndmask_b32_e32 v39, v39, v221, vcc
	v_cndmask_b32_e32 v40, v40, v222, vcc
	v_cndmask_b32_e32 v41, v41, v223, vcc
	global_store_dwordx4 v[140:141], v[38:41], off offset:128
	global_store_dwordx4 v[142:143], v[6:9], off offset:128
	v_lshl_add_u64 v[140:141], v[140:141], 0, s[10:11]
	v_lshl_add_u64 v[142:143], v[142:143], 0, s[10:11]
	s_waitcnt vmcnt(29)
	v_permlane16_swap_b32_e32 v208, v210
	v_permlane16_swap_b32_e32 v209, v211
	v_lshlrev_b32_e32 v216, 16, v208
	v_and_b32_e32 v208, 0xffff0000, v208
	v_lshlrev_b32_e32 v217, 16, v209
	v_and_b32_e32 v209, 0xffff0000, v209
	v_fmac_f32_e32 v98, s45, v216
	v_fmac_f32_e32 v99, s45, v208
	v_fmac_f32_e32 v100, s45, v217
	v_fmac_f32_e32 v101, s45, v209
	v_lshlrev_b32_e32 v216, 16, v210
	v_and_b32_e32 v210, 0xffff0000, v210
	v_lshlrev_b32_e32 v217, 16, v211
	v_and_b32_e32 v211, 0xffff0000, v211
	v_fmac_f32_e32 v66, s45, v216
	v_fmac_f32_e32 v67, s45, v210
	v_fmac_f32_e32 v68, s45, v217
	v_fmac_f32_e32 v69, s45, v211
	v_mov_b32_dpp v220, v66 quad_perm:[1,0,3,2] row_mask:0xf bank_mask:0xf
	v_mov_b32_dpp v221, v67 quad_perm:[1,0,3,2] row_mask:0xf bank_mask:0xf
	v_mov_b32_dpp v222, v68 quad_perm:[1,0,3,2] row_mask:0xf bank_mask:0xf
	v_mov_b32_dpp v223, v69 quad_perm:[1,0,3,2] row_mask:0xf bank_mask:0xf
	v_mov_b32_dpp v224, v98 quad_perm:[1,0,3,2] row_mask:0xf bank_mask:0xf
	v_mov_b32_dpp v225, v99 quad_perm:[1,0,3,2] row_mask:0xf bank_mask:0xf
	v_mov_b32_dpp v226, v100 quad_perm:[1,0,3,2] row_mask:0xf bank_mask:0xf
	v_mov_b32_dpp v227, v101 quad_perm:[1,0,3,2] row_mask:0xf bank_mask:0xf
	v_cndmask_b32_e32 v66, v224, v66, vcc
	v_cndmask_b32_e32 v67, v225, v67, vcc
	v_cndmask_b32_e32 v68, v226, v68, vcc
	v_cndmask_b32_e32 v69, v227, v69, vcc
	v_cndmask_b32_e32 v98, v98, v220, vcc
	v_cndmask_b32_e32 v99, v99, v221, vcc
	v_cndmask_b32_e32 v100, v100, v222, vcc
	v_cndmask_b32_e32 v101, v101, v223, vcc
	global_store_dwordx4 v[140:141], v[98:101], off
	global_store_dwordx4 v[142:143], v[66:69], off
	s_waitcnt vmcnt(30)
	v_permlane16_swap_b32_e32 v212, v214
	v_permlane16_swap_b32_e32 v213, v215
	v_lshlrev_b32_e32 v216, 16, v212
	v_and_b32_e32 v212, 0xffff0000, v212
	v_lshlrev_b32_e32 v217, 16, v213
	v_and_b32_e32 v213, 0xffff0000, v213
	v_fmac_f32_e32 v34, s45, v216
	v_fmac_f32_e32 v35, s45, v212
	v_fmac_f32_e32 v36, s45, v217
	v_fmac_f32_e32 v37, s45, v213
	v_lshlrev_b32_e32 v216, 16, v214
	v_and_b32_e32 v214, 0xffff0000, v214
	v_lshlrev_b32_e32 v217, 16, v215
	v_and_b32_e32 v215, 0xffff0000, v215
	v_fmac_f32_e32 v2, s45, v216
	v_fmac_f32_e32 v3, s45, v214
	v_fmac_f32_e32 v4, s45, v217
	v_fmac_f32_e32 v5, s45, v215
	v_mov_b32_dpp v220, v2 quad_perm:[1,0,3,2] row_mask:0xf bank_mask:0xf
	v_mov_b32_dpp v221, v3 quad_perm:[1,0,3,2] row_mask:0xf bank_mask:0xf
	v_mov_b32_dpp v222, v4 quad_perm:[1,0,3,2] row_mask:0xf bank_mask:0xf
	v_mov_b32_dpp v223, v5 quad_perm:[1,0,3,2] row_mask:0xf bank_mask:0xf
	v_mov_b32_dpp v224, v34 quad_perm:[1,0,3,2] row_mask:0xf bank_mask:0xf
	v_mov_b32_dpp v225, v35 quad_perm:[1,0,3,2] row_mask:0xf bank_mask:0xf
	v_mov_b32_dpp v226, v36 quad_perm:[1,0,3,2] row_mask:0xf bank_mask:0xf
	v_mov_b32_dpp v227, v37 quad_perm:[1,0,3,2] row_mask:0xf bank_mask:0xf
	v_cndmask_b32_e32 v2, v224, v2, vcc
	v_cndmask_b32_e32 v3, v225, v3, vcc
	v_cndmask_b32_e32 v4, v226, v4, vcc
	v_cndmask_b32_e32 v5, v227, v5, vcc
	v_cndmask_b32_e32 v34, v34, v220, vcc
	v_cndmask_b32_e32 v35, v35, v221, vcc
	v_cndmask_b32_e32 v36, v36, v222, vcc
	v_cndmask_b32_e32 v37, v37, v223, vcc
	global_store_dwordx4 v[140:141], v[34:37], off offset:128
	global_store_dwordx4 v[142:143], v[2:5], off offset:128
	v_readlane_b32 s40, v250, 7
	s_cmpk_lg_u32 s40, 0x200
	s_cbranch_scc1 .LBB0_757
	v_readlane_b32 s41, v250, 0
	s_lshr_b32 s42, s41, 3
	s_and_b32 s41, s41, 7
	s_mul_i32 s41, s41, 16
	s_add_i32 s41, s41, s42
	s_cmp_lt_u32 s42, 16
	s_movk_i32 s39, 0x4000
	s_branch .LBB0_757

;     ...
;   for (int kt = 0; kt < nk; kt++) {
;     if (kt + 1 < nk) asm volatile("s_waitcnt vmcnt(6)" ::: "memory");
;     else asm volatile("s_waitcnt vmcnt(0)" ::: "memory");
;     __builtin_amdgcn_s_barrier();
;     asm volatile("" ::: "memory");
;     if (kt + 2 < nk) G2_STAGE(kt + 2);
;     const char* cS = smem + (kt % 3) * 24576;
;     bf16x8 xa[8], wb[4];
; #pragma unroll
;     for (int f = 0; f < 8; f++) xa[f] = *(const bf16x8*)(cS + aoff + f * 1024);
; #pragma unroll
;     for (int f = 0; f < 4; f++) wb[f] = *(const bf16x8*)(cS + boff + f * 1024);
; #pragma unroll
;     for (int nf = 0; nf < 4; nf++)
; #pragma unroll
;       for (int mf = 0; mf < 8; mf++)
;         acc[nf][mf] = __builtin_amdgcn_mfma_f32_16x16x32_bf16(wb[nf], xa[mf], acc[nf][mf], 0, 0, 0);
;   }
.Lt0_loop:
	.p2align 3
	s_waitcnt vmcnt(6) lgkmcnt(0)
	s_barrier
	s_setprio 1
	v_add_u32_e32 v144, s38, v136
	v_mfma_f32_16x16x32_bf16 v[126:129], v[184:187], v[146:149], v[126:129]
	ds_read_b128 v[200:203], v144 offset:0
	v_mfma_f32_16x16x32_bf16 v[122:125], v[184:187], v[152:155], v[122:125]
	ds_read_b128 v[204:207], v144 offset:1024
	v_mfma_f32_16x16x32_bf16 v[118:121], v[184:187], v[156:159], v[118:121]
	ds_read_b128 v[208:211], v144 offset:2048
	v_mfma_f32_16x16x32_bf16 v[114:117], v[184:187], v[162:165], v[114:117]
	ds_read_b128 v[212:215], v144 offset:3072
	v_mfma_f32_16x16x32_bf16 v[110:113], v[184:187], v[166:169], v[110:113]
	ds_read_b128 v[216:219], v144 offset:4096
	v_mfma_f32_16x16x32_bf16 v[106:109], v[184:187], v[170:173], v[106:109]
	ds_read_b128 v[220:223], v144 offset:5120
	v_mfma_f32_16x16x32_bf16 v[102:105], v[184:187], v[176:179], v[102:105]
	ds_read_b128 v[224:227], v144 offset:6144
	v_mfma_f32_16x16x32_bf16 v[98:101], v[184:187], v[180:183], v[98:101]
	ds_read_b128 v[228:231], v144 offset:7168
	v_mfma_f32_16x16x32_bf16 v[94:97], v[188:191], v[146:149], v[94:97]
	v_add_u32_e64 v144, s38, v137
	v_mfma_f32_16x16x32_bf16 v[90:93], v[188:191], v[152:155], v[90:93]
	v_mfma_f32_16x16x32_bf16 v[86:89], v[188:191], v[156:159], v[86:89]
	ds_read_b128 v[232:235], v144 offset:16384
	v_mfma_f32_16x16x32_bf16 v[82:85], v[188:191], v[162:165], v[82:85]
	ds_read_b128 v[236:239], v144 offset:17408
	v_mfma_f32_16x16x32_bf16 v[78:81], v[188:191], v[166:169], v[78:81]
	ds_read_b128 v[240:243], v144 offset:18432
	v_mfma_f32_16x16x32_bf16 v[74:77], v[188:191], v[170:173], v[74:77]
	ds_read_b128 v[244:247], v144 offset:19456
	v_mfma_f32_16x16x32_bf16 v[70:73], v[188:191], v[176:179], v[70:73]
	s_add_i32 s40, s44, s39
	s_mov_b32 m0, s40
	v_lshl_add_u64 v[142:143], v[132:133], 0, s[2:3]
	v_mfma_f32_16x16x32_bf16 v[66:69], v[188:191], v[180:183], v[66:69]
	global_load_lds_dwordx4 v[132:133], off
	s_add_i32 m0, m0, 0x1000
	v_mfma_f32_16x16x32_bf16 v[62:65], v[192:195], v[146:149], v[62:65]
	v_mfma_f32_16x16x32_bf16 v[58:61], v[192:195], v[152:155], v[58:61]
	v_mfma_f32_16x16x32_bf16 v[54:57], v[192:195], v[156:159], v[54:57]
	global_load_lds_dwordx4 v[142:143], off
	v_lshl_add_u64 v[142:143], v[142:143], 0, s[2:3]
	s_add_i32 m0, m0, 0x1000
	v_mfma_f32_16x16x32_bf16 v[50:53], v[192:195], v[162:165], v[50:53]
	v_mfma_f32_16x16x32_bf16 v[46:49], v[192:195], v[166:169], v[46:49]
	s_setprio 0
	s_nop 0
	v_mfma_f32_16x16x32_bf16 v[42:45], v[192:195], v[170:173], v[42:45]
	global_load_lds_dwordx4 v[142:143], off
	v_lshl_add_u64 v[142:143], v[142:143], 0, s[2:3]
	s_add_i32 m0, m0, 0x1000
	v_mfma_f32_16x16x32_bf16 v[38:41], v[192:195], v[176:179], v[38:41]
	v_mfma_f32_16x16x32_bf16 v[34:37], v[192:195], v[180:183], v[34:37]
	v_mfma_f32_16x16x32_bf16 v[30:33], v[196:199], v[146:149], v[30:33]
	global_load_lds_dwordx4 v[142:143], off
	s_add_i32 m0, m0, 0x1000
	v_lshl_add_u64 v[142:143], v[134:135], 0, s[2:3]
	v_mfma_f32_16x16x32_bf16 v[26:29], v[196:199], v[152:155], v[26:29]
	v_mfma_f32_16x16x32_bf16 v[22:25], v[196:199], v[156:159], v[22:25]
	v_mfma_f32_16x16x32_bf16 v[18:21], v[196:199], v[162:165], v[18:21]
	global_load_lds_dwordx4 v[134:135], off
	s_add_i32 m0, m0, 0x1000
	v_lshl_add_u64 v[132:133], v[132:133], 0, s[36:37]
	v_mfma_f32_16x16x32_bf16 v[14:17], v[196:199], v[166:169], v[14:17]
	v_mfma_f32_16x16x32_bf16 v[10:13], v[196:199], v[170:173], v[10:13]
	v_mfma_f32_16x16x32_bf16 v[6:9], v[196:199], v[176:179], v[6:9]
	global_load_lds_dwordx4 v[142:143], off
	v_lshl_add_u64 v[134:135], v[134:135], 0, s[8:9]
	v_mfma_f32_16x16x32_bf16 v[2:5], v[196:199], v[180:183], v[2:5]
	s_mov_b32 s39, s38
	s_nop 0
	s_add_i32 s38, s38, 0x6000
	s_cmp_eq_u32 s38, 0x12000
	s_cselect_b32 s38, 0, s38
	s_nop 0
	.p2align 3
	s_waitcnt vmcnt(6) lgkmcnt(0)
	s_barrier
	s_setprio 1
	v_add_u32_e32 v144, s38, v136
	v_mfma_f32_16x16x32_bf16 v[126:129], v[232:235], v[200:203], v[126:129]
	ds_read_b128 v[146:149], v144 offset:0
	v_mfma_f32_16x16x32_bf16 v[122:125], v[232:235], v[204:207], v[122:125]
	ds_read_b128 v[152:155], v144 offset:1024
	v_mfma_f32_16x16x32_bf16 v[118:121], v[232:235], v[208:211], v[118:121]
	ds_read_b128 v[156:159], v144 offset:2048
	v_mfma_f32_16x16x32_bf16 v[114:117], v[232:235], v[212:215], v[114:117]
	ds_read_b128 v[162:165], v144 offset:3072
	v_mfma_f32_16x16x32_bf16 v[110:113], v[232:235], v[216:219], v[110:113]
	ds_read_b128 v[166:169], v144 offset:4096
	v_mfma_f32_16x16x32_bf16 v[106:109], v[232:235], v[220:223], v[106:109]
	ds_read_b128 v[170:173], v144 offset:5120
	v_mfma_f32_16x16x32_bf16 v[102:105], v[232:235], v[224:227], v[102:105]
	ds_read_b128 v[176:179], v144 offset:6144
	v_mfma_f32_16x16x32_bf16 v[98:101], v[232:235], v[228:231], v[98:101]
	ds_read_b128 v[180:183], v144 offset:7168
	v_mfma_f32_16x16x32_bf16 v[94:97], v[236:239], v[200:203], v[94:97]
	v_add_u32_e64 v144, s38, v137
	v_mfma_f32_16x16x32_bf16 v[90:93], v[236:239], v[204:207], v[90:93]
	v_mfma_f32_16x16x32_bf16 v[86:89], v[236:239], v[208:211], v[86:89]
	ds_read_b128 v[184:187], v144 offset:16384
	v_mfma_f32_16x16x32_bf16 v[82:85], v[236:239], v[212:215], v[82:85]
	ds_read_b128 v[188:191], v144 offset:17408
	v_mfma_f32_16x16x32_bf16 v[78:81], v[236:239], v[216:219], v[78:81]
	ds_read_b128 v[192:195], v144 offset:18432
	v_mfma_f32_16x16x32_bf16 v[74:77], v[236:239], v[220:223], v[74:77]
	ds_read_b128 v[196:199], v144 offset:19456
	v_mfma_f32_16x16x32_bf16 v[70:73], v[236:239], v[224:227], v[70:73]
	s_add_i32 s40, s44, s39
	s_mov_b32 m0, s40
	v_lshl_add_u64 v[142:143], v[132:133], 0, s[2:3]
	v_mfma_f32_16x16x32_bf16 v[66:69], v[236:239], v[228:231], v[66:69]
;     ...
;   for (int kt = 0; kt < nk; kt++) {
;     if (kt + 1 < nk) asm volatile("s_waitcnt vmcnt(6)" ::: "memory");
;     else asm volatile("s_waitcnt vmcnt(0)" ::: "memory");
;     __builtin_amdgcn_s_barrier();
;     asm volatile("" ::: "memory");
;     if (kt + 2 < nk) G2_STAGE(kt + 2);
;     const char* cS = smem + (kt % 3) * 24576;
;     bf16x8 xa[8], wb[4];
; #pragma unroll
;     for (int f = 0; f < 8; f++) xa[f] = *(const bf16x8*)(cS + aoff + f * 1024);
; #pragma unroll
;     for (int f = 0; f < 4; f++) wb[f] = *(const bf16x8*)(cS + boff + f * 1024);
; #pragma unroll
;     for (int nf = 0; nf < 4; nf++)
; #pragma unroll
;       for (int mf = 0; mf < 8; mf++)
;         acc[nf][mf] = __builtin_amdgcn_mfma_f32_16x16x32_bf16(wb[nf], xa[mf], acc[nf][mf], 0, 0, 0);
;   }
	global_load_lds_dwordx4 v[132:133], off
	s_add_i32 m0, m0, 0x1000
	v_mfma_f32_16x16x32_bf16 v[62:65], v[240:243], v[200:203], v[62:65]
	v_mfma_f32_16x16x32_bf16 v[58:61], v[240:243], v[204:207], v[58:61]
	v_mfma_f32_16x16x32_bf16 v[54:57], v[240:243], v[208:211], v[54:57]
	global_load_lds_dwordx4 v[142:143], off
	v_lshl_add_u64 v[142:143], v[142:143], 0, s[2:3]
	s_add_i32 m0, m0, 0x1000
	v_mfma_f32_16x16x32_bf16 v[50:53], v[240:243], v[212:215], v[50:53]
	v_mfma_f32_16x16x32_bf16 v[46:49], v[240:243], v[216:219], v[46:49]
	s_setprio 0
	s_nop 0
	v_mfma_f32_16x16x32_bf16 v[42:45], v[240:243], v[220:223], v[42:45]
	global_load_lds_dwordx4 v[142:143], off
	v_lshl_add_u64 v[142:143], v[142:143], 0, s[2:3]
	s_add_i32 m0, m0, 0x1000
	v_mfma_f32_16x16x32_bf16 v[38:41], v[240:243], v[224:227], v[38:41]
	v_mfma_f32_16x16x32_bf16 v[34:37], v[240:243], v[228:231], v[34:37]
	v_mfma_f32_16x16x32_bf16 v[30:33], v[244:247], v[200:203], v[30:33]
	global_load_lds_dwordx4 v[142:143], off
	s_add_i32 m0, m0, 0x1000
	v_lshl_add_u64 v[142:143], v[134:135], 0, s[2:3]
	v_mfma_f32_16x16x32_bf16 v[26:29], v[244:247], v[204:207], v[26:29]
	v_mfma_f32_16x16x32_bf16 v[22:25], v[244:247], v[208:211], v[22:25]
	v_mfma_f32_16x16x32_bf16 v[18:21], v[244:247], v[212:215], v[18:21]
	global_load_lds_dwordx4 v[134:135], off
	s_add_i32 m0, m0, 0x1000
	v_lshl_add_u64 v[132:133], v[132:133], 0, s[36:37]
	v_mfma_f32_16x16x32_bf16 v[14:17], v[244:247], v[216:219], v[14:17]
	v_mfma_f32_16x16x32_bf16 v[10:13], v[244:247], v[220:223], v[10:13]
	v_mfma_f32_16x16x32_bf16 v[6:9], v[244:247], v[224:227], v[6:9]
	global_load_lds_dwordx4 v[142:143], off
	v_lshl_add_u64 v[134:135], v[134:135], 0, s[8:9]
	v_mfma_f32_16x16x32_bf16 v[2:5], v[244:247], v[228:231], v[2:5]
	s_mov_b32 s39, s38
	s_nop 0
	s_add_i32 s38, s38, 0x6000
	s_cmp_eq_u32 s38, 0x12000
	s_cselect_b32 s38, 0, s38
	s_nop 0
	s_sub_i32 s15, s15, 1
	s_cmp_lg_u32 s15, 0
	s_cbranch_scc1 .Lt0_loop
	.p2align 3
	s_waitcnt vmcnt(6) lgkmcnt(0)
	s_barrier
	s_setprio 1
	v_add_u32_e32 v144, s38, v136
	v_mfma_f32_16x16x32_bf16 v[126:129], v[184:187], v[146:149], v[126:129]
	ds_read_b128 v[200:203], v144 offset:0
	v_mfma_f32_16x16x32_bf16 v[122:125], v[184:187], v[152:155], v[122:125]
	ds_read_b128 v[204:207], v144 offset:1024
	v_mfma_f32_16x16x32_bf16 v[118:121], v[184:187], v[156:159], v[118:121]
	ds_read_b128 v[208:211], v144 offset:2048
	v_mfma_f32_16x16x32_bf16 v[114:117], v[184:187], v[162:165], v[114:117]
	ds_read_b128 v[212:215], v144 offset:3072
	v_mfma_f32_16x16x32_bf16 v[110:113], v[184:187], v[166:169], v[110:113]
	ds_read_b128 v[216:219], v144 offset:4096
	v_mfma_f32_16x16x32_bf16 v[106:109], v[184:187], v[170:173], v[106:109]
	ds_read_b128 v[220:223], v144 offset:5120
	v_mfma_f32_16x16x32_bf16 v[102:105], v[184:187], v[176:179], v[102:105]
	ds_read_b128 v[224:227], v144 offset:6144
	v_mfma_f32_16x16x32_bf16 v[98:101], v[184:187], v[180:183], v[98:101]
	ds_read_b128 v[228:231], v144 offset:7168
	v_mfma_f32_16x16x32_bf16 v[94:97], v[188:191], v[146:149], v[94:97]
	v_add_u32_e64 v144, s38, v137
	v_mfma_f32_16x16x32_bf16 v[90:93], v[188:191], v[152:155], v[90:93]
	v_mfma_f32_16x16x32_bf16 v[86:89], v[188:191], v[156:159], v[86:89]
	ds_read_b128 v[232:235], v144 offset:16384
	v_mfma_f32_16x16x32_bf16 v[82:85], v[188:191], v[162:165], v[82:85]
	ds_read_b128 v[236:239], v144 offset:17408
	v_mfma_f32_16x16x32_bf16 v[78:81], v[188:191], v[166:169], v[78:81]
	ds_read_b128 v[240:243], v144 offset:18432
	v_mfma_f32_16x16x32_bf16 v[74:77], v[188:191], v[170:173], v[74:77]
	ds_read_b128 v[244:247], v144 offset:19456
	v_mfma_f32_16x16x32_bf16 v[70:73], v[188:191], v[176:179], v[70:73]
	s_add_i32 s40, s44, s39
	s_mov_b32 m0, s40
	v_lshl_add_u64 v[142:143], v[132:133], 0, s[2:3]
	v_mfma_f32_16x16x32_bf16 v[66:69], v[188:191], v[180:183], v[66:69]
	global_load_lds_dwordx4 v[132:133], off
	s_add_i32 m0, m0, 0x1000
	v_mfma_f32_16x16x32_bf16 v[62:65], v[192:195], v[146:149], v[62:65]
	v_mfma_f32_16x16x32_bf16 v[58:61], v[192:195], v[152:155], v[58:61]
	v_mfma_f32_16x16x32_bf16 v[54:57], v[192:195], v[156:159], v[54:57]
	global_load_lds_dwordx4 v[142:143], off
	v_lshl_add_u64 v[142:143], v[142:143], 0, s[2:3]
	s_add_i32 m0, m0, 0x1000
	v_mfma_f32_16x16x32_bf16 v[50:53], v[192:195], v[162:165], v[50:53]
	v_mfma_f32_16x16x32_bf16 v[46:49], v[192:195], v[166:169], v[46:49]
	s_setprio 0
	s_nop 0
	v_mfma_f32_16x16x32_bf16 v[42:45], v[192:195], v[170:173], v[42:45]
	global_load_lds_dwordx4 v[142:143], off
	v_lshl_add_u64 v[142:143], v[142:143], 0, s[2:3]
	s_add_i32 m0, m0, 0x1000
	v_mfma_f32_16x16x32_bf16 v[38:41], v[192:195], v[176:179], v[38:41]
	v_mfma_f32_16x16x32_bf16 v[34:37], v[192:195], v[180:183], v[34:37]
	v_mfma_f32_16x16x32_bf16 v[30:33], v[196:199], v[146:149], v[30:33]
	global_load_lds_dwordx4 v[142:143], off
	s_add_i32 m0, m0, 0x1000
	v_lshl_add_u64 v[142:143], v[134:135], 0, s[2:3]
	v_mfma_f32_16x16x32_bf16 v[26:29], v[196:199], v[152:155], v[26:29]
	v_mfma_f32_16x16x32_bf16 v[22:25], v[196:199], v[156:159], v[22:25]
	v_mfma_f32_16x16x32_bf16 v[18:21], v[196:199], v[162:165], v[18:21]
	global_load_lds_dwordx4 v[134:135], off
	s_add_i32 m0, m0, 0x1000
	v_lshl_add_u64 v[132:133], v[132:133], 0, s[36:37]
	v_mfma_f32_16x16x32_bf16 v[14:17], v[196:199], v[166:169], v[14:17]
	v_mfma_f32_16x16x32_bf16 v[10:13], v[196:199], v[170:173], v[10:13]
	v_mfma_f32_16x16x32_bf16 v[6:9], v[196:199], v[176:179], v[6:9]
	global_load_lds_dwordx4 v[142:143], off
	v_lshl_add_u64 v[134:135], v[134:135], 0, s[8:9]
	v_mfma_f32_16x16x32_bf16 v[2:5], v[196:199], v[180:183], v[2:5]
	s_mov_b32 s39, s38
	s_nop 0
	s_add_i32 s38, s38, 0x6000
	s_cmp_eq_u32 s38, 0x12000
	s_cselect_b32 s38, 0, s38
	s_nop 0
	.p2align 3
	s_waitcnt vmcnt(6) lgkmcnt(0)
	s_barrier
;     ...
;   for (int kt = 0; kt < nk; kt++) {
;     if (kt + 1 < nk) asm volatile("s_waitcnt vmcnt(6)" ::: "memory");
;     else asm volatile("s_waitcnt vmcnt(0)" ::: "memory");
;     __builtin_amdgcn_s_barrier();
;     asm volatile("" ::: "memory");
;     if (kt + 2 < nk) G2_STAGE(kt + 2);
;     const char* cS = smem + (kt % 3) * 24576;
;     bf16x8 xa[8], wb[4];
; #pragma unroll
;     for (int f = 0; f < 8; f++) xa[f] = *(const bf16x8*)(cS + aoff + f * 1024);
; #pragma unroll
;     for (int f = 0; f < 4; f++) wb[f] = *(const bf16x8*)(cS + boff + f * 1024);
; #pragma unroll
;     for (int nf = 0; nf < 4; nf++)
; #pragma unroll
;       for (int mf = 0; mf < 8; mf++)
;         acc[nf][mf] = __builtin_amdgcn_mfma_f32_16x16x32_bf16(wb[nf], xa[mf], acc[nf][mf], 0, 0, 0);
;   }
	s_setprio 1
	v_add_u32_e32 v144, s38, v136
	v_mfma_f32_16x16x32_bf16 v[126:129], v[232:235], v[200:203], v[126:129]
	ds_read_b128 v[146:149], v144 offset:0
	v_mfma_f32_16x16x32_bf16 v[122:125], v[232:235], v[204:207], v[122:125]
	ds_read_b128 v[152:155], v144 offset:1024
	v_mfma_f32_16x16x32_bf16 v[118:121], v[232:235], v[208:211], v[118:121]
	ds_read_b128 v[156:159], v144 offset:2048
	v_mfma_f32_16x16x32_bf16 v[114:117], v[232:235], v[212:215], v[114:117]
	ds_read_b128 v[162:165], v144 offset:3072
	v_mfma_f32_16x16x32_bf16 v[110:113], v[232:235], v[216:219], v[110:113]
	ds_read_b128 v[166:169], v144 offset:4096
	v_mfma_f32_16x16x32_bf16 v[106:109], v[232:235], v[220:223], v[106:109]
	ds_read_b128 v[170:173], v144 offset:5120
	v_mfma_f32_16x16x32_bf16 v[102:105], v[232:235], v[224:227], v[102:105]
	ds_read_b128 v[176:179], v144 offset:6144
	v_mfma_f32_16x16x32_bf16 v[98:101], v[232:235], v[228:231], v[98:101]
	ds_read_b128 v[180:183], v144 offset:7168
	v_mfma_f32_16x16x32_bf16 v[94:97], v[236:239], v[200:203], v[94:97]
	v_add_u32_e64 v144, s38, v137
	v_mfma_f32_16x16x32_bf16 v[90:93], v[236:239], v[204:207], v[90:93]
	v_mfma_f32_16x16x32_bf16 v[86:89], v[236:239], v[208:211], v[86:89]
	ds_read_b128 v[184:187], v144 offset:16384
	v_mfma_f32_16x16x32_bf16 v[82:85], v[236:239], v[212:215], v[82:85]
	ds_read_b128 v[188:191], v144 offset:17408
	v_mfma_f32_16x16x32_bf16 v[78:81], v[236:239], v[216:219], v[78:81]
	ds_read_b128 v[192:195], v144 offset:18432
	v_mfma_f32_16x16x32_bf16 v[74:77], v[236:239], v[220:223], v[74:77]
	ds_read_b128 v[196:199], v144 offset:19456
	v_mfma_f32_16x16x32_bf16 v[70:73], v[236:239], v[224:227], v[70:73]
	v_mfma_f32_16x16x32_bf16 v[66:69], v[236:239], v[228:231], v[66:69]
	v_mfma_f32_16x16x32_bf16 v[62:65], v[240:243], v[200:203], v[62:65]
	v_mfma_f32_16x16x32_bf16 v[58:61], v[240:243], v[204:207], v[58:61]
	v_mfma_f32_16x16x32_bf16 v[54:57], v[240:243], v[208:211], v[54:57]
	v_mfma_f32_16x16x32_bf16 v[50:53], v[240:243], v[212:215], v[50:53]
	v_mfma_f32_16x16x32_bf16 v[46:49], v[240:243], v[216:219], v[46:49]
	s_setprio 0
	s_nop 0
	v_mfma_f32_16x16x32_bf16 v[42:45], v[240:243], v[220:223], v[42:45]
	v_mfma_f32_16x16x32_bf16 v[38:41], v[240:243], v[224:227], v[38:41]
	v_mfma_f32_16x16x32_bf16 v[34:37], v[240:243], v[228:231], v[34:37]
	v_mfma_f32_16x16x32_bf16 v[30:33], v[244:247], v[200:203], v[30:33]
	v_mfma_f32_16x16x32_bf16 v[26:29], v[244:247], v[204:207], v[26:29]
	v_mfma_f32_16x16x32_bf16 v[22:25], v[244:247], v[208:211], v[22:25]
	v_mfma_f32_16x16x32_bf16 v[18:21], v[244:247], v[212:215], v[18:21]
	v_mfma_f32_16x16x32_bf16 v[14:17], v[244:247], v[216:219], v[14:17]
	v_mfma_f32_16x16x32_bf16 v[10:13], v[244:247], v[220:223], v[10:13]
	v_mfma_f32_16x16x32_bf16 v[6:9], v[244:247], v[224:227], v[6:9]
	v_mfma_f32_16x16x32_bf16 v[2:5], v[244:247], v[228:231], v[2:5]
	s_mov_b32 s39, s38
	s_nop 0
	s_add_i32 s38, s38, 0x6000
	s_cmp_eq_u32 s38, 0x12000
	s_cselect_b32 s38, 0, s38
	s_nop 0
	.p2align 3
	s_waitcnt vmcnt(0) lgkmcnt(0)
	s_barrier
	s_setprio 1
	v_add_u32_e32 v144, s38, v136
	v_mfma_f32_16x16x32_bf16 v[126:129], v[184:187], v[146:149], v[126:129]
	ds_read_b128 v[200:203], v144 offset:0
	v_mfma_f32_16x16x32_bf16 v[122:125], v[184:187], v[152:155], v[122:125]
	ds_read_b128 v[204:207], v144 offset:1024
	v_mfma_f32_16x16x32_bf16 v[118:121], v[184:187], v[156:159], v[118:121]
	ds_read_b128 v[208:211], v144 offset:2048
	v_mfma_f32_16x16x32_bf16 v[114:117], v[184:187], v[162:165], v[114:117]
	ds_read_b128 v[212:215], v144 offset:3072
	v_mfma_f32_16x16x32_bf16 v[110:113], v[184:187], v[166:169], v[110:113]
	ds_read_b128 v[216:219], v144 offset:4096
	v_mfma_f32_16x16x32_bf16 v[106:109], v[184:187], v[170:173], v[106:109]
	ds_read_b128 v[220:223], v144 offset:5120
	v_mfma_f32_16x16x32_bf16 v[102:105], v[184:187], v[176:179], v[102:105]
	ds_read_b128 v[224:227], v144 offset:6144
	v_mfma_f32_16x16x32_bf16 v[98:101], v[184:187], v[180:183], v[98:101]
	ds_read_b128 v[228:231], v144 offset:7168
	v_mfma_f32_16x16x32_bf16 v[94:97], v[188:191], v[146:149], v[94:97]
	v_add_u32_e64 v144, s38, v137
	v_mfma_f32_16x16x32_bf16 v[90:93], v[188:191], v[152:155], v[90:93]
	v_mfma_f32_16x16x32_bf16 v[86:89], v[188:191], v[156:159], v[86:89]
	ds_read_b128 v[232:235], v144 offset:16384
	v_mfma_f32_16x16x32_bf16 v[82:85], v[188:191], v[162:165], v[82:85]
	ds_read_b128 v[236:239], v144 offset:17408
	v_mfma_f32_16x16x32_bf16 v[78:81], v[188:191], v[166:169], v[78:81]
	ds_read_b128 v[240:243], v144 offset:18432
	v_mfma_f32_16x16x32_bf16 v[74:77], v[188:191], v[170:173], v[74:77]
	ds_read_b128 v[244:247], v144 offset:19456
	v_mfma_f32_16x16x32_bf16 v[70:73], v[188:191], v[176:179], v[70:73]
	v_mfma_f32_16x16x32_bf16 v[66:69], v[188:191], v[180:183], v[66:69]
	v_mfma_f32_16x16x32_bf16 v[62:65], v[192:195], v[146:149], v[62:65]
	v_mfma_f32_16x16x32_bf16 v[58:61], v[192:195], v[152:155], v[58:61]
	v_mfma_f32_16x16x32_bf16 v[54:57], v[192:195], v[156:159], v[54:57]
	v_mfma_f32_16x16x32_bf16 v[50:53], v[192:195], v[162:165], v[50:53]
	v_mfma_f32_16x16x32_bf16 v[46:49], v[192:195], v[166:169], v[46:49]
	s_setprio 0
	s_nop 0
	v_mfma_f32_16x16x32_bf16 v[42:45], v[192:195], v[170:173], v[42:45]
	v_mfma_f32_16x16x32_bf16 v[38:41], v[192:195], v[176:179], v[38:41]
	v_mfma_f32_16x16x32_bf16 v[34:37], v[192:195], v[180:183], v[34:37]
	v_mfma_f32_16x16x32_bf16 v[30:33], v[196:199], v[146:149], v[30:33]
	v_mfma_f32_16x16x32_bf16 v[26:29], v[196:199], v[152:155], v[26:29]
	v_mfma_f32_16x16x32_bf16 v[22:25], v[196:199], v[156:159], v[22:25]
	v_mfma_f32_16x16x32_bf16 v[18:21], v[196:199], v[162:165], v[18:21]
	v_mfma_f32_16x16x32_bf16 v[14:17], v[196:199], v[166:169], v[14:17]
	v_mfma_f32_16x16x32_bf16 v[10:13], v[196:199], v[170:173], v[10:13]
	v_mfma_f32_16x16x32_bf16 v[6:9], v[196:199], v[176:179], v[6:9]
	v_mfma_f32_16x16x32_bf16 v[2:5], v[196:199], v[180:183], v[2:5]
	s_mov_b32 s39, s38
	s_nop 0
	s_add_i32 s38, s38, 0x6000
	s_cmp_eq_u32 s38, 0x12000
	s_cselect_b32 s38, 0, s38
	s_nop 0
	.p2align 3
	s_waitcnt lgkmcnt(0)
; DEVI unsigned pack2(float a, float b) { return __builtin_bit_cast(unsigned, __builtin_convertvector((f32x2_t){a, b}, bf16x2_t)); }
; DEVI float blo(unsigned u) { return __uint_as_float(u << 16); }
; DEVI float bhi(unsigned u) { return __uint_as_float(u & 0xffff0000u); }
;     ...
; #pragma unroll
;     for (int nf = 0; nf < 4; nf++)
; #pragma unroll
;       for (int mf = 0; mf < 8; mf++)
;         acc[nf][mf] = __builtin_amdgcn_mfma_f32_16x16x32_bf16(wb[nf], xa[mf], acc[nf][mf], 0, 0, 0);
;     ...
; #pragma unroll
;       for (int nf = 0; nf < 4; nf++) {
;         const int col = n0 + wn * 64 + nf * 16 + quad * 4;
;         f32x4 a = acc[nf][mf];
;         if (EPI == EPI_RESID || EPI == EPI_RESID_ATOMIC) {
;           f32x4 x = a;
;           if (EPI == EPI_RESID || kpart == 0) {
;             const u32x2 xr = *(const u32x2*)((const u16*)(p.ws + WS_XB) + (size_t)row * 1024 + col);
;             x[0] += ALPHA * blo(xr[0]); x[1] += ALPHA * bhi(xr[0]); x[2] += ALPHA * blo(xr[1]); x[3] += ALPHA * bhi(xr[1]);
;           }
;           if (EPI == EPI_RESID) *(f32x4*)((float*)(p.ws + WS_XF) + (size_t)row * 1024 + col) = x;
;           else *(f32x4*)((float*)(p.ws + WS_SLAB) + ((size_t)kpart * 512 + (row - T_P)) * 1024 + col) = x;
;         } else {
;           u32x2 pk; pk[0] = pack2(a[0], a[1]); pk[1] = pack2(a[2], a[3]);
;           *(u32x2*)(outb + (size_t)row * ldc + col) = pk;
;         }
	s_nop 0
	v_mfma_f32_16x16x32_bf16 v[126:129], v[232:235], v[200:203], v[126:129]
	v_mfma_f32_16x16x32_bf16 v[122:125], v[232:235], v[204:207], v[122:125]
	v_mfma_f32_16x16x32_bf16 v[118:121], v[232:235], v[208:211], v[118:121]
	v_mfma_f32_16x16x32_bf16 v[114:117], v[232:235], v[212:215], v[114:117]
	v_mfma_f32_16x16x32_bf16 v[110:113], v[232:235], v[216:219], v[110:113]
	v_mfma_f32_16x16x32_bf16 v[106:109], v[232:235], v[220:223], v[106:109]
	v_mfma_f32_16x16x32_bf16 v[102:105], v[232:235], v[224:227], v[102:105]
	v_mfma_f32_16x16x32_bf16 v[98:101], v[232:235], v[228:231], v[98:101]
	v_mfma_f32_16x16x32_bf16 v[94:97], v[236:239], v[200:203], v[94:97]
	v_mfma_f32_16x16x32_bf16 v[90:93], v[236:239], v[204:207], v[90:93]
	v_mfma_f32_16x16x32_bf16 v[86:89], v[236:239], v[208:211], v[86:89]
	v_mfma_f32_16x16x32_bf16 v[82:85], v[236:239], v[212:215], v[82:85]
	v_mfma_f32_16x16x32_bf16 v[78:81], v[236:239], v[216:219], v[78:81]
	v_mfma_f32_16x16x32_bf16 v[74:77], v[236:239], v[220:223], v[74:77]
	v_mfma_f32_16x16x32_bf16 v[70:73], v[236:239], v[224:227], v[70:73]
	v_mfma_f32_16x16x32_bf16 v[66:69], v[236:239], v[228:231], v[66:69]
	v_mfma_f32_16x16x32_bf16 v[62:65], v[240:243], v[200:203], v[62:65]
	v_mfma_f32_16x16x32_bf16 v[58:61], v[240:243], v[204:207], v[58:61]
	v_mfma_f32_16x16x32_bf16 v[54:57], v[240:243], v[208:211], v[54:57]
	v_mfma_f32_16x16x32_bf16 v[50:53], v[240:243], v[212:215], v[50:53]
	v_mfma_f32_16x16x32_bf16 v[46:49], v[240:243], v[216:219], v[46:49]
	v_mfma_f32_16x16x32_bf16 v[42:45], v[240:243], v[220:223], v[42:45]
	v_mfma_f32_16x16x32_bf16 v[38:41], v[240:243], v[224:227], v[38:41]
	v_mfma_f32_16x16x32_bf16 v[34:37], v[240:243], v[228:231], v[34:37]
	v_mfma_f32_16x16x32_bf16 v[30:33], v[244:247], v[200:203], v[30:33]
	v_mfma_f32_16x16x32_bf16 v[26:29], v[244:247], v[204:207], v[26:29]
	v_mfma_f32_16x16x32_bf16 v[22:25], v[244:247], v[208:211], v[22:25]
	v_mfma_f32_16x16x32_bf16 v[18:21], v[244:247], v[212:215], v[18:21]
	v_mfma_f32_16x16x32_bf16 v[14:17], v[244:247], v[216:219], v[14:17]
	v_mfma_f32_16x16x32_bf16 v[10:13], v[244:247], v[220:223], v[10:13]
	v_mfma_f32_16x16x32_bf16 v[6:9], v[244:247], v[224:227], v[6:9]
	v_mfma_f32_16x16x32_bf16 v[2:5], v[244:247], v[228:231], v[2:5]
	s_mov_b32 m0, s41
	s_mov_b32 s8, 0x14000
	s_mov_b32 s9, 0
	s_nop 7
	v_and_b32_e32 v228, 1, v145
	v_cmp_ne_u32_e32 vcc, 0, v228
	v_mov_b32_e32 v229, 0xffffec40
	v_cndmask_b32_e32 v230, 0, v229, vcc
	v_ashrrev_i32_e32 v231, 31, v230
	v_lshl_add_u64 v[140:141], v[140:141], 0, v[230:231]
	v_add_co_u32_e32 v142, vcc, 0x1400, v140
	s_nop 0
	v_addc_co_u32_e32 v143, vcc, 0, v141, vcc
	v_cmp_ne_u32_e32 vcc, 0, v228
	v_cvt_pk_bf16_f32 v126, v126, v127
	v_cvt_pk_bf16_f32 v127, v128, v129
	v_cvt_pk_bf16_f32 v128, v94, v95
	v_cvt_pk_bf16_f32 v129, v96, v97
	v_cvt_pk_bf16_f32 v62, v62, v63
	v_cvt_pk_bf16_f32 v63, v64, v65
	v_cvt_pk_bf16_f32 v64, v30, v31
	v_cvt_pk_bf16_f32 v65, v32, v33
	v_permlane16_swap_b32_e32 v126, v128
	v_permlane16_swap_b32_e32 v127, v129
	v_permlane16_swap_b32_e32 v62, v64
	v_permlane16_swap_b32_e32 v63, v65
	v_mov_b32_dpp v224, v126 quad_perm:[1,0,3,2] row_mask:0xf bank_mask:0xf
	v_mov_b32_dpp v225, v127 quad_perm:[1,0,3,2] row_mask:0xf bank_mask:0xf
	v_mov_b32_dpp v226, v128 quad_perm:[1,0,3,2] row_mask:0xf bank_mask:0xf
	v_mov_b32_dpp v227, v129 quad_perm:[1,0,3,2] row_mask:0xf bank_mask:0xf
	v_mov_b32_dpp v220, v62 quad_perm:[1,0,3,2] row_mask:0xf bank_mask:0xf
	v_mov_b32_dpp v221, v63 quad_perm:[1,0,3,2] row_mask:0xf bank_mask:0xf
	v_mov_b32_dpp v222, v64 quad_perm:[1,0,3,2] row_mask:0xf bank_mask:0xf
	v_mov_b32_dpp v223, v65 quad_perm:[1,0,3,2] row_mask:0xf bank_mask:0xf
	v_cndmask_b32_e32 v62, v224, v62, vcc
	v_cndmask_b32_e32 v63, v225, v63, vcc
	v_cndmask_b32_e32 v64, v226, v64, vcc
	v_cndmask_b32_e32 v65, v227, v65, vcc
	v_cndmask_b32_e32 v126, v126, v220, vcc
	v_cndmask_b32_e32 v127, v127, v221, vcc
	v_cndmask_b32_e32 v128, v128, v222, vcc
	v_cndmask_b32_e32 v129, v129, v223, vcc
	global_store_dwordx4 v[140:141], v[126:129], off
	global_store_dwordx4 v[142:143], v[62:65], off
	v_lshl_add_u64 v[140:141], v[140:141], 0, s[8:9]
	v_lshl_add_u64 v[142:143], v[142:143], 0, s[8:9]
	v_cvt_pk_bf16_f32 v122, v122, v123
	v_cvt_pk_bf16_f32 v123, v124, v125
	v_cvt_pk_bf16_f32 v124, v90, v91
	v_cvt_pk_bf16_f32 v125, v92, v93
	v_cvt_pk_bf16_f32 v58, v58, v59
	v_cvt_pk_bf16_f32 v59, v60, v61
	v_cvt_pk_bf16_f32 v60, v26, v27
	v_cvt_pk_bf16_f32 v61, v28, v29
	v_permlane16_swap_b32_e32 v122, v124
	v_permlane16_swap_b32_e32 v123, v125
	v_permlane16_swap_b32_e32 v58, v60
	v_permlane16_swap_b32_e32 v59, v61
	v_mov_b32_dpp v224, v122 quad_perm:[1,0,3,2] row_mask:0xf bank_mask:0xf
	v_mov_b32_dpp v225, v123 quad_perm:[1,0,3,2] row_mask:0xf bank_mask:0xf
	v_mov_b32_dpp v226, v124 quad_perm:[1,0,3,2] row_mask:0xf bank_mask:0xf
	v_mov_b32_dpp v227, v125 quad_perm:[1,0,3,2] row_mask:0xf bank_mask:0xf
	v_mov_b32_dpp v220, v58 quad_perm:[1,0,3,2] row_mask:0xf bank_mask:0xf
	v_mov_b32_dpp v221, v59 quad_perm:[1,0,3,2] row_mask:0xf bank_mask:0xf
	v_mov_b32_dpp v222, v60 quad_perm:[1,0,3,2] row_mask:0xf bank_mask:0xf
	v_mov_b32_dpp v223, v61 quad_perm:[1,0,3,2] row_mask:0xf bank_mask:0xf
	v_cndmask_b32_e32 v58, v224, v58, vcc
	v_cndmask_b32_e32 v59, v225, v59, vcc
	v_cndmask_b32_e32 v60, v226, v60, vcc
	v_cndmask_b32_e32 v61, v227, v61, vcc
	v_cndmask_b32_e32 v122, v122, v220, vcc
	v_cndmask_b32_e32 v123, v123, v221, vcc
	v_cndmask_b32_e32 v124, v124, v222, vcc
	v_cndmask_b32_e32 v125, v125, v223, vcc
	global_store_dwordx4 v[140:141], v[122:125], off
	global_store_dwordx4 v[142:143], v[58:61], off
	v_lshl_add_u64 v[140:141], v[140:141], 0, s[8:9]
; DEVI unsigned pack2(float a, float b) { return __builtin_bit_cast(unsigned, __builtin_convertvector((f32x2_t){a, b}, bf16x2_t)); }
; DEVI float blo(unsigned u) { return __uint_as_float(u << 16); }
; DEVI float bhi(unsigned u) { return __uint_as_float(u & 0xffff0000u); }
;     ...
; #pragma unroll
;       for (int nf = 0; nf < 4; nf++) {
;         const int col = n0 + wn * 64 + nf * 16 + quad * 4;
;         f32x4 a = acc[nf][mf];
;         if (EPI == EPI_RESID || EPI == EPI_RESID_ATOMIC) {
;           f32x4 x = a;
;           if (EPI == EPI_RESID || kpart == 0) {
;             const u32x2 xr = *(const u32x2*)((const u16*)(p.ws + WS_XB) + (size_t)row * 1024 + col);
;             x[0] += ALPHA * blo(xr[0]); x[1] += ALPHA * bhi(xr[0]); x[2] += ALPHA * blo(xr[1]); x[3] += ALPHA * bhi(xr[1]);
;           }
;           if (EPI == EPI_RESID) *(f32x4*)((float*)(p.ws + WS_XF) + (size_t)row * 1024 + col) = x;
;           else *(f32x4*)((float*)(p.ws + WS_SLAB) + ((size_t)kpart * 512 + (row - T_P)) * 1024 + col) = x;
;         } else {
;           u32x2 pk; pk[0] = pack2(a[0], a[1]); pk[1] = pack2(a[2], a[3]);
;           *(u32x2*)(outb + (size_t)row * ldc + col) = pk;
;         }
	v_lshl_add_u64 v[142:143], v[142:143], 0, s[8:9]
	v_cvt_pk_bf16_f32 v118, v118, v119
	v_cvt_pk_bf16_f32 v119, v120, v121
	v_cvt_pk_bf16_f32 v120, v86, v87
	v_cvt_pk_bf16_f32 v121, v88, v89
	v_cvt_pk_bf16_f32 v54, v54, v55
	v_cvt_pk_bf16_f32 v55, v56, v57
	v_cvt_pk_bf16_f32 v56, v22, v23
	v_cvt_pk_bf16_f32 v57, v24, v25
	v_permlane16_swap_b32_e32 v118, v120
	v_permlane16_swap_b32_e32 v119, v121
	v_permlane16_swap_b32_e32 v54, v56
	v_permlane16_swap_b32_e32 v55, v57
	v_mov_b32_dpp v224, v118 quad_perm:[1,0,3,2] row_mask:0xf bank_mask:0xf
	v_mov_b32_dpp v225, v119 quad_perm:[1,0,3,2] row_mask:0xf bank_mask:0xf
	v_mov_b32_dpp v226, v120 quad_perm:[1,0,3,2] row_mask:0xf bank_mask:0xf
	v_mov_b32_dpp v227, v121 quad_perm:[1,0,3,2] row_mask:0xf bank_mask:0xf
	v_mov_b32_dpp v220, v54 quad_perm:[1,0,3,2] row_mask:0xf bank_mask:0xf
	v_mov_b32_dpp v221, v55 quad_perm:[1,0,3,2] row_mask:0xf bank_mask:0xf
	v_mov_b32_dpp v222, v56 quad_perm:[1,0,3,2] row_mask:0xf bank_mask:0xf
	v_mov_b32_dpp v223, v57 quad_perm:[1,0,3,2] row_mask:0xf bank_mask:0xf
	v_cndmask_b32_e32 v54, v224, v54, vcc
	v_cndmask_b32_e32 v55, v225, v55, vcc
	v_cndmask_b32_e32 v56, v226, v56, vcc
	v_cndmask_b32_e32 v57, v227, v57, vcc
	v_cndmask_b32_e32 v118, v118, v220, vcc
	v_cndmask_b32_e32 v119, v119, v221, vcc
	v_cndmask_b32_e32 v120, v120, v222, vcc
	v_cndmask_b32_e32 v121, v121, v223, vcc
	global_store_dwordx4 v[140:141], v[118:121], off
	global_store_dwordx4 v[142:143], v[54:57], off
	v_lshl_add_u64 v[140:141], v[140:141], 0, s[8:9]
	v_lshl_add_u64 v[142:143], v[142:143], 0, s[8:9]
	v_cvt_pk_bf16_f32 v114, v114, v115
	v_cvt_pk_bf16_f32 v115, v116, v117
	v_cvt_pk_bf16_f32 v116, v82, v83
	v_cvt_pk_bf16_f32 v117, v84, v85
	v_cvt_pk_bf16_f32 v50, v50, v51
	v_cvt_pk_bf16_f32 v51, v52, v53
	v_cvt_pk_bf16_f32 v52, v18, v19
	v_cvt_pk_bf16_f32 v53, v20, v21
	v_permlane16_swap_b32_e32 v114, v116
	v_permlane16_swap_b32_e32 v115, v117
	v_permlane16_swap_b32_e32 v50, v52
	v_permlane16_swap_b32_e32 v51, v53
	v_mov_b32_dpp v224, v114 quad_perm:[1,0,3,2] row_mask:0xf bank_mask:0xf
	v_mov_b32_dpp v225, v115 quad_perm:[1,0,3,2] row_mask:0xf bank_mask:0xf
	v_mov_b32_dpp v226, v116 quad_perm:[1,0,3,2] row_mask:0xf bank_mask:0xf
	v_mov_b32_dpp v227, v117 quad_perm:[1,0,3,2] row_mask:0xf bank_mask:0xf
	v_mov_b32_dpp v220, v50 quad_perm:[1,0,3,2] row_mask:0xf bank_mask:0xf
	v_mov_b32_dpp v221, v51 quad_perm:[1,0,3,2] row_mask:0xf bank_mask:0xf
	v_mov_b32_dpp v222, v52 quad_perm:[1,0,3,2] row_mask:0xf bank_mask:0xf
	v_mov_b32_dpp v223, v53 quad_perm:[1,0,3,2] row_mask:0xf bank_mask:0xf
	v_cndmask_b32_e32 v50, v224, v50, vcc
	v_cndmask_b32_e32 v51, v225, v51, vcc
	v_cndmask_b32_e32 v52, v226, v52, vcc
	v_cndmask_b32_e32 v53, v227, v53, vcc
	v_cndmask_b32_e32 v114, v114, v220, vcc
	v_cndmask_b32_e32 v115, v115, v221, vcc
	v_cndmask_b32_e32 v116, v116, v222, vcc
	v_cndmask_b32_e32 v117, v117, v223, vcc
	global_store_dwordx4 v[140:141], v[114:117], off
	global_store_dwordx4 v[142:143], v[50:53], off
	v_lshl_add_u64 v[140:141], v[140:141], 0, s[8:9]
	v_lshl_add_u64 v[142:143], v[142:143], 0, s[8:9]
	v_cvt_pk_bf16_f32 v110, v110, v111
	v_cvt_pk_bf16_f32 v111, v112, v113
	v_cvt_pk_bf16_f32 v112, v78, v79
	v_cvt_pk_bf16_f32 v113, v80, v81
	v_cvt_pk_bf16_f32 v46, v46, v47
	v_cvt_pk_bf16_f32 v47, v48, v49
	v_cvt_pk_bf16_f32 v48, v14, v15
	v_cvt_pk_bf16_f32 v49, v16, v17
	v_permlane16_swap_b32_e32 v110, v112
	v_permlane16_swap_b32_e32 v111, v113
	v_permlane16_swap_b32_e32 v46, v48
	v_permlane16_swap_b32_e32 v47, v49
	v_mov_b32_dpp v224, v110 quad_perm:[1,0,3,2] row_mask:0xf bank_mask:0xf
	v_mov_b32_dpp v225, v111 quad_perm:[1,0,3,2] row_mask:0xf bank_mask:0xf
	v_mov_b32_dpp v226, v112 quad_perm:[1,0,3,2] row_mask:0xf bank_mask:0xf
	v_mov_b32_dpp v227, v113 quad_perm:[1,0,3,2] row_mask:0xf bank_mask:0xf
	v_mov_b32_dpp v220, v46 quad_perm:[1,0,3,2] row_mask:0xf bank_mask:0xf
	v_mov_b32_dpp v221, v47 quad_perm:[1,0,3,2] row_mask:0xf bank_mask:0xf
	v_mov_b32_dpp v222, v48 quad_perm:[1,0,3,2] row_mask:0xf bank_mask:0xf
	v_mov_b32_dpp v223, v49 quad_perm:[1,0,3,2] row_mask:0xf bank_mask:0xf
	v_cndmask_b32_e32 v46, v224, v46, vcc
	v_cndmask_b32_e32 v47, v225, v47, vcc
	v_cndmask_b32_e32 v48, v226, v48, vcc
	v_cndmask_b32_e32 v49, v227, v49, vcc
	v_cndmask_b32_e32 v110, v110, v220, vcc
	v_cndmask_b32_e32 v111, v111, v221, vcc
	v_cndmask_b32_e32 v112, v112, v222, vcc
	v_cndmask_b32_e32 v113, v113, v223, vcc
	global_store_dwordx4 v[140:141], v[110:113], off
	global_store_dwordx4 v[142:143], v[46:49], off
; DEVI unsigned pack2(float a, float b) { return __builtin_bit_cast(unsigned, __builtin_convertvector((f32x2_t){a, b}, bf16x2_t)); }
; DEVI float blo(unsigned u) { return __uint_as_float(u << 16); }
; DEVI float bhi(unsigned u) { return __uint_as_float(u & 0xffff0000u); }
;     ...
; #pragma unroll
;       for (int nf = 0; nf < 4; nf++) {
;         const int col = n0 + wn * 64 + nf * 16 + quad * 4;
;         f32x4 a = acc[nf][mf];
;         if (EPI == EPI_RESID || EPI == EPI_RESID_ATOMIC) {
;           f32x4 x = a;
;           if (EPI == EPI_RESID || kpart == 0) {
;             const u32x2 xr = *(const u32x2*)((const u16*)(p.ws + WS_XB) + (size_t)row * 1024 + col);
;             x[0] += ALPHA * blo(xr[0]); x[1] += ALPHA * bhi(xr[0]); x[2] += ALPHA * blo(xr[1]); x[3] += ALPHA * bhi(xr[1]);
;           }
;           if (EPI == EPI_RESID) *(f32x4*)((float*)(p.ws + WS_XF) + (size_t)row * 1024 + col) = x;
;           else *(f32x4*)((float*)(p.ws + WS_SLAB) + ((size_t)kpart * 512 + (row - T_P)) * 1024 + col) = x;
;         } else {
;           u32x2 pk; pk[0] = pack2(a[0], a[1]); pk[1] = pack2(a[2], a[3]);
;           *(u32x2*)(outb + (size_t)row * ldc + col) = pk;
;         }
	v_lshl_add_u64 v[140:141], v[140:141], 0, s[8:9]
	v_lshl_add_u64 v[142:143], v[142:143], 0, s[8:9]
	v_cvt_pk_bf16_f32 v106, v106, v107
	v_cvt_pk_bf16_f32 v107, v108, v109
	v_cvt_pk_bf16_f32 v108, v74, v75
	v_cvt_pk_bf16_f32 v109, v76, v77
	v_cvt_pk_bf16_f32 v42, v42, v43
	v_cvt_pk_bf16_f32 v43, v44, v45
	v_cvt_pk_bf16_f32 v44, v10, v11
	v_cvt_pk_bf16_f32 v45, v12, v13
	v_permlane16_swap_b32_e32 v106, v108
	v_permlane16_swap_b32_e32 v107, v109
	v_permlane16_swap_b32_e32 v42, v44
	v_permlane16_swap_b32_e32 v43, v45
	v_mov_b32_dpp v224, v106 quad_perm:[1,0,3,2] row_mask:0xf bank_mask:0xf
	v_mov_b32_dpp v225, v107 quad_perm:[1,0,3,2] row_mask:0xf bank_mask:0xf
	v_mov_b32_dpp v226, v108 quad_perm:[1,0,3,2] row_mask:0xf bank_mask:0xf
	v_mov_b32_dpp v227, v109 quad_perm:[1,0,3,2] row_mask:0xf bank_mask:0xf
	v_mov_b32_dpp v220, v42 quad_perm:[1,0,3,2] row_mask:0xf bank_mask:0xf
	v_mov_b32_dpp v221, v43 quad_perm:[1,0,3,2] row_mask:0xf bank_mask:0xf
	v_mov_b32_dpp v222, v44 quad_perm:[1,0,3,2] row_mask:0xf bank_mask:0xf
	v_mov_b32_dpp v223, v45 quad_perm:[1,0,3,2] row_mask:0xf bank_mask:0xf
	v_cndmask_b32_e32 v42, v224, v42, vcc
	v_cndmask_b32_e32 v43, v225, v43, vcc
	v_cndmask_b32_e32 v44, v226, v44, vcc
	v_cndmask_b32_e32 v45, v227, v45, vcc
	v_cndmask_b32_e32 v106, v106, v220, vcc
	v_cndmask_b32_e32 v107, v107, v221, vcc
	v_cndmask_b32_e32 v108, v108, v222, vcc
	v_cndmask_b32_e32 v109, v109, v223, vcc
	global_store_dwordx4 v[140:141], v[106:109], off
	global_store_dwordx4 v[142:143], v[42:45], off
	v_lshl_add_u64 v[140:141], v[140:141], 0, s[8:9]
	v_lshl_add_u64 v[142:143], v[142:143], 0, s[8:9]
	v_cvt_pk_bf16_f32 v102, v102, v103
	v_cvt_pk_bf16_f32 v103, v104, v105
	v_cvt_pk_bf16_f32 v104, v70, v71
	v_cvt_pk_bf16_f32 v105, v72, v73
	v_cvt_pk_bf16_f32 v38, v38, v39
	v_cvt_pk_bf16_f32 v39, v40, v41
	v_cvt_pk_bf16_f32 v40, v6, v7
	v_cvt_pk_bf16_f32 v41, v8, v9
	v_permlane16_swap_b32_e32 v102, v104
	v_permlane16_swap_b32_e32 v103, v105
	v_permlane16_swap_b32_e32 v38, v40
	v_permlane16_swap_b32_e32 v39, v41
	v_mov_b32_dpp v224, v102 quad_perm:[1,0,3,2] row_mask:0xf bank_mask:0xf
	v_mov_b32_dpp v225, v103 quad_perm:[1,0,3,2] row_mask:0xf bank_mask:0xf
	v_mov_b32_dpp v226, v104 quad_perm:[1,0,3,2] row_mask:0xf bank_mask:0xf
	v_mov_b32_dpp v227, v105 quad_perm:[1,0,3,2] row_mask:0xf bank_mask:0xf
	v_mov_b32_dpp v220, v38 quad_perm:[1,0,3,2] row_mask:0xf bank_mask:0xf
	v_mov_b32_dpp v221, v39 quad_perm:[1,0,3,2] row_mask:0xf bank_mask:0xf
	v_mov_b32_dpp v222, v40 quad_perm:[1,0,3,2] row_mask:0xf bank_mask:0xf
	v_mov_b32_dpp v223, v41 quad_perm:[1,0,3,2] row_mask:0xf bank_mask:0xf
	v_cndmask_b32_e32 v38, v224, v38, vcc
	v_cndmask_b32_e32 v39, v225, v39, vcc
	v_cndmask_b32_e32 v40, v226, v40, vcc
	v_cndmask_b32_e32 v41, v227, v41, vcc
	v_cndmask_b32_e32 v102, v102, v220, vcc
	v_cndmask_b32_e32 v103, v103, v221, vcc
	v_cndmask_b32_e32 v104, v104, v222, vcc
	v_cndmask_b32_e32 v105, v105, v223, vcc
	global_store_dwordx4 v[140:141], v[102:105], off
	global_store_dwordx4 v[142:143], v[38:41], off
	v_lshl_add_u64 v[140:141], v[140:141], 0, s[8:9]
	v_lshl_add_u64 v[142:143], v[142:143], 0, s[8:9]
	v_cvt_pk_bf16_f32 v98, v98, v99
	v_cvt_pk_bf16_f32 v99, v100, v101
	v_cvt_pk_bf16_f32 v100, v66, v67
	v_cvt_pk_bf16_f32 v101, v68, v69
	v_cvt_pk_bf16_f32 v34, v34, v35
	v_cvt_pk_bf16_f32 v35, v36, v37
	v_cvt_pk_bf16_f32 v36, v2, v3
	v_cvt_pk_bf16_f32 v37, v4, v5
	v_permlane16_swap_b32_e32 v98, v100
	v_permlane16_swap_b32_e32 v99, v101
	v_permlane16_swap_b32_e32 v34, v36
	v_permlane16_swap_b32_e32 v35, v37
	v_mov_b32_dpp v224, v98 quad_perm:[1,0,3,2] row_mask:0xf bank_mask:0xf
	v_mov_b32_dpp v225, v99 quad_perm:[1,0,3,2] row_mask:0xf bank_mask:0xf
	v_mov_b32_dpp v226, v100 quad_perm:[1,0,3,2] row_mask:0xf bank_mask:0xf
	v_mov_b32_dpp v227, v101 quad_perm:[1,0,3,2] row_mask:0xf bank_mask:0xf
	v_mov_b32_dpp v220, v34 quad_perm:[1,0,3,2] row_mask:0xf bank_mask:0xf
	v_mov_b32_dpp v221, v35 quad_perm:[1,0,3,2] row_mask:0xf bank_mask:0xf
	v_mov_b32_dpp v222, v36 quad_perm:[1,0,3,2] row_mask:0xf bank_mask:0xf
	v_mov_b32_dpp v223, v37 quad_perm:[1,0,3,2] row_mask:0xf bank_mask:0xf
	v_cndmask_b32_e32 v34, v224, v34, vcc
	v_cndmask_b32_e32 v35, v225, v35, vcc
	v_cndmask_b32_e32 v36, v226, v36, vcc
	v_cndmask_b32_e32 v37, v227, v37, vcc
	v_cndmask_b32_e32 v98, v98, v220, vcc
	v_cndmask_b32_e32 v99, v99, v221, vcc
	v_cndmask_b32_e32 v100, v100, v222, vcc
	v_cndmask_b32_e32 v101, v101, v223, vcc
	global_store_dwordx4 v[140:141], v[98:101], off
	global_store_dwordx4 v[142:143], v[34:37], off
	s_branch .LBB0_886
